# GEMM K-loops: back-edge rotation - counter / pointer updates and exit test moved in front of the loop-closing barrier; chained DMA base adds in front of the block-1 barrier
# baseline (speedup 1.0000x reference)
.LBB0_154:
	ds_read_b128 v[180:183], v163
	ds_read_b128 v[184:187], v164
	ds_read_b128 v[188:191], v165
	ds_read_b128 v[196:199], v167
	ds_read_b128 v[200:203], v168
	ds_read_b128 v[204:207], v169
	ds_read_b128 v[208:211], v170
	ds_read_b128 v[212:215], v171
	s_add_u32 s12, s10, 0xfffc0080
	s_addc_u32 s13, s11, -1
	s_cmp_eq_u32 s54, 12
	s_cselect_b32 s37, s5, s13
	s_cselect_b32 s36, s7, s12
	s_cselect_b32 s13, s27, s39
	s_cselect_b32 s12, s29, s38
	s_mov_b32 m0, s85
	ds_read_b128 v[216:219], v145
	ds_read_b128 v[220:223], v145 offset:1024
	ds_read_b128 v[224:227], v145 offset:2048
	ds_read_b128 v[228:231], v145 offset:3072
	ds_read_b128 v[232:235], v145 offset:4096
	ds_read_b128 v[236:239], v145 offset:5120
	ds_read_b128 v[240:243], v145 offset:6144
	ds_read_b128 v[244:247], v145 offset:7168
	global_load_lds_dwordx4 v138, s[10:11]
	s_mov_b32 m0, s86
	s_nop 0
	global_load_lds_dwordx4 v140, s[10:11]
	s_waitcnt vmcnt(8)
	s_waitcnt lgkmcnt(0)
	s_barrier
	v_mfma_f32_16x16x32_bf16 v[124:127], v[180:183], v[216:219], v[124:127]
	v_mfma_f32_16x16x32_bf16 v[120:123], v[188:191], v[216:219], v[120:123]
	v_mfma_f32_16x16x32_bf16 v[108:111], v[180:183], v[224:227], v[108:111]
	v_mfma_f32_16x16x32_bf16 v[104:107], v[188:191], v[224:227], v[104:107]
	v_mfma_f32_16x16x32_bf16 v[92:95], v[180:183], v[232:235], v[92:95]
	v_mfma_f32_16x16x32_bf16 v[88:91], v[188:191], v[232:235], v[88:91]
	v_mfma_f32_16x16x32_bf16 v[76:79], v[180:183], v[240:243], v[76:79]
	v_mfma_f32_16x16x32_bf16 v[72:75], v[188:191], v[240:243], v[72:75]
	v_mfma_f32_16x16x32_bf16 v[124:127], v[184:187], v[220:223], v[124:127]
	v_mfma_f32_16x16x32_bf16 v[120:123], v[196:199], v[220:223], v[120:123]
	v_mfma_f32_16x16x32_bf16 v[108:111], v[184:187], v[228:231], v[108:111]
	v_mfma_f32_16x16x32_bf16 v[104:107], v[196:199], v[228:231], v[104:107]
	v_mfma_f32_16x16x32_bf16 v[92:95], v[184:187], v[236:239], v[92:95]
	v_mfma_f32_16x16x32_bf16 v[88:91], v[196:199], v[236:239], v[88:91]
	v_mfma_f32_16x16x32_bf16 v[76:79], v[184:187], v[244:247], v[76:79]
	v_mfma_f32_16x16x32_bf16 v[72:75], v[196:199], v[244:247], v[72:75]
	v_mfma_f32_16x16x32_bf16 v[116:119], v[200:203], v[216:219], v[116:119]
	v_mfma_f32_16x16x32_bf16 v[112:115], v[208:211], v[216:219], v[112:115]
	v_mfma_f32_16x16x32_bf16 v[100:103], v[200:203], v[224:227], v[100:103]
	v_mfma_f32_16x16x32_bf16 v[96:99], v[208:211], v[224:227], v[96:99]
	v_mfma_f32_16x16x32_bf16 v[84:87], v[200:203], v[232:235], v[84:87]
	v_mfma_f32_16x16x32_bf16 v[80:83], v[208:211], v[232:235], v[80:83]
	v_mfma_f32_16x16x32_bf16 v[68:71], v[200:203], v[240:243], v[68:71]
	v_mfma_f32_16x16x32_bf16 v[64:67], v[208:211], v[240:243], v[64:67]
	v_mfma_f32_16x16x32_bf16 v[116:119], v[204:207], v[220:223], v[116:119]
	v_mfma_f32_16x16x32_bf16 v[112:115], v[212:215], v[220:223], v[112:115]
	v_mfma_f32_16x16x32_bf16 v[100:103], v[204:207], v[228:231], v[100:103]
	v_mfma_f32_16x16x32_bf16 v[96:99], v[212:215], v[228:231], v[96:99]
	v_mfma_f32_16x16x32_bf16 v[84:87], v[204:207], v[236:239], v[84:87]
	v_mfma_f32_16x16x32_bf16 v[80:83], v[212:215], v[236:239], v[80:83]
	v_mfma_f32_16x16x32_bf16 v[68:71], v[204:207], v[244:247], v[68:71]
	v_mfma_f32_16x16x32_bf16 v[64:67], v[212:215], v[244:247], v[64:67]
	s_add_u32 s98, s12, s20
	s_addc_u32 s99, s13, s21
	s_add_u32 s100, s36, s20
	s_addc_u32 s101, s37, s21
	s_barrier
	s_mov_b32 m0, s25
	s_add_u32 s56, s12, 0x40000
	ds_read_b128 v[216:219], v145 offset:16384
	ds_read_b128 v[220:223], v145 offset:17408
	ds_read_b128 v[224:227], v145 offset:18432
	ds_read_b128 v[228:231], v145 offset:19456
	ds_read_b128 v[232:235], v145 offset:20480
	ds_read_b128 v[236:239], v145 offset:21504
	ds_read_b128 v[240:243], v145 offset:22528
	ds_read_b128 v[244:247], v145 offset:23552
	global_load_lds_dwordx4 v132, s[12:13]
	s_mov_b32 m0, s33
	s_addc_u32 s57, s13, 0
	global_load_lds_dwordx4 v134, s[12:13]
	s_mov_b32 m0, s62
	s_nop 0
	global_load_lds_dwordx4 v132, s[56:57]
	s_mov_b32 m0, s63
	s_nop 0
	global_load_lds_dwordx4 v134, s[56:57]
	s_mov_b32 m0, s2
	s_nop 0
	global_load_lds_dwordx4 v132, s[36:37]
	s_mov_b32 m0, s64
	s_nop 0
	global_load_lds_dwordx4 v134, s[36:37]
	s_waitcnt vmcnt(8)
	s_waitcnt lgkmcnt(0)
	s_barrier
	v_mfma_f32_16x16x32_bf16 v[60:63], v[180:183], v[216:219], v[60:63]
	v_mfma_f32_16x16x32_bf16 v[56:59], v[188:191], v[216:219], v[56:59]
	v_mfma_f32_16x16x32_bf16 v[44:47], v[180:183], v[224:227], v[44:47]
	v_mfma_f32_16x16x32_bf16 v[40:43], v[188:191], v[224:227], v[40:43]
	v_mfma_f32_16x16x32_bf16 v[28:31], v[180:183], v[232:235], v[28:31]
	v_mfma_f32_16x16x32_bf16 v[24:27], v[188:191], v[232:235], v[24:27]
	v_mfma_f32_16x16x32_bf16 v[12:15], v[180:183], v[240:243], v[12:15]
	v_mfma_f32_16x16x32_bf16 v[8:11], v[188:191], v[240:243], v[8:11]
	v_mfma_f32_16x16x32_bf16 v[60:63], v[184:187], v[220:223], v[60:63]
	v_mfma_f32_16x16x32_bf16 v[56:59], v[196:199], v[220:223], v[56:59]
	v_mfma_f32_16x16x32_bf16 v[44:47], v[184:187], v[228:231], v[44:47]
	v_mfma_f32_16x16x32_bf16 v[40:43], v[196:199], v[228:231], v[40:43]
	v_mfma_f32_16x16x32_bf16 v[28:31], v[184:187], v[236:239], v[28:31]
	v_mfma_f32_16x16x32_bf16 v[24:27], v[196:199], v[236:239], v[24:27]
	v_mfma_f32_16x16x32_bf16 v[12:15], v[184:187], v[244:247], v[12:15]
	v_mfma_f32_16x16x32_bf16 v[8:11], v[196:199], v[244:247], v[8:11]
	v_mfma_f32_16x16x32_bf16 v[52:55], v[200:203], v[216:219], v[52:55]
	v_mfma_f32_16x16x32_bf16 v[48:51], v[208:211], v[216:219], v[48:51]
	v_mfma_f32_16x16x32_bf16 v[36:39], v[200:203], v[224:227], v[36:39]
	v_mfma_f32_16x16x32_bf16 v[32:35], v[208:211], v[224:227], v[32:35]
	v_mfma_f32_16x16x32_bf16 v[20:23], v[200:203], v[232:235], v[20:23]
	v_mfma_f32_16x16x32_bf16 v[16:19], v[208:211], v[232:235], v[16:19]
	v_mfma_f32_16x16x32_bf16 v[4:7], v[200:203], v[240:243], v[4:7]
	v_mfma_f32_16x16x32_bf16 v[0:3], v[208:211], v[240:243], v[0:3]
	v_mfma_f32_16x16x32_bf16 v[52:55], v[204:207], v[220:223], v[52:55]
	v_mfma_f32_16x16x32_bf16 v[48:51], v[212:215], v[220:223], v[48:51]
	v_mfma_f32_16x16x32_bf16 v[36:39], v[204:207], v[228:231], v[36:39]
	v_mfma_f32_16x16x32_bf16 v[32:35], v[212:215], v[228:231], v[32:35]
	v_mfma_f32_16x16x32_bf16 v[20:23], v[204:207], v[236:239], v[20:23]
	v_mfma_f32_16x16x32_bf16 v[16:19], v[212:215], v[236:239], v[16:19]
	v_mfma_f32_16x16x32_bf16 v[4:7], v[204:207], v[244:247], v[4:7]
	v_mfma_f32_16x16x32_bf16 v[0:3], v[212:215], v[244:247], v[0:3]
	s_barrier
	ds_read_b128 v[180:183], v172
	ds_read_b128 v[184:187], v173
	ds_read_b128 v[188:191], v174
	ds_read_b128 v[196:199], v175
	ds_read_b128 v[200:203], v176
	ds_read_b128 v[204:207], v177
	ds_read_b128 v[208:211], v178
	ds_read_b128 v[212:215], v179
	s_add_u32 s36, s36, 0x40000
	s_addc_u32 s37, s37, 0
	s_mov_b32 m0, s65
	ds_read_b128 v[216:219], v145 offset:32768
	ds_read_b128 v[220:223], v145 offset:33792
	ds_read_b128 v[224:227], v145 offset:34816
	ds_read_b128 v[228:231], v145 offset:35840
	ds_read_b128 v[232:235], v145 offset:36864
	ds_read_b128 v[236:239], v145 offset:37888
	ds_read_b128 v[240:243], v145 offset:38912
	ds_read_b128 v[244:247], v145 offset:39936
	global_load_lds_dwordx4 v132, s[36:37]
	s_mov_b32 m0, s66
	s_nop 0
	global_load_lds_dwordx4 v134, s[36:37]
	s_waitcnt vmcnt(8)
	s_waitcnt lgkmcnt(0)
	s_barrier
	v_mfma_f32_16x16x32_bf16 v[124:127], v[180:183], v[216:219], v[124:127]
	v_mfma_f32_16x16x32_bf16 v[120:123], v[188:191], v[216:219], v[120:123]
	v_mfma_f32_16x16x32_bf16 v[108:111], v[180:183], v[224:227], v[108:111]
	v_mfma_f32_16x16x32_bf16 v[104:107], v[188:191], v[224:227], v[104:107]
	v_mfma_f32_16x16x32_bf16 v[92:95], v[180:183], v[232:235], v[92:95]
	v_mfma_f32_16x16x32_bf16 v[88:91], v[188:191], v[232:235], v[88:91]
	v_mfma_f32_16x16x32_bf16 v[76:79], v[180:183], v[240:243], v[76:79]
	v_mfma_f32_16x16x32_bf16 v[72:75], v[188:191], v[240:243], v[72:75]
	v_mfma_f32_16x16x32_bf16 v[124:127], v[184:187], v[220:223], v[124:127]
	v_mfma_f32_16x16x32_bf16 v[120:123], v[196:199], v[220:223], v[120:123]
	v_mfma_f32_16x16x32_bf16 v[108:111], v[184:187], v[228:231], v[108:111]
	v_mfma_f32_16x16x32_bf16 v[104:107], v[196:199], v[228:231], v[104:107]
	v_mfma_f32_16x16x32_bf16 v[92:95], v[184:187], v[236:239], v[92:95]
	v_mfma_f32_16x16x32_bf16 v[88:91], v[196:199], v[236:239], v[88:91]
	v_mfma_f32_16x16x32_bf16 v[76:79], v[184:187], v[244:247], v[76:79]
	v_mfma_f32_16x16x32_bf16 v[72:75], v[196:199], v[244:247], v[72:75]
	v_mfma_f32_16x16x32_bf16 v[116:119], v[200:203], v[216:219], v[116:119]
	v_mfma_f32_16x16x32_bf16 v[112:115], v[208:211], v[216:219], v[112:115]
	v_mfma_f32_16x16x32_bf16 v[100:103], v[200:203], v[224:227], v[100:103]
	v_mfma_f32_16x16x32_bf16 v[96:99], v[208:211], v[224:227], v[96:99]
	v_mfma_f32_16x16x32_bf16 v[84:87], v[200:203], v[232:235], v[84:87]
	v_mfma_f32_16x16x32_bf16 v[80:83], v[208:211], v[232:235], v[80:83]
	v_mfma_f32_16x16x32_bf16 v[68:71], v[200:203], v[240:243], v[68:71]
	v_mfma_f32_16x16x32_bf16 v[64:67], v[208:211], v[240:243], v[64:67]
	v_mfma_f32_16x16x32_bf16 v[116:119], v[204:207], v[220:223], v[116:119]
	v_mfma_f32_16x16x32_bf16 v[112:115], v[212:215], v[220:223], v[112:115]
	v_mfma_f32_16x16x32_bf16 v[100:103], v[204:207], v[228:231], v[100:103]
	v_mfma_f32_16x16x32_bf16 v[96:99], v[212:215], v[228:231], v[96:99]
	v_mfma_f32_16x16x32_bf16 v[84:87], v[204:207], v[236:239], v[84:87]
	v_mfma_f32_16x16x32_bf16 v[80:83], v[212:215], v[236:239], v[80:83]
	v_mfma_f32_16x16x32_bf16 v[68:71], v[204:207], v[244:247], v[68:71]
	v_mfma_f32_16x16x32_bf16 v[64:67], v[212:215], v[244:247], v[64:67]
	s_barrier
	s_mov_b32 m0, s67
	s_add_u32 s12, s12, 0x40080
	ds_read_b128 v[216:219], v145 offset:49152
	ds_read_b128 v[220:223], v145 offset:50176
	ds_read_b128 v[224:227], v145 offset:51200
	ds_read_b128 v[228:231], v145 offset:52224
	ds_read_b128 v[232:235], v145 offset:53248
	ds_read_b128 v[236:239], v145 offset:54272
	ds_read_b128 v[240:243], v145 offset:55296
	ds_read_b128 v[244:247], v145 offset:56320
	global_load_lds_dwordx4 v132, s[98:99]
	s_mov_b32 m0, s72
	s_addc_u32 s13, s13, 0
	global_load_lds_dwordx4 v134, s[98:99]
	s_mov_b32 m0, s75
	s_nop 0
	global_load_lds_dwordx4 v132, s[12:13]
	s_mov_b32 m0, s78
	s_nop 0
	global_load_lds_dwordx4 v134, s[12:13]
	s_mov_b32 m0, s73
	s_nop 0
	global_load_lds_dwordx4 v132, s[100:101]
	s_mov_b32 m0, s74
	s_nop 0
	global_load_lds_dwordx4 v134, s[100:101]
	s_waitcnt vmcnt(8)
	s_waitcnt lgkmcnt(0)
	s_barrier
	v_mfma_f32_16x16x32_bf16 v[60:63], v[180:183], v[216:219], v[60:63]
	v_mfma_f32_16x16x32_bf16 v[56:59], v[188:191], v[216:219], v[56:59]
	v_mfma_f32_16x16x32_bf16 v[44:47], v[180:183], v[224:227], v[44:47]
	v_mfma_f32_16x16x32_bf16 v[40:43], v[188:191], v[224:227], v[40:43]
	v_mfma_f32_16x16x32_bf16 v[28:31], v[180:183], v[232:235], v[28:31]
	v_mfma_f32_16x16x32_bf16 v[24:27], v[188:191], v[232:235], v[24:27]
	v_mfma_f32_16x16x32_bf16 v[12:15], v[180:183], v[240:243], v[12:15]
	v_mfma_f32_16x16x32_bf16 v[8:11], v[188:191], v[240:243], v[8:11]
	v_mfma_f32_16x16x32_bf16 v[60:63], v[184:187], v[220:223], v[60:63]
	v_mfma_f32_16x16x32_bf16 v[56:59], v[196:199], v[220:223], v[56:59]
	v_mfma_f32_16x16x32_bf16 v[44:47], v[184:187], v[228:231], v[44:47]
	v_mfma_f32_16x16x32_bf16 v[40:43], v[196:199], v[228:231], v[40:43]
	v_mfma_f32_16x16x32_bf16 v[28:31], v[184:187], v[236:239], v[28:31]
	v_mfma_f32_16x16x32_bf16 v[24:27], v[196:199], v[236:239], v[24:27]
	v_mfma_f32_16x16x32_bf16 v[12:15], v[184:187], v[244:247], v[12:15]
	v_mfma_f32_16x16x32_bf16 v[8:11], v[196:199], v[244:247], v[8:11]
	v_mfma_f32_16x16x32_bf16 v[52:55], v[200:203], v[216:219], v[52:55]
	v_mfma_f32_16x16x32_bf16 v[48:51], v[208:211], v[216:219], v[48:51]
	v_mfma_f32_16x16x32_bf16 v[36:39], v[200:203], v[224:227], v[36:39]
	v_mfma_f32_16x16x32_bf16 v[32:35], v[208:211], v[224:227], v[32:35]
	v_mfma_f32_16x16x32_bf16 v[20:23], v[200:203], v[232:235], v[20:23]
	v_mfma_f32_16x16x32_bf16 v[16:19], v[208:211], v[232:235], v[16:19]
	v_mfma_f32_16x16x32_bf16 v[4:7], v[200:203], v[240:243], v[4:7]
	v_mfma_f32_16x16x32_bf16 v[0:3], v[208:211], v[240:243], v[0:3]
	v_mfma_f32_16x16x32_bf16 v[52:55], v[204:207], v[220:223], v[52:55]
	v_mfma_f32_16x16x32_bf16 v[48:51], v[212:215], v[220:223], v[48:51]
	v_mfma_f32_16x16x32_bf16 v[36:39], v[204:207], v[228:231], v[36:39]
	v_mfma_f32_16x16x32_bf16 v[32:35], v[212:215], v[228:231], v[32:35]
	v_mfma_f32_16x16x32_bf16 v[20:23], v[204:207], v[236:239], v[20:23]
	v_mfma_f32_16x16x32_bf16 v[16:19], v[212:215], v[236:239], v[16:19]
	v_mfma_f32_16x16x32_bf16 v[4:7], v[204:207], v[244:247], v[4:7]
	v_mfma_f32_16x16x32_bf16 v[0:3], v[212:215], v[244:247], v[0:3]
	s_add_i32 s54, s54, 2
	s_add_u32 s10, s10, 0x100
	s_addc_u32 s11, s11, 0
	s_add_u32 s38, s38, 0x100
	s_addc_u32 s39, s39, 0
	s_cmp_gt_u32 s54, 13
	s_barrier
	s_cbranch_scc0 .LBB0_154
	s_and_b64 vcc, exec, s[22:23]
	s_cbranch_vccz .LBB0_157
	s_barrier

.LBB0_251:
	ds_read_b128 v[160:163], v165
	ds_read_b128 v[182:185], v167
	ds_read_b128 v[186:189], v168
	ds_read_b128 v[190:193], v169
	ds_read_b128 v[196:199], v170
	ds_read_b128 v[200:203], v171
	ds_read_b128 v[204:207], v172
	ds_read_b128 v[208:211], v173
	s_add_u32 s14, s12, 0xfffc0080
	s_addc_u32 s15, s13, -1
	s_cmp_eq_u32 s54, 12
	s_cselect_b32 s29, s7, s15
	s_cselect_b32 s28, s11, s14
	s_cselect_b32 s15, s21, s39
	s_cselect_b32 s14, s23, s38
	s_mov_b32 m0, s82
	ds_read_b128 v[212:215], v145
	ds_read_b128 v[216:219], v145 offset:1024
	ds_read_b128 v[220:223], v145 offset:2048
	ds_read_b128 v[224:227], v145 offset:3072
	ds_read_b128 v[228:231], v145 offset:4096
	ds_read_b128 v[232:235], v145 offset:5120
	ds_read_b128 v[236:239], v145 offset:6144
	ds_read_b128 v[240:243], v145 offset:7168
	global_load_lds_dwordx4 v138, s[12:13]
	s_mov_b32 m0, s83
	s_nop 0
	global_load_lds_dwordx4 v140, s[12:13]
	s_waitcnt vmcnt(8)
	s_waitcnt lgkmcnt(0)
	s_barrier
	v_mfma_f32_16x16x32_bf16 v[124:127], v[160:163], v[212:215], v[124:127]
	v_mfma_f32_16x16x32_bf16 v[120:123], v[186:189], v[212:215], v[120:123]
	v_mfma_f32_16x16x32_bf16 v[108:111], v[160:163], v[220:223], v[108:111]
	v_mfma_f32_16x16x32_bf16 v[104:107], v[186:189], v[220:223], v[104:107]
	v_mfma_f32_16x16x32_bf16 v[92:95], v[160:163], v[228:231], v[92:95]
	v_mfma_f32_16x16x32_bf16 v[88:91], v[186:189], v[228:231], v[88:91]
	v_mfma_f32_16x16x32_bf16 v[76:79], v[160:163], v[236:239], v[76:79]
	v_mfma_f32_16x16x32_bf16 v[72:75], v[186:189], v[236:239], v[72:75]
	v_mfma_f32_16x16x32_bf16 v[124:127], v[182:185], v[216:219], v[124:127]
	v_mfma_f32_16x16x32_bf16 v[120:123], v[190:193], v[216:219], v[120:123]
	v_mfma_f32_16x16x32_bf16 v[108:111], v[182:185], v[224:227], v[108:111]
	v_mfma_f32_16x16x32_bf16 v[104:107], v[190:193], v[224:227], v[104:107]
	v_mfma_f32_16x16x32_bf16 v[92:95], v[182:185], v[232:235], v[92:95]
	v_mfma_f32_16x16x32_bf16 v[88:91], v[190:193], v[232:235], v[88:91]
	v_mfma_f32_16x16x32_bf16 v[76:79], v[182:185], v[240:243], v[76:79]
	v_mfma_f32_16x16x32_bf16 v[72:75], v[190:193], v[240:243], v[72:75]
	v_mfma_f32_16x16x32_bf16 v[116:119], v[196:199], v[212:215], v[116:119]
	v_mfma_f32_16x16x32_bf16 v[112:115], v[204:207], v[212:215], v[112:115]
	v_mfma_f32_16x16x32_bf16 v[100:103], v[196:199], v[220:223], v[100:103]
	v_mfma_f32_16x16x32_bf16 v[96:99], v[204:207], v[220:223], v[96:99]
	v_mfma_f32_16x16x32_bf16 v[84:87], v[196:199], v[228:231], v[84:87]
	v_mfma_f32_16x16x32_bf16 v[80:83], v[204:207], v[228:231], v[80:83]
	v_mfma_f32_16x16x32_bf16 v[68:71], v[196:199], v[236:239], v[68:71]
	v_mfma_f32_16x16x32_bf16 v[64:67], v[204:207], v[236:239], v[64:67]
	v_mfma_f32_16x16x32_bf16 v[116:119], v[200:203], v[216:219], v[116:119]
	v_mfma_f32_16x16x32_bf16 v[112:115], v[208:211], v[216:219], v[112:115]
	v_mfma_f32_16x16x32_bf16 v[100:103], v[200:203], v[224:227], v[100:103]
	v_mfma_f32_16x16x32_bf16 v[96:99], v[208:211], v[224:227], v[96:99]
	v_mfma_f32_16x16x32_bf16 v[84:87], v[200:203], v[232:235], v[84:87]
	v_mfma_f32_16x16x32_bf16 v[80:83], v[208:211], v[232:235], v[80:83]
	v_mfma_f32_16x16x32_bf16 v[68:71], v[200:203], v[240:243], v[68:71]
	v_mfma_f32_16x16x32_bf16 v[64:67], v[208:211], v[240:243], v[64:67]
	s_add_u32 s98, s14, s16
	s_addc_u32 s99, s15, s17
	s_add_u32 s100, s28, s16
	s_addc_u32 s101, s29, s17
	s_barrier
	s_mov_b32 m0, s33
	s_add_u32 s56, s14, 0x40000
	ds_read_b128 v[212:215], v145 offset:16384
	ds_read_b128 v[216:219], v145 offset:17408
	ds_read_b128 v[220:223], v145 offset:18432
	ds_read_b128 v[224:227], v145 offset:19456
	ds_read_b128 v[228:231], v145 offset:20480
	ds_read_b128 v[232:235], v145 offset:21504
	ds_read_b128 v[236:239], v145 offset:22528
	ds_read_b128 v[240:243], v145 offset:23552
	global_load_lds_dwordx4 v132, s[14:15]
	s_mov_b32 m0, s34
	s_addc_u32 s57, s15, 0
	global_load_lds_dwordx4 v134, s[14:15]
	s_mov_b32 m0, s35
	s_nop 0
	global_load_lds_dwordx4 v132, s[56:57]
	s_mov_b32 m0, s36
	s_nop 0
	global_load_lds_dwordx4 v134, s[56:57]
	s_mov_b32 m0, s31
	s_nop 0
	global_load_lds_dwordx4 v132, s[28:29]
	s_mov_b32 m0, s37
	s_nop 0
	global_load_lds_dwordx4 v134, s[28:29]
	s_waitcnt vmcnt(8)
	s_waitcnt lgkmcnt(0)
	s_barrier
	v_mfma_f32_16x16x32_bf16 v[60:63], v[160:163], v[212:215], v[60:63]
	v_mfma_f32_16x16x32_bf16 v[56:59], v[186:189], v[212:215], v[56:59]
	v_mfma_f32_16x16x32_bf16 v[44:47], v[160:163], v[220:223], v[44:47]
	v_mfma_f32_16x16x32_bf16 v[40:43], v[186:189], v[220:223], v[40:43]
	v_mfma_f32_16x16x32_bf16 v[28:31], v[160:163], v[228:231], v[28:31]
	v_mfma_f32_16x16x32_bf16 v[24:27], v[186:189], v[228:231], v[24:27]
	v_mfma_f32_16x16x32_bf16 v[12:15], v[160:163], v[236:239], v[12:15]
	v_mfma_f32_16x16x32_bf16 v[8:11], v[186:189], v[236:239], v[8:11]
	v_mfma_f32_16x16x32_bf16 v[60:63], v[182:185], v[216:219], v[60:63]
	v_mfma_f32_16x16x32_bf16 v[56:59], v[190:193], v[216:219], v[56:59]
	v_mfma_f32_16x16x32_bf16 v[44:47], v[182:185], v[224:227], v[44:47]
	v_mfma_f32_16x16x32_bf16 v[40:43], v[190:193], v[224:227], v[40:43]
	v_mfma_f32_16x16x32_bf16 v[28:31], v[182:185], v[232:235], v[28:31]
	v_mfma_f32_16x16x32_bf16 v[24:27], v[190:193], v[232:235], v[24:27]
	v_mfma_f32_16x16x32_bf16 v[12:15], v[182:185], v[240:243], v[12:15]
	v_mfma_f32_16x16x32_bf16 v[8:11], v[190:193], v[240:243], v[8:11]
	v_mfma_f32_16x16x32_bf16 v[52:55], v[196:199], v[212:215], v[52:55]
	v_mfma_f32_16x16x32_bf16 v[48:51], v[204:207], v[212:215], v[48:51]
	v_mfma_f32_16x16x32_bf16 v[36:39], v[196:199], v[220:223], v[36:39]
	v_mfma_f32_16x16x32_bf16 v[32:35], v[204:207], v[220:223], v[32:35]
	v_mfma_f32_16x16x32_bf16 v[20:23], v[196:199], v[228:231], v[20:23]
	v_mfma_f32_16x16x32_bf16 v[16:19], v[204:207], v[228:231], v[16:19]
	v_mfma_f32_16x16x32_bf16 v[4:7], v[196:199], v[236:239], v[4:7]
	v_mfma_f32_16x16x32_bf16 v[0:3], v[204:207], v[236:239], v[0:3]
	v_mfma_f32_16x16x32_bf16 v[52:55], v[200:203], v[216:219], v[52:55]
	v_mfma_f32_16x16x32_bf16 v[48:51], v[208:211], v[216:219], v[48:51]
	v_mfma_f32_16x16x32_bf16 v[36:39], v[200:203], v[224:227], v[36:39]
	v_mfma_f32_16x16x32_bf16 v[32:35], v[208:211], v[224:227], v[32:35]
	v_mfma_f32_16x16x32_bf16 v[20:23], v[200:203], v[232:235], v[20:23]
	v_mfma_f32_16x16x32_bf16 v[16:19], v[208:211], v[232:235], v[16:19]
	v_mfma_f32_16x16x32_bf16 v[4:7], v[200:203], v[240:243], v[4:7]
	v_mfma_f32_16x16x32_bf16 v[0:3], v[208:211], v[240:243], v[0:3]
	s_barrier
	ds_read_b128 v[160:163], v174
	ds_read_b128 v[182:185], v175
	ds_read_b128 v[186:189], v176
	ds_read_b128 v[190:193], v177
	ds_read_b128 v[196:199], v178
	ds_read_b128 v[200:203], v179
	ds_read_b128 v[204:207], v180
	ds_read_b128 v[208:211], v181
	s_add_u32 s28, s28, 0x40000
	s_addc_u32 s29, s29, 0
	s_mov_b32 m0, s62
	ds_read_b128 v[212:215], v145 offset:32768
	ds_read_b128 v[216:219], v145 offset:33792
	ds_read_b128 v[220:223], v145 offset:34816
	ds_read_b128 v[224:227], v145 offset:35840
	ds_read_b128 v[228:231], v145 offset:36864
	ds_read_b128 v[232:235], v145 offset:37888
	ds_read_b128 v[236:239], v145 offset:38912
	ds_read_b128 v[240:243], v145 offset:39936
	global_load_lds_dwordx4 v132, s[28:29]
	s_mov_b32 m0, s63
	s_nop 0
	global_load_lds_dwordx4 v134, s[28:29]
	s_waitcnt vmcnt(8)
	s_waitcnt lgkmcnt(0)
	s_barrier
	v_mfma_f32_16x16x32_bf16 v[124:127], v[160:163], v[212:215], v[124:127]
	v_mfma_f32_16x16x32_bf16 v[120:123], v[186:189], v[212:215], v[120:123]
	v_mfma_f32_16x16x32_bf16 v[108:111], v[160:163], v[220:223], v[108:111]
	v_mfma_f32_16x16x32_bf16 v[104:107], v[186:189], v[220:223], v[104:107]
	v_mfma_f32_16x16x32_bf16 v[92:95], v[160:163], v[228:231], v[92:95]
	v_mfma_f32_16x16x32_bf16 v[88:91], v[186:189], v[228:231], v[88:91]
	v_mfma_f32_16x16x32_bf16 v[76:79], v[160:163], v[236:239], v[76:79]
	v_mfma_f32_16x16x32_bf16 v[72:75], v[186:189], v[236:239], v[72:75]
	v_mfma_f32_16x16x32_bf16 v[124:127], v[182:185], v[216:219], v[124:127]
	v_mfma_f32_16x16x32_bf16 v[120:123], v[190:193], v[216:219], v[120:123]
	v_mfma_f32_16x16x32_bf16 v[108:111], v[182:185], v[224:227], v[108:111]
	v_mfma_f32_16x16x32_bf16 v[104:107], v[190:193], v[224:227], v[104:107]
	v_mfma_f32_16x16x32_bf16 v[92:95], v[182:185], v[232:235], v[92:95]
	v_mfma_f32_16x16x32_bf16 v[88:91], v[190:193], v[232:235], v[88:91]
	v_mfma_f32_16x16x32_bf16 v[76:79], v[182:185], v[240:243], v[76:79]
	v_mfma_f32_16x16x32_bf16 v[72:75], v[190:193], v[240:243], v[72:75]
	v_mfma_f32_16x16x32_bf16 v[116:119], v[196:199], v[212:215], v[116:119]
	v_mfma_f32_16x16x32_bf16 v[112:115], v[204:207], v[212:215], v[112:115]
	v_mfma_f32_16x16x32_bf16 v[100:103], v[196:199], v[220:223], v[100:103]
	v_mfma_f32_16x16x32_bf16 v[96:99], v[204:207], v[220:223], v[96:99]
	v_mfma_f32_16x16x32_bf16 v[84:87], v[196:199], v[228:231], v[84:87]
	v_mfma_f32_16x16x32_bf16 v[80:83], v[204:207], v[228:231], v[80:83]
	v_mfma_f32_16x16x32_bf16 v[68:71], v[196:199], v[236:239], v[68:71]
	v_mfma_f32_16x16x32_bf16 v[64:67], v[204:207], v[236:239], v[64:67]
	v_mfma_f32_16x16x32_bf16 v[116:119], v[200:203], v[216:219], v[116:119]
	v_mfma_f32_16x16x32_bf16 v[112:115], v[208:211], v[216:219], v[112:115]
	v_mfma_f32_16x16x32_bf16 v[100:103], v[200:203], v[224:227], v[100:103]
	v_mfma_f32_16x16x32_bf16 v[96:99], v[208:211], v[224:227], v[96:99]
	v_mfma_f32_16x16x32_bf16 v[84:87], v[200:203], v[232:235], v[84:87]
	v_mfma_f32_16x16x32_bf16 v[80:83], v[208:211], v[232:235], v[80:83]
	v_mfma_f32_16x16x32_bf16 v[68:71], v[200:203], v[240:243], v[68:71]
	v_mfma_f32_16x16x32_bf16 v[64:67], v[208:211], v[240:243], v[64:67]
	s_barrier
	s_mov_b32 m0, s64
	s_add_u32 s14, s14, 0x40080
	ds_read_b128 v[212:215], v145 offset:49152
	ds_read_b128 v[216:219], v145 offset:50176
	ds_read_b128 v[220:223], v145 offset:51200
	ds_read_b128 v[224:227], v145 offset:52224
	ds_read_b128 v[228:231], v145 offset:53248
	ds_read_b128 v[232:235], v145 offset:54272
	ds_read_b128 v[236:239], v145 offset:55296
	ds_read_b128 v[240:243], v145 offset:56320
	global_load_lds_dwordx4 v132, s[98:99]
	s_mov_b32 m0, s65
	s_addc_u32 s15, s15, 0
	global_load_lds_dwordx4 v134, s[98:99]
	s_mov_b32 m0, s72
	s_nop 0
	global_load_lds_dwordx4 v132, s[14:15]
	s_mov_b32 m0, s73
	s_nop 0
	global_load_lds_dwordx4 v134, s[14:15]
	s_mov_b32 m0, s66
	s_nop 0
	global_load_lds_dwordx4 v132, s[100:101]
	s_mov_b32 m0, s67
	s_nop 0
	global_load_lds_dwordx4 v134, s[100:101]
	s_waitcnt vmcnt(8)
	s_waitcnt lgkmcnt(0)
	s_barrier
	v_mfma_f32_16x16x32_bf16 v[60:63], v[160:163], v[212:215], v[60:63]
	v_mfma_f32_16x16x32_bf16 v[56:59], v[186:189], v[212:215], v[56:59]
	v_mfma_f32_16x16x32_bf16 v[44:47], v[160:163], v[220:223], v[44:47]
	v_mfma_f32_16x16x32_bf16 v[40:43], v[186:189], v[220:223], v[40:43]
	v_mfma_f32_16x16x32_bf16 v[28:31], v[160:163], v[228:231], v[28:31]
	v_mfma_f32_16x16x32_bf16 v[24:27], v[186:189], v[228:231], v[24:27]
	v_mfma_f32_16x16x32_bf16 v[12:15], v[160:163], v[236:239], v[12:15]
	v_mfma_f32_16x16x32_bf16 v[8:11], v[186:189], v[236:239], v[8:11]
	v_mfma_f32_16x16x32_bf16 v[60:63], v[182:185], v[216:219], v[60:63]
	v_mfma_f32_16x16x32_bf16 v[56:59], v[190:193], v[216:219], v[56:59]
	v_mfma_f32_16x16x32_bf16 v[44:47], v[182:185], v[224:227], v[44:47]
	v_mfma_f32_16x16x32_bf16 v[40:43], v[190:193], v[224:227], v[40:43]
	v_mfma_f32_16x16x32_bf16 v[28:31], v[182:185], v[232:235], v[28:31]
	v_mfma_f32_16x16x32_bf16 v[24:27], v[190:193], v[232:235], v[24:27]
	v_mfma_f32_16x16x32_bf16 v[12:15], v[182:185], v[240:243], v[12:15]
	v_mfma_f32_16x16x32_bf16 v[8:11], v[190:193], v[240:243], v[8:11]
	v_mfma_f32_16x16x32_bf16 v[52:55], v[196:199], v[212:215], v[52:55]
	v_mfma_f32_16x16x32_bf16 v[48:51], v[204:207], v[212:215], v[48:51]
	v_mfma_f32_16x16x32_bf16 v[36:39], v[196:199], v[220:223], v[36:39]
	v_mfma_f32_16x16x32_bf16 v[32:35], v[204:207], v[220:223], v[32:35]
	v_mfma_f32_16x16x32_bf16 v[20:23], v[196:199], v[228:231], v[20:23]
	v_mfma_f32_16x16x32_bf16 v[16:19], v[204:207], v[228:231], v[16:19]
	v_mfma_f32_16x16x32_bf16 v[4:7], v[196:199], v[236:239], v[4:7]
	v_mfma_f32_16x16x32_bf16 v[0:3], v[204:207], v[236:239], v[0:3]
	v_mfma_f32_16x16x32_bf16 v[52:55], v[200:203], v[216:219], v[52:55]
	v_mfma_f32_16x16x32_bf16 v[48:51], v[208:211], v[216:219], v[48:51]
	v_mfma_f32_16x16x32_bf16 v[36:39], v[200:203], v[224:227], v[36:39]
	v_mfma_f32_16x16x32_bf16 v[32:35], v[208:211], v[224:227], v[32:35]
	v_mfma_f32_16x16x32_bf16 v[20:23], v[200:203], v[232:235], v[20:23]
	v_mfma_f32_16x16x32_bf16 v[16:19], v[208:211], v[232:235], v[16:19]
	v_mfma_f32_16x16x32_bf16 v[4:7], v[200:203], v[240:243], v[4:7]
	v_mfma_f32_16x16x32_bf16 v[0:3], v[208:211], v[240:243], v[0:3]
	s_add_i32 s54, s54, 2
	s_add_u32 s12, s12, 0x100
	s_addc_u32 s13, s13, 0
	s_add_u32 s38, s38, 0x100
	s_addc_u32 s39, s39, 0
	s_cmp_gt_u32 s54, 13
	s_barrier
	s_cbranch_scc0 .LBB0_251
	s_and_b64 vcc, exec, s[18:19]
	s_cbranch_vccz .LBB0_254
	s_barrier

.LBB0_586:
	ds_read_b128 v[160:163], v165
	ds_read_b128 v[182:185], v167
	ds_read_b128 v[186:189], v168
	ds_read_b128 v[190:193], v169
	ds_read_b128 v[196:199], v170
	ds_read_b128 v[200:203], v171
	ds_read_b128 v[204:207], v172
	ds_read_b128 v[208:211], v173
	s_add_u32 s12, s10, 0xfffc0080
	s_addc_u32 s13, s11, -1
	s_cmp_eq_u32 s54, 12
	s_cselect_b32 s15, s7, s13
	s_cselect_b32 s14, s9, s12
	s_cselect_b32 s13, s21, s39
	s_cselect_b32 s12, s23, s38
	s_mov_b32 m0, s82
	ds_read_b128 v[212:215], v145
	ds_read_b128 v[216:219], v145 offset:1024
	ds_read_b128 v[220:223], v145 offset:2048
	ds_read_b128 v[224:227], v145 offset:3072
	ds_read_b128 v[228:231], v145 offset:4096
	ds_read_b128 v[232:235], v145 offset:5120
	ds_read_b128 v[236:239], v145 offset:6144
	ds_read_b128 v[240:243], v145 offset:7168
	global_load_lds_dwordx4 v138, s[10:11]
	s_mov_b32 m0, s83
	s_nop 0
	global_load_lds_dwordx4 v140, s[10:11]
	s_waitcnt vmcnt(8)
	s_waitcnt lgkmcnt(0)
	s_barrier
	v_mfma_f32_16x16x32_bf16 v[124:127], v[160:163], v[212:215], v[124:127]
	v_mfma_f32_16x16x32_bf16 v[120:123], v[186:189], v[212:215], v[120:123]
	v_mfma_f32_16x16x32_bf16 v[108:111], v[160:163], v[220:223], v[108:111]
	v_mfma_f32_16x16x32_bf16 v[104:107], v[186:189], v[220:223], v[104:107]
	v_mfma_f32_16x16x32_bf16 v[92:95], v[160:163], v[228:231], v[92:95]
	v_mfma_f32_16x16x32_bf16 v[88:91], v[186:189], v[228:231], v[88:91]
	v_mfma_f32_16x16x32_bf16 v[76:79], v[160:163], v[236:239], v[76:79]
	v_mfma_f32_16x16x32_bf16 v[72:75], v[186:189], v[236:239], v[72:75]
	v_mfma_f32_16x16x32_bf16 v[124:127], v[182:185], v[216:219], v[124:127]
	v_mfma_f32_16x16x32_bf16 v[120:123], v[190:193], v[216:219], v[120:123]
	v_mfma_f32_16x16x32_bf16 v[108:111], v[182:185], v[224:227], v[108:111]
	v_mfma_f32_16x16x32_bf16 v[104:107], v[190:193], v[224:227], v[104:107]
	v_mfma_f32_16x16x32_bf16 v[92:95], v[182:185], v[232:235], v[92:95]
	v_mfma_f32_16x16x32_bf16 v[88:91], v[190:193], v[232:235], v[88:91]
	v_mfma_f32_16x16x32_bf16 v[76:79], v[182:185], v[240:243], v[76:79]
	v_mfma_f32_16x16x32_bf16 v[72:75], v[190:193], v[240:243], v[72:75]
	v_mfma_f32_16x16x32_bf16 v[116:119], v[196:199], v[212:215], v[116:119]
	v_mfma_f32_16x16x32_bf16 v[112:115], v[204:207], v[212:215], v[112:115]
	v_mfma_f32_16x16x32_bf16 v[100:103], v[196:199], v[220:223], v[100:103]
	v_mfma_f32_16x16x32_bf16 v[96:99], v[204:207], v[220:223], v[96:99]
	v_mfma_f32_16x16x32_bf16 v[84:87], v[196:199], v[228:231], v[84:87]
	v_mfma_f32_16x16x32_bf16 v[80:83], v[204:207], v[228:231], v[80:83]
	v_mfma_f32_16x16x32_bf16 v[68:71], v[196:199], v[236:239], v[68:71]
	v_mfma_f32_16x16x32_bf16 v[64:67], v[204:207], v[236:239], v[64:67]
	v_mfma_f32_16x16x32_bf16 v[116:119], v[200:203], v[216:219], v[116:119]
	v_mfma_f32_16x16x32_bf16 v[112:115], v[208:211], v[216:219], v[112:115]
	v_mfma_f32_16x16x32_bf16 v[100:103], v[200:203], v[224:227], v[100:103]
	v_mfma_f32_16x16x32_bf16 v[96:99], v[208:211], v[224:227], v[96:99]
	v_mfma_f32_16x16x32_bf16 v[84:87], v[200:203], v[232:235], v[84:87]
	v_mfma_f32_16x16x32_bf16 v[80:83], v[208:211], v[232:235], v[80:83]
	v_mfma_f32_16x16x32_bf16 v[68:71], v[200:203], v[240:243], v[68:71]
	v_mfma_f32_16x16x32_bf16 v[64:67], v[208:211], v[240:243], v[64:67]
	s_add_u32 s98, s12, s16
	s_addc_u32 s99, s13, s17
	s_add_u32 s100, s14, s16
	s_addc_u32 s101, s15, s17
	s_barrier
	s_mov_b32 m0, s30
	s_add_u32 s56, s12, 0x40000
	ds_read_b128 v[212:215], v145 offset:16384
	ds_read_b128 v[216:219], v145 offset:17408
	ds_read_b128 v[220:223], v145 offset:18432
	ds_read_b128 v[224:227], v145 offset:19456
	ds_read_b128 v[228:231], v145 offset:20480
	ds_read_b128 v[232:235], v145 offset:21504
	ds_read_b128 v[236:239], v145 offset:22528
	ds_read_b128 v[240:243], v145 offset:23552
	global_load_lds_dwordx4 v132, s[12:13]
	s_mov_b32 m0, s31
	s_addc_u32 s57, s13, 0
	global_load_lds_dwordx4 v134, s[12:13]
	s_mov_b32 m0, s33
	s_nop 0
	global_load_lds_dwordx4 v132, s[56:57]
	s_mov_b32 m0, s34
	s_nop 0
	global_load_lds_dwordx4 v134, s[56:57]
	s_mov_b32 m0, s29
	s_nop 0
	global_load_lds_dwordx4 v132, s[14:15]
	s_mov_b32 m0, s35
	s_nop 0
	global_load_lds_dwordx4 v134, s[14:15]
	s_waitcnt vmcnt(8)
	s_waitcnt lgkmcnt(0)
	s_barrier
	v_mfma_f32_16x16x32_bf16 v[60:63], v[160:163], v[212:215], v[60:63]
	v_mfma_f32_16x16x32_bf16 v[56:59], v[186:189], v[212:215], v[56:59]
	v_mfma_f32_16x16x32_bf16 v[44:47], v[160:163], v[220:223], v[44:47]
	v_mfma_f32_16x16x32_bf16 v[40:43], v[186:189], v[220:223], v[40:43]
	v_mfma_f32_16x16x32_bf16 v[28:31], v[160:163], v[228:231], v[28:31]
	v_mfma_f32_16x16x32_bf16 v[24:27], v[186:189], v[228:231], v[24:27]
	v_mfma_f32_16x16x32_bf16 v[12:15], v[160:163], v[236:239], v[12:15]
	v_mfma_f32_16x16x32_bf16 v[8:11], v[186:189], v[236:239], v[8:11]
	v_mfma_f32_16x16x32_bf16 v[60:63], v[182:185], v[216:219], v[60:63]
	v_mfma_f32_16x16x32_bf16 v[56:59], v[190:193], v[216:219], v[56:59]
	v_mfma_f32_16x16x32_bf16 v[44:47], v[182:185], v[224:227], v[44:47]
	v_mfma_f32_16x16x32_bf16 v[40:43], v[190:193], v[224:227], v[40:43]
	v_mfma_f32_16x16x32_bf16 v[28:31], v[182:185], v[232:235], v[28:31]
	v_mfma_f32_16x16x32_bf16 v[24:27], v[190:193], v[232:235], v[24:27]
	v_mfma_f32_16x16x32_bf16 v[12:15], v[182:185], v[240:243], v[12:15]
	v_mfma_f32_16x16x32_bf16 v[8:11], v[190:193], v[240:243], v[8:11]
	v_mfma_f32_16x16x32_bf16 v[52:55], v[196:199], v[212:215], v[52:55]
	v_mfma_f32_16x16x32_bf16 v[48:51], v[204:207], v[212:215], v[48:51]
	v_mfma_f32_16x16x32_bf16 v[36:39], v[196:199], v[220:223], v[36:39]
	v_mfma_f32_16x16x32_bf16 v[32:35], v[204:207], v[220:223], v[32:35]
	v_mfma_f32_16x16x32_bf16 v[20:23], v[196:199], v[228:231], v[20:23]
	v_mfma_f32_16x16x32_bf16 v[16:19], v[204:207], v[228:231], v[16:19]
	v_mfma_f32_16x16x32_bf16 v[4:7], v[196:199], v[236:239], v[4:7]
	v_mfma_f32_16x16x32_bf16 v[0:3], v[204:207], v[236:239], v[0:3]
	v_mfma_f32_16x16x32_bf16 v[52:55], v[200:203], v[216:219], v[52:55]
	v_mfma_f32_16x16x32_bf16 v[48:51], v[208:211], v[216:219], v[48:51]
	v_mfma_f32_16x16x32_bf16 v[36:39], v[200:203], v[224:227], v[36:39]
	v_mfma_f32_16x16x32_bf16 v[32:35], v[208:211], v[224:227], v[32:35]
	v_mfma_f32_16x16x32_bf16 v[20:23], v[200:203], v[232:235], v[20:23]
	v_mfma_f32_16x16x32_bf16 v[16:19], v[208:211], v[232:235], v[16:19]
	v_mfma_f32_16x16x32_bf16 v[4:7], v[200:203], v[240:243], v[4:7]
	v_mfma_f32_16x16x32_bf16 v[0:3], v[208:211], v[240:243], v[0:3]
	s_barrier
	ds_read_b128 v[160:163], v174
	ds_read_b128 v[182:185], v175
	ds_read_b128 v[186:189], v176
	ds_read_b128 v[190:193], v177
	ds_read_b128 v[196:199], v178
	ds_read_b128 v[200:203], v179
	ds_read_b128 v[204:207], v180
	ds_read_b128 v[208:211], v181
	s_add_u32 s14, s14, 0x40000
	s_addc_u32 s15, s15, 0
	s_mov_b32 m0, s36
	ds_read_b128 v[212:215], v145 offset:32768
	ds_read_b128 v[216:219], v145 offset:33792
	ds_read_b128 v[220:223], v145 offset:34816
	ds_read_b128 v[224:227], v145 offset:35840
	ds_read_b128 v[228:231], v145 offset:36864
	ds_read_b128 v[232:235], v145 offset:37888
	ds_read_b128 v[236:239], v145 offset:38912
	ds_read_b128 v[240:243], v145 offset:39936
	global_load_lds_dwordx4 v132, s[14:15]
	s_mov_b32 m0, s37
	s_nop 0
	global_load_lds_dwordx4 v134, s[14:15]
	s_waitcnt vmcnt(8)
	s_waitcnt lgkmcnt(0)
	s_barrier
	v_mfma_f32_16x16x32_bf16 v[124:127], v[160:163], v[212:215], v[124:127]
	v_mfma_f32_16x16x32_bf16 v[120:123], v[186:189], v[212:215], v[120:123]
	v_mfma_f32_16x16x32_bf16 v[108:111], v[160:163], v[220:223], v[108:111]
	v_mfma_f32_16x16x32_bf16 v[104:107], v[186:189], v[220:223], v[104:107]
	v_mfma_f32_16x16x32_bf16 v[92:95], v[160:163], v[228:231], v[92:95]
	v_mfma_f32_16x16x32_bf16 v[88:91], v[186:189], v[228:231], v[88:91]
	v_mfma_f32_16x16x32_bf16 v[76:79], v[160:163], v[236:239], v[76:79]
	v_mfma_f32_16x16x32_bf16 v[72:75], v[186:189], v[236:239], v[72:75]
	v_mfma_f32_16x16x32_bf16 v[124:127], v[182:185], v[216:219], v[124:127]
	v_mfma_f32_16x16x32_bf16 v[120:123], v[190:193], v[216:219], v[120:123]
	v_mfma_f32_16x16x32_bf16 v[108:111], v[182:185], v[224:227], v[108:111]
	v_mfma_f32_16x16x32_bf16 v[104:107], v[190:193], v[224:227], v[104:107]
	v_mfma_f32_16x16x32_bf16 v[92:95], v[182:185], v[232:235], v[92:95]
	v_mfma_f32_16x16x32_bf16 v[88:91], v[190:193], v[232:235], v[88:91]
	v_mfma_f32_16x16x32_bf16 v[76:79], v[182:185], v[240:243], v[76:79]
	v_mfma_f32_16x16x32_bf16 v[72:75], v[190:193], v[240:243], v[72:75]
	v_mfma_f32_16x16x32_bf16 v[116:119], v[196:199], v[212:215], v[116:119]
	v_mfma_f32_16x16x32_bf16 v[112:115], v[204:207], v[212:215], v[112:115]
	v_mfma_f32_16x16x32_bf16 v[100:103], v[196:199], v[220:223], v[100:103]
	v_mfma_f32_16x16x32_bf16 v[96:99], v[204:207], v[220:223], v[96:99]
	v_mfma_f32_16x16x32_bf16 v[84:87], v[196:199], v[228:231], v[84:87]
	v_mfma_f32_16x16x32_bf16 v[80:83], v[204:207], v[228:231], v[80:83]
	v_mfma_f32_16x16x32_bf16 v[68:71], v[196:199], v[236:239], v[68:71]
	v_mfma_f32_16x16x32_bf16 v[64:67], v[204:207], v[236:239], v[64:67]
	v_mfma_f32_16x16x32_bf16 v[116:119], v[200:203], v[216:219], v[116:119]
	v_mfma_f32_16x16x32_bf16 v[112:115], v[208:211], v[216:219], v[112:115]
	v_mfma_f32_16x16x32_bf16 v[100:103], v[200:203], v[224:227], v[100:103]
	v_mfma_f32_16x16x32_bf16 v[96:99], v[208:211], v[224:227], v[96:99]
	v_mfma_f32_16x16x32_bf16 v[84:87], v[200:203], v[232:235], v[84:87]
	v_mfma_f32_16x16x32_bf16 v[80:83], v[208:211], v[232:235], v[80:83]
	v_mfma_f32_16x16x32_bf16 v[68:71], v[200:203], v[240:243], v[68:71]
	v_mfma_f32_16x16x32_bf16 v[64:67], v[208:211], v[240:243], v[64:67]
	s_barrier
	s_mov_b32 m0, s64
	s_add_u32 s12, s12, 0x40080
	ds_read_b128 v[212:215], v145 offset:49152
	ds_read_b128 v[216:219], v145 offset:50176
	ds_read_b128 v[220:223], v145 offset:51200
	ds_read_b128 v[224:227], v145 offset:52224
	ds_read_b128 v[228:231], v145 offset:53248
	ds_read_b128 v[232:235], v145 offset:54272
	ds_read_b128 v[236:239], v145 offset:55296
	ds_read_b128 v[240:243], v145 offset:56320
	global_load_lds_dwordx4 v132, s[98:99]
	s_mov_b32 m0, s65
	s_addc_u32 s13, s13, 0
	global_load_lds_dwordx4 v134, s[98:99]
	s_mov_b32 m0, s72
	s_nop 0
	global_load_lds_dwordx4 v132, s[12:13]
	s_mov_b32 m0, s73
	s_nop 0
	global_load_lds_dwordx4 v134, s[12:13]
	s_mov_b32 m0, s66
	s_nop 0
	global_load_lds_dwordx4 v132, s[100:101]
	s_mov_b32 m0, s67
	s_nop 0
	global_load_lds_dwordx4 v134, s[100:101]
	s_waitcnt vmcnt(8)
	s_waitcnt lgkmcnt(0)
	s_barrier
	v_mfma_f32_16x16x32_bf16 v[60:63], v[160:163], v[212:215], v[60:63]
	v_mfma_f32_16x16x32_bf16 v[56:59], v[186:189], v[212:215], v[56:59]
	v_mfma_f32_16x16x32_bf16 v[44:47], v[160:163], v[220:223], v[44:47]
	v_mfma_f32_16x16x32_bf16 v[40:43], v[186:189], v[220:223], v[40:43]
	v_mfma_f32_16x16x32_bf16 v[28:31], v[160:163], v[228:231], v[28:31]
	v_mfma_f32_16x16x32_bf16 v[24:27], v[186:189], v[228:231], v[24:27]
	v_mfma_f32_16x16x32_bf16 v[12:15], v[160:163], v[236:239], v[12:15]
	v_mfma_f32_16x16x32_bf16 v[8:11], v[186:189], v[236:239], v[8:11]
	v_mfma_f32_16x16x32_bf16 v[60:63], v[182:185], v[216:219], v[60:63]
	v_mfma_f32_16x16x32_bf16 v[56:59], v[190:193], v[216:219], v[56:59]
	v_mfma_f32_16x16x32_bf16 v[44:47], v[182:185], v[224:227], v[44:47]
	v_mfma_f32_16x16x32_bf16 v[40:43], v[190:193], v[224:227], v[40:43]
	v_mfma_f32_16x16x32_bf16 v[28:31], v[182:185], v[232:235], v[28:31]
	v_mfma_f32_16x16x32_bf16 v[24:27], v[190:193], v[232:235], v[24:27]
	v_mfma_f32_16x16x32_bf16 v[12:15], v[182:185], v[240:243], v[12:15]
	v_mfma_f32_16x16x32_bf16 v[8:11], v[190:193], v[240:243], v[8:11]
	v_mfma_f32_16x16x32_bf16 v[52:55], v[196:199], v[212:215], v[52:55]
	v_mfma_f32_16x16x32_bf16 v[48:51], v[204:207], v[212:215], v[48:51]
	v_mfma_f32_16x16x32_bf16 v[36:39], v[196:199], v[220:223], v[36:39]
	v_mfma_f32_16x16x32_bf16 v[32:35], v[204:207], v[220:223], v[32:35]
	v_mfma_f32_16x16x32_bf16 v[20:23], v[196:199], v[228:231], v[20:23]
	v_mfma_f32_16x16x32_bf16 v[16:19], v[204:207], v[228:231], v[16:19]
	v_mfma_f32_16x16x32_bf16 v[4:7], v[196:199], v[236:239], v[4:7]
	v_mfma_f32_16x16x32_bf16 v[0:3], v[204:207], v[236:239], v[0:3]
	v_mfma_f32_16x16x32_bf16 v[52:55], v[200:203], v[216:219], v[52:55]
	v_mfma_f32_16x16x32_bf16 v[48:51], v[208:211], v[216:219], v[48:51]
	v_mfma_f32_16x16x32_bf16 v[36:39], v[200:203], v[224:227], v[36:39]
	v_mfma_f32_16x16x32_bf16 v[32:35], v[208:211], v[224:227], v[32:35]
	v_mfma_f32_16x16x32_bf16 v[20:23], v[200:203], v[232:235], v[20:23]
	v_mfma_f32_16x16x32_bf16 v[16:19], v[208:211], v[232:235], v[16:19]
	v_mfma_f32_16x16x32_bf16 v[4:7], v[200:203], v[240:243], v[4:7]
	v_mfma_f32_16x16x32_bf16 v[0:3], v[208:211], v[240:243], v[0:3]
	s_add_i32 s54, s54, 2
	s_add_u32 s10, s10, 0x100
	s_addc_u32 s11, s11, 0
	s_add_u32 s38, s38, 0x100
	s_addc_u32 s39, s39, 0
	s_cmp_gt_u32 s54, 13
	s_barrier
	s_cbranch_scc0 .LBB0_586
	s_and_b64 vcc, exec, s[18:19]
	s_cbranch_vccz .LBB0_589
	s_barrier

.LBB0_856:
	ds_read_b128 v[178:181], v160
	ds_read_b128 v[182:185], v161
	ds_read_b128 v[186:189], v162
	ds_read_b128 v[190:193], v163
	ds_read_b128 v[198:201], v164
	ds_read_b128 v[202:205], v165
	ds_read_b128 v[206:209], v167
	ds_read_b128 v[210:213], v168
	s_add_u32 s28, s10, 0x100
	s_addc_u32 s29, s11, 0
	s_cmp_eq_u32 s56, 28
	s_cselect_b32 s35, s4, s29
	s_cselect_b32 s34, s5, s28
	s_cselect_b32 s31, s21, vcc_hi
	s_cselect_b32 s30, s23, vcc_lo
	s_mov_b32 m0, s55
	ds_read_b128 v[214:217], v152
	ds_read_b128 v[218:221], v152 offset:1024
	ds_read_b128 v[222:225], v152 offset:2048
	ds_read_b128 v[226:229], v152 offset:3072
	ds_read_b128 v[230:233], v152 offset:4096
	ds_read_b128 v[234:237], v152 offset:5120
	ds_read_b128 v[238:241], v152 offset:6144
	ds_read_b128 v[242:245], v152 offset:7168
	global_load_lds_dwordx4 v136, s[10:11]
	s_mov_b32 m0, s36
	s_nop 0
	global_load_lds_dwordx4 v138, s[10:11]
	s_waitcnt vmcnt(8)
	s_waitcnt lgkmcnt(0)
	s_barrier
	v_mfma_f32_16x16x32_bf16 v[124:127], v[178:181], v[214:217], v[124:127]
	v_mfma_f32_16x16x32_bf16 v[120:123], v[186:189], v[214:217], v[120:123]
	v_mfma_f32_16x16x32_bf16 v[108:111], v[178:181], v[222:225], v[108:111]
	v_mfma_f32_16x16x32_bf16 v[104:107], v[186:189], v[222:225], v[104:107]
	v_mfma_f32_16x16x32_bf16 v[92:95], v[178:181], v[230:233], v[92:95]
	v_mfma_f32_16x16x32_bf16 v[88:91], v[186:189], v[230:233], v[88:91]
	v_mfma_f32_16x16x32_bf16 v[76:79], v[178:181], v[238:241], v[76:79]
	v_mfma_f32_16x16x32_bf16 v[72:75], v[186:189], v[238:241], v[72:75]
	v_mfma_f32_16x16x32_bf16 v[124:127], v[182:185], v[218:221], v[124:127]
	v_mfma_f32_16x16x32_bf16 v[120:123], v[190:193], v[218:221], v[120:123]
	v_mfma_f32_16x16x32_bf16 v[108:111], v[182:185], v[226:229], v[108:111]
	v_mfma_f32_16x16x32_bf16 v[104:107], v[190:193], v[226:229], v[104:107]
	v_mfma_f32_16x16x32_bf16 v[92:95], v[182:185], v[234:237], v[92:95]
	v_mfma_f32_16x16x32_bf16 v[88:91], v[190:193], v[234:237], v[88:91]
	v_mfma_f32_16x16x32_bf16 v[76:79], v[182:185], v[242:245], v[76:79]
	v_mfma_f32_16x16x32_bf16 v[72:75], v[190:193], v[242:245], v[72:75]
	v_mfma_f32_16x16x32_bf16 v[116:119], v[198:201], v[214:217], v[116:119]
	v_mfma_f32_16x16x32_bf16 v[112:115], v[206:209], v[214:217], v[112:115]
	v_mfma_f32_16x16x32_bf16 v[100:103], v[198:201], v[222:225], v[100:103]
	v_mfma_f32_16x16x32_bf16 v[96:99], v[206:209], v[222:225], v[96:99]
	v_mfma_f32_16x16x32_bf16 v[84:87], v[198:201], v[230:233], v[84:87]
	v_mfma_f32_16x16x32_bf16 v[80:83], v[206:209], v[230:233], v[80:83]
	v_mfma_f32_16x16x32_bf16 v[68:71], v[198:201], v[238:241], v[68:71]
	v_mfma_f32_16x16x32_bf16 v[64:67], v[206:209], v[238:241], v[64:67]
	v_mfma_f32_16x16x32_bf16 v[116:119], v[202:205], v[218:221], v[116:119]
	v_mfma_f32_16x16x32_bf16 v[112:115], v[210:213], v[218:221], v[112:115]
	v_mfma_f32_16x16x32_bf16 v[100:103], v[202:205], v[226:229], v[100:103]
	v_mfma_f32_16x16x32_bf16 v[96:99], v[210:213], v[226:229], v[96:99]
	v_mfma_f32_16x16x32_bf16 v[84:87], v[202:205], v[234:237], v[84:87]
	v_mfma_f32_16x16x32_bf16 v[80:83], v[210:213], v[234:237], v[80:83]
	v_mfma_f32_16x16x32_bf16 v[68:71], v[202:205], v[242:245], v[68:71]
	v_mfma_f32_16x16x32_bf16 v[64:67], v[210:213], v[242:245], v[64:67]
	s_add_u32 s98, s30, s14
	s_addc_u32 s99, s31, s15
	s_add_u32 s100, s34, s14
	s_addc_u32 s101, s35, s15
	s_barrier
	s_mov_b32 m0, s37
	s_add_u32 s10, s30, 0x80000
	ds_read_b128 v[214:217], v152 offset:16384
	ds_read_b128 v[218:221], v152 offset:17408
	ds_read_b128 v[222:225], v152 offset:18432
	ds_read_b128 v[226:229], v152 offset:19456
	ds_read_b128 v[230:233], v152 offset:20480
	ds_read_b128 v[234:237], v152 offset:21504
	ds_read_b128 v[238:241], v152 offset:22528
	ds_read_b128 v[242:245], v152 offset:23552
	global_load_lds_dwordx4 v132, s[30:31]
	s_mov_b32 m0, s41
	s_addc_u32 s11, s31, 0
	global_load_lds_dwordx4 v134, s[30:31]
	s_mov_b32 m0, s42
	s_nop 0
	global_load_lds_dwordx4 v132, s[10:11]
	s_mov_b32 m0, s43
	s_nop 0
	global_load_lds_dwordx4 v134, s[10:11]
	s_mov_b32 m0, s40
	s_nop 0
	global_load_lds_dwordx4 v132, s[34:35]
	s_mov_b32 m0, s72
	s_nop 0
	global_load_lds_dwordx4 v134, s[34:35]
	s_waitcnt vmcnt(8)
	s_waitcnt lgkmcnt(0)
	s_barrier
	v_mfma_f32_16x16x32_bf16 v[60:63], v[178:181], v[214:217], v[60:63]
	v_mfma_f32_16x16x32_bf16 v[56:59], v[186:189], v[214:217], v[56:59]
	v_mfma_f32_16x16x32_bf16 v[44:47], v[178:181], v[222:225], v[44:47]
	v_mfma_f32_16x16x32_bf16 v[40:43], v[186:189], v[222:225], v[40:43]
	v_mfma_f32_16x16x32_bf16 v[28:31], v[178:181], v[230:233], v[28:31]
	v_mfma_f32_16x16x32_bf16 v[24:27], v[186:189], v[230:233], v[24:27]
	v_mfma_f32_16x16x32_bf16 v[16:19], v[178:181], v[238:241], v[16:19]
	v_mfma_f32_16x16x32_bf16 v[8:11], v[186:189], v[238:241], v[8:11]
	v_mfma_f32_16x16x32_bf16 v[60:63], v[182:185], v[218:221], v[60:63]
	v_mfma_f32_16x16x32_bf16 v[56:59], v[190:193], v[218:221], v[56:59]
	v_mfma_f32_16x16x32_bf16 v[44:47], v[182:185], v[226:229], v[44:47]
	v_mfma_f32_16x16x32_bf16 v[40:43], v[190:193], v[226:229], v[40:43]
	v_mfma_f32_16x16x32_bf16 v[28:31], v[182:185], v[234:237], v[28:31]
	v_mfma_f32_16x16x32_bf16 v[24:27], v[190:193], v[234:237], v[24:27]
	v_mfma_f32_16x16x32_bf16 v[16:19], v[182:185], v[242:245], v[16:19]
	v_mfma_f32_16x16x32_bf16 v[8:11], v[190:193], v[242:245], v[8:11]
	v_mfma_f32_16x16x32_bf16 v[52:55], v[198:201], v[214:217], v[52:55]
	v_mfma_f32_16x16x32_bf16 v[48:51], v[206:209], v[214:217], v[48:51]
	v_mfma_f32_16x16x32_bf16 v[36:39], v[198:201], v[222:225], v[36:39]
	v_mfma_f32_16x16x32_bf16 v[32:35], v[206:209], v[222:225], v[32:35]
	v_mfma_f32_16x16x32_bf16 v[20:23], v[198:201], v[230:233], v[20:23]
	v_mfma_f32_16x16x32_bf16 v[12:15], v[206:209], v[230:233], v[12:15]
	v_mfma_f32_16x16x32_bf16 v[4:7], v[198:201], v[238:241], v[4:7]
	v_mfma_f32_16x16x32_bf16 v[0:3], v[206:209], v[238:241], v[0:3]
	v_mfma_f32_16x16x32_bf16 v[52:55], v[202:205], v[218:221], v[52:55]
	v_mfma_f32_16x16x32_bf16 v[48:51], v[210:213], v[218:221], v[48:51]
	v_mfma_f32_16x16x32_bf16 v[36:39], v[202:205], v[226:229], v[36:39]
	v_mfma_f32_16x16x32_bf16 v[32:35], v[210:213], v[226:229], v[32:35]
	v_mfma_f32_16x16x32_bf16 v[20:23], v[202:205], v[234:237], v[20:23]
	v_mfma_f32_16x16x32_bf16 v[12:15], v[210:213], v[234:237], v[12:15]
	v_mfma_f32_16x16x32_bf16 v[4:7], v[202:205], v[242:245], v[4:7]
	v_mfma_f32_16x16x32_bf16 v[0:3], v[210:213], v[242:245], v[0:3]
	s_barrier
	ds_read_b128 v[178:181], v169
	ds_read_b128 v[182:185], v170
	ds_read_b128 v[186:189], v171
	ds_read_b128 v[190:193], v172
	ds_read_b128 v[198:201], v173
	ds_read_b128 v[202:205], v174
	ds_read_b128 v[206:209], v175
	ds_read_b128 v[210:213], v176
	s_add_u32 s10, s34, 0x80000
	s_addc_u32 s11, s35, 0
	s_mov_b32 m0, s73
	ds_read_b128 v[214:217], v152 offset:32768
	ds_read_b128 v[218:221], v152 offset:33792
	ds_read_b128 v[222:225], v152 offset:34816
	ds_read_b128 v[226:229], v152 offset:35840
	ds_read_b128 v[230:233], v152 offset:36864
	ds_read_b128 v[234:237], v152 offset:37888
	ds_read_b128 v[238:241], v152 offset:38912
	ds_read_b128 v[242:245], v152 offset:39936
	global_load_lds_dwordx4 v132, s[10:11]
	s_mov_b32 m0, s74
	s_nop 0
	global_load_lds_dwordx4 v134, s[10:11]
	s_waitcnt vmcnt(8)
	s_waitcnt lgkmcnt(0)
	s_barrier
	v_mfma_f32_16x16x32_bf16 v[124:127], v[178:181], v[214:217], v[124:127]
	v_mfma_f32_16x16x32_bf16 v[120:123], v[186:189], v[214:217], v[120:123]
	v_mfma_f32_16x16x32_bf16 v[108:111], v[178:181], v[222:225], v[108:111]
	v_mfma_f32_16x16x32_bf16 v[104:107], v[186:189], v[222:225], v[104:107]
	v_mfma_f32_16x16x32_bf16 v[92:95], v[178:181], v[230:233], v[92:95]
	v_mfma_f32_16x16x32_bf16 v[88:91], v[186:189], v[230:233], v[88:91]
	v_mfma_f32_16x16x32_bf16 v[76:79], v[178:181], v[238:241], v[76:79]
	v_mfma_f32_16x16x32_bf16 v[72:75], v[186:189], v[238:241], v[72:75]
	v_mfma_f32_16x16x32_bf16 v[124:127], v[182:185], v[218:221], v[124:127]
	v_mfma_f32_16x16x32_bf16 v[120:123], v[190:193], v[218:221], v[120:123]
	v_mfma_f32_16x16x32_bf16 v[108:111], v[182:185], v[226:229], v[108:111]
	v_mfma_f32_16x16x32_bf16 v[104:107], v[190:193], v[226:229], v[104:107]
	v_mfma_f32_16x16x32_bf16 v[92:95], v[182:185], v[234:237], v[92:95]
	v_mfma_f32_16x16x32_bf16 v[88:91], v[190:193], v[234:237], v[88:91]
	v_mfma_f32_16x16x32_bf16 v[76:79], v[182:185], v[242:245], v[76:79]
	v_mfma_f32_16x16x32_bf16 v[72:75], v[190:193], v[242:245], v[72:75]
	v_mfma_f32_16x16x32_bf16 v[116:119], v[198:201], v[214:217], v[116:119]
	v_mfma_f32_16x16x32_bf16 v[112:115], v[206:209], v[214:217], v[112:115]
	v_mfma_f32_16x16x32_bf16 v[100:103], v[198:201], v[222:225], v[100:103]
	v_mfma_f32_16x16x32_bf16 v[96:99], v[206:209], v[222:225], v[96:99]
	v_mfma_f32_16x16x32_bf16 v[84:87], v[198:201], v[230:233], v[84:87]
	v_mfma_f32_16x16x32_bf16 v[80:83], v[206:209], v[230:233], v[80:83]
	v_mfma_f32_16x16x32_bf16 v[68:71], v[198:201], v[238:241], v[68:71]
	v_mfma_f32_16x16x32_bf16 v[64:67], v[206:209], v[238:241], v[64:67]
	v_mfma_f32_16x16x32_bf16 v[116:119], v[202:205], v[218:221], v[116:119]
	v_mfma_f32_16x16x32_bf16 v[112:115], v[210:213], v[218:221], v[112:115]
	v_mfma_f32_16x16x32_bf16 v[100:103], v[202:205], v[226:229], v[100:103]
	v_mfma_f32_16x16x32_bf16 v[96:99], v[210:213], v[226:229], v[96:99]
	v_mfma_f32_16x16x32_bf16 v[84:87], v[202:205], v[234:237], v[84:87]
	v_mfma_f32_16x16x32_bf16 v[80:83], v[210:213], v[234:237], v[80:83]
	v_mfma_f32_16x16x32_bf16 v[68:71], v[202:205], v[242:245], v[68:71]
	v_mfma_f32_16x16x32_bf16 v[64:67], v[210:213], v[242:245], v[64:67]
	s_barrier
	s_mov_b32 m0, s75
	s_add_u32 s10, s30, 0x80080
	ds_read_b128 v[214:217], v152 offset:49152
	ds_read_b128 v[218:221], v152 offset:50176
	ds_read_b128 v[222:225], v152 offset:51200
	ds_read_b128 v[226:229], v152 offset:52224
	ds_read_b128 v[230:233], v152 offset:53248
	ds_read_b128 v[234:237], v152 offset:54272
	ds_read_b128 v[238:241], v152 offset:55296
	ds_read_b128 v[242:245], v152 offset:56320
	global_load_lds_dwordx4 v132, s[98:99]
	s_mov_b32 m0, s78
	s_addc_u32 s11, s31, 0
	global_load_lds_dwordx4 v134, s[98:99]
	s_mov_b32 m0, s83
	s_nop 0
	global_load_lds_dwordx4 v132, s[10:11]
	s_mov_b32 m0, s84
	s_nop 0
	global_load_lds_dwordx4 v134, s[10:11]
	s_mov_b32 m0, s79
	s_nop 0
	global_load_lds_dwordx4 v132, s[100:101]
	s_mov_b32 m0, s82
	s_nop 0
	global_load_lds_dwordx4 v134, s[100:101]
	s_waitcnt vmcnt(8)
	s_waitcnt lgkmcnt(0)
	s_barrier
	v_mfma_f32_16x16x32_bf16 v[60:63], v[178:181], v[214:217], v[60:63]
	v_mfma_f32_16x16x32_bf16 v[56:59], v[186:189], v[214:217], v[56:59]
	v_mfma_f32_16x16x32_bf16 v[44:47], v[178:181], v[222:225], v[44:47]
	v_mfma_f32_16x16x32_bf16 v[40:43], v[186:189], v[222:225], v[40:43]
	v_mfma_f32_16x16x32_bf16 v[28:31], v[178:181], v[230:233], v[28:31]
	v_mfma_f32_16x16x32_bf16 v[24:27], v[186:189], v[230:233], v[24:27]
	v_mfma_f32_16x16x32_bf16 v[16:19], v[178:181], v[238:241], v[16:19]
	v_mfma_f32_16x16x32_bf16 v[8:11], v[186:189], v[238:241], v[8:11]
	v_mfma_f32_16x16x32_bf16 v[60:63], v[182:185], v[218:221], v[60:63]
	v_mfma_f32_16x16x32_bf16 v[56:59], v[190:193], v[218:221], v[56:59]
	v_mfma_f32_16x16x32_bf16 v[44:47], v[182:185], v[226:229], v[44:47]
	v_mfma_f32_16x16x32_bf16 v[40:43], v[190:193], v[226:229], v[40:43]
	v_mfma_f32_16x16x32_bf16 v[28:31], v[182:185], v[234:237], v[28:31]
	v_mfma_f32_16x16x32_bf16 v[24:27], v[190:193], v[234:237], v[24:27]
	v_mfma_f32_16x16x32_bf16 v[16:19], v[182:185], v[242:245], v[16:19]
	v_mfma_f32_16x16x32_bf16 v[8:11], v[190:193], v[242:245], v[8:11]
	v_mfma_f32_16x16x32_bf16 v[52:55], v[198:201], v[214:217], v[52:55]
	v_mfma_f32_16x16x32_bf16 v[48:51], v[206:209], v[214:217], v[48:51]
	v_mfma_f32_16x16x32_bf16 v[36:39], v[198:201], v[222:225], v[36:39]
	v_mfma_f32_16x16x32_bf16 v[32:35], v[206:209], v[222:225], v[32:35]
	v_mfma_f32_16x16x32_bf16 v[20:23], v[198:201], v[230:233], v[20:23]
	v_mfma_f32_16x16x32_bf16 v[12:15], v[206:209], v[230:233], v[12:15]
	v_mfma_f32_16x16x32_bf16 v[4:7], v[198:201], v[238:241], v[4:7]
	v_mfma_f32_16x16x32_bf16 v[0:3], v[206:209], v[238:241], v[0:3]
	v_mfma_f32_16x16x32_bf16 v[52:55], v[202:205], v[218:221], v[52:55]
	v_mfma_f32_16x16x32_bf16 v[48:51], v[210:213], v[218:221], v[48:51]
	v_mfma_f32_16x16x32_bf16 v[36:39], v[202:205], v[226:229], v[36:39]
	v_mfma_f32_16x16x32_bf16 v[32:35], v[210:213], v[226:229], v[32:35]
	v_mfma_f32_16x16x32_bf16 v[20:23], v[202:205], v[234:237], v[20:23]
	v_mfma_f32_16x16x32_bf16 v[12:15], v[210:213], v[234:237], v[12:15]
	v_mfma_f32_16x16x32_bf16 v[4:7], v[202:205], v[242:245], v[4:7]
	v_mfma_f32_16x16x32_bf16 v[0:3], v[210:213], v[242:245], v[0:3]
	s_add_i32 s56, s56, 2
	s_add_u32 vcc_lo, vcc_lo, 0x100
	s_addc_u32 vcc_hi, vcc_hi, 0
	s_cmp_gt_u32 s56, 29
	s_mov_b64 s[10:11], s[28:29]
	s_barrier
	s_cbranch_scc0 .LBB0_856
	s_and_b64 vcc, exec, s[16:17]
	s_cbranch_vccz .LBB0_859
	s_barrier

.LBB0_1096:
	ds_read_b128 v[174:177], v143
	ds_read_b128 v[178:181], v153
	ds_read_b128 v[182:185], v159
	ds_read_b128 v[186:189], v160
	ds_read_b128 v[190:193], v161
	ds_read_b128 v[198:201], v162
	ds_read_b128 v[202:205], v163
	ds_read_b128 v[206:209], v164
	s_add_u32 s48, s24, 0xfffc0080
	s_addc_u32 s49, s25, -1
	s_cmp_eq_u32 s55, 12
	s_cselect_b32 s51, s4, s49
	s_cselect_b32 s50, s5, s48
	s_cselect_b32 s49, s15, s54
	s_cselect_b32 s48, s27, s39
	s_mov_b32 m0, s65
	ds_read_b128 v[210:213], v141
	ds_read_b128 v[214:217], v141 offset:1024
	ds_read_b128 v[218:221], v141 offset:2048
	ds_read_b128 v[222:225], v141 offset:3072
	ds_read_b128 v[226:229], v141 offset:4096
	ds_read_b128 v[230:233], v141 offset:5120
	ds_read_b128 v[234:237], v141 offset:6144
	ds_read_b128 v[238:241], v141 offset:7168
	global_load_lds_dwordx4 v132, s[24:25]
	s_mov_b32 m0, s67
	s_nop 0
	global_load_lds_dwordx4 v134, s[24:25]
	s_waitcnt vmcnt(8)
	s_waitcnt lgkmcnt(0)
	s_barrier
	v_mfma_f32_16x16x32_bf16 v[124:127], v[174:177], v[210:213], v[124:127]
	v_mfma_f32_16x16x32_bf16 v[120:123], v[182:185], v[210:213], v[120:123]
	v_mfma_f32_16x16x32_bf16 v[108:111], v[174:177], v[218:221], v[108:111]
	v_mfma_f32_16x16x32_bf16 v[104:107], v[182:185], v[218:221], v[104:107]
	v_mfma_f32_16x16x32_bf16 v[92:95], v[174:177], v[226:229], v[92:95]
	v_mfma_f32_16x16x32_bf16 v[88:91], v[182:185], v[226:229], v[88:91]
	v_mfma_f32_16x16x32_bf16 v[76:79], v[174:177], v[234:237], v[76:79]
	v_mfma_f32_16x16x32_bf16 v[72:75], v[182:185], v[234:237], v[72:75]
	v_mfma_f32_16x16x32_bf16 v[124:127], v[178:181], v[214:217], v[124:127]
	v_mfma_f32_16x16x32_bf16 v[120:123], v[186:189], v[214:217], v[120:123]
	v_mfma_f32_16x16x32_bf16 v[108:111], v[178:181], v[222:225], v[108:111]
	v_mfma_f32_16x16x32_bf16 v[104:107], v[186:189], v[222:225], v[104:107]
	v_mfma_f32_16x16x32_bf16 v[92:95], v[178:181], v[230:233], v[92:95]
	v_mfma_f32_16x16x32_bf16 v[88:91], v[186:189], v[230:233], v[88:91]
	v_mfma_f32_16x16x32_bf16 v[76:79], v[178:181], v[238:241], v[76:79]
	v_mfma_f32_16x16x32_bf16 v[72:75], v[186:189], v[238:241], v[72:75]
	v_mfma_f32_16x16x32_bf16 v[116:119], v[190:193], v[210:213], v[116:119]
	v_mfma_f32_16x16x32_bf16 v[112:115], v[202:205], v[210:213], v[112:115]
	v_mfma_f32_16x16x32_bf16 v[100:103], v[190:193], v[218:221], v[100:103]
	v_mfma_f32_16x16x32_bf16 v[96:99], v[202:205], v[218:221], v[96:99]
	v_mfma_f32_16x16x32_bf16 v[84:87], v[190:193], v[226:229], v[84:87]
	v_mfma_f32_16x16x32_bf16 v[80:83], v[202:205], v[226:229], v[80:83]
	v_mfma_f32_16x16x32_bf16 v[68:71], v[190:193], v[234:237], v[68:71]
	v_mfma_f32_16x16x32_bf16 v[64:67], v[202:205], v[234:237], v[64:67]
	v_mfma_f32_16x16x32_bf16 v[116:119], v[198:201], v[214:217], v[116:119]
	v_mfma_f32_16x16x32_bf16 v[112:115], v[206:209], v[214:217], v[112:115]
	v_mfma_f32_16x16x32_bf16 v[100:103], v[198:201], v[222:225], v[100:103]
	v_mfma_f32_16x16x32_bf16 v[96:99], v[206:209], v[222:225], v[96:99]
	v_mfma_f32_16x16x32_bf16 v[84:87], v[198:201], v[230:233], v[84:87]
	v_mfma_f32_16x16x32_bf16 v[80:83], v[206:209], v[230:233], v[80:83]
	v_mfma_f32_16x16x32_bf16 v[68:71], v[198:201], v[238:241], v[68:71]
	v_mfma_f32_16x16x32_bf16 v[64:67], v[206:209], v[238:241], v[64:67]
	s_add_u32 s98, s48, s8
	s_addc_u32 s99, s49, s9
	s_add_u32 s100, s50, s8
	s_addc_u32 s101, s51, s9
	s_barrier
	s_mov_b32 m0, s28
	s_add_u32 s68, s48, 0x40000
	ds_read_b128 v[210:213], v141 offset:16384
	ds_read_b128 v[214:217], v141 offset:17408
	ds_read_b128 v[218:221], v141 offset:18432
	ds_read_b128 v[222:225], v141 offset:19456
	ds_read_b128 v[226:229], v141 offset:20480
	ds_read_b128 v[230:233], v141 offset:21504
	ds_read_b128 v[234:237], v141 offset:22528
	ds_read_b128 v[238:241], v141 offset:23552
	global_load_lds_dwordx4 v130, s[48:49]
	s_mov_b32 m0, s29
	s_addc_u32 s69, s49, 0
	global_load_lds_dwordx4 v128, s[48:49]
	s_mov_b32 m0, s30
	s_nop 0
	global_load_lds_dwordx4 v130, s[68:69]
	s_mov_b32 m0, s31
	s_nop 0
	global_load_lds_dwordx4 v128, s[68:69]
	s_mov_b32 m0, s2
	s_nop 0
	global_load_lds_dwordx4 v130, s[50:51]
	s_mov_b32 m0, s33
	s_nop 0
	global_load_lds_dwordx4 v128, s[50:51]
	s_waitcnt vmcnt(8)
	s_waitcnt lgkmcnt(0)
	s_barrier
	v_mfma_f32_16x16x32_bf16 v[60:63], v[174:177], v[210:213], v[60:63]
	v_mfma_f32_16x16x32_bf16 v[56:59], v[182:185], v[210:213], v[56:59]
	v_mfma_f32_16x16x32_bf16 v[44:47], v[174:177], v[218:221], v[44:47]
	v_mfma_f32_16x16x32_bf16 v[40:43], v[182:185], v[218:221], v[40:43]
	v_mfma_f32_16x16x32_bf16 v[28:31], v[174:177], v[226:229], v[28:31]
	v_mfma_f32_16x16x32_bf16 v[24:27], v[182:185], v[226:229], v[24:27]
	v_mfma_f32_16x16x32_bf16 v[12:15], v[174:177], v[234:237], v[12:15]
	v_mfma_f32_16x16x32_bf16 v[8:11], v[182:185], v[234:237], v[8:11]
	v_mfma_f32_16x16x32_bf16 v[60:63], v[178:181], v[214:217], v[60:63]
	v_mfma_f32_16x16x32_bf16 v[56:59], v[186:189], v[214:217], v[56:59]
	v_mfma_f32_16x16x32_bf16 v[44:47], v[178:181], v[222:225], v[44:47]
	v_mfma_f32_16x16x32_bf16 v[40:43], v[186:189], v[222:225], v[40:43]
	v_mfma_f32_16x16x32_bf16 v[28:31], v[178:181], v[230:233], v[28:31]
	v_mfma_f32_16x16x32_bf16 v[24:27], v[186:189], v[230:233], v[24:27]
	v_mfma_f32_16x16x32_bf16 v[12:15], v[178:181], v[238:241], v[12:15]
	v_mfma_f32_16x16x32_bf16 v[8:11], v[186:189], v[238:241], v[8:11]
	v_mfma_f32_16x16x32_bf16 v[52:55], v[190:193], v[210:213], v[52:55]
	v_mfma_f32_16x16x32_bf16 v[48:51], v[202:205], v[210:213], v[48:51]
	v_mfma_f32_16x16x32_bf16 v[36:39], v[190:193], v[218:221], v[36:39]
	v_mfma_f32_16x16x32_bf16 v[32:35], v[202:205], v[218:221], v[32:35]
	v_mfma_f32_16x16x32_bf16 v[20:23], v[190:193], v[226:229], v[20:23]
	v_mfma_f32_16x16x32_bf16 v[16:19], v[202:205], v[226:229], v[16:19]
	v_mfma_f32_16x16x32_bf16 v[4:7], v[190:193], v[234:237], v[4:7]
	v_mfma_f32_16x16x32_bf16 v[0:3], v[202:205], v[234:237], v[0:3]
	v_mfma_f32_16x16x32_bf16 v[52:55], v[198:201], v[214:217], v[52:55]
	v_mfma_f32_16x16x32_bf16 v[48:51], v[206:209], v[214:217], v[48:51]
	v_mfma_f32_16x16x32_bf16 v[36:39], v[198:201], v[222:225], v[36:39]
	v_mfma_f32_16x16x32_bf16 v[32:35], v[206:209], v[222:225], v[32:35]
	v_mfma_f32_16x16x32_bf16 v[20:23], v[198:201], v[230:233], v[20:23]
	v_mfma_f32_16x16x32_bf16 v[16:19], v[206:209], v[230:233], v[16:19]
	v_mfma_f32_16x16x32_bf16 v[4:7], v[198:201], v[238:241], v[4:7]
	v_mfma_f32_16x16x32_bf16 v[0:3], v[206:209], v[238:241], v[0:3]
	s_barrier
	ds_read_b128 v[174:177], v165
	ds_read_b128 v[178:181], v166
	ds_read_b128 v[182:185], v167
	ds_read_b128 v[186:189], v168
	ds_read_b128 v[190:193], v169
	ds_read_b128 v[198:201], v170
	ds_read_b128 v[202:205], v171
	ds_read_b128 v[206:209], v172
	s_add_u32 s50, s50, 0x40000
	s_addc_u32 s51, s51, 0
	s_mov_b32 m0, s34
	ds_read_b128 v[210:213], v141 offset:32768
	ds_read_b128 v[214:217], v141 offset:33792
	ds_read_b128 v[218:221], v141 offset:34816
	ds_read_b128 v[222:225], v141 offset:35840
	ds_read_b128 v[226:229], v141 offset:36864
	ds_read_b128 v[230:233], v141 offset:37888
	ds_read_b128 v[234:237], v141 offset:38912
	ds_read_b128 v[238:241], v141 offset:39936
	global_load_lds_dwordx4 v130, s[50:51]
	s_mov_b32 m0, s35
	s_nop 0
	global_load_lds_dwordx4 v128, s[50:51]
	s_waitcnt vmcnt(8)
	s_waitcnt lgkmcnt(0)
	s_barrier
	v_mfma_f32_16x16x32_bf16 v[124:127], v[174:177], v[210:213], v[124:127]
	v_mfma_f32_16x16x32_bf16 v[120:123], v[182:185], v[210:213], v[120:123]
	v_mfma_f32_16x16x32_bf16 v[108:111], v[174:177], v[218:221], v[108:111]
	v_mfma_f32_16x16x32_bf16 v[104:107], v[182:185], v[218:221], v[104:107]
	v_mfma_f32_16x16x32_bf16 v[92:95], v[174:177], v[226:229], v[92:95]
	v_mfma_f32_16x16x32_bf16 v[88:91], v[182:185], v[226:229], v[88:91]
	v_mfma_f32_16x16x32_bf16 v[76:79], v[174:177], v[234:237], v[76:79]
	v_mfma_f32_16x16x32_bf16 v[72:75], v[182:185], v[234:237], v[72:75]
	v_mfma_f32_16x16x32_bf16 v[124:127], v[178:181], v[214:217], v[124:127]
	v_mfma_f32_16x16x32_bf16 v[120:123], v[186:189], v[214:217], v[120:123]
	v_mfma_f32_16x16x32_bf16 v[108:111], v[178:181], v[222:225], v[108:111]
	v_mfma_f32_16x16x32_bf16 v[104:107], v[186:189], v[222:225], v[104:107]
	v_mfma_f32_16x16x32_bf16 v[92:95], v[178:181], v[230:233], v[92:95]
	v_mfma_f32_16x16x32_bf16 v[88:91], v[186:189], v[230:233], v[88:91]
	v_mfma_f32_16x16x32_bf16 v[76:79], v[178:181], v[238:241], v[76:79]
	v_mfma_f32_16x16x32_bf16 v[72:75], v[186:189], v[238:241], v[72:75]
	v_mfma_f32_16x16x32_bf16 v[116:119], v[190:193], v[210:213], v[116:119]
	v_mfma_f32_16x16x32_bf16 v[112:115], v[202:205], v[210:213], v[112:115]
	v_mfma_f32_16x16x32_bf16 v[100:103], v[190:193], v[218:221], v[100:103]
	v_mfma_f32_16x16x32_bf16 v[96:99], v[202:205], v[218:221], v[96:99]
	v_mfma_f32_16x16x32_bf16 v[84:87], v[190:193], v[226:229], v[84:87]
	v_mfma_f32_16x16x32_bf16 v[80:83], v[202:205], v[226:229], v[80:83]
	v_mfma_f32_16x16x32_bf16 v[68:71], v[190:193], v[234:237], v[68:71]
	v_mfma_f32_16x16x32_bf16 v[64:67], v[202:205], v[234:237], v[64:67]
	v_mfma_f32_16x16x32_bf16 v[116:119], v[198:201], v[214:217], v[116:119]
	v_mfma_f32_16x16x32_bf16 v[112:115], v[206:209], v[214:217], v[112:115]
	v_mfma_f32_16x16x32_bf16 v[100:103], v[198:201], v[222:225], v[100:103]
	v_mfma_f32_16x16x32_bf16 v[96:99], v[206:209], v[222:225], v[96:99]
	v_mfma_f32_16x16x32_bf16 v[84:87], v[198:201], v[230:233], v[84:87]
	v_mfma_f32_16x16x32_bf16 v[80:83], v[206:209], v[230:233], v[80:83]
	v_mfma_f32_16x16x32_bf16 v[68:71], v[198:201], v[238:241], v[68:71]
	v_mfma_f32_16x16x32_bf16 v[64:67], v[206:209], v[238:241], v[64:67]
	s_barrier
	s_mov_b32 m0, s40
	s_add_u32 s48, s48, 0x40080
	ds_read_b128 v[210:213], v141 offset:49152
	ds_read_b128 v[214:217], v141 offset:50176
	ds_read_b128 v[218:221], v141 offset:51200
	ds_read_b128 v[222:225], v141 offset:52224
	ds_read_b128 v[226:229], v141 offset:53248
	ds_read_b128 v[230:233], v141 offset:54272
	ds_read_b128 v[234:237], v141 offset:55296
	ds_read_b128 v[238:241], v141 offset:56320
	global_load_lds_dwordx4 v130, s[98:99]
	s_mov_b32 m0, s41
	s_addc_u32 s49, s49, 0
	global_load_lds_dwordx4 v128, s[98:99]
	s_mov_b32 m0, s53
	s_nop 0
	global_load_lds_dwordx4 v130, s[48:49]
	s_mov_b32 m0, s60
	s_nop 0
	global_load_lds_dwordx4 v128, s[48:49]
	s_mov_b32 m0, s47
	s_nop 0
	global_load_lds_dwordx4 v130, s[100:101]
	s_mov_b32 m0, s52
	s_nop 0
	global_load_lds_dwordx4 v128, s[100:101]
	s_waitcnt vmcnt(8)
	s_waitcnt lgkmcnt(0)
	s_barrier
	v_mfma_f32_16x16x32_bf16 v[60:63], v[174:177], v[210:213], v[60:63]
	v_mfma_f32_16x16x32_bf16 v[56:59], v[182:185], v[210:213], v[56:59]
	v_mfma_f32_16x16x32_bf16 v[44:47], v[174:177], v[218:221], v[44:47]
	v_mfma_f32_16x16x32_bf16 v[40:43], v[182:185], v[218:221], v[40:43]
	v_mfma_f32_16x16x32_bf16 v[28:31], v[174:177], v[226:229], v[28:31]
	v_mfma_f32_16x16x32_bf16 v[24:27], v[182:185], v[226:229], v[24:27]
	v_mfma_f32_16x16x32_bf16 v[12:15], v[174:177], v[234:237], v[12:15]
	v_mfma_f32_16x16x32_bf16 v[8:11], v[182:185], v[234:237], v[8:11]
	v_mfma_f32_16x16x32_bf16 v[60:63], v[178:181], v[214:217], v[60:63]
	v_mfma_f32_16x16x32_bf16 v[56:59], v[186:189], v[214:217], v[56:59]
	v_mfma_f32_16x16x32_bf16 v[44:47], v[178:181], v[222:225], v[44:47]
	v_mfma_f32_16x16x32_bf16 v[40:43], v[186:189], v[222:225], v[40:43]
	v_mfma_f32_16x16x32_bf16 v[28:31], v[178:181], v[230:233], v[28:31]
	v_mfma_f32_16x16x32_bf16 v[24:27], v[186:189], v[230:233], v[24:27]
	v_mfma_f32_16x16x32_bf16 v[12:15], v[178:181], v[238:241], v[12:15]
	v_mfma_f32_16x16x32_bf16 v[8:11], v[186:189], v[238:241], v[8:11]
	v_mfma_f32_16x16x32_bf16 v[52:55], v[190:193], v[210:213], v[52:55]
	v_mfma_f32_16x16x32_bf16 v[48:51], v[202:205], v[210:213], v[48:51]
	v_mfma_f32_16x16x32_bf16 v[36:39], v[190:193], v[218:221], v[36:39]
	v_mfma_f32_16x16x32_bf16 v[32:35], v[202:205], v[218:221], v[32:35]
	v_mfma_f32_16x16x32_bf16 v[20:23], v[190:193], v[226:229], v[20:23]
	v_mfma_f32_16x16x32_bf16 v[16:19], v[202:205], v[226:229], v[16:19]
	v_mfma_f32_16x16x32_bf16 v[4:7], v[190:193], v[234:237], v[4:7]
	v_mfma_f32_16x16x32_bf16 v[0:3], v[202:205], v[234:237], v[0:3]
	v_mfma_f32_16x16x32_bf16 v[52:55], v[198:201], v[214:217], v[52:55]
	v_mfma_f32_16x16x32_bf16 v[48:51], v[206:209], v[214:217], v[48:51]
	v_mfma_f32_16x16x32_bf16 v[36:39], v[198:201], v[222:225], v[36:39]
	v_mfma_f32_16x16x32_bf16 v[32:35], v[206:209], v[222:225], v[32:35]
	v_mfma_f32_16x16x32_bf16 v[20:23], v[198:201], v[230:233], v[20:23]
	v_mfma_f32_16x16x32_bf16 v[16:19], v[206:209], v[230:233], v[16:19]
	v_mfma_f32_16x16x32_bf16 v[4:7], v[198:201], v[238:241], v[4:7]
	v_mfma_f32_16x16x32_bf16 v[0:3], v[206:209], v[238:241], v[0:3]
	s_add_i32 s55, s55, 2
	s_add_u32 s24, s24, 0x100
	s_addc_u32 s25, s25, 0
	s_add_u32 s39, s39, 0x100
	s_addc_u32 s54, s54, 0
	s_cmp_gt_u32 s55, 13
	s_barrier
	s_cbranch_scc0 .LBB0_1096
	s_and_b64 vcc, exec, s[12:13]
	s_cbranch_vccz .LBB0_1099
	s_barrier

.LBB0_1176:
	ds_read_b128 v[128:131], v183
	ds_read_b128 v[132:135], v184
	ds_read_b128 v[136:139], v185
	ds_read_b128 v[168:171], v186
	ds_read_b128 v[172:175], v187
	ds_read_b128 v[176:179], v188
	ds_read_b128 v[204:207], v189
	ds_read_b128 v[208:211], v190
	s_add_u32 s46, s24, 0x100
	s_addc_u32 s47, s25, 0
	s_cmp_eq_u32 s66, 40
	s_cselect_b32 s51, s13, s47
	s_cselect_b32 s50, s12, s46
	s_cselect_b32 s49, s45, s5
	s_cselect_b32 s48, s44, s4
	s_mov_b32 m0, s60
	ds_read_b128 v[212:215], v159
	ds_read_b128 v[216:219], v159 offset:1024
	ds_read_b128 v[220:223], v159 offset:2048
	ds_read_b128 v[224:227], v159 offset:3072
	ds_read_b128 v[228:231], v159 offset:4096
	ds_read_b128 v[232:235], v159 offset:5120
	ds_read_b128 v[236:239], v159 offset:6144
	ds_read_b128 v[240:243], v159 offset:7168
	global_load_lds_dwordx4 v160, s[24:25]
	s_mov_b32 m0, s61
	s_nop 0
	global_load_lds_dwordx4 v162, s[24:25]
	s_waitcnt vmcnt(8)
	s_waitcnt lgkmcnt(0)
	s_barrier
	v_mfma_f32_16x16x32_bf16 v[124:127], v[128:131], v[212:215], v[124:127]
	v_mfma_f32_16x16x32_bf16 v[120:123], v[136:139], v[212:215], v[120:123]
	v_mfma_f32_16x16x32_bf16 v[108:111], v[128:131], v[220:223], v[108:111]
	v_mfma_f32_16x16x32_bf16 v[104:107], v[136:139], v[220:223], v[104:107]
	v_mfma_f32_16x16x32_bf16 v[92:95], v[128:131], v[228:231], v[92:95]
	v_mfma_f32_16x16x32_bf16 v[88:91], v[136:139], v[228:231], v[88:91]
	v_mfma_f32_16x16x32_bf16 v[76:79], v[128:131], v[236:239], v[76:79]
	v_mfma_f32_16x16x32_bf16 v[72:75], v[136:139], v[236:239], v[72:75]
	v_mfma_f32_16x16x32_bf16 v[124:127], v[132:135], v[216:219], v[124:127]
	v_mfma_f32_16x16x32_bf16 v[120:123], v[168:171], v[216:219], v[120:123]
	v_mfma_f32_16x16x32_bf16 v[108:111], v[132:135], v[224:227], v[108:111]
	v_mfma_f32_16x16x32_bf16 v[104:107], v[168:171], v[224:227], v[104:107]
	v_mfma_f32_16x16x32_bf16 v[92:95], v[132:135], v[232:235], v[92:95]
	v_mfma_f32_16x16x32_bf16 v[88:91], v[168:171], v[232:235], v[88:91]
	v_mfma_f32_16x16x32_bf16 v[76:79], v[132:135], v[240:243], v[76:79]
	v_mfma_f32_16x16x32_bf16 v[72:75], v[168:171], v[240:243], v[72:75]
	v_mfma_f32_16x16x32_bf16 v[116:119], v[172:175], v[212:215], v[116:119]
	v_mfma_f32_16x16x32_bf16 v[112:115], v[204:207], v[212:215], v[112:115]
	v_mfma_f32_16x16x32_bf16 v[100:103], v[172:175], v[220:223], v[100:103]
	v_mfma_f32_16x16x32_bf16 v[96:99], v[204:207], v[220:223], v[96:99]
	v_mfma_f32_16x16x32_bf16 v[84:87], v[172:175], v[228:231], v[84:87]
	v_mfma_f32_16x16x32_bf16 v[80:83], v[204:207], v[228:231], v[80:83]
	v_mfma_f32_16x16x32_bf16 v[68:71], v[172:175], v[236:239], v[68:71]
	v_mfma_f32_16x16x32_bf16 v[64:67], v[204:207], v[236:239], v[64:67]
	v_mfma_f32_16x16x32_bf16 v[116:119], v[176:179], v[216:219], v[116:119]
	v_mfma_f32_16x16x32_bf16 v[112:115], v[208:211], v[216:219], v[112:115]
	v_mfma_f32_16x16x32_bf16 v[100:103], v[176:179], v[224:227], v[100:103]
	v_mfma_f32_16x16x32_bf16 v[96:99], v[208:211], v[224:227], v[96:99]
	v_mfma_f32_16x16x32_bf16 v[84:87], v[176:179], v[232:235], v[84:87]
	v_mfma_f32_16x16x32_bf16 v[80:83], v[208:211], v[232:235], v[80:83]
	v_mfma_f32_16x16x32_bf16 v[68:71], v[176:179], v[240:243], v[68:71]
	v_mfma_f32_16x16x32_bf16 v[64:67], v[208:211], v[240:243], v[64:67]
	s_add_u32 s98, s48, s14
	s_addc_u32 s99, s49, s15
	s_add_u32 s100, s50, s14
	s_addc_u32 s101, s51, s15
	s_barrier
	s_mov_b32 m0, s7
	s_add_u32 s24, s48, 0xb0000
	ds_read_b128 v[212:215], v159 offset:16384
	ds_read_b128 v[216:219], v159 offset:17408
	ds_read_b128 v[220:223], v159 offset:18432
	ds_read_b128 v[224:227], v159 offset:19456
	ds_read_b128 v[228:231], v159 offset:20480
	ds_read_b128 v[232:235], v159 offset:21504
	ds_read_b128 v[236:239], v159 offset:22528
	ds_read_b128 v[240:243], v159 offset:23552
	global_load_lds_dwordx4 v140, s[48:49]
	s_mov_b32 m0, s28
	s_addc_u32 s25, s49, 0
	global_load_lds_dwordx4 v142, s[48:49]
	s_mov_b32 m0, s29
	s_nop 0
	global_load_lds_dwordx4 v140, s[24:25]
	s_mov_b32 m0, s30
	s_nop 0
	global_load_lds_dwordx4 v142, s[24:25]
	s_mov_b32 m0, s6
	s_nop 0
	global_load_lds_dwordx4 v140, s[50:51]
	s_mov_b32 m0, s31
	s_nop 0
	global_load_lds_dwordx4 v142, s[50:51]
	s_waitcnt vmcnt(8)
	s_waitcnt lgkmcnt(0)
	s_barrier
	v_mfma_f32_16x16x32_bf16 v[60:63], v[128:131], v[212:215], v[60:63]
	v_mfma_f32_16x16x32_bf16 v[56:59], v[136:139], v[212:215], v[56:59]
	v_mfma_f32_16x16x32_bf16 v[44:47], v[128:131], v[220:223], v[44:47]
	v_mfma_f32_16x16x32_bf16 v[40:43], v[136:139], v[220:223], v[40:43]
	v_mfma_f32_16x16x32_bf16 v[28:31], v[128:131], v[228:231], v[28:31]
	v_mfma_f32_16x16x32_bf16 v[24:27], v[136:139], v[228:231], v[24:27]
	v_mfma_f32_16x16x32_bf16 v[12:15], v[128:131], v[236:239], v[12:15]
	v_mfma_f32_16x16x32_bf16 v[8:11], v[136:139], v[236:239], v[8:11]
	v_mfma_f32_16x16x32_bf16 v[60:63], v[132:135], v[216:219], v[60:63]
	v_mfma_f32_16x16x32_bf16 v[56:59], v[168:171], v[216:219], v[56:59]
	v_mfma_f32_16x16x32_bf16 v[44:47], v[132:135], v[224:227], v[44:47]
	v_mfma_f32_16x16x32_bf16 v[40:43], v[168:171], v[224:227], v[40:43]
	v_mfma_f32_16x16x32_bf16 v[28:31], v[132:135], v[232:235], v[28:31]
	v_mfma_f32_16x16x32_bf16 v[24:27], v[168:171], v[232:235], v[24:27]
	v_mfma_f32_16x16x32_bf16 v[12:15], v[132:135], v[240:243], v[12:15]
	v_mfma_f32_16x16x32_bf16 v[8:11], v[168:171], v[240:243], v[8:11]
	v_mfma_f32_16x16x32_bf16 v[52:55], v[172:175], v[212:215], v[52:55]
	v_mfma_f32_16x16x32_bf16 v[48:51], v[204:207], v[212:215], v[48:51]
	v_mfma_f32_16x16x32_bf16 v[36:39], v[172:175], v[220:223], v[36:39]
	v_mfma_f32_16x16x32_bf16 v[32:35], v[204:207], v[220:223], v[32:35]
	v_mfma_f32_16x16x32_bf16 v[20:23], v[172:175], v[228:231], v[20:23]
	v_mfma_f32_16x16x32_bf16 v[16:19], v[204:207], v[228:231], v[16:19]
	v_mfma_f32_16x16x32_bf16 v[4:7], v[172:175], v[236:239], v[4:7]
	v_mfma_f32_16x16x32_bf16 v[0:3], v[204:207], v[236:239], v[0:3]
	v_mfma_f32_16x16x32_bf16 v[52:55], v[176:179], v[216:219], v[52:55]
	v_mfma_f32_16x16x32_bf16 v[48:51], v[208:211], v[216:219], v[48:51]
	v_mfma_f32_16x16x32_bf16 v[36:39], v[176:179], v[224:227], v[36:39]
	v_mfma_f32_16x16x32_bf16 v[32:35], v[208:211], v[224:227], v[32:35]
	v_mfma_f32_16x16x32_bf16 v[20:23], v[176:179], v[232:235], v[20:23]
	v_mfma_f32_16x16x32_bf16 v[16:19], v[208:211], v[232:235], v[16:19]
	v_mfma_f32_16x16x32_bf16 v[4:7], v[176:179], v[240:243], v[4:7]
	v_mfma_f32_16x16x32_bf16 v[0:3], v[208:211], v[240:243], v[0:3]
	s_barrier
	ds_read_b128 v[128:131], v191
	ds_read_b128 v[132:135], v192
	ds_read_b128 v[136:139], v193
	ds_read_b128 v[168:171], v197
	ds_read_b128 v[172:175], v198
	ds_read_b128 v[176:179], v199
	ds_read_b128 v[204:207], v200
	ds_read_b128 v[208:211], v201
	s_add_u32 s24, s50, 0xb0000
	s_addc_u32 s25, s51, 0
	s_mov_b32 m0, s33
	ds_read_b128 v[212:215], v159 offset:32768
	ds_read_b128 v[216:219], v159 offset:33792
	ds_read_b128 v[220:223], v159 offset:34816
	ds_read_b128 v[224:227], v159 offset:35840
	ds_read_b128 v[228:231], v159 offset:36864
	ds_read_b128 v[232:235], v159 offset:37888
	ds_read_b128 v[236:239], v159 offset:38912
	ds_read_b128 v[240:243], v159 offset:39936
	global_load_lds_dwordx4 v140, s[24:25]
	s_mov_b32 m0, s34
	s_nop 0
	global_load_lds_dwordx4 v142, s[24:25]
	s_waitcnt vmcnt(8)
	s_waitcnt lgkmcnt(0)
	s_barrier
	v_mfma_f32_16x16x32_bf16 v[124:127], v[128:131], v[212:215], v[124:127]
	v_mfma_f32_16x16x32_bf16 v[120:123], v[136:139], v[212:215], v[120:123]
	v_mfma_f32_16x16x32_bf16 v[108:111], v[128:131], v[220:223], v[108:111]
	v_mfma_f32_16x16x32_bf16 v[104:107], v[136:139], v[220:223], v[104:107]
	v_mfma_f32_16x16x32_bf16 v[92:95], v[128:131], v[228:231], v[92:95]
	v_mfma_f32_16x16x32_bf16 v[88:91], v[136:139], v[228:231], v[88:91]
	v_mfma_f32_16x16x32_bf16 v[76:79], v[128:131], v[236:239], v[76:79]
	v_mfma_f32_16x16x32_bf16 v[72:75], v[136:139], v[236:239], v[72:75]
	v_mfma_f32_16x16x32_bf16 v[124:127], v[132:135], v[216:219], v[124:127]
	v_mfma_f32_16x16x32_bf16 v[120:123], v[168:171], v[216:219], v[120:123]
	v_mfma_f32_16x16x32_bf16 v[108:111], v[132:135], v[224:227], v[108:111]
	v_mfma_f32_16x16x32_bf16 v[104:107], v[168:171], v[224:227], v[104:107]
	v_mfma_f32_16x16x32_bf16 v[92:95], v[132:135], v[232:235], v[92:95]
	v_mfma_f32_16x16x32_bf16 v[88:91], v[168:171], v[232:235], v[88:91]
	v_mfma_f32_16x16x32_bf16 v[76:79], v[132:135], v[240:243], v[76:79]
	v_mfma_f32_16x16x32_bf16 v[72:75], v[168:171], v[240:243], v[72:75]
	v_mfma_f32_16x16x32_bf16 v[116:119], v[172:175], v[212:215], v[116:119]
	v_mfma_f32_16x16x32_bf16 v[112:115], v[204:207], v[212:215], v[112:115]
	v_mfma_f32_16x16x32_bf16 v[100:103], v[172:175], v[220:223], v[100:103]
	v_mfma_f32_16x16x32_bf16 v[96:99], v[204:207], v[220:223], v[96:99]
	v_mfma_f32_16x16x32_bf16 v[84:87], v[172:175], v[228:231], v[84:87]
	v_mfma_f32_16x16x32_bf16 v[80:83], v[204:207], v[228:231], v[80:83]
	v_mfma_f32_16x16x32_bf16 v[68:71], v[172:175], v[236:239], v[68:71]
	v_mfma_f32_16x16x32_bf16 v[64:67], v[204:207], v[236:239], v[64:67]
	v_mfma_f32_16x16x32_bf16 v[116:119], v[176:179], v[216:219], v[116:119]
	v_mfma_f32_16x16x32_bf16 v[112:115], v[208:211], v[216:219], v[112:115]
	v_mfma_f32_16x16x32_bf16 v[100:103], v[176:179], v[224:227], v[100:103]
	v_mfma_f32_16x16x32_bf16 v[96:99], v[208:211], v[224:227], v[96:99]
	v_mfma_f32_16x16x32_bf16 v[84:87], v[176:179], v[232:235], v[84:87]
	v_mfma_f32_16x16x32_bf16 v[80:83], v[208:211], v[232:235], v[80:83]
	v_mfma_f32_16x16x32_bf16 v[68:71], v[176:179], v[240:243], v[68:71]
	v_mfma_f32_16x16x32_bf16 v[64:67], v[208:211], v[240:243], v[64:67]
	s_barrier
	s_mov_b32 m0, s35
	s_add_u32 s24, s48, 0xb0080
	ds_read_b128 v[212:215], v159 offset:49152
	ds_read_b128 v[216:219], v159 offset:50176
	ds_read_b128 v[220:223], v159 offset:51200
	ds_read_b128 v[224:227], v159 offset:52224
	ds_read_b128 v[228:231], v159 offset:53248
	ds_read_b128 v[232:235], v159 offset:54272
	ds_read_b128 v[236:239], v159 offset:55296
	ds_read_b128 v[240:243], v159 offset:56320
	global_load_lds_dwordx4 v140, s[98:99]
	s_mov_b32 m0, s36
	s_addc_u32 s25, s49, 0
	global_load_lds_dwordx4 v142, s[98:99]
	s_mov_b32 m0, s41
	s_nop 0
	global_load_lds_dwordx4 v140, s[24:25]
	s_mov_b32 m0, s43
	s_nop 0
	global_load_lds_dwordx4 v142, s[24:25]
	s_mov_b32 m0, s37
	s_nop 0
	global_load_lds_dwordx4 v140, s[100:101]
	s_mov_b32 m0, s40
	s_nop 0
	global_load_lds_dwordx4 v142, s[100:101]
	s_waitcnt vmcnt(8)
	s_waitcnt lgkmcnt(0)
	s_barrier
	v_mfma_f32_16x16x32_bf16 v[60:63], v[128:131], v[212:215], v[60:63]
	v_mfma_f32_16x16x32_bf16 v[56:59], v[136:139], v[212:215], v[56:59]
	v_mfma_f32_16x16x32_bf16 v[44:47], v[128:131], v[220:223], v[44:47]
	v_mfma_f32_16x16x32_bf16 v[40:43], v[136:139], v[220:223], v[40:43]
	v_mfma_f32_16x16x32_bf16 v[28:31], v[128:131], v[228:231], v[28:31]
	v_mfma_f32_16x16x32_bf16 v[24:27], v[136:139], v[228:231], v[24:27]
	v_mfma_f32_16x16x32_bf16 v[12:15], v[128:131], v[236:239], v[12:15]
	v_mfma_f32_16x16x32_bf16 v[8:11], v[136:139], v[236:239], v[8:11]
	v_mfma_f32_16x16x32_bf16 v[60:63], v[132:135], v[216:219], v[60:63]
	v_mfma_f32_16x16x32_bf16 v[56:59], v[168:171], v[216:219], v[56:59]
	v_mfma_f32_16x16x32_bf16 v[44:47], v[132:135], v[224:227], v[44:47]
	v_mfma_f32_16x16x32_bf16 v[40:43], v[168:171], v[224:227], v[40:43]
	v_mfma_f32_16x16x32_bf16 v[28:31], v[132:135], v[232:235], v[28:31]
	v_mfma_f32_16x16x32_bf16 v[24:27], v[168:171], v[232:235], v[24:27]
	v_mfma_f32_16x16x32_bf16 v[12:15], v[132:135], v[240:243], v[12:15]
	v_mfma_f32_16x16x32_bf16 v[8:11], v[168:171], v[240:243], v[8:11]
	v_mfma_f32_16x16x32_bf16 v[52:55], v[172:175], v[212:215], v[52:55]
	v_mfma_f32_16x16x32_bf16 v[48:51], v[204:207], v[212:215], v[48:51]
	v_mfma_f32_16x16x32_bf16 v[36:39], v[172:175], v[220:223], v[36:39]
	v_mfma_f32_16x16x32_bf16 v[32:35], v[204:207], v[220:223], v[32:35]
	v_mfma_f32_16x16x32_bf16 v[20:23], v[172:175], v[228:231], v[20:23]
	v_mfma_f32_16x16x32_bf16 v[16:19], v[204:207], v[228:231], v[16:19]
	v_mfma_f32_16x16x32_bf16 v[4:7], v[172:175], v[236:239], v[4:7]
	v_mfma_f32_16x16x32_bf16 v[0:3], v[204:207], v[236:239], v[0:3]
	v_mfma_f32_16x16x32_bf16 v[52:55], v[176:179], v[216:219], v[52:55]
	v_mfma_f32_16x16x32_bf16 v[48:51], v[208:211], v[216:219], v[48:51]
	v_mfma_f32_16x16x32_bf16 v[36:39], v[176:179], v[224:227], v[36:39]
	v_mfma_f32_16x16x32_bf16 v[32:35], v[208:211], v[224:227], v[32:35]
	v_mfma_f32_16x16x32_bf16 v[20:23], v[176:179], v[232:235], v[20:23]
	v_mfma_f32_16x16x32_bf16 v[16:19], v[208:211], v[232:235], v[16:19]
	v_mfma_f32_16x16x32_bf16 v[4:7], v[176:179], v[240:243], v[4:7]
	v_mfma_f32_16x16x32_bf16 v[0:3], v[208:211], v[240:243], v[0:3]
	s_add_i32 s66, s66, 2
	s_add_u32 s4, s4, 0x100
	s_addc_u32 s5, s5, 0
	s_cmp_gt_u32 s66, 41
	s_mov_b64 s[24:25], s[46:47]
	s_barrier
	s_cbranch_scc0 .LBB0_1176
	s_mov_b64 s[88:89], s[78:79]
	s_and_b64 vcc, exec, s[26:27]
	s_cbranch_vccz .LBB0_1179
	s_barrier

.LBB0_1334:
	ds_read_b128 v[160:163], v167
	ds_read_b128 v[184:187], v168
	ds_read_b128 v[188:191], v169
	ds_read_b128 v[198:201], v170
	ds_read_b128 v[202:205], v171
	ds_read_b128 v[206:209], v172
	ds_read_b128 v[210:213], v173
	ds_read_b128 v[214:217], v174
	s_add_u32 s24, s14, 0xfffc0080
	s_addc_u32 s25, s15, -1
	s_cmp_eq_u32 s66, 12
	s_cselect_b32 s65, s4, s25
	s_cselect_b32 s64, s5, s24
	s_cselect_b32 s25, s11, s49
	s_cselect_b32 s24, s13, s47
	s_mov_b32 m0, s61
	ds_read_b128 v[218:221], v159
	ds_read_b128 v[222:225], v159 offset:1024
	ds_read_b128 v[226:229], v159 offset:2048
	ds_read_b128 v[230:233], v159 offset:3072
	ds_read_b128 v[234:237], v159 offset:4096
	ds_read_b128 v[238:241], v159 offset:5120
	ds_read_b128 v[242:245], v159 offset:6144
	ds_read_b128 v[246:249], v159 offset:7168
	global_load_lds_dwordx4 v134, s[14:15]
	s_mov_b32 m0, s67
	s_nop 0
	global_load_lds_dwordx4 v136, s[14:15]
	s_waitcnt vmcnt(8)
	s_waitcnt lgkmcnt(0)
	s_barrier
	v_mfma_f32_16x16x32_bf16 v[124:127], v[160:163], v[218:221], v[124:127]
	v_mfma_f32_16x16x32_bf16 v[120:123], v[188:191], v[218:221], v[120:123]
	v_mfma_f32_16x16x32_bf16 v[108:111], v[160:163], v[226:229], v[108:111]
	v_mfma_f32_16x16x32_bf16 v[104:107], v[188:191], v[226:229], v[104:107]
	v_mfma_f32_16x16x32_bf16 v[92:95], v[160:163], v[234:237], v[92:95]
	v_mfma_f32_16x16x32_bf16 v[88:91], v[188:191], v[234:237], v[88:91]
	v_mfma_f32_16x16x32_bf16 v[76:79], v[160:163], v[242:245], v[76:79]
	v_mfma_f32_16x16x32_bf16 v[72:75], v[188:191], v[242:245], v[72:75]
	v_mfma_f32_16x16x32_bf16 v[124:127], v[184:187], v[222:225], v[124:127]
	v_mfma_f32_16x16x32_bf16 v[120:123], v[198:201], v[222:225], v[120:123]
	v_mfma_f32_16x16x32_bf16 v[108:111], v[184:187], v[230:233], v[108:111]
	v_mfma_f32_16x16x32_bf16 v[104:107], v[198:201], v[230:233], v[104:107]
	v_mfma_f32_16x16x32_bf16 v[92:95], v[184:187], v[238:241], v[92:95]
	v_mfma_f32_16x16x32_bf16 v[88:91], v[198:201], v[238:241], v[88:91]
	v_mfma_f32_16x16x32_bf16 v[76:79], v[184:187], v[246:249], v[76:79]
	v_mfma_f32_16x16x32_bf16 v[72:75], v[198:201], v[246:249], v[72:75]
	v_mfma_f32_16x16x32_bf16 v[116:119], v[202:205], v[218:221], v[116:119]
	v_mfma_f32_16x16x32_bf16 v[112:115], v[210:213], v[218:221], v[112:115]
	v_mfma_f32_16x16x32_bf16 v[100:103], v[202:205], v[226:229], v[100:103]
	v_mfma_f32_16x16x32_bf16 v[96:99], v[210:213], v[226:229], v[96:99]
	v_mfma_f32_16x16x32_bf16 v[84:87], v[202:205], v[234:237], v[84:87]
	v_mfma_f32_16x16x32_bf16 v[80:83], v[210:213], v[234:237], v[80:83]
	v_mfma_f32_16x16x32_bf16 v[68:71], v[202:205], v[242:245], v[68:71]
	v_mfma_f32_16x16x32_bf16 v[64:67], v[210:213], v[242:245], v[64:67]
	v_mfma_f32_16x16x32_bf16 v[116:119], v[206:209], v[222:225], v[116:119]
	v_mfma_f32_16x16x32_bf16 v[112:115], v[214:217], v[222:225], v[112:115]
	v_mfma_f32_16x16x32_bf16 v[100:103], v[206:209], v[230:233], v[100:103]
	v_mfma_f32_16x16x32_bf16 v[96:99], v[214:217], v[230:233], v[96:99]
	v_mfma_f32_16x16x32_bf16 v[84:87], v[206:209], v[238:241], v[84:87]
	v_mfma_f32_16x16x32_bf16 v[80:83], v[214:217], v[238:241], v[80:83]
	v_mfma_f32_16x16x32_bf16 v[68:71], v[206:209], v[246:249], v[68:71]
	v_mfma_f32_16x16x32_bf16 v[64:67], v[214:217], v[246:249], v[64:67]
	s_add_u32 s98, s24, s38
	s_addc_u32 s99, s25, s39
	s_add_u32 s100, s64, s38
	s_addc_u32 s101, s65, s39
	s_barrier
	s_mov_b32 m0, s6
	s_add_u32 s68, s24, 0x40000
	ds_read_b128 v[218:221], v159 offset:16384
	ds_read_b128 v[222:225], v159 offset:17408
	ds_read_b128 v[226:229], v159 offset:18432
	ds_read_b128 v[230:233], v159 offset:19456
	ds_read_b128 v[234:237], v159 offset:20480
	ds_read_b128 v[238:241], v159 offset:21504
	ds_read_b128 v[242:245], v159 offset:22528
	ds_read_b128 v[246:249], v159 offset:23552
	global_load_lds_dwordx4 v128, s[24:25]
	s_mov_b32 m0, s7
	s_addc_u32 s69, s25, 0
	global_load_lds_dwordx4 v130, s[24:25]
	s_mov_b32 m0, s28
	s_nop 0
	global_load_lds_dwordx4 v128, s[68:69]
	s_mov_b32 m0, s29
	s_nop 0
	global_load_lds_dwordx4 v130, s[68:69]
	s_mov_b32 m0, s2
	s_nop 0
	global_load_lds_dwordx4 v128, s[64:65]
	s_mov_b32 m0, s30
	s_nop 0
	global_load_lds_dwordx4 v130, s[64:65]
	s_waitcnt vmcnt(8)
	s_waitcnt lgkmcnt(0)
	s_barrier
	v_mfma_f32_16x16x32_bf16 v[60:63], v[160:163], v[218:221], v[60:63]
	v_mfma_f32_16x16x32_bf16 v[56:59], v[188:191], v[218:221], v[56:59]
	v_mfma_f32_16x16x32_bf16 v[44:47], v[160:163], v[226:229], v[44:47]
	v_mfma_f32_16x16x32_bf16 v[40:43], v[188:191], v[226:229], v[40:43]
	v_mfma_f32_16x16x32_bf16 v[28:31], v[160:163], v[234:237], v[28:31]
	v_mfma_f32_16x16x32_bf16 v[24:27], v[188:191], v[234:237], v[24:27]
	v_mfma_f32_16x16x32_bf16 v[12:15], v[160:163], v[242:245], v[12:15]
	v_mfma_f32_16x16x32_bf16 v[8:11], v[188:191], v[242:245], v[8:11]
	v_mfma_f32_16x16x32_bf16 v[60:63], v[184:187], v[222:225], v[60:63]
	v_mfma_f32_16x16x32_bf16 v[56:59], v[198:201], v[222:225], v[56:59]
	v_mfma_f32_16x16x32_bf16 v[44:47], v[184:187], v[230:233], v[44:47]
	v_mfma_f32_16x16x32_bf16 v[40:43], v[198:201], v[230:233], v[40:43]
	v_mfma_f32_16x16x32_bf16 v[28:31], v[184:187], v[238:241], v[28:31]
	v_mfma_f32_16x16x32_bf16 v[24:27], v[198:201], v[238:241], v[24:27]
	v_mfma_f32_16x16x32_bf16 v[12:15], v[184:187], v[246:249], v[12:15]
	v_mfma_f32_16x16x32_bf16 v[8:11], v[198:201], v[246:249], v[8:11]
	v_mfma_f32_16x16x32_bf16 v[52:55], v[202:205], v[218:221], v[52:55]
	v_mfma_f32_16x16x32_bf16 v[48:51], v[210:213], v[218:221], v[48:51]
	v_mfma_f32_16x16x32_bf16 v[36:39], v[202:205], v[226:229], v[36:39]
	v_mfma_f32_16x16x32_bf16 v[32:35], v[210:213], v[226:229], v[32:35]
	v_mfma_f32_16x16x32_bf16 v[20:23], v[202:205], v[234:237], v[20:23]
	v_mfma_f32_16x16x32_bf16 v[16:19], v[210:213], v[234:237], v[16:19]
	v_mfma_f32_16x16x32_bf16 v[4:7], v[202:205], v[242:245], v[4:7]
	v_mfma_f32_16x16x32_bf16 v[0:3], v[210:213], v[242:245], v[0:3]
	v_mfma_f32_16x16x32_bf16 v[52:55], v[206:209], v[222:225], v[52:55]
	v_mfma_f32_16x16x32_bf16 v[48:51], v[214:217], v[222:225], v[48:51]
	v_mfma_f32_16x16x32_bf16 v[36:39], v[206:209], v[230:233], v[36:39]
	v_mfma_f32_16x16x32_bf16 v[32:35], v[214:217], v[230:233], v[32:35]
	v_mfma_f32_16x16x32_bf16 v[20:23], v[206:209], v[238:241], v[20:23]
	v_mfma_f32_16x16x32_bf16 v[16:19], v[214:217], v[238:241], v[16:19]
	v_mfma_f32_16x16x32_bf16 v[4:7], v[206:209], v[246:249], v[4:7]
	v_mfma_f32_16x16x32_bf16 v[0:3], v[214:217], v[246:249], v[0:3]
	s_barrier
	ds_read_b128 v[160:163], v175
	ds_read_b128 v[184:187], v176
	ds_read_b128 v[188:191], v177
	ds_read_b128 v[198:201], v178
	ds_read_b128 v[202:205], v179
	ds_read_b128 v[206:209], v180
	ds_read_b128 v[210:213], v181
	ds_read_b128 v[214:217], v182
	s_add_u32 s64, s64, 0x40000
	s_addc_u32 s65, s65, 0
	s_mov_b32 m0, s31
	ds_read_b128 v[218:221], v159 offset:32768
	ds_read_b128 v[222:225], v159 offset:33792
	ds_read_b128 v[226:229], v159 offset:34816
	ds_read_b128 v[230:233], v159 offset:35840
	ds_read_b128 v[234:237], v159 offset:36864
	ds_read_b128 v[238:241], v159 offset:37888
	ds_read_b128 v[242:245], v159 offset:38912
	ds_read_b128 v[246:249], v159 offset:39936
	global_load_lds_dwordx4 v128, s[64:65]
	s_mov_b32 m0, s33
	s_nop 0
	global_load_lds_dwordx4 v130, s[64:65]
	s_waitcnt vmcnt(8)
	s_waitcnt lgkmcnt(0)
	s_barrier
	v_mfma_f32_16x16x32_bf16 v[124:127], v[160:163], v[218:221], v[124:127]
	v_mfma_f32_16x16x32_bf16 v[120:123], v[188:191], v[218:221], v[120:123]
	v_mfma_f32_16x16x32_bf16 v[108:111], v[160:163], v[226:229], v[108:111]
	v_mfma_f32_16x16x32_bf16 v[104:107], v[188:191], v[226:229], v[104:107]
	v_mfma_f32_16x16x32_bf16 v[92:95], v[160:163], v[234:237], v[92:95]
	v_mfma_f32_16x16x32_bf16 v[88:91], v[188:191], v[234:237], v[88:91]
	v_mfma_f32_16x16x32_bf16 v[76:79], v[160:163], v[242:245], v[76:79]
	v_mfma_f32_16x16x32_bf16 v[72:75], v[188:191], v[242:245], v[72:75]
	v_mfma_f32_16x16x32_bf16 v[124:127], v[184:187], v[222:225], v[124:127]
	v_mfma_f32_16x16x32_bf16 v[120:123], v[198:201], v[222:225], v[120:123]
	v_mfma_f32_16x16x32_bf16 v[108:111], v[184:187], v[230:233], v[108:111]
	v_mfma_f32_16x16x32_bf16 v[104:107], v[198:201], v[230:233], v[104:107]
	v_mfma_f32_16x16x32_bf16 v[92:95], v[184:187], v[238:241], v[92:95]
	v_mfma_f32_16x16x32_bf16 v[88:91], v[198:201], v[238:241], v[88:91]
	v_mfma_f32_16x16x32_bf16 v[76:79], v[184:187], v[246:249], v[76:79]
	v_mfma_f32_16x16x32_bf16 v[72:75], v[198:201], v[246:249], v[72:75]
	v_mfma_f32_16x16x32_bf16 v[116:119], v[202:205], v[218:221], v[116:119]
	v_mfma_f32_16x16x32_bf16 v[112:115], v[210:213], v[218:221], v[112:115]
	v_mfma_f32_16x16x32_bf16 v[100:103], v[202:205], v[226:229], v[100:103]
	v_mfma_f32_16x16x32_bf16 v[96:99], v[210:213], v[226:229], v[96:99]
	v_mfma_f32_16x16x32_bf16 v[84:87], v[202:205], v[234:237], v[84:87]
	v_mfma_f32_16x16x32_bf16 v[80:83], v[210:213], v[234:237], v[80:83]
	v_mfma_f32_16x16x32_bf16 v[68:71], v[202:205], v[242:245], v[68:71]
	v_mfma_f32_16x16x32_bf16 v[64:67], v[210:213], v[242:245], v[64:67]
	v_mfma_f32_16x16x32_bf16 v[116:119], v[206:209], v[222:225], v[116:119]
	v_mfma_f32_16x16x32_bf16 v[112:115], v[214:217], v[222:225], v[112:115]
	v_mfma_f32_16x16x32_bf16 v[100:103], v[206:209], v[230:233], v[100:103]
	v_mfma_f32_16x16x32_bf16 v[96:99], v[214:217], v[230:233], v[96:99]
	v_mfma_f32_16x16x32_bf16 v[84:87], v[206:209], v[238:241], v[84:87]
	v_mfma_f32_16x16x32_bf16 v[80:83], v[214:217], v[238:241], v[80:83]
	v_mfma_f32_16x16x32_bf16 v[68:71], v[206:209], v[246:249], v[68:71]
	v_mfma_f32_16x16x32_bf16 v[64:67], v[214:217], v[246:249], v[64:67]
	s_barrier
	s_mov_b32 m0, s34
	s_add_u32 s24, s24, 0x40080
	ds_read_b128 v[218:221], v159 offset:49152
	ds_read_b128 v[222:225], v159 offset:50176
	ds_read_b128 v[226:229], v159 offset:51200
	ds_read_b128 v[230:233], v159 offset:52224
	ds_read_b128 v[234:237], v159 offset:53248
	ds_read_b128 v[238:241], v159 offset:54272
	ds_read_b128 v[242:245], v159 offset:55296
	ds_read_b128 v[246:249], v159 offset:56320
	global_load_lds_dwordx4 v128, s[98:99]
	s_mov_b32 m0, s35
	s_addc_u32 s25, s25, 0
	global_load_lds_dwordx4 v130, s[98:99]
	s_mov_b32 m0, s40
	s_nop 0
	global_load_lds_dwordx4 v128, s[24:25]
	s_mov_b32 m0, s41
	s_nop 0
	global_load_lds_dwordx4 v130, s[24:25]
	s_mov_b32 m0, s36
	s_nop 0
	global_load_lds_dwordx4 v128, s[100:101]
	s_mov_b32 m0, s37
	s_nop 0
	global_load_lds_dwordx4 v130, s[100:101]
	s_waitcnt vmcnt(8)
	s_waitcnt lgkmcnt(0)
	s_barrier
	v_mfma_f32_16x16x32_bf16 v[60:63], v[160:163], v[218:221], v[60:63]
	v_mfma_f32_16x16x32_bf16 v[56:59], v[188:191], v[218:221], v[56:59]
	v_mfma_f32_16x16x32_bf16 v[44:47], v[160:163], v[226:229], v[44:47]
	v_mfma_f32_16x16x32_bf16 v[40:43], v[188:191], v[226:229], v[40:43]
	v_mfma_f32_16x16x32_bf16 v[28:31], v[160:163], v[234:237], v[28:31]
	v_mfma_f32_16x16x32_bf16 v[24:27], v[188:191], v[234:237], v[24:27]
	v_mfma_f32_16x16x32_bf16 v[12:15], v[160:163], v[242:245], v[12:15]
	v_mfma_f32_16x16x32_bf16 v[8:11], v[188:191], v[242:245], v[8:11]
	v_mfma_f32_16x16x32_bf16 v[60:63], v[184:187], v[222:225], v[60:63]
	v_mfma_f32_16x16x32_bf16 v[56:59], v[198:201], v[222:225], v[56:59]
	v_mfma_f32_16x16x32_bf16 v[44:47], v[184:187], v[230:233], v[44:47]
	v_mfma_f32_16x16x32_bf16 v[40:43], v[198:201], v[230:233], v[40:43]
	v_mfma_f32_16x16x32_bf16 v[28:31], v[184:187], v[238:241], v[28:31]
	v_mfma_f32_16x16x32_bf16 v[24:27], v[198:201], v[238:241], v[24:27]
	v_mfma_f32_16x16x32_bf16 v[12:15], v[184:187], v[246:249], v[12:15]
	v_mfma_f32_16x16x32_bf16 v[8:11], v[198:201], v[246:249], v[8:11]
	v_mfma_f32_16x16x32_bf16 v[52:55], v[202:205], v[218:221], v[52:55]
	v_mfma_f32_16x16x32_bf16 v[48:51], v[210:213], v[218:221], v[48:51]
	v_mfma_f32_16x16x32_bf16 v[36:39], v[202:205], v[226:229], v[36:39]
	v_mfma_f32_16x16x32_bf16 v[32:35], v[210:213], v[226:229], v[32:35]
	v_mfma_f32_16x16x32_bf16 v[20:23], v[202:205], v[234:237], v[20:23]
	v_mfma_f32_16x16x32_bf16 v[16:19], v[210:213], v[234:237], v[16:19]
	v_mfma_f32_16x16x32_bf16 v[4:7], v[202:205], v[242:245], v[4:7]
	v_mfma_f32_16x16x32_bf16 v[0:3], v[210:213], v[242:245], v[0:3]
	v_mfma_f32_16x16x32_bf16 v[52:55], v[206:209], v[222:225], v[52:55]
	v_mfma_f32_16x16x32_bf16 v[48:51], v[214:217], v[222:225], v[48:51]
	v_mfma_f32_16x16x32_bf16 v[36:39], v[206:209], v[230:233], v[36:39]
	v_mfma_f32_16x16x32_bf16 v[32:35], v[214:217], v[230:233], v[32:35]
	v_mfma_f32_16x16x32_bf16 v[20:23], v[206:209], v[238:241], v[20:23]
	v_mfma_f32_16x16x32_bf16 v[16:19], v[214:217], v[238:241], v[16:19]
	v_mfma_f32_16x16x32_bf16 v[4:7], v[206:209], v[246:249], v[4:7]
	v_mfma_f32_16x16x32_bf16 v[0:3], v[214:217], v[246:249], v[0:3]
	s_add_i32 s66, s66, 2
	s_add_u32 s14, s14, 0x100
	s_addc_u32 s15, s15, 0
	s_add_u32 s47, s47, 0x100
	s_addc_u32 s49, s49, 0
	s_cmp_gt_u32 s66, 13
	s_barrier
	s_cbranch_scc0 .LBB0_1334
	s_and_b64 vcc, exec, s[42:43]
	s_cbranch_vccz .LBB0_1337
	s_barrier

.LBB0_1497:
	ds_read_b128 v[176:179], v159
	ds_read_b128 v[180:183], v160
	ds_read_b128 v[184:187], v161
	ds_read_b128 v[188:191], v162
	ds_read_b128 v[198:201], v163
	ds_read_b128 v[202:205], v164
	ds_read_b128 v[206:209], v165
	ds_read_b128 v[210:213], v166
	s_add_u32 s50, s24, 0x100
	s_addc_u32 s51, s25, 0
	s_cmp_eq_u32 s68, 12
	s_cselect_b32 s65, s4, s51
	s_cselect_b32 s64, s5, s50
	s_cselect_b32 s55, s39, s87
	s_cselect_b32 s54, s43, s86
	s_mov_b32 m0, s76
	ds_read_b128 v[214:217], v143
	ds_read_b128 v[218:221], v143 offset:1024
	ds_read_b128 v[222:225], v143 offset:2048
	ds_read_b128 v[226:229], v143 offset:3072
	ds_read_b128 v[230:233], v143 offset:4096
	ds_read_b128 v[234:237], v143 offset:5120
	ds_read_b128 v[238:241], v143 offset:6144
	ds_read_b128 v[242:245], v143 offset:7168
	global_load_lds_dwordx4 v132, s[24:25]
	s_mov_b32 m0, s77
	s_nop 0
	global_load_lds_dwordx4 v134, s[24:25]
	s_waitcnt vmcnt(8)
	s_waitcnt lgkmcnt(0)
	s_barrier
	v_mfma_f32_16x16x32_bf16 v[124:127], v[176:179], v[214:217], v[124:127]
	v_mfma_f32_16x16x32_bf16 v[120:123], v[184:187], v[214:217], v[120:123]
	v_mfma_f32_16x16x32_bf16 v[108:111], v[176:179], v[222:225], v[108:111]
	v_mfma_f32_16x16x32_bf16 v[104:107], v[184:187], v[222:225], v[104:107]
	v_mfma_f32_16x16x32_bf16 v[92:95], v[176:179], v[230:233], v[92:95]
	v_mfma_f32_16x16x32_bf16 v[88:91], v[184:187], v[230:233], v[88:91]
	v_mfma_f32_16x16x32_bf16 v[76:79], v[176:179], v[238:241], v[76:79]
	v_mfma_f32_16x16x32_bf16 v[72:75], v[184:187], v[238:241], v[72:75]
	v_mfma_f32_16x16x32_bf16 v[124:127], v[180:183], v[218:221], v[124:127]
	v_mfma_f32_16x16x32_bf16 v[120:123], v[188:191], v[218:221], v[120:123]
	v_mfma_f32_16x16x32_bf16 v[108:111], v[180:183], v[226:229], v[108:111]
	v_mfma_f32_16x16x32_bf16 v[104:107], v[188:191], v[226:229], v[104:107]
	v_mfma_f32_16x16x32_bf16 v[92:95], v[180:183], v[234:237], v[92:95]
	v_mfma_f32_16x16x32_bf16 v[88:91], v[188:191], v[234:237], v[88:91]
	v_mfma_f32_16x16x32_bf16 v[76:79], v[180:183], v[242:245], v[76:79]
	v_mfma_f32_16x16x32_bf16 v[72:75], v[188:191], v[242:245], v[72:75]
	v_mfma_f32_16x16x32_bf16 v[116:119], v[198:201], v[214:217], v[116:119]
	v_mfma_f32_16x16x32_bf16 v[112:115], v[206:209], v[214:217], v[112:115]
	v_mfma_f32_16x16x32_bf16 v[100:103], v[198:201], v[222:225], v[100:103]
	v_mfma_f32_16x16x32_bf16 v[96:99], v[206:209], v[222:225], v[96:99]
	v_mfma_f32_16x16x32_bf16 v[84:87], v[198:201], v[230:233], v[84:87]
	v_mfma_f32_16x16x32_bf16 v[80:83], v[206:209], v[230:233], v[80:83]
	v_mfma_f32_16x16x32_bf16 v[68:71], v[198:201], v[238:241], v[68:71]
	v_mfma_f32_16x16x32_bf16 v[64:67], v[206:209], v[238:241], v[64:67]
	v_mfma_f32_16x16x32_bf16 v[116:119], v[202:205], v[218:221], v[116:119]
	v_mfma_f32_16x16x32_bf16 v[112:115], v[210:213], v[218:221], v[112:115]
	v_mfma_f32_16x16x32_bf16 v[100:103], v[202:205], v[226:229], v[100:103]
	v_mfma_f32_16x16x32_bf16 v[96:99], v[210:213], v[226:229], v[96:99]
	v_mfma_f32_16x16x32_bf16 v[84:87], v[202:205], v[234:237], v[84:87]
	v_mfma_f32_16x16x32_bf16 v[80:83], v[210:213], v[234:237], v[80:83]
	v_mfma_f32_16x16x32_bf16 v[68:71], v[202:205], v[242:245], v[68:71]
	v_mfma_f32_16x16x32_bf16 v[64:67], v[210:213], v[242:245], v[64:67]
	s_add_u32 s98, s54, s10
	s_addc_u32 s99, s55, s11
	s_add_u32 s100, s64, s10
	s_addc_u32 s101, s65, s11
	s_barrier
	s_mov_b32 m0, s29
	s_add_u32 s24, s54, 0x40000
	ds_read_b128 v[214:217], v143 offset:16384
	ds_read_b128 v[218:221], v143 offset:17408
	ds_read_b128 v[222:225], v143 offset:18432
	ds_read_b128 v[226:229], v143 offset:19456
	ds_read_b128 v[230:233], v143 offset:20480
	ds_read_b128 v[234:237], v143 offset:21504
	ds_read_b128 v[238:241], v143 offset:22528
	ds_read_b128 v[242:245], v143 offset:23552
	global_load_lds_dwordx4 v128, s[54:55]
	s_mov_b32 m0, s30
	s_addc_u32 s25, s55, 0
	global_load_lds_dwordx4 v130, s[54:55]
	s_mov_b32 m0, s31
	s_nop 0
	global_load_lds_dwordx4 v128, s[24:25]
	s_mov_b32 m0, s33
	s_nop 0
	global_load_lds_dwordx4 v130, s[24:25]
	s_mov_b32 m0, s28
	s_nop 0
	global_load_lds_dwordx4 v128, s[64:65]
	s_mov_b32 m0, s34
	s_nop 0
	global_load_lds_dwordx4 v130, s[64:65]
	s_waitcnt vmcnt(8)
	s_waitcnt lgkmcnt(0)
	s_barrier
	v_mfma_f32_16x16x32_bf16 v[60:63], v[176:179], v[214:217], v[60:63]
	v_mfma_f32_16x16x32_bf16 v[56:59], v[184:187], v[214:217], v[56:59]
	v_mfma_f32_16x16x32_bf16 v[44:47], v[176:179], v[222:225], v[44:47]
	v_mfma_f32_16x16x32_bf16 v[40:43], v[184:187], v[222:225], v[40:43]
	v_mfma_f32_16x16x32_bf16 v[28:31], v[176:179], v[230:233], v[28:31]
	v_mfma_f32_16x16x32_bf16 v[24:27], v[184:187], v[230:233], v[24:27]
	v_mfma_f32_16x16x32_bf16 v[12:15], v[176:179], v[238:241], v[12:15]
	v_mfma_f32_16x16x32_bf16 v[8:11], v[184:187], v[238:241], v[8:11]
	v_mfma_f32_16x16x32_bf16 v[60:63], v[180:183], v[218:221], v[60:63]
	v_mfma_f32_16x16x32_bf16 v[56:59], v[188:191], v[218:221], v[56:59]
	v_mfma_f32_16x16x32_bf16 v[44:47], v[180:183], v[226:229], v[44:47]
	v_mfma_f32_16x16x32_bf16 v[40:43], v[188:191], v[226:229], v[40:43]
	v_mfma_f32_16x16x32_bf16 v[28:31], v[180:183], v[234:237], v[28:31]
	v_mfma_f32_16x16x32_bf16 v[24:27], v[188:191], v[234:237], v[24:27]
	v_mfma_f32_16x16x32_bf16 v[12:15], v[180:183], v[242:245], v[12:15]
	v_mfma_f32_16x16x32_bf16 v[8:11], v[188:191], v[242:245], v[8:11]
	v_mfma_f32_16x16x32_bf16 v[52:55], v[198:201], v[214:217], v[52:55]
	v_mfma_f32_16x16x32_bf16 v[48:51], v[206:209], v[214:217], v[48:51]
	v_mfma_f32_16x16x32_bf16 v[36:39], v[198:201], v[222:225], v[36:39]
	v_mfma_f32_16x16x32_bf16 v[32:35], v[206:209], v[222:225], v[32:35]
	v_mfma_f32_16x16x32_bf16 v[20:23], v[198:201], v[230:233], v[20:23]
	v_mfma_f32_16x16x32_bf16 v[16:19], v[206:209], v[230:233], v[16:19]
	v_mfma_f32_16x16x32_bf16 v[4:7], v[198:201], v[238:241], v[4:7]
	v_mfma_f32_16x16x32_bf16 v[0:3], v[206:209], v[238:241], v[0:3]
	v_mfma_f32_16x16x32_bf16 v[52:55], v[202:205], v[218:221], v[52:55]
	v_mfma_f32_16x16x32_bf16 v[48:51], v[210:213], v[218:221], v[48:51]
	v_mfma_f32_16x16x32_bf16 v[36:39], v[202:205], v[226:229], v[36:39]
	v_mfma_f32_16x16x32_bf16 v[32:35], v[210:213], v[226:229], v[32:35]
	v_mfma_f32_16x16x32_bf16 v[20:23], v[202:205], v[234:237], v[20:23]
	v_mfma_f32_16x16x32_bf16 v[16:19], v[210:213], v[234:237], v[16:19]
	v_mfma_f32_16x16x32_bf16 v[4:7], v[202:205], v[242:245], v[4:7]
	v_mfma_f32_16x16x32_bf16 v[0:3], v[210:213], v[242:245], v[0:3]
	s_barrier
	ds_read_b128 v[176:179], v167
	ds_read_b128 v[180:183], v168
	ds_read_b128 v[184:187], v169
	ds_read_b128 v[188:191], v170
	ds_read_b128 v[198:201], v171
	ds_read_b128 v[202:205], v172
	ds_read_b128 v[206:209], v173
	ds_read_b128 v[210:213], v174
	s_add_u32 s24, s64, 0x40000
	s_addc_u32 s25, s65, 0
	s_mov_b32 m0, s35
	ds_read_b128 v[214:217], v143 offset:32768
	ds_read_b128 v[218:221], v143 offset:33792
	ds_read_b128 v[222:225], v143 offset:34816
	ds_read_b128 v[226:229], v143 offset:35840
	ds_read_b128 v[230:233], v143 offset:36864
	ds_read_b128 v[234:237], v143 offset:37888
	ds_read_b128 v[238:241], v143 offset:38912
	ds_read_b128 v[242:245], v143 offset:39936
	global_load_lds_dwordx4 v128, s[24:25]
	s_mov_b32 m0, s36
	s_nop 0
	global_load_lds_dwordx4 v130, s[24:25]
	s_waitcnt vmcnt(8)
	s_waitcnt lgkmcnt(0)
	s_barrier
	v_mfma_f32_16x16x32_bf16 v[124:127], v[176:179], v[214:217], v[124:127]
	v_mfma_f32_16x16x32_bf16 v[120:123], v[184:187], v[214:217], v[120:123]
	v_mfma_f32_16x16x32_bf16 v[108:111], v[176:179], v[222:225], v[108:111]
	v_mfma_f32_16x16x32_bf16 v[104:107], v[184:187], v[222:225], v[104:107]
	v_mfma_f32_16x16x32_bf16 v[92:95], v[176:179], v[230:233], v[92:95]
	v_mfma_f32_16x16x32_bf16 v[88:91], v[184:187], v[230:233], v[88:91]
	v_mfma_f32_16x16x32_bf16 v[76:79], v[176:179], v[238:241], v[76:79]
	v_mfma_f32_16x16x32_bf16 v[72:75], v[184:187], v[238:241], v[72:75]
	v_mfma_f32_16x16x32_bf16 v[124:127], v[180:183], v[218:221], v[124:127]
	v_mfma_f32_16x16x32_bf16 v[120:123], v[188:191], v[218:221], v[120:123]
	v_mfma_f32_16x16x32_bf16 v[108:111], v[180:183], v[226:229], v[108:111]
	v_mfma_f32_16x16x32_bf16 v[104:107], v[188:191], v[226:229], v[104:107]
	v_mfma_f32_16x16x32_bf16 v[92:95], v[180:183], v[234:237], v[92:95]
	v_mfma_f32_16x16x32_bf16 v[88:91], v[188:191], v[234:237], v[88:91]
	v_mfma_f32_16x16x32_bf16 v[76:79], v[180:183], v[242:245], v[76:79]
	v_mfma_f32_16x16x32_bf16 v[72:75], v[188:191], v[242:245], v[72:75]
	v_mfma_f32_16x16x32_bf16 v[116:119], v[198:201], v[214:217], v[116:119]
	v_mfma_f32_16x16x32_bf16 v[112:115], v[206:209], v[214:217], v[112:115]
	v_mfma_f32_16x16x32_bf16 v[100:103], v[198:201], v[222:225], v[100:103]
	v_mfma_f32_16x16x32_bf16 v[96:99], v[206:209], v[222:225], v[96:99]
	v_mfma_f32_16x16x32_bf16 v[84:87], v[198:201], v[230:233], v[84:87]
	v_mfma_f32_16x16x32_bf16 v[80:83], v[206:209], v[230:233], v[80:83]
	v_mfma_f32_16x16x32_bf16 v[68:71], v[198:201], v[238:241], v[68:71]
	v_mfma_f32_16x16x32_bf16 v[64:67], v[206:209], v[238:241], v[64:67]
	v_mfma_f32_16x16x32_bf16 v[116:119], v[202:205], v[218:221], v[116:119]
	v_mfma_f32_16x16x32_bf16 v[112:115], v[210:213], v[218:221], v[112:115]
	v_mfma_f32_16x16x32_bf16 v[100:103], v[202:205], v[226:229], v[100:103]
	v_mfma_f32_16x16x32_bf16 v[96:99], v[210:213], v[226:229], v[96:99]
	v_mfma_f32_16x16x32_bf16 v[84:87], v[202:205], v[234:237], v[84:87]
	v_mfma_f32_16x16x32_bf16 v[80:83], v[210:213], v[234:237], v[80:83]
	v_mfma_f32_16x16x32_bf16 v[68:71], v[202:205], v[242:245], v[68:71]
	v_mfma_f32_16x16x32_bf16 v[64:67], v[210:213], v[242:245], v[64:67]
	s_barrier
	s_mov_b32 m0, s40
	s_add_u32 s24, s54, 0x40080
	ds_read_b128 v[214:217], v143 offset:49152
	ds_read_b128 v[218:221], v143 offset:50176
	ds_read_b128 v[222:225], v143 offset:51200
	ds_read_b128 v[226:229], v143 offset:52224
	ds_read_b128 v[230:233], v143 offset:53248
	ds_read_b128 v[234:237], v143 offset:54272
	ds_read_b128 v[238:241], v143 offset:55296
	ds_read_b128 v[242:245], v143 offset:56320
	global_load_lds_dwordx4 v128, s[98:99]
	s_mov_b32 m0, s41
	s_addc_u32 s25, s55, 0
	global_load_lds_dwordx4 v130, s[98:99]
	s_mov_b32 m0, s53
	s_nop 0
	global_load_lds_dwordx4 v128, s[24:25]
	s_mov_b32 m0, s60
	s_nop 0
	global_load_lds_dwordx4 v130, s[24:25]
	s_mov_b32 m0, s49
	s_nop 0
	global_load_lds_dwordx4 v128, s[100:101]
	s_mov_b32 m0, s52
	s_nop 0
	global_load_lds_dwordx4 v130, s[100:101]
	s_waitcnt vmcnt(8)
	s_waitcnt lgkmcnt(0)
	s_barrier
	v_mfma_f32_16x16x32_bf16 v[60:63], v[176:179], v[214:217], v[60:63]
	v_mfma_f32_16x16x32_bf16 v[56:59], v[184:187], v[214:217], v[56:59]
	v_mfma_f32_16x16x32_bf16 v[44:47], v[176:179], v[222:225], v[44:47]
	v_mfma_f32_16x16x32_bf16 v[40:43], v[184:187], v[222:225], v[40:43]
	v_mfma_f32_16x16x32_bf16 v[28:31], v[176:179], v[230:233], v[28:31]
	v_mfma_f32_16x16x32_bf16 v[24:27], v[184:187], v[230:233], v[24:27]
	v_mfma_f32_16x16x32_bf16 v[12:15], v[176:179], v[238:241], v[12:15]
	v_mfma_f32_16x16x32_bf16 v[8:11], v[184:187], v[238:241], v[8:11]
	v_mfma_f32_16x16x32_bf16 v[60:63], v[180:183], v[218:221], v[60:63]
	v_mfma_f32_16x16x32_bf16 v[56:59], v[188:191], v[218:221], v[56:59]
	v_mfma_f32_16x16x32_bf16 v[44:47], v[180:183], v[226:229], v[44:47]
	v_mfma_f32_16x16x32_bf16 v[40:43], v[188:191], v[226:229], v[40:43]
	v_mfma_f32_16x16x32_bf16 v[28:31], v[180:183], v[234:237], v[28:31]
	v_mfma_f32_16x16x32_bf16 v[24:27], v[188:191], v[234:237], v[24:27]
	v_mfma_f32_16x16x32_bf16 v[12:15], v[180:183], v[242:245], v[12:15]
	v_mfma_f32_16x16x32_bf16 v[8:11], v[188:191], v[242:245], v[8:11]
	v_mfma_f32_16x16x32_bf16 v[52:55], v[198:201], v[214:217], v[52:55]
	v_mfma_f32_16x16x32_bf16 v[48:51], v[206:209], v[214:217], v[48:51]
	v_mfma_f32_16x16x32_bf16 v[36:39], v[198:201], v[222:225], v[36:39]
	v_mfma_f32_16x16x32_bf16 v[32:35], v[206:209], v[222:225], v[32:35]
	v_mfma_f32_16x16x32_bf16 v[20:23], v[198:201], v[230:233], v[20:23]
	v_mfma_f32_16x16x32_bf16 v[16:19], v[206:209], v[230:233], v[16:19]
	v_mfma_f32_16x16x32_bf16 v[4:7], v[198:201], v[238:241], v[4:7]
	v_mfma_f32_16x16x32_bf16 v[0:3], v[206:209], v[238:241], v[0:3]
	v_mfma_f32_16x16x32_bf16 v[52:55], v[202:205], v[218:221], v[52:55]
	v_mfma_f32_16x16x32_bf16 v[48:51], v[210:213], v[218:221], v[48:51]
	v_mfma_f32_16x16x32_bf16 v[36:39], v[202:205], v[226:229], v[36:39]
	v_mfma_f32_16x16x32_bf16 v[32:35], v[210:213], v[226:229], v[32:35]
	v_mfma_f32_16x16x32_bf16 v[20:23], v[202:205], v[234:237], v[20:23]
	v_mfma_f32_16x16x32_bf16 v[16:19], v[210:213], v[234:237], v[16:19]
	v_mfma_f32_16x16x32_bf16 v[4:7], v[202:205], v[242:245], v[4:7]
	v_mfma_f32_16x16x32_bf16 v[0:3], v[210:213], v[242:245], v[0:3]
	s_add_i32 s68, s68, 2
	s_add_u32 s86, s86, 0x100
	s_addc_u32 s87, s87, 0
	s_cmp_gt_u32 s68, 13
	s_mov_b64 s[24:25], s[50:51]
	s_barrier
	s_cbranch_scc0 .LBB0_1497
	s_and_b64 vcc, exec, s[14:15]
	s_cbranch_vccz .LBB0_1500
	s_barrier

.LBB0_1766:
	ds_read_b128 v[128:131], v199
	ds_read_b128 v[132:135], v200
	ds_read_b128 v[136:139], v201
	ds_read_b128 v[140:143], v202
	ds_read_b128 v[172:175], v203
	ds_read_b128 v[176:179], v204
	ds_read_b128 v[180:183], v205
	ds_read_b128 v[184:187], v206
	s_add_u32 s74, s24, 0x100
	s_addc_u32 s75, s25, 0
	s_cmp_eq_u32 s68, 12
	s_cselect_b32 s85, s4, s75
	s_cselect_b32 s84, s5, s74
	s_cselect_b32 s81, s47, s87
	s_cselect_b32 s80, s49, s86
	s_mov_b32 m0, s65
	ds_read_b128 v[188:191], v159
	ds_read_b128 v[216:219], v159 offset:1024
	ds_read_b128 v[220:223], v159 offset:2048
	ds_read_b128 v[224:227], v159 offset:3072
	ds_read_b128 v[228:231], v159 offset:4096
	ds_read_b128 v[232:235], v159 offset:5120
	ds_read_b128 v[236:239], v159 offset:6144
	ds_read_b128 v[240:243], v159 offset:7168
	global_load_lds_dwordx4 v164, s[24:25]
	s_mov_b32 m0, s67
	s_nop 0
	global_load_lds_dwordx4 v166, s[24:25]
	s_waitcnt vmcnt(8)
	s_waitcnt lgkmcnt(0)
	s_barrier
	v_mfma_f32_16x16x32_bf16 v[124:127], v[128:131], v[188:191], v[124:127]
	v_mfma_f32_16x16x32_bf16 v[120:123], v[136:139], v[188:191], v[120:123]
	v_mfma_f32_16x16x32_bf16 v[108:111], v[128:131], v[220:223], v[108:111]
	v_mfma_f32_16x16x32_bf16 v[104:107], v[136:139], v[220:223], v[104:107]
	v_mfma_f32_16x16x32_bf16 v[92:95], v[128:131], v[228:231], v[92:95]
	v_mfma_f32_16x16x32_bf16 v[88:91], v[136:139], v[228:231], v[88:91]
	v_mfma_f32_16x16x32_bf16 v[76:79], v[128:131], v[236:239], v[76:79]
	v_mfma_f32_16x16x32_bf16 v[72:75], v[136:139], v[236:239], v[72:75]
	v_mfma_f32_16x16x32_bf16 v[124:127], v[132:135], v[216:219], v[124:127]
	v_mfma_f32_16x16x32_bf16 v[120:123], v[140:143], v[216:219], v[120:123]
	v_mfma_f32_16x16x32_bf16 v[108:111], v[132:135], v[224:227], v[108:111]
	v_mfma_f32_16x16x32_bf16 v[104:107], v[140:143], v[224:227], v[104:107]
	v_mfma_f32_16x16x32_bf16 v[92:95], v[132:135], v[232:235], v[92:95]
	v_mfma_f32_16x16x32_bf16 v[88:91], v[140:143], v[232:235], v[88:91]
	v_mfma_f32_16x16x32_bf16 v[76:79], v[132:135], v[240:243], v[76:79]
	v_mfma_f32_16x16x32_bf16 v[72:75], v[140:143], v[240:243], v[72:75]
	v_mfma_f32_16x16x32_bf16 v[116:119], v[172:175], v[188:191], v[116:119]
	v_mfma_f32_16x16x32_bf16 v[112:115], v[180:183], v[188:191], v[112:115]
	v_mfma_f32_16x16x32_bf16 v[100:103], v[172:175], v[220:223], v[100:103]
	v_mfma_f32_16x16x32_bf16 v[96:99], v[180:183], v[220:223], v[96:99]
	v_mfma_f32_16x16x32_bf16 v[84:87], v[172:175], v[228:231], v[84:87]
	v_mfma_f32_16x16x32_bf16 v[80:83], v[180:183], v[228:231], v[80:83]
	v_mfma_f32_16x16x32_bf16 v[68:71], v[172:175], v[236:239], v[68:71]
	v_mfma_f32_16x16x32_bf16 v[64:67], v[180:183], v[236:239], v[64:67]
	v_mfma_f32_16x16x32_bf16 v[116:119], v[176:179], v[216:219], v[116:119]
	v_mfma_f32_16x16x32_bf16 v[112:115], v[184:187], v[216:219], v[112:115]
	v_mfma_f32_16x16x32_bf16 v[100:103], v[176:179], v[224:227], v[100:103]
	v_mfma_f32_16x16x32_bf16 v[96:99], v[184:187], v[224:227], v[96:99]
	v_mfma_f32_16x16x32_bf16 v[84:87], v[176:179], v[232:235], v[84:87]
	v_mfma_f32_16x16x32_bf16 v[80:83], v[184:187], v[232:235], v[80:83]
	v_mfma_f32_16x16x32_bf16 v[68:71], v[176:179], v[240:243], v[68:71]
	v_mfma_f32_16x16x32_bf16 v[64:67], v[184:187], v[240:243], v[64:67]
	s_add_u32 s98, s80, s38
	s_addc_u32 s99, s81, s39
	s_add_u32 s100, s84, s38
	s_addc_u32 s101, s85, s39
	s_barrier
	s_mov_b32 m0, s7
	s_add_u32 s24, s80, 0x40000
	ds_read_b128 v[188:191], v159 offset:16384
	ds_read_b128 v[216:219], v159 offset:17408
	ds_read_b128 v[220:223], v159 offset:18432
	ds_read_b128 v[224:227], v159 offset:19456
	ds_read_b128 v[228:231], v159 offset:20480
	ds_read_b128 v[232:235], v159 offset:21504
	ds_read_b128 v[236:239], v159 offset:22528
	ds_read_b128 v[240:243], v159 offset:23552
	global_load_lds_dwordx4 v160, s[80:81]
	s_mov_b32 m0, s28
	s_addc_u32 s25, s81, 0
	global_load_lds_dwordx4 v162, s[80:81]
	s_mov_b32 m0, s29
	s_nop 0
	global_load_lds_dwordx4 v160, s[24:25]
	s_mov_b32 m0, s30
	s_nop 0
	global_load_lds_dwordx4 v162, s[24:25]
	s_mov_b32 m0, s6
	s_nop 0
	global_load_lds_dwordx4 v160, s[84:85]
	s_mov_b32 m0, s31
	s_nop 0
	global_load_lds_dwordx4 v162, s[84:85]
	s_waitcnt vmcnt(8)
	s_waitcnt lgkmcnt(0)
	s_barrier
	v_mfma_f32_16x16x32_bf16 v[60:63], v[128:131], v[188:191], v[60:63]
	v_mfma_f32_16x16x32_bf16 v[56:59], v[136:139], v[188:191], v[56:59]
	v_mfma_f32_16x16x32_bf16 v[44:47], v[128:131], v[220:223], v[44:47]
	v_mfma_f32_16x16x32_bf16 v[40:43], v[136:139], v[220:223], v[40:43]
	v_mfma_f32_16x16x32_bf16 v[28:31], v[128:131], v[228:231], v[28:31]
	v_mfma_f32_16x16x32_bf16 v[24:27], v[136:139], v[228:231], v[24:27]
	v_mfma_f32_16x16x32_bf16 v[12:15], v[128:131], v[236:239], v[12:15]
	v_mfma_f32_16x16x32_bf16 v[8:11], v[136:139], v[236:239], v[8:11]
	v_mfma_f32_16x16x32_bf16 v[60:63], v[132:135], v[216:219], v[60:63]
	v_mfma_f32_16x16x32_bf16 v[56:59], v[140:143], v[216:219], v[56:59]
	v_mfma_f32_16x16x32_bf16 v[44:47], v[132:135], v[224:227], v[44:47]
	v_mfma_f32_16x16x32_bf16 v[40:43], v[140:143], v[224:227], v[40:43]
	v_mfma_f32_16x16x32_bf16 v[28:31], v[132:135], v[232:235], v[28:31]
	v_mfma_f32_16x16x32_bf16 v[24:27], v[140:143], v[232:235], v[24:27]
	v_mfma_f32_16x16x32_bf16 v[12:15], v[132:135], v[240:243], v[12:15]
	v_mfma_f32_16x16x32_bf16 v[8:11], v[140:143], v[240:243], v[8:11]
	v_mfma_f32_16x16x32_bf16 v[52:55], v[172:175], v[188:191], v[52:55]
	v_mfma_f32_16x16x32_bf16 v[48:51], v[180:183], v[188:191], v[48:51]
	v_mfma_f32_16x16x32_bf16 v[36:39], v[172:175], v[220:223], v[36:39]
	v_mfma_f32_16x16x32_bf16 v[32:35], v[180:183], v[220:223], v[32:35]
	v_mfma_f32_16x16x32_bf16 v[20:23], v[172:175], v[228:231], v[20:23]
	v_mfma_f32_16x16x32_bf16 v[16:19], v[180:183], v[228:231], v[16:19]
	v_mfma_f32_16x16x32_bf16 v[4:7], v[172:175], v[236:239], v[4:7]
	v_mfma_f32_16x16x32_bf16 v[0:3], v[180:183], v[236:239], v[0:3]
	v_mfma_f32_16x16x32_bf16 v[52:55], v[176:179], v[216:219], v[52:55]
	v_mfma_f32_16x16x32_bf16 v[48:51], v[184:187], v[216:219], v[48:51]
	v_mfma_f32_16x16x32_bf16 v[36:39], v[176:179], v[224:227], v[36:39]
	v_mfma_f32_16x16x32_bf16 v[32:35], v[184:187], v[224:227], v[32:35]
	v_mfma_f32_16x16x32_bf16 v[20:23], v[176:179], v[232:235], v[20:23]
	v_mfma_f32_16x16x32_bf16 v[16:19], v[184:187], v[232:235], v[16:19]
	v_mfma_f32_16x16x32_bf16 v[4:7], v[176:179], v[240:243], v[4:7]
	v_mfma_f32_16x16x32_bf16 v[0:3], v[184:187], v[240:243], v[0:3]
	s_barrier
	ds_read_b128 v[128:131], v207
	ds_read_b128 v[132:135], v208
	ds_read_b128 v[136:139], v209
	ds_read_b128 v[140:143], v210
	ds_read_b128 v[172:175], v211
	ds_read_b128 v[176:179], v212
	ds_read_b128 v[180:183], v213
	ds_read_b128 v[184:187], v214
	s_add_u32 s24, s84, 0x40000
	s_addc_u32 s25, s85, 0
	s_mov_b32 m0, s33
	ds_read_b128 v[188:191], v159 offset:32768
	ds_read_b128 v[216:219], v159 offset:33792
	ds_read_b128 v[220:223], v159 offset:34816
	ds_read_b128 v[224:227], v159 offset:35840
	ds_read_b128 v[228:231], v159 offset:36864
	ds_read_b128 v[232:235], v159 offset:37888
	ds_read_b128 v[236:239], v159 offset:38912
	ds_read_b128 v[240:243], v159 offset:39936
	global_load_lds_dwordx4 v160, s[24:25]
	s_mov_b32 m0, s34
	s_nop 0
	global_load_lds_dwordx4 v162, s[24:25]
	s_waitcnt vmcnt(8)
	s_waitcnt lgkmcnt(0)
	s_barrier
	v_mfma_f32_16x16x32_bf16 v[124:127], v[128:131], v[188:191], v[124:127]
	v_mfma_f32_16x16x32_bf16 v[120:123], v[136:139], v[188:191], v[120:123]
	v_mfma_f32_16x16x32_bf16 v[108:111], v[128:131], v[220:223], v[108:111]
	v_mfma_f32_16x16x32_bf16 v[104:107], v[136:139], v[220:223], v[104:107]
	v_mfma_f32_16x16x32_bf16 v[92:95], v[128:131], v[228:231], v[92:95]
	v_mfma_f32_16x16x32_bf16 v[88:91], v[136:139], v[228:231], v[88:91]
	v_mfma_f32_16x16x32_bf16 v[76:79], v[128:131], v[236:239], v[76:79]
	v_mfma_f32_16x16x32_bf16 v[72:75], v[136:139], v[236:239], v[72:75]
	v_mfma_f32_16x16x32_bf16 v[124:127], v[132:135], v[216:219], v[124:127]
	v_mfma_f32_16x16x32_bf16 v[120:123], v[140:143], v[216:219], v[120:123]
	v_mfma_f32_16x16x32_bf16 v[108:111], v[132:135], v[224:227], v[108:111]
	v_mfma_f32_16x16x32_bf16 v[104:107], v[140:143], v[224:227], v[104:107]
	v_mfma_f32_16x16x32_bf16 v[92:95], v[132:135], v[232:235], v[92:95]
	v_mfma_f32_16x16x32_bf16 v[88:91], v[140:143], v[232:235], v[88:91]
	v_mfma_f32_16x16x32_bf16 v[76:79], v[132:135], v[240:243], v[76:79]
	v_mfma_f32_16x16x32_bf16 v[72:75], v[140:143], v[240:243], v[72:75]
	v_mfma_f32_16x16x32_bf16 v[116:119], v[172:175], v[188:191], v[116:119]
	v_mfma_f32_16x16x32_bf16 v[112:115], v[180:183], v[188:191], v[112:115]
	v_mfma_f32_16x16x32_bf16 v[100:103], v[172:175], v[220:223], v[100:103]
	v_mfma_f32_16x16x32_bf16 v[96:99], v[180:183], v[220:223], v[96:99]
	v_mfma_f32_16x16x32_bf16 v[84:87], v[172:175], v[228:231], v[84:87]
	v_mfma_f32_16x16x32_bf16 v[80:83], v[180:183], v[228:231], v[80:83]
	v_mfma_f32_16x16x32_bf16 v[68:71], v[172:175], v[236:239], v[68:71]
	v_mfma_f32_16x16x32_bf16 v[64:67], v[180:183], v[236:239], v[64:67]
	v_mfma_f32_16x16x32_bf16 v[116:119], v[176:179], v[216:219], v[116:119]
	v_mfma_f32_16x16x32_bf16 v[112:115], v[184:187], v[216:219], v[112:115]
	v_mfma_f32_16x16x32_bf16 v[100:103], v[176:179], v[224:227], v[100:103]
	v_mfma_f32_16x16x32_bf16 v[96:99], v[184:187], v[224:227], v[96:99]
	v_mfma_f32_16x16x32_bf16 v[84:87], v[176:179], v[232:235], v[84:87]
	v_mfma_f32_16x16x32_bf16 v[80:83], v[184:187], v[232:235], v[80:83]
	v_mfma_f32_16x16x32_bf16 v[68:71], v[176:179], v[240:243], v[68:71]
	v_mfma_f32_16x16x32_bf16 v[64:67], v[184:187], v[240:243], v[64:67]
	s_barrier
	s_mov_b32 m0, s35
	s_add_u32 s24, s80, 0x40080
	ds_read_b128 v[188:191], v159 offset:49152
	ds_read_b128 v[216:219], v159 offset:50176
	ds_read_b128 v[220:223], v159 offset:51200
	ds_read_b128 v[224:227], v159 offset:52224
	ds_read_b128 v[228:231], v159 offset:53248
	ds_read_b128 v[232:235], v159 offset:54272
	ds_read_b128 v[236:239], v159 offset:55296
	ds_read_b128 v[240:243], v159 offset:56320
	global_load_lds_dwordx4 v160, s[98:99]
	s_mov_b32 m0, s36
	s_addc_u32 s25, s81, 0
	global_load_lds_dwordx4 v162, s[98:99]
	s_mov_b32 m0, s41
	s_nop 0
	global_load_lds_dwordx4 v160, s[24:25]
	s_mov_b32 m0, s45
	s_nop 0
	global_load_lds_dwordx4 v162, s[24:25]
	s_mov_b32 m0, s37
	s_nop 0
	global_load_lds_dwordx4 v160, s[100:101]
	s_mov_b32 m0, s40
	s_nop 0
	global_load_lds_dwordx4 v162, s[100:101]
	s_waitcnt vmcnt(8)
	s_waitcnt lgkmcnt(0)
	s_barrier
	v_mfma_f32_16x16x32_bf16 v[60:63], v[128:131], v[188:191], v[60:63]
	v_mfma_f32_16x16x32_bf16 v[56:59], v[136:139], v[188:191], v[56:59]
	v_mfma_f32_16x16x32_bf16 v[44:47], v[128:131], v[220:223], v[44:47]
	v_mfma_f32_16x16x32_bf16 v[40:43], v[136:139], v[220:223], v[40:43]
	v_mfma_f32_16x16x32_bf16 v[28:31], v[128:131], v[228:231], v[28:31]
	v_mfma_f32_16x16x32_bf16 v[24:27], v[136:139], v[228:231], v[24:27]
	v_mfma_f32_16x16x32_bf16 v[12:15], v[128:131], v[236:239], v[12:15]
	v_mfma_f32_16x16x32_bf16 v[8:11], v[136:139], v[236:239], v[8:11]
	v_mfma_f32_16x16x32_bf16 v[60:63], v[132:135], v[216:219], v[60:63]
	v_mfma_f32_16x16x32_bf16 v[56:59], v[140:143], v[216:219], v[56:59]
	v_mfma_f32_16x16x32_bf16 v[44:47], v[132:135], v[224:227], v[44:47]
	v_mfma_f32_16x16x32_bf16 v[40:43], v[140:143], v[224:227], v[40:43]
	v_mfma_f32_16x16x32_bf16 v[28:31], v[132:135], v[232:235], v[28:31]
	v_mfma_f32_16x16x32_bf16 v[24:27], v[140:143], v[232:235], v[24:27]
	v_mfma_f32_16x16x32_bf16 v[12:15], v[132:135], v[240:243], v[12:15]
	v_mfma_f32_16x16x32_bf16 v[8:11], v[140:143], v[240:243], v[8:11]
	v_mfma_f32_16x16x32_bf16 v[52:55], v[172:175], v[188:191], v[52:55]
	v_mfma_f32_16x16x32_bf16 v[48:51], v[180:183], v[188:191], v[48:51]
	v_mfma_f32_16x16x32_bf16 v[36:39], v[172:175], v[220:223], v[36:39]
	v_mfma_f32_16x16x32_bf16 v[32:35], v[180:183], v[220:223], v[32:35]
	v_mfma_f32_16x16x32_bf16 v[20:23], v[172:175], v[228:231], v[20:23]
	v_mfma_f32_16x16x32_bf16 v[16:19], v[180:183], v[228:231], v[16:19]
	v_mfma_f32_16x16x32_bf16 v[4:7], v[172:175], v[236:239], v[4:7]
	v_mfma_f32_16x16x32_bf16 v[0:3], v[180:183], v[236:239], v[0:3]
	v_mfma_f32_16x16x32_bf16 v[52:55], v[176:179], v[216:219], v[52:55]
	v_mfma_f32_16x16x32_bf16 v[48:51], v[184:187], v[216:219], v[48:51]
	v_mfma_f32_16x16x32_bf16 v[36:39], v[176:179], v[224:227], v[36:39]
	v_mfma_f32_16x16x32_bf16 v[32:35], v[184:187], v[224:227], v[32:35]
	v_mfma_f32_16x16x32_bf16 v[20:23], v[176:179], v[232:235], v[20:23]
	v_mfma_f32_16x16x32_bf16 v[16:19], v[184:187], v[232:235], v[16:19]
	v_mfma_f32_16x16x32_bf16 v[4:7], v[176:179], v[240:243], v[4:7]
	v_mfma_f32_16x16x32_bf16 v[0:3], v[184:187], v[240:243], v[0:3]
	s_add_i32 s68, s68, 2
	s_add_u32 s86, s86, 0x100
	s_addc_u32 s87, s87, 0
	s_cmp_gt_u32 s68, 13
	s_mov_b64 s[24:25], s[74:75]
	s_barrier
	s_cbranch_scc0 .LBB0_1766
	s_and_b64 vcc, exec, s[42:43]
	s_cbranch_vccz .LBB0_1769
	s_barrier

.LBB0_1914:
	ds_read_b128 v[174:177], v143
	ds_read_b128 v[178:181], v153
	ds_read_b128 v[182:185], v159
	ds_read_b128 v[186:189], v160
	ds_read_b128 v[190:193], v161
	ds_read_b128 v[198:201], v162
	ds_read_b128 v[202:205], v163
	ds_read_b128 v[206:209], v164
	s_add_u32 s48, s24, 0xfffc0080
	s_addc_u32 s49, s25, -1
	s_cmp_eq_u32 s75, 12
	s_cselect_b32 s51, s4, s49
	s_cselect_b32 s50, s5, s48
	s_cselect_b32 s49, s39, s74
	s_cselect_b32 s48, s41, s67
	s_mov_b32 m0, s61
	ds_read_b128 v[210:213], v141
	ds_read_b128 v[214:217], v141 offset:1024
	ds_read_b128 v[218:221], v141 offset:2048
	ds_read_b128 v[222:225], v141 offset:3072
	ds_read_b128 v[226:229], v141 offset:4096
	ds_read_b128 v[230:233], v141 offset:5120
	ds_read_b128 v[234:237], v141 offset:6144
	ds_read_b128 v[238:241], v141 offset:7168
	global_load_lds_dwordx4 v132, s[24:25]
	s_mov_b32 m0, s64
	s_nop 0
	global_load_lds_dwordx4 v134, s[24:25]
	s_waitcnt vmcnt(8)
	s_waitcnt lgkmcnt(0)
	s_barrier
	v_mfma_f32_16x16x32_bf16 v[124:127], v[174:177], v[210:213], v[124:127]
	v_mfma_f32_16x16x32_bf16 v[120:123], v[182:185], v[210:213], v[120:123]
	v_mfma_f32_16x16x32_bf16 v[108:111], v[174:177], v[218:221], v[108:111]
	v_mfma_f32_16x16x32_bf16 v[104:107], v[182:185], v[218:221], v[104:107]
	v_mfma_f32_16x16x32_bf16 v[92:95], v[174:177], v[226:229], v[92:95]
	v_mfma_f32_16x16x32_bf16 v[88:91], v[182:185], v[226:229], v[88:91]
	v_mfma_f32_16x16x32_bf16 v[76:79], v[174:177], v[234:237], v[76:79]
	v_mfma_f32_16x16x32_bf16 v[72:75], v[182:185], v[234:237], v[72:75]
	v_mfma_f32_16x16x32_bf16 v[124:127], v[178:181], v[214:217], v[124:127]
	v_mfma_f32_16x16x32_bf16 v[120:123], v[186:189], v[214:217], v[120:123]
	v_mfma_f32_16x16x32_bf16 v[108:111], v[178:181], v[222:225], v[108:111]
	v_mfma_f32_16x16x32_bf16 v[104:107], v[186:189], v[222:225], v[104:107]
	v_mfma_f32_16x16x32_bf16 v[92:95], v[178:181], v[230:233], v[92:95]
	v_mfma_f32_16x16x32_bf16 v[88:91], v[186:189], v[230:233], v[88:91]
	v_mfma_f32_16x16x32_bf16 v[76:79], v[178:181], v[238:241], v[76:79]
	v_mfma_f32_16x16x32_bf16 v[72:75], v[186:189], v[238:241], v[72:75]
	v_mfma_f32_16x16x32_bf16 v[116:119], v[190:193], v[210:213], v[116:119]
	v_mfma_f32_16x16x32_bf16 v[112:115], v[202:205], v[210:213], v[112:115]
	v_mfma_f32_16x16x32_bf16 v[100:103], v[190:193], v[218:221], v[100:103]
	v_mfma_f32_16x16x32_bf16 v[96:99], v[202:205], v[218:221], v[96:99]
	v_mfma_f32_16x16x32_bf16 v[84:87], v[190:193], v[226:229], v[84:87]
	v_mfma_f32_16x16x32_bf16 v[80:83], v[202:205], v[226:229], v[80:83]
	v_mfma_f32_16x16x32_bf16 v[68:71], v[190:193], v[234:237], v[68:71]
	v_mfma_f32_16x16x32_bf16 v[64:67], v[202:205], v[234:237], v[64:67]
	v_mfma_f32_16x16x32_bf16 v[116:119], v[198:201], v[214:217], v[116:119]
	v_mfma_f32_16x16x32_bf16 v[112:115], v[206:209], v[214:217], v[112:115]
	v_mfma_f32_16x16x32_bf16 v[100:103], v[198:201], v[222:225], v[100:103]
	v_mfma_f32_16x16x32_bf16 v[96:99], v[206:209], v[222:225], v[96:99]
	v_mfma_f32_16x16x32_bf16 v[84:87], v[198:201], v[230:233], v[84:87]
	v_mfma_f32_16x16x32_bf16 v[80:83], v[206:209], v[230:233], v[80:83]
	v_mfma_f32_16x16x32_bf16 v[68:71], v[198:201], v[238:241], v[68:71]
	v_mfma_f32_16x16x32_bf16 v[64:67], v[206:209], v[238:241], v[64:67]
	s_add_u32 s98, s48, s12
	s_addc_u32 s99, s49, s13
	s_add_u32 s100, s50, s12
	s_addc_u32 s101, s51, s13
	s_barrier
	s_mov_b32 m0, s8
	s_add_u32 s68, s48, 0x40000
	ds_read_b128 v[210:213], v141 offset:16384
	ds_read_b128 v[214:217], v141 offset:17408
	ds_read_b128 v[218:221], v141 offset:18432
	ds_read_b128 v[222:225], v141 offset:19456
	ds_read_b128 v[226:229], v141 offset:20480
	ds_read_b128 v[230:233], v141 offset:21504
	ds_read_b128 v[234:237], v141 offset:22528
	ds_read_b128 v[238:241], v141 offset:23552
	global_load_lds_dwordx4 v130, s[48:49]
	s_mov_b32 m0, s9
	s_addc_u32 s69, s49, 0
	global_load_lds_dwordx4 v128, s[48:49]
	s_mov_b32 m0, s28
	s_nop 0
	global_load_lds_dwordx4 v130, s[68:69]
	s_mov_b32 m0, s29
	s_nop 0
	global_load_lds_dwordx4 v128, s[68:69]
	s_mov_b32 m0, s2
	s_nop 0
	global_load_lds_dwordx4 v130, s[50:51]
	s_mov_b32 m0, s30
	s_nop 0
	global_load_lds_dwordx4 v128, s[50:51]
	s_waitcnt vmcnt(8)
	s_waitcnt lgkmcnt(0)
	s_barrier
	v_mfma_f32_16x16x32_bf16 v[60:63], v[174:177], v[210:213], v[60:63]
	v_mfma_f32_16x16x32_bf16 v[56:59], v[182:185], v[210:213], v[56:59]
	v_mfma_f32_16x16x32_bf16 v[44:47], v[174:177], v[218:221], v[44:47]
	v_mfma_f32_16x16x32_bf16 v[40:43], v[182:185], v[218:221], v[40:43]
	v_mfma_f32_16x16x32_bf16 v[28:31], v[174:177], v[226:229], v[28:31]
	v_mfma_f32_16x16x32_bf16 v[24:27], v[182:185], v[226:229], v[24:27]
	v_mfma_f32_16x16x32_bf16 v[12:15], v[174:177], v[234:237], v[12:15]
	v_mfma_f32_16x16x32_bf16 v[8:11], v[182:185], v[234:237], v[8:11]
	v_mfma_f32_16x16x32_bf16 v[60:63], v[178:181], v[214:217], v[60:63]
	v_mfma_f32_16x16x32_bf16 v[56:59], v[186:189], v[214:217], v[56:59]
	v_mfma_f32_16x16x32_bf16 v[44:47], v[178:181], v[222:225], v[44:47]
	v_mfma_f32_16x16x32_bf16 v[40:43], v[186:189], v[222:225], v[40:43]
	v_mfma_f32_16x16x32_bf16 v[28:31], v[178:181], v[230:233], v[28:31]
	v_mfma_f32_16x16x32_bf16 v[24:27], v[186:189], v[230:233], v[24:27]
	v_mfma_f32_16x16x32_bf16 v[12:15], v[178:181], v[238:241], v[12:15]
	v_mfma_f32_16x16x32_bf16 v[8:11], v[186:189], v[238:241], v[8:11]
	v_mfma_f32_16x16x32_bf16 v[52:55], v[190:193], v[210:213], v[52:55]
	v_mfma_f32_16x16x32_bf16 v[48:51], v[202:205], v[210:213], v[48:51]
	v_mfma_f32_16x16x32_bf16 v[36:39], v[190:193], v[218:221], v[36:39]
	v_mfma_f32_16x16x32_bf16 v[32:35], v[202:205], v[218:221], v[32:35]
	v_mfma_f32_16x16x32_bf16 v[20:23], v[190:193], v[226:229], v[20:23]
	v_mfma_f32_16x16x32_bf16 v[16:19], v[202:205], v[226:229], v[16:19]
	v_mfma_f32_16x16x32_bf16 v[4:7], v[190:193], v[234:237], v[4:7]
	v_mfma_f32_16x16x32_bf16 v[0:3], v[202:205], v[234:237], v[0:3]
	v_mfma_f32_16x16x32_bf16 v[52:55], v[198:201], v[214:217], v[52:55]
	v_mfma_f32_16x16x32_bf16 v[48:51], v[206:209], v[214:217], v[48:51]
	v_mfma_f32_16x16x32_bf16 v[36:39], v[198:201], v[222:225], v[36:39]
	v_mfma_f32_16x16x32_bf16 v[32:35], v[206:209], v[222:225], v[32:35]
	v_mfma_f32_16x16x32_bf16 v[20:23], v[198:201], v[230:233], v[20:23]
	v_mfma_f32_16x16x32_bf16 v[16:19], v[206:209], v[230:233], v[16:19]
	v_mfma_f32_16x16x32_bf16 v[4:7], v[198:201], v[238:241], v[4:7]
	v_mfma_f32_16x16x32_bf16 v[0:3], v[206:209], v[238:241], v[0:3]
	s_barrier
	ds_read_b128 v[174:177], v165
	ds_read_b128 v[178:181], v166
	ds_read_b128 v[182:185], v167
	ds_read_b128 v[186:189], v168
	ds_read_b128 v[190:193], v169
	ds_read_b128 v[198:201], v170
	ds_read_b128 v[202:205], v171
	ds_read_b128 v[206:209], v172
	s_add_u32 s50, s50, 0x40000
	s_addc_u32 s51, s51, 0
	s_mov_b32 m0, s31
	ds_read_b128 v[210:213], v141 offset:32768
	ds_read_b128 v[214:217], v141 offset:33792
	ds_read_b128 v[218:221], v141 offset:34816
	ds_read_b128 v[222:225], v141 offset:35840
	ds_read_b128 v[226:229], v141 offset:36864
	ds_read_b128 v[230:233], v141 offset:37888
	ds_read_b128 v[234:237], v141 offset:38912
	ds_read_b128 v[238:241], v141 offset:39936
	global_load_lds_dwordx4 v130, s[50:51]
	s_mov_b32 m0, s33
	s_nop 0
	global_load_lds_dwordx4 v128, s[50:51]
	s_waitcnt vmcnt(8)
	s_waitcnt lgkmcnt(0)
	s_barrier
	v_mfma_f32_16x16x32_bf16 v[124:127], v[174:177], v[210:213], v[124:127]
	v_mfma_f32_16x16x32_bf16 v[120:123], v[182:185], v[210:213], v[120:123]
	v_mfma_f32_16x16x32_bf16 v[108:111], v[174:177], v[218:221], v[108:111]
	v_mfma_f32_16x16x32_bf16 v[104:107], v[182:185], v[218:221], v[104:107]
	v_mfma_f32_16x16x32_bf16 v[92:95], v[174:177], v[226:229], v[92:95]
	v_mfma_f32_16x16x32_bf16 v[88:91], v[182:185], v[226:229], v[88:91]
	v_mfma_f32_16x16x32_bf16 v[76:79], v[174:177], v[234:237], v[76:79]
	v_mfma_f32_16x16x32_bf16 v[72:75], v[182:185], v[234:237], v[72:75]
	v_mfma_f32_16x16x32_bf16 v[124:127], v[178:181], v[214:217], v[124:127]
	v_mfma_f32_16x16x32_bf16 v[120:123], v[186:189], v[214:217], v[120:123]
	v_mfma_f32_16x16x32_bf16 v[108:111], v[178:181], v[222:225], v[108:111]
	v_mfma_f32_16x16x32_bf16 v[104:107], v[186:189], v[222:225], v[104:107]
	v_mfma_f32_16x16x32_bf16 v[92:95], v[178:181], v[230:233], v[92:95]
	v_mfma_f32_16x16x32_bf16 v[88:91], v[186:189], v[230:233], v[88:91]
	v_mfma_f32_16x16x32_bf16 v[76:79], v[178:181], v[238:241], v[76:79]
	v_mfma_f32_16x16x32_bf16 v[72:75], v[186:189], v[238:241], v[72:75]
	v_mfma_f32_16x16x32_bf16 v[116:119], v[190:193], v[210:213], v[116:119]
	v_mfma_f32_16x16x32_bf16 v[112:115], v[202:205], v[210:213], v[112:115]
	v_mfma_f32_16x16x32_bf16 v[100:103], v[190:193], v[218:221], v[100:103]
	v_mfma_f32_16x16x32_bf16 v[96:99], v[202:205], v[218:221], v[96:99]
	v_mfma_f32_16x16x32_bf16 v[84:87], v[190:193], v[226:229], v[84:87]
	v_mfma_f32_16x16x32_bf16 v[80:83], v[202:205], v[226:229], v[80:83]
	v_mfma_f32_16x16x32_bf16 v[68:71], v[190:193], v[234:237], v[68:71]
	v_mfma_f32_16x16x32_bf16 v[64:67], v[202:205], v[234:237], v[64:67]
	v_mfma_f32_16x16x32_bf16 v[116:119], v[198:201], v[214:217], v[116:119]
	v_mfma_f32_16x16x32_bf16 v[112:115], v[206:209], v[214:217], v[112:115]
	v_mfma_f32_16x16x32_bf16 v[100:103], v[198:201], v[222:225], v[100:103]
	v_mfma_f32_16x16x32_bf16 v[96:99], v[206:209], v[222:225], v[96:99]
	v_mfma_f32_16x16x32_bf16 v[84:87], v[198:201], v[230:233], v[84:87]
	v_mfma_f32_16x16x32_bf16 v[80:83], v[206:209], v[230:233], v[80:83]
	v_mfma_f32_16x16x32_bf16 v[68:71], v[198:201], v[238:241], v[68:71]
	v_mfma_f32_16x16x32_bf16 v[64:67], v[206:209], v[238:241], v[64:67]
	s_barrier
	s_mov_b32 m0, s36
	s_add_u32 s48, s48, 0x40080
	ds_read_b128 v[210:213], v141 offset:49152
	ds_read_b128 v[214:217], v141 offset:50176
	ds_read_b128 v[218:221], v141 offset:51200
	ds_read_b128 v[222:225], v141 offset:52224
	ds_read_b128 v[226:229], v141 offset:53248
	ds_read_b128 v[230:233], v141 offset:54272
	ds_read_b128 v[234:237], v141 offset:55296
	ds_read_b128 v[238:241], v141 offset:56320
	global_load_lds_dwordx4 v130, s[98:99]
	s_mov_b32 m0, s37
	s_addc_u32 s49, s49, 0
	global_load_lds_dwordx4 v128, s[98:99]
	s_mov_b32 m0, s53
	s_nop 0
	global_load_lds_dwordx4 v130, s[48:49]
	s_mov_b32 m0, s54
	s_nop 0
	global_load_lds_dwordx4 v128, s[48:49]
	s_mov_b32 m0, s47
	s_nop 0
	global_load_lds_dwordx4 v130, s[100:101]
	s_mov_b32 m0, s52
	s_nop 0
	global_load_lds_dwordx4 v128, s[100:101]
	s_waitcnt vmcnt(8)
	s_waitcnt lgkmcnt(0)
	s_barrier
	v_mfma_f32_16x16x32_bf16 v[60:63], v[174:177], v[210:213], v[60:63]
	v_mfma_f32_16x16x32_bf16 v[56:59], v[182:185], v[210:213], v[56:59]
	v_mfma_f32_16x16x32_bf16 v[44:47], v[174:177], v[218:221], v[44:47]
	v_mfma_f32_16x16x32_bf16 v[40:43], v[182:185], v[218:221], v[40:43]
	v_mfma_f32_16x16x32_bf16 v[28:31], v[174:177], v[226:229], v[28:31]
	v_mfma_f32_16x16x32_bf16 v[24:27], v[182:185], v[226:229], v[24:27]
	v_mfma_f32_16x16x32_bf16 v[12:15], v[174:177], v[234:237], v[12:15]
	v_mfma_f32_16x16x32_bf16 v[8:11], v[182:185], v[234:237], v[8:11]
	v_mfma_f32_16x16x32_bf16 v[60:63], v[178:181], v[214:217], v[60:63]
	v_mfma_f32_16x16x32_bf16 v[56:59], v[186:189], v[214:217], v[56:59]
	v_mfma_f32_16x16x32_bf16 v[44:47], v[178:181], v[222:225], v[44:47]
	v_mfma_f32_16x16x32_bf16 v[40:43], v[186:189], v[222:225], v[40:43]
	v_mfma_f32_16x16x32_bf16 v[28:31], v[178:181], v[230:233], v[28:31]
	v_mfma_f32_16x16x32_bf16 v[24:27], v[186:189], v[230:233], v[24:27]
	v_mfma_f32_16x16x32_bf16 v[12:15], v[178:181], v[238:241], v[12:15]
	v_mfma_f32_16x16x32_bf16 v[8:11], v[186:189], v[238:241], v[8:11]
	v_mfma_f32_16x16x32_bf16 v[52:55], v[190:193], v[210:213], v[52:55]
	v_mfma_f32_16x16x32_bf16 v[48:51], v[202:205], v[210:213], v[48:51]
	v_mfma_f32_16x16x32_bf16 v[36:39], v[190:193], v[218:221], v[36:39]
	v_mfma_f32_16x16x32_bf16 v[32:35], v[202:205], v[218:221], v[32:35]
	v_mfma_f32_16x16x32_bf16 v[20:23], v[190:193], v[226:229], v[20:23]
	v_mfma_f32_16x16x32_bf16 v[16:19], v[202:205], v[226:229], v[16:19]
	v_mfma_f32_16x16x32_bf16 v[4:7], v[190:193], v[234:237], v[4:7]
	v_mfma_f32_16x16x32_bf16 v[0:3], v[202:205], v[234:237], v[0:3]
	v_mfma_f32_16x16x32_bf16 v[52:55], v[198:201], v[214:217], v[52:55]
	v_mfma_f32_16x16x32_bf16 v[48:51], v[206:209], v[214:217], v[48:51]
	v_mfma_f32_16x16x32_bf16 v[36:39], v[198:201], v[222:225], v[36:39]
	v_mfma_f32_16x16x32_bf16 v[32:35], v[206:209], v[222:225], v[32:35]
	v_mfma_f32_16x16x32_bf16 v[20:23], v[198:201], v[230:233], v[20:23]
	v_mfma_f32_16x16x32_bf16 v[16:19], v[206:209], v[230:233], v[16:19]
	v_mfma_f32_16x16x32_bf16 v[4:7], v[198:201], v[238:241], v[4:7]
	v_mfma_f32_16x16x32_bf16 v[0:3], v[206:209], v[238:241], v[0:3]
	s_add_i32 s75, s75, 2
	s_add_u32 s24, s24, 0x100
	s_addc_u32 s25, s25, 0
	s_add_u32 s67, s67, 0x100
	s_addc_u32 s74, s74, 0
	s_cmp_gt_u32 s75, 13
	s_barrier
	s_cbranch_scc0 .LBB0_1914
	s_and_b64 vcc, exec, s[14:15]
	s_cbranch_vccz .LBB0_1917
	s_barrier

.LBB0_1994:
	ds_read_b128 v[128:131], v199
	ds_read_b128 v[132:135], v200
	ds_read_b128 v[136:139], v201
	ds_read_b128 v[140:143], v202
	ds_read_b128 v[172:175], v203
	ds_read_b128 v[176:179], v204
	ds_read_b128 v[180:183], v205
	ds_read_b128 v[184:187], v206
	s_add_u32 s48, s24, 0x100
	s_addc_u32 s49, s25, 0
	s_cmp_eq_u32 s68, 40
	s_cselect_b32 s55, s13, s49
	s_cselect_b32 s54, s12, s48
	s_cselect_b32 s51, s47, s5
	s_cselect_b32 s50, s46, s4
	s_mov_b32 m0, s64
	ds_read_b128 v[188:191], v159
	ds_read_b128 v[216:219], v159 offset:1024
	ds_read_b128 v[220:223], v159 offset:2048
	ds_read_b128 v[224:227], v159 offset:3072
	ds_read_b128 v[228:231], v159 offset:4096
	ds_read_b128 v[232:235], v159 offset:5120
	ds_read_b128 v[236:239], v159 offset:6144
	ds_read_b128 v[240:243], v159 offset:7168
	global_load_lds_dwordx4 v164, s[24:25]
	s_mov_b32 m0, s65
	s_nop 0
	global_load_lds_dwordx4 v166, s[24:25]
	s_waitcnt vmcnt(8)
	s_waitcnt lgkmcnt(0)
	s_barrier
	v_mfma_f32_16x16x32_bf16 v[124:127], v[128:131], v[188:191], v[124:127]
	v_mfma_f32_16x16x32_bf16 v[120:123], v[136:139], v[188:191], v[120:123]
	v_mfma_f32_16x16x32_bf16 v[108:111], v[128:131], v[220:223], v[108:111]
	v_mfma_f32_16x16x32_bf16 v[104:107], v[136:139], v[220:223], v[104:107]
	v_mfma_f32_16x16x32_bf16 v[92:95], v[128:131], v[228:231], v[92:95]
	v_mfma_f32_16x16x32_bf16 v[88:91], v[136:139], v[228:231], v[88:91]
	v_mfma_f32_16x16x32_bf16 v[76:79], v[128:131], v[236:239], v[76:79]
	v_mfma_f32_16x16x32_bf16 v[72:75], v[136:139], v[236:239], v[72:75]
	v_mfma_f32_16x16x32_bf16 v[124:127], v[132:135], v[216:219], v[124:127]
	v_mfma_f32_16x16x32_bf16 v[120:123], v[140:143], v[216:219], v[120:123]
	v_mfma_f32_16x16x32_bf16 v[108:111], v[132:135], v[224:227], v[108:111]
	v_mfma_f32_16x16x32_bf16 v[104:107], v[140:143], v[224:227], v[104:107]
	v_mfma_f32_16x16x32_bf16 v[92:95], v[132:135], v[232:235], v[92:95]
	v_mfma_f32_16x16x32_bf16 v[88:91], v[140:143], v[232:235], v[88:91]
	v_mfma_f32_16x16x32_bf16 v[76:79], v[132:135], v[240:243], v[76:79]
	v_mfma_f32_16x16x32_bf16 v[72:75], v[140:143], v[240:243], v[72:75]
	v_mfma_f32_16x16x32_bf16 v[116:119], v[172:175], v[188:191], v[116:119]
	v_mfma_f32_16x16x32_bf16 v[112:115], v[180:183], v[188:191], v[112:115]
	v_mfma_f32_16x16x32_bf16 v[100:103], v[172:175], v[220:223], v[100:103]
	v_mfma_f32_16x16x32_bf16 v[96:99], v[180:183], v[220:223], v[96:99]
	v_mfma_f32_16x16x32_bf16 v[84:87], v[172:175], v[228:231], v[84:87]
	v_mfma_f32_16x16x32_bf16 v[80:83], v[180:183], v[228:231], v[80:83]
	v_mfma_f32_16x16x32_bf16 v[68:71], v[172:175], v[236:239], v[68:71]
	v_mfma_f32_16x16x32_bf16 v[64:67], v[180:183], v[236:239], v[64:67]
	v_mfma_f32_16x16x32_bf16 v[116:119], v[176:179], v[216:219], v[116:119]
	v_mfma_f32_16x16x32_bf16 v[112:115], v[184:187], v[216:219], v[112:115]
	v_mfma_f32_16x16x32_bf16 v[100:103], v[176:179], v[224:227], v[100:103]
	v_mfma_f32_16x16x32_bf16 v[96:99], v[184:187], v[224:227], v[96:99]
	v_mfma_f32_16x16x32_bf16 v[84:87], v[176:179], v[232:235], v[84:87]
	v_mfma_f32_16x16x32_bf16 v[80:83], v[184:187], v[232:235], v[80:83]
	v_mfma_f32_16x16x32_bf16 v[68:71], v[176:179], v[240:243], v[68:71]
	v_mfma_f32_16x16x32_bf16 v[64:67], v[184:187], v[240:243], v[64:67]
	s_add_u32 s98, s50, s40
	s_addc_u32 s99, s51, s41
	s_add_u32 s100, s54, s40
	s_addc_u32 s101, s55, s41
	s_barrier
	s_mov_b32 m0, s7
	s_add_u32 s24, s50, 0xb0000
	ds_read_b128 v[188:191], v159 offset:16384
	ds_read_b128 v[216:219], v159 offset:17408
	ds_read_b128 v[220:223], v159 offset:18432
	ds_read_b128 v[224:227], v159 offset:19456
	ds_read_b128 v[228:231], v159 offset:20480
	ds_read_b128 v[232:235], v159 offset:21504
	ds_read_b128 v[236:239], v159 offset:22528
	ds_read_b128 v[240:243], v159 offset:23552
	global_load_lds_dwordx4 v160, s[50:51]
	s_mov_b32 m0, s8
	s_addc_u32 s25, s51, 0
	global_load_lds_dwordx4 v162, s[50:51]
	s_mov_b32 m0, s9
	s_nop 0
	global_load_lds_dwordx4 v160, s[24:25]
	s_mov_b32 m0, s28
	s_nop 0
	global_load_lds_dwordx4 v162, s[24:25]
	s_mov_b32 m0, s6
	s_nop 0
	global_load_lds_dwordx4 v160, s[54:55]
	s_mov_b32 m0, s29
	s_nop 0
	global_load_lds_dwordx4 v162, s[54:55]
	s_waitcnt vmcnt(8)
	s_waitcnt lgkmcnt(0)
	s_barrier
	v_mfma_f32_16x16x32_bf16 v[60:63], v[128:131], v[188:191], v[60:63]
	v_mfma_f32_16x16x32_bf16 v[56:59], v[136:139], v[188:191], v[56:59]
	v_mfma_f32_16x16x32_bf16 v[44:47], v[128:131], v[220:223], v[44:47]
	v_mfma_f32_16x16x32_bf16 v[40:43], v[136:139], v[220:223], v[40:43]
	v_mfma_f32_16x16x32_bf16 v[28:31], v[128:131], v[228:231], v[28:31]
	v_mfma_f32_16x16x32_bf16 v[24:27], v[136:139], v[228:231], v[24:27]
	v_mfma_f32_16x16x32_bf16 v[12:15], v[128:131], v[236:239], v[12:15]
	v_mfma_f32_16x16x32_bf16 v[8:11], v[136:139], v[236:239], v[8:11]
	v_mfma_f32_16x16x32_bf16 v[60:63], v[132:135], v[216:219], v[60:63]
	v_mfma_f32_16x16x32_bf16 v[56:59], v[140:143], v[216:219], v[56:59]
	v_mfma_f32_16x16x32_bf16 v[44:47], v[132:135], v[224:227], v[44:47]
	v_mfma_f32_16x16x32_bf16 v[40:43], v[140:143], v[224:227], v[40:43]
	v_mfma_f32_16x16x32_bf16 v[28:31], v[132:135], v[232:235], v[28:31]
	v_mfma_f32_16x16x32_bf16 v[24:27], v[140:143], v[232:235], v[24:27]
	v_mfma_f32_16x16x32_bf16 v[12:15], v[132:135], v[240:243], v[12:15]
	v_mfma_f32_16x16x32_bf16 v[8:11], v[140:143], v[240:243], v[8:11]
	v_mfma_f32_16x16x32_bf16 v[52:55], v[172:175], v[188:191], v[52:55]
	v_mfma_f32_16x16x32_bf16 v[48:51], v[180:183], v[188:191], v[48:51]
	v_mfma_f32_16x16x32_bf16 v[36:39], v[172:175], v[220:223], v[36:39]
	v_mfma_f32_16x16x32_bf16 v[32:35], v[180:183], v[220:223], v[32:35]
	v_mfma_f32_16x16x32_bf16 v[20:23], v[172:175], v[228:231], v[20:23]
	v_mfma_f32_16x16x32_bf16 v[16:19], v[180:183], v[228:231], v[16:19]
	v_mfma_f32_16x16x32_bf16 v[4:7], v[172:175], v[236:239], v[4:7]
	v_mfma_f32_16x16x32_bf16 v[0:3], v[180:183], v[236:239], v[0:3]
	v_mfma_f32_16x16x32_bf16 v[52:55], v[176:179], v[216:219], v[52:55]
	v_mfma_f32_16x16x32_bf16 v[48:51], v[184:187], v[216:219], v[48:51]
	v_mfma_f32_16x16x32_bf16 v[36:39], v[176:179], v[224:227], v[36:39]
	v_mfma_f32_16x16x32_bf16 v[32:35], v[184:187], v[224:227], v[32:35]
	v_mfma_f32_16x16x32_bf16 v[20:23], v[176:179], v[232:235], v[20:23]
	v_mfma_f32_16x16x32_bf16 v[16:19], v[184:187], v[232:235], v[16:19]
	v_mfma_f32_16x16x32_bf16 v[4:7], v[176:179], v[240:243], v[4:7]
	v_mfma_f32_16x16x32_bf16 v[0:3], v[184:187], v[240:243], v[0:3]
	s_barrier
	ds_read_b128 v[128:131], v207
	ds_read_b128 v[132:135], v208
	ds_read_b128 v[136:139], v209
	ds_read_b128 v[140:143], v210
	ds_read_b128 v[172:175], v211
	ds_read_b128 v[176:179], v212
	ds_read_b128 v[180:183], v213
	ds_read_b128 v[184:187], v214
	s_add_u32 s24, s54, 0xb0000
	s_addc_u32 s25, s55, 0
	s_mov_b32 m0, s30
	ds_read_b128 v[188:191], v159 offset:32768
	ds_read_b128 v[216:219], v159 offset:33792
	ds_read_b128 v[220:223], v159 offset:34816
	ds_read_b128 v[224:227], v159 offset:35840
	ds_read_b128 v[228:231], v159 offset:36864
	ds_read_b128 v[232:235], v159 offset:37888
	ds_read_b128 v[236:239], v159 offset:38912
	ds_read_b128 v[240:243], v159 offset:39936
	global_load_lds_dwordx4 v160, s[24:25]
	s_mov_b32 m0, s31
	s_nop 0
	global_load_lds_dwordx4 v162, s[24:25]
	s_waitcnt vmcnt(8)
	s_waitcnt lgkmcnt(0)
	s_barrier
	v_mfma_f32_16x16x32_bf16 v[124:127], v[128:131], v[188:191], v[124:127]
	v_mfma_f32_16x16x32_bf16 v[120:123], v[136:139], v[188:191], v[120:123]
	v_mfma_f32_16x16x32_bf16 v[108:111], v[128:131], v[220:223], v[108:111]
	v_mfma_f32_16x16x32_bf16 v[104:107], v[136:139], v[220:223], v[104:107]
	v_mfma_f32_16x16x32_bf16 v[92:95], v[128:131], v[228:231], v[92:95]
	v_mfma_f32_16x16x32_bf16 v[88:91], v[136:139], v[228:231], v[88:91]
	v_mfma_f32_16x16x32_bf16 v[76:79], v[128:131], v[236:239], v[76:79]
	v_mfma_f32_16x16x32_bf16 v[72:75], v[136:139], v[236:239], v[72:75]
	v_mfma_f32_16x16x32_bf16 v[124:127], v[132:135], v[216:219], v[124:127]
	v_mfma_f32_16x16x32_bf16 v[120:123], v[140:143], v[216:219], v[120:123]
	v_mfma_f32_16x16x32_bf16 v[108:111], v[132:135], v[224:227], v[108:111]
	v_mfma_f32_16x16x32_bf16 v[104:107], v[140:143], v[224:227], v[104:107]
	v_mfma_f32_16x16x32_bf16 v[92:95], v[132:135], v[232:235], v[92:95]
	v_mfma_f32_16x16x32_bf16 v[88:91], v[140:143], v[232:235], v[88:91]
	v_mfma_f32_16x16x32_bf16 v[76:79], v[132:135], v[240:243], v[76:79]
	v_mfma_f32_16x16x32_bf16 v[72:75], v[140:143], v[240:243], v[72:75]
	v_mfma_f32_16x16x32_bf16 v[116:119], v[172:175], v[188:191], v[116:119]
	v_mfma_f32_16x16x32_bf16 v[112:115], v[180:183], v[188:191], v[112:115]
	v_mfma_f32_16x16x32_bf16 v[100:103], v[172:175], v[220:223], v[100:103]
	v_mfma_f32_16x16x32_bf16 v[96:99], v[180:183], v[220:223], v[96:99]
	v_mfma_f32_16x16x32_bf16 v[84:87], v[172:175], v[228:231], v[84:87]
	v_mfma_f32_16x16x32_bf16 v[80:83], v[180:183], v[228:231], v[80:83]
	v_mfma_f32_16x16x32_bf16 v[68:71], v[172:175], v[236:239], v[68:71]
	v_mfma_f32_16x16x32_bf16 v[64:67], v[180:183], v[236:239], v[64:67]
	v_mfma_f32_16x16x32_bf16 v[116:119], v[176:179], v[216:219], v[116:119]
	v_mfma_f32_16x16x32_bf16 v[112:115], v[184:187], v[216:219], v[112:115]
	v_mfma_f32_16x16x32_bf16 v[100:103], v[176:179], v[224:227], v[100:103]
	v_mfma_f32_16x16x32_bf16 v[96:99], v[184:187], v[224:227], v[96:99]
	v_mfma_f32_16x16x32_bf16 v[84:87], v[176:179], v[232:235], v[84:87]
	v_mfma_f32_16x16x32_bf16 v[80:83], v[184:187], v[232:235], v[80:83]
	v_mfma_f32_16x16x32_bf16 v[68:71], v[176:179], v[240:243], v[68:71]
	v_mfma_f32_16x16x32_bf16 v[64:67], v[184:187], v[240:243], v[64:67]
	s_barrier
	s_mov_b32 m0, s33
	s_add_u32 s24, s50, 0xb0080
	ds_read_b128 v[188:191], v159 offset:49152
	ds_read_b128 v[216:219], v159 offset:50176
	ds_read_b128 v[220:223], v159 offset:51200
	ds_read_b128 v[224:227], v159 offset:52224
	ds_read_b128 v[228:231], v159 offset:53248
	ds_read_b128 v[232:235], v159 offset:54272
	ds_read_b128 v[236:239], v159 offset:55296
	ds_read_b128 v[240:243], v159 offset:56320
	global_load_lds_dwordx4 v160, s[98:99]
	s_mov_b32 m0, s34
	s_addc_u32 s25, s51, 0
	global_load_lds_dwordx4 v162, s[98:99]
	s_mov_b32 m0, s37
	s_nop 0
	global_load_lds_dwordx4 v160, s[24:25]
	s_mov_b32 m0, s45
	s_nop 0
	global_load_lds_dwordx4 v162, s[24:25]
	s_mov_b32 m0, s35
	s_nop 0
	global_load_lds_dwordx4 v160, s[100:101]
	s_mov_b32 m0, s36
	s_nop 0
	global_load_lds_dwordx4 v162, s[100:101]
	s_waitcnt vmcnt(8)
	s_waitcnt lgkmcnt(0)
	s_barrier
	v_mfma_f32_16x16x32_bf16 v[60:63], v[128:131], v[188:191], v[60:63]
	v_mfma_f32_16x16x32_bf16 v[56:59], v[136:139], v[188:191], v[56:59]
	v_mfma_f32_16x16x32_bf16 v[44:47], v[128:131], v[220:223], v[44:47]
	v_mfma_f32_16x16x32_bf16 v[40:43], v[136:139], v[220:223], v[40:43]
	v_mfma_f32_16x16x32_bf16 v[28:31], v[128:131], v[228:231], v[28:31]
	v_mfma_f32_16x16x32_bf16 v[24:27], v[136:139], v[228:231], v[24:27]
	v_mfma_f32_16x16x32_bf16 v[12:15], v[128:131], v[236:239], v[12:15]
	v_mfma_f32_16x16x32_bf16 v[8:11], v[136:139], v[236:239], v[8:11]
	v_mfma_f32_16x16x32_bf16 v[60:63], v[132:135], v[216:219], v[60:63]
	v_mfma_f32_16x16x32_bf16 v[56:59], v[140:143], v[216:219], v[56:59]
	v_mfma_f32_16x16x32_bf16 v[44:47], v[132:135], v[224:227], v[44:47]
	v_mfma_f32_16x16x32_bf16 v[40:43], v[140:143], v[224:227], v[40:43]
	v_mfma_f32_16x16x32_bf16 v[28:31], v[132:135], v[232:235], v[28:31]
	v_mfma_f32_16x16x32_bf16 v[24:27], v[140:143], v[232:235], v[24:27]
	v_mfma_f32_16x16x32_bf16 v[12:15], v[132:135], v[240:243], v[12:15]
	v_mfma_f32_16x16x32_bf16 v[8:11], v[140:143], v[240:243], v[8:11]
	v_mfma_f32_16x16x32_bf16 v[52:55], v[172:175], v[188:191], v[52:55]
	v_mfma_f32_16x16x32_bf16 v[48:51], v[180:183], v[188:191], v[48:51]
	v_mfma_f32_16x16x32_bf16 v[36:39], v[172:175], v[220:223], v[36:39]
	v_mfma_f32_16x16x32_bf16 v[32:35], v[180:183], v[220:223], v[32:35]
	v_mfma_f32_16x16x32_bf16 v[20:23], v[172:175], v[228:231], v[20:23]
	v_mfma_f32_16x16x32_bf16 v[16:19], v[180:183], v[228:231], v[16:19]
	v_mfma_f32_16x16x32_bf16 v[4:7], v[172:175], v[236:239], v[4:7]
	v_mfma_f32_16x16x32_bf16 v[0:3], v[180:183], v[236:239], v[0:3]
	v_mfma_f32_16x16x32_bf16 v[52:55], v[176:179], v[216:219], v[52:55]
	v_mfma_f32_16x16x32_bf16 v[48:51], v[184:187], v[216:219], v[48:51]
	v_mfma_f32_16x16x32_bf16 v[36:39], v[176:179], v[224:227], v[36:39]
	v_mfma_f32_16x16x32_bf16 v[32:35], v[184:187], v[224:227], v[32:35]
	v_mfma_f32_16x16x32_bf16 v[20:23], v[176:179], v[232:235], v[20:23]
	v_mfma_f32_16x16x32_bf16 v[16:19], v[184:187], v[232:235], v[16:19]
	v_mfma_f32_16x16x32_bf16 v[4:7], v[176:179], v[240:243], v[4:7]
	v_mfma_f32_16x16x32_bf16 v[0:3], v[184:187], v[240:243], v[0:3]
	s_add_i32 s68, s68, 2
	s_add_u32 s4, s4, 0x100
	s_addc_u32 s5, s5, 0
	s_cmp_gt_u32 s68, 41
	s_mov_b64 s[24:25], s[48:49]
	s_barrier
	s_cbranch_scc0 .LBB0_1994
	s_and_b64 vcc, exec, s[42:43]
	s_cbranch_vccz .LBB0_1997
	s_barrier

.LBB0_2152:
	ds_read_b128 v[160:163], v169
	ds_read_b128 v[164:167], v170
	ds_read_b128 v[186:189], v171
	ds_read_b128 v[190:193], v172
	ds_read_b128 v[198:201], v173
	ds_read_b128 v[202:205], v174
	ds_read_b128 v[206:209], v175
	ds_read_b128 v[210:213], v176
	s_add_u32 s18, s16, 0xfffc0080
	s_addc_u32 s19, s17, -1
	s_cmp_eq_u32 s66, 12
	s_cselect_b32 s25, s4, s19
	s_cselect_b32 s24, s5, s18
	s_cselect_b32 s19, s13, s49
	s_cselect_b32 s18, s15, s47
	s_mov_b32 m0, s64
	ds_read_b128 v[214:217], v159
	ds_read_b128 v[218:221], v159 offset:1024
	ds_read_b128 v[222:225], v159 offset:2048
	ds_read_b128 v[226:229], v159 offset:3072
	ds_read_b128 v[230:233], v159 offset:4096
	ds_read_b128 v[234:237], v159 offset:5120
	ds_read_b128 v[238:241], v159 offset:6144
	ds_read_b128 v[242:245], v159 offset:7168
	global_load_lds_dwordx4 v134, s[16:17]
	s_mov_b32 m0, s65
	s_nop 0
	global_load_lds_dwordx4 v136, s[16:17]
	s_waitcnt vmcnt(8)
	s_waitcnt lgkmcnt(0)
	s_barrier
	v_mfma_f32_16x16x32_bf16 v[124:127], v[160:163], v[214:217], v[124:127]
	v_mfma_f32_16x16x32_bf16 v[120:123], v[186:189], v[214:217], v[120:123]
	v_mfma_f32_16x16x32_bf16 v[108:111], v[160:163], v[222:225], v[108:111]
	v_mfma_f32_16x16x32_bf16 v[104:107], v[186:189], v[222:225], v[104:107]
	v_mfma_f32_16x16x32_bf16 v[92:95], v[160:163], v[230:233], v[92:95]
	v_mfma_f32_16x16x32_bf16 v[88:91], v[186:189], v[230:233], v[88:91]
	v_mfma_f32_16x16x32_bf16 v[76:79], v[160:163], v[238:241], v[76:79]
	v_mfma_f32_16x16x32_bf16 v[72:75], v[186:189], v[238:241], v[72:75]
	v_mfma_f32_16x16x32_bf16 v[124:127], v[164:167], v[218:221], v[124:127]
	v_mfma_f32_16x16x32_bf16 v[120:123], v[190:193], v[218:221], v[120:123]
	v_mfma_f32_16x16x32_bf16 v[108:111], v[164:167], v[226:229], v[108:111]
	v_mfma_f32_16x16x32_bf16 v[104:107], v[190:193], v[226:229], v[104:107]
	v_mfma_f32_16x16x32_bf16 v[92:95], v[164:167], v[234:237], v[92:95]
	v_mfma_f32_16x16x32_bf16 v[88:91], v[190:193], v[234:237], v[88:91]
	v_mfma_f32_16x16x32_bf16 v[76:79], v[164:167], v[242:245], v[76:79]
	v_mfma_f32_16x16x32_bf16 v[72:75], v[190:193], v[242:245], v[72:75]
	v_mfma_f32_16x16x32_bf16 v[116:119], v[198:201], v[214:217], v[116:119]
	v_mfma_f32_16x16x32_bf16 v[112:115], v[206:209], v[214:217], v[112:115]
	v_mfma_f32_16x16x32_bf16 v[100:103], v[198:201], v[222:225], v[100:103]
	v_mfma_f32_16x16x32_bf16 v[96:99], v[206:209], v[222:225], v[96:99]
	v_mfma_f32_16x16x32_bf16 v[84:87], v[198:201], v[230:233], v[84:87]
	v_mfma_f32_16x16x32_bf16 v[80:83], v[206:209], v[230:233], v[80:83]
	v_mfma_f32_16x16x32_bf16 v[68:71], v[198:201], v[238:241], v[68:71]
	v_mfma_f32_16x16x32_bf16 v[64:67], v[206:209], v[238:241], v[64:67]
	v_mfma_f32_16x16x32_bf16 v[116:119], v[202:205], v[218:221], v[116:119]
	v_mfma_f32_16x16x32_bf16 v[112:115], v[210:213], v[218:221], v[112:115]
	v_mfma_f32_16x16x32_bf16 v[100:103], v[202:205], v[226:229], v[100:103]
	v_mfma_f32_16x16x32_bf16 v[96:99], v[210:213], v[226:229], v[96:99]
	v_mfma_f32_16x16x32_bf16 v[84:87], v[202:205], v[234:237], v[84:87]
	v_mfma_f32_16x16x32_bf16 v[80:83], v[210:213], v[234:237], v[80:83]
	v_mfma_f32_16x16x32_bf16 v[68:71], v[202:205], v[242:245], v[68:71]
	v_mfma_f32_16x16x32_bf16 v[64:67], v[210:213], v[242:245], v[64:67]
	s_add_u32 s98, s18, s42
	s_addc_u32 s99, s19, s43
	s_add_u32 s100, s24, s42
	s_addc_u32 s101, s25, s43
	s_barrier
	s_mov_b32 m0, s6
	s_add_u32 s68, s18, 0x40000
	ds_read_b128 v[214:217], v159 offset:16384
	ds_read_b128 v[218:221], v159 offset:17408
	ds_read_b128 v[222:225], v159 offset:18432
	ds_read_b128 v[226:229], v159 offset:19456
	ds_read_b128 v[230:233], v159 offset:20480
	ds_read_b128 v[234:237], v159 offset:21504
	ds_read_b128 v[238:241], v159 offset:22528
	ds_read_b128 v[242:245], v159 offset:23552
	global_load_lds_dwordx4 v128, s[18:19]
	s_mov_b32 m0, s7
	s_addc_u32 s69, s19, 0
	global_load_lds_dwordx4 v130, s[18:19]
	s_mov_b32 m0, s8
	s_nop 0
	global_load_lds_dwordx4 v128, s[68:69]
	s_mov_b32 m0, s9
	s_nop 0
	global_load_lds_dwordx4 v130, s[68:69]
	s_mov_b32 m0, s2
	s_nop 0
	global_load_lds_dwordx4 v128, s[24:25]
	s_mov_b32 m0, s28
	s_nop 0
	global_load_lds_dwordx4 v130, s[24:25]
	s_waitcnt vmcnt(8)
	s_waitcnt lgkmcnt(0)
	s_barrier
	v_mfma_f32_16x16x32_bf16 v[60:63], v[160:163], v[214:217], v[60:63]
	v_mfma_f32_16x16x32_bf16 v[56:59], v[186:189], v[214:217], v[56:59]
	v_mfma_f32_16x16x32_bf16 v[44:47], v[160:163], v[222:225], v[44:47]
	v_mfma_f32_16x16x32_bf16 v[40:43], v[186:189], v[222:225], v[40:43]
	v_mfma_f32_16x16x32_bf16 v[28:31], v[160:163], v[230:233], v[28:31]
	v_mfma_f32_16x16x32_bf16 v[24:27], v[186:189], v[230:233], v[24:27]
	v_mfma_f32_16x16x32_bf16 v[12:15], v[160:163], v[238:241], v[12:15]
	v_mfma_f32_16x16x32_bf16 v[8:11], v[186:189], v[238:241], v[8:11]
	v_mfma_f32_16x16x32_bf16 v[60:63], v[164:167], v[218:221], v[60:63]
	v_mfma_f32_16x16x32_bf16 v[56:59], v[190:193], v[218:221], v[56:59]
	v_mfma_f32_16x16x32_bf16 v[44:47], v[164:167], v[226:229], v[44:47]
	v_mfma_f32_16x16x32_bf16 v[40:43], v[190:193], v[226:229], v[40:43]
	v_mfma_f32_16x16x32_bf16 v[28:31], v[164:167], v[234:237], v[28:31]
	v_mfma_f32_16x16x32_bf16 v[24:27], v[190:193], v[234:237], v[24:27]
	v_mfma_f32_16x16x32_bf16 v[12:15], v[164:167], v[242:245], v[12:15]
	v_mfma_f32_16x16x32_bf16 v[8:11], v[190:193], v[242:245], v[8:11]
	v_mfma_f32_16x16x32_bf16 v[52:55], v[198:201], v[214:217], v[52:55]
	v_mfma_f32_16x16x32_bf16 v[48:51], v[206:209], v[214:217], v[48:51]
	v_mfma_f32_16x16x32_bf16 v[36:39], v[198:201], v[222:225], v[36:39]
	v_mfma_f32_16x16x32_bf16 v[32:35], v[206:209], v[222:225], v[32:35]
	v_mfma_f32_16x16x32_bf16 v[20:23], v[198:201], v[230:233], v[20:23]
	v_mfma_f32_16x16x32_bf16 v[16:19], v[206:209], v[230:233], v[16:19]
	v_mfma_f32_16x16x32_bf16 v[4:7], v[198:201], v[238:241], v[4:7]
	v_mfma_f32_16x16x32_bf16 v[0:3], v[206:209], v[238:241], v[0:3]
	v_mfma_f32_16x16x32_bf16 v[52:55], v[202:205], v[218:221], v[52:55]
	v_mfma_f32_16x16x32_bf16 v[48:51], v[210:213], v[218:221], v[48:51]
	v_mfma_f32_16x16x32_bf16 v[36:39], v[202:205], v[226:229], v[36:39]
	v_mfma_f32_16x16x32_bf16 v[32:35], v[210:213], v[226:229], v[32:35]
	v_mfma_f32_16x16x32_bf16 v[20:23], v[202:205], v[234:237], v[20:23]
	v_mfma_f32_16x16x32_bf16 v[16:19], v[210:213], v[234:237], v[16:19]
	v_mfma_f32_16x16x32_bf16 v[4:7], v[202:205], v[242:245], v[4:7]
	v_mfma_f32_16x16x32_bf16 v[0:3], v[210:213], v[242:245], v[0:3]
	s_barrier
	ds_read_b128 v[160:163], v177
	ds_read_b128 v[164:167], v178
	ds_read_b128 v[186:189], v179
	ds_read_b128 v[190:193], v180
	ds_read_b128 v[198:201], v181
	ds_read_b128 v[202:205], v182
	ds_read_b128 v[206:209], v183
	ds_read_b128 v[210:213], v184
	s_add_u32 s24, s24, 0x40000
	s_addc_u32 s25, s25, 0
	s_mov_b32 m0, s29
	ds_read_b128 v[214:217], v159 offset:32768
	ds_read_b128 v[218:221], v159 offset:33792
	ds_read_b128 v[222:225], v159 offset:34816
	ds_read_b128 v[226:229], v159 offset:35840
	ds_read_b128 v[230:233], v159 offset:36864
	ds_read_b128 v[234:237], v159 offset:37888
	ds_read_b128 v[238:241], v159 offset:38912
	ds_read_b128 v[242:245], v159 offset:39936
	global_load_lds_dwordx4 v128, s[24:25]
	s_mov_b32 m0, s30
	s_nop 0
	global_load_lds_dwordx4 v130, s[24:25]
	s_waitcnt vmcnt(8)
	s_waitcnt lgkmcnt(0)
	s_barrier
	v_mfma_f32_16x16x32_bf16 v[124:127], v[160:163], v[214:217], v[124:127]
	v_mfma_f32_16x16x32_bf16 v[120:123], v[186:189], v[214:217], v[120:123]
	v_mfma_f32_16x16x32_bf16 v[108:111], v[160:163], v[222:225], v[108:111]
	v_mfma_f32_16x16x32_bf16 v[104:107], v[186:189], v[222:225], v[104:107]
	v_mfma_f32_16x16x32_bf16 v[92:95], v[160:163], v[230:233], v[92:95]
	v_mfma_f32_16x16x32_bf16 v[88:91], v[186:189], v[230:233], v[88:91]
	v_mfma_f32_16x16x32_bf16 v[76:79], v[160:163], v[238:241], v[76:79]
	v_mfma_f32_16x16x32_bf16 v[72:75], v[186:189], v[238:241], v[72:75]
	v_mfma_f32_16x16x32_bf16 v[124:127], v[164:167], v[218:221], v[124:127]
	v_mfma_f32_16x16x32_bf16 v[120:123], v[190:193], v[218:221], v[120:123]
	v_mfma_f32_16x16x32_bf16 v[108:111], v[164:167], v[226:229], v[108:111]
	v_mfma_f32_16x16x32_bf16 v[104:107], v[190:193], v[226:229], v[104:107]
	v_mfma_f32_16x16x32_bf16 v[92:95], v[164:167], v[234:237], v[92:95]
	v_mfma_f32_16x16x32_bf16 v[88:91], v[190:193], v[234:237], v[88:91]
	v_mfma_f32_16x16x32_bf16 v[76:79], v[164:167], v[242:245], v[76:79]
	v_mfma_f32_16x16x32_bf16 v[72:75], v[190:193], v[242:245], v[72:75]
	v_mfma_f32_16x16x32_bf16 v[116:119], v[198:201], v[214:217], v[116:119]
	v_mfma_f32_16x16x32_bf16 v[112:115], v[206:209], v[214:217], v[112:115]
	v_mfma_f32_16x16x32_bf16 v[100:103], v[198:201], v[222:225], v[100:103]
	v_mfma_f32_16x16x32_bf16 v[96:99], v[206:209], v[222:225], v[96:99]
	v_mfma_f32_16x16x32_bf16 v[84:87], v[198:201], v[230:233], v[84:87]
	v_mfma_f32_16x16x32_bf16 v[80:83], v[206:209], v[230:233], v[80:83]
	v_mfma_f32_16x16x32_bf16 v[68:71], v[198:201], v[238:241], v[68:71]
	v_mfma_f32_16x16x32_bf16 v[64:67], v[206:209], v[238:241], v[64:67]
	v_mfma_f32_16x16x32_bf16 v[116:119], v[202:205], v[218:221], v[116:119]
	v_mfma_f32_16x16x32_bf16 v[112:115], v[210:213], v[218:221], v[112:115]
	v_mfma_f32_16x16x32_bf16 v[100:103], v[202:205], v[226:229], v[100:103]
	v_mfma_f32_16x16x32_bf16 v[96:99], v[210:213], v[226:229], v[96:99]
	v_mfma_f32_16x16x32_bf16 v[84:87], v[202:205], v[234:237], v[84:87]
	v_mfma_f32_16x16x32_bf16 v[80:83], v[210:213], v[234:237], v[80:83]
	v_mfma_f32_16x16x32_bf16 v[68:71], v[202:205], v[242:245], v[68:71]
	v_mfma_f32_16x16x32_bf16 v[64:67], v[210:213], v[242:245], v[64:67]
	s_barrier
	s_mov_b32 m0, s31
	s_add_u32 s18, s18, 0x40080
	ds_read_b128 v[214:217], v159 offset:49152
	ds_read_b128 v[218:221], v159 offset:50176
	ds_read_b128 v[222:225], v159 offset:51200
	ds_read_b128 v[226:229], v159 offset:52224
	ds_read_b128 v[230:233], v159 offset:53248
	ds_read_b128 v[234:237], v159 offset:54272
	ds_read_b128 v[238:241], v159 offset:55296
	ds_read_b128 v[242:245], v159 offset:56320
	global_load_lds_dwordx4 v128, s[98:99]
	s_mov_b32 m0, s33
	s_addc_u32 s19, s19, 0
	global_load_lds_dwordx4 v130, s[98:99]
	s_mov_b32 m0, s36
	s_nop 0
	global_load_lds_dwordx4 v128, s[18:19]
	s_mov_b32 m0, s37
	s_nop 0
	global_load_lds_dwordx4 v130, s[18:19]
	s_mov_b32 m0, s34
	s_nop 0
	global_load_lds_dwordx4 v128, s[100:101]
	s_mov_b32 m0, s35
	s_nop 0
	global_load_lds_dwordx4 v130, s[100:101]
	s_waitcnt vmcnt(8)
	s_waitcnt lgkmcnt(0)
	s_barrier
	v_mfma_f32_16x16x32_bf16 v[60:63], v[160:163], v[214:217], v[60:63]
	v_mfma_f32_16x16x32_bf16 v[56:59], v[186:189], v[214:217], v[56:59]
	v_mfma_f32_16x16x32_bf16 v[44:47], v[160:163], v[222:225], v[44:47]
	v_mfma_f32_16x16x32_bf16 v[40:43], v[186:189], v[222:225], v[40:43]
	v_mfma_f32_16x16x32_bf16 v[28:31], v[160:163], v[230:233], v[28:31]
	v_mfma_f32_16x16x32_bf16 v[24:27], v[186:189], v[230:233], v[24:27]
	v_mfma_f32_16x16x32_bf16 v[12:15], v[160:163], v[238:241], v[12:15]
	v_mfma_f32_16x16x32_bf16 v[8:11], v[186:189], v[238:241], v[8:11]
	v_mfma_f32_16x16x32_bf16 v[60:63], v[164:167], v[218:221], v[60:63]
	v_mfma_f32_16x16x32_bf16 v[56:59], v[190:193], v[218:221], v[56:59]
	v_mfma_f32_16x16x32_bf16 v[44:47], v[164:167], v[226:229], v[44:47]
	v_mfma_f32_16x16x32_bf16 v[40:43], v[190:193], v[226:229], v[40:43]
	v_mfma_f32_16x16x32_bf16 v[28:31], v[164:167], v[234:237], v[28:31]
	v_mfma_f32_16x16x32_bf16 v[24:27], v[190:193], v[234:237], v[24:27]
	v_mfma_f32_16x16x32_bf16 v[12:15], v[164:167], v[242:245], v[12:15]
	v_mfma_f32_16x16x32_bf16 v[8:11], v[190:193], v[242:245], v[8:11]
	v_mfma_f32_16x16x32_bf16 v[52:55], v[198:201], v[214:217], v[52:55]
	v_mfma_f32_16x16x32_bf16 v[48:51], v[206:209], v[214:217], v[48:51]
	v_mfma_f32_16x16x32_bf16 v[36:39], v[198:201], v[222:225], v[36:39]
	v_mfma_f32_16x16x32_bf16 v[32:35], v[206:209], v[222:225], v[32:35]
	v_mfma_f32_16x16x32_bf16 v[20:23], v[198:201], v[230:233], v[20:23]
	v_mfma_f32_16x16x32_bf16 v[16:19], v[206:209], v[230:233], v[16:19]
	v_mfma_f32_16x16x32_bf16 v[4:7], v[198:201], v[238:241], v[4:7]
	v_mfma_f32_16x16x32_bf16 v[0:3], v[206:209], v[238:241], v[0:3]
	v_mfma_f32_16x16x32_bf16 v[52:55], v[202:205], v[218:221], v[52:55]
	v_mfma_f32_16x16x32_bf16 v[48:51], v[210:213], v[218:221], v[48:51]
	v_mfma_f32_16x16x32_bf16 v[36:39], v[202:205], v[226:229], v[36:39]
	v_mfma_f32_16x16x32_bf16 v[32:35], v[210:213], v[226:229], v[32:35]
	v_mfma_f32_16x16x32_bf16 v[20:23], v[202:205], v[234:237], v[20:23]
	v_mfma_f32_16x16x32_bf16 v[16:19], v[210:213], v[234:237], v[16:19]
	v_mfma_f32_16x16x32_bf16 v[4:7], v[202:205], v[242:245], v[4:7]
	v_mfma_f32_16x16x32_bf16 v[0:3], v[210:213], v[242:245], v[0:3]
	s_add_i32 s66, s66, 2
	s_add_u32 s16, s16, 0x100
	s_addc_u32 s17, s17, 0
	s_add_u32 s47, s47, 0x100
	s_addc_u32 s49, s49, 0
	s_cmp_gt_u32 s66, 13
	s_barrier
	s_cbranch_scc0 .LBB0_2152
	s_and_b64 vcc, exec, s[44:45]
	s_cbranch_vccz .LBB0_2155
	s_barrier

.LBB0_2530:
	ds_read_b128 v[140:143], v162
	ds_read_b128 v[178:181], v163
	ds_read_b128 v[182:185], v164
	ds_read_b128 v[186:189], v165
	ds_read_b128 v[190:193], v166
	ds_read_b128 v[198:201], v167
	ds_read_b128 v[202:205], v168
	ds_read_b128 v[206:209], v169
	s_add_u32 s16, s0, 0xfffe0080
	s_addc_u32 s17, s1, -1
	s_cmp_eq_u32 s64, 4
	s_cselect_b32 s19, s4, s17
	s_cselect_b32 s18, s5, s16
	s_cselect_b32 s17, s13, s51
	s_cselect_b32 s16, s15, s49
	s_mov_b32 m0, s77
	ds_read_b128 v[210:213], v160
	ds_read_b128 v[214:217], v160 offset:1024
	ds_read_b128 v[218:221], v160 offset:2048
	ds_read_b128 v[222:225], v160 offset:3072
	ds_read_b128 v[226:229], v160 offset:4096
	ds_read_b128 v[230:233], v160 offset:5120
	ds_read_b128 v[234:237], v160 offset:6144
	ds_read_b128 v[238:241], v160 offset:7168
	global_load_lds_dwordx4 v132, s[0:1]
	s_mov_b32 m0, s78
	s_nop 0
	global_load_lds_dwordx4 v134, s[0:1]
	s_waitcnt vmcnt(8)
	s_waitcnt lgkmcnt(0)
	s_barrier
	v_mfma_f32_16x16x32_bf16 v[124:127], v[140:143], v[210:213], v[124:127]
	v_mfma_f32_16x16x32_bf16 v[120:123], v[182:185], v[210:213], v[120:123]
	v_mfma_f32_16x16x32_bf16 v[108:111], v[140:143], v[218:221], v[108:111]
	v_mfma_f32_16x16x32_bf16 v[104:107], v[182:185], v[218:221], v[104:107]
	v_mfma_f32_16x16x32_bf16 v[92:95], v[140:143], v[226:229], v[92:95]
	v_mfma_f32_16x16x32_bf16 v[88:91], v[182:185], v[226:229], v[88:91]
	v_mfma_f32_16x16x32_bf16 v[76:79], v[140:143], v[234:237], v[76:79]
	v_mfma_f32_16x16x32_bf16 v[72:75], v[182:185], v[234:237], v[72:75]
	v_mfma_f32_16x16x32_bf16 v[124:127], v[178:181], v[214:217], v[124:127]
	v_mfma_f32_16x16x32_bf16 v[120:123], v[186:189], v[214:217], v[120:123]
	v_mfma_f32_16x16x32_bf16 v[108:111], v[178:181], v[222:225], v[108:111]
	v_mfma_f32_16x16x32_bf16 v[104:107], v[186:189], v[222:225], v[104:107]
	v_mfma_f32_16x16x32_bf16 v[92:95], v[178:181], v[230:233], v[92:95]
	v_mfma_f32_16x16x32_bf16 v[88:91], v[186:189], v[230:233], v[88:91]
	v_mfma_f32_16x16x32_bf16 v[76:79], v[178:181], v[238:241], v[76:79]
	v_mfma_f32_16x16x32_bf16 v[72:75], v[186:189], v[238:241], v[72:75]
	v_mfma_f32_16x16x32_bf16 v[116:119], v[190:193], v[210:213], v[116:119]
	v_mfma_f32_16x16x32_bf16 v[112:115], v[202:205], v[210:213], v[112:115]
	v_mfma_f32_16x16x32_bf16 v[100:103], v[190:193], v[218:221], v[100:103]
	v_mfma_f32_16x16x32_bf16 v[96:99], v[202:205], v[218:221], v[96:99]
	v_mfma_f32_16x16x32_bf16 v[84:87], v[190:193], v[226:229], v[84:87]
	v_mfma_f32_16x16x32_bf16 v[80:83], v[202:205], v[226:229], v[80:83]
	v_mfma_f32_16x16x32_bf16 v[68:71], v[190:193], v[234:237], v[68:71]
	v_mfma_f32_16x16x32_bf16 v[64:67], v[202:205], v[234:237], v[64:67]
	v_mfma_f32_16x16x32_bf16 v[116:119], v[198:201], v[214:217], v[116:119]
	v_mfma_f32_16x16x32_bf16 v[112:115], v[206:209], v[214:217], v[112:115]
	v_mfma_f32_16x16x32_bf16 v[100:103], v[198:201], v[222:225], v[100:103]
	v_mfma_f32_16x16x32_bf16 v[96:99], v[206:209], v[222:225], v[96:99]
	v_mfma_f32_16x16x32_bf16 v[84:87], v[198:201], v[230:233], v[84:87]
	v_mfma_f32_16x16x32_bf16 v[80:83], v[206:209], v[230:233], v[80:83]
	v_mfma_f32_16x16x32_bf16 v[68:71], v[198:201], v[238:241], v[68:71]
	v_mfma_f32_16x16x32_bf16 v[64:67], v[206:209], v[238:241], v[64:67]
	s_add_u32 s98, s16, s44
	s_addc_u32 s99, s17, s45
	s_add_u32 s100, s18, s44
	s_addc_u32 s101, s19, s45
	s_barrier
	s_mov_b32 m0, s6
	s_add_u32 s68, s16, 0x20000
	ds_read_b128 v[210:213], v160 offset:16384
	ds_read_b128 v[214:217], v160 offset:17408
	ds_read_b128 v[218:221], v160 offset:18432
	ds_read_b128 v[222:225], v160 offset:19456
	ds_read_b128 v[226:229], v160 offset:20480
	ds_read_b128 v[230:233], v160 offset:21504
	ds_read_b128 v[234:237], v160 offset:22528
	ds_read_b128 v[238:241], v160 offset:23552
	global_load_lds_dwordx4 v128, s[16:17]
	s_mov_b32 m0, s7
	s_addc_u32 s69, s17, 0
	global_load_lds_dwordx4 v130, s[16:17]
	s_mov_b32 m0, s8
	s_nop 0
	global_load_lds_dwordx4 v128, s[68:69]
	s_mov_b32 m0, s9
	s_nop 0
	global_load_lds_dwordx4 v130, s[68:69]
	s_mov_b32 m0, s2
	s_nop 0
	global_load_lds_dwordx4 v128, s[18:19]
	s_mov_b32 m0, s28
	s_nop 0
	global_load_lds_dwordx4 v130, s[18:19]
	s_waitcnt vmcnt(8)
	s_waitcnt lgkmcnt(0)
	s_barrier
	v_mfma_f32_16x16x32_bf16 v[60:63], v[140:143], v[210:213], v[60:63]
	v_mfma_f32_16x16x32_bf16 v[56:59], v[182:185], v[210:213], v[56:59]
	v_mfma_f32_16x16x32_bf16 v[44:47], v[140:143], v[218:221], v[44:47]
	v_mfma_f32_16x16x32_bf16 v[40:43], v[182:185], v[218:221], v[40:43]
	v_mfma_f32_16x16x32_bf16 v[28:31], v[140:143], v[226:229], v[28:31]
	v_mfma_f32_16x16x32_bf16 v[24:27], v[182:185], v[226:229], v[24:27]
	v_mfma_f32_16x16x32_bf16 v[12:15], v[140:143], v[234:237], v[12:15]
	v_mfma_f32_16x16x32_bf16 v[8:11], v[182:185], v[234:237], v[8:11]
	v_mfma_f32_16x16x32_bf16 v[60:63], v[178:181], v[214:217], v[60:63]
	v_mfma_f32_16x16x32_bf16 v[56:59], v[186:189], v[214:217], v[56:59]
	v_mfma_f32_16x16x32_bf16 v[44:47], v[178:181], v[222:225], v[44:47]
	v_mfma_f32_16x16x32_bf16 v[40:43], v[186:189], v[222:225], v[40:43]
	v_mfma_f32_16x16x32_bf16 v[28:31], v[178:181], v[230:233], v[28:31]
	v_mfma_f32_16x16x32_bf16 v[24:27], v[186:189], v[230:233], v[24:27]
	v_mfma_f32_16x16x32_bf16 v[12:15], v[178:181], v[238:241], v[12:15]
	v_mfma_f32_16x16x32_bf16 v[8:11], v[186:189], v[238:241], v[8:11]
	v_mfma_f32_16x16x32_bf16 v[52:55], v[190:193], v[210:213], v[52:55]
	v_mfma_f32_16x16x32_bf16 v[48:51], v[202:205], v[210:213], v[48:51]
	v_mfma_f32_16x16x32_bf16 v[36:39], v[190:193], v[218:221], v[36:39]
	v_mfma_f32_16x16x32_bf16 v[32:35], v[202:205], v[218:221], v[32:35]
	v_mfma_f32_16x16x32_bf16 v[20:23], v[190:193], v[226:229], v[20:23]
	v_mfma_f32_16x16x32_bf16 v[16:19], v[202:205], v[226:229], v[16:19]
	v_mfma_f32_16x16x32_bf16 v[4:7], v[190:193], v[234:237], v[4:7]
	v_mfma_f32_16x16x32_bf16 v[0:3], v[202:205], v[234:237], v[0:3]
	v_mfma_f32_16x16x32_bf16 v[52:55], v[198:201], v[214:217], v[52:55]
	v_mfma_f32_16x16x32_bf16 v[48:51], v[206:209], v[214:217], v[48:51]
	v_mfma_f32_16x16x32_bf16 v[36:39], v[198:201], v[222:225], v[36:39]
	v_mfma_f32_16x16x32_bf16 v[32:35], v[206:209], v[222:225], v[32:35]
	v_mfma_f32_16x16x32_bf16 v[20:23], v[198:201], v[230:233], v[20:23]
	v_mfma_f32_16x16x32_bf16 v[16:19], v[206:209], v[230:233], v[16:19]
	v_mfma_f32_16x16x32_bf16 v[4:7], v[198:201], v[238:241], v[4:7]
	v_mfma_f32_16x16x32_bf16 v[0:3], v[206:209], v[238:241], v[0:3]
	s_barrier
	ds_read_b128 v[140:143], v170
	ds_read_b128 v[178:181], v171
	ds_read_b128 v[182:185], v172
	ds_read_b128 v[186:189], v173
	ds_read_b128 v[190:193], v174
	ds_read_b128 v[198:201], v175
	ds_read_b128 v[202:205], v176
	ds_read_b128 v[206:209], v177
	s_add_u32 s18, s18, 0x20000
	s_addc_u32 s19, s19, 0
	s_mov_b32 m0, s29
	ds_read_b128 v[210:213], v160 offset:32768
	ds_read_b128 v[214:217], v160 offset:33792
	ds_read_b128 v[218:221], v160 offset:34816
	ds_read_b128 v[222:225], v160 offset:35840
	ds_read_b128 v[226:229], v160 offset:36864
	ds_read_b128 v[230:233], v160 offset:37888
	ds_read_b128 v[234:237], v160 offset:38912
	ds_read_b128 v[238:241], v160 offset:39936
	global_load_lds_dwordx4 v128, s[18:19]
	s_mov_b32 m0, s30
	s_nop 0
	global_load_lds_dwordx4 v130, s[18:19]
	s_waitcnt vmcnt(8)
	s_waitcnt lgkmcnt(0)
	s_barrier
	v_mfma_f32_16x16x32_bf16 v[124:127], v[140:143], v[210:213], v[124:127]
	v_mfma_f32_16x16x32_bf16 v[120:123], v[182:185], v[210:213], v[120:123]
	v_mfma_f32_16x16x32_bf16 v[108:111], v[140:143], v[218:221], v[108:111]
	v_mfma_f32_16x16x32_bf16 v[104:107], v[182:185], v[218:221], v[104:107]
	v_mfma_f32_16x16x32_bf16 v[92:95], v[140:143], v[226:229], v[92:95]
	v_mfma_f32_16x16x32_bf16 v[88:91], v[182:185], v[226:229], v[88:91]
	v_mfma_f32_16x16x32_bf16 v[76:79], v[140:143], v[234:237], v[76:79]
	v_mfma_f32_16x16x32_bf16 v[72:75], v[182:185], v[234:237], v[72:75]
	v_mfma_f32_16x16x32_bf16 v[124:127], v[178:181], v[214:217], v[124:127]
	v_mfma_f32_16x16x32_bf16 v[120:123], v[186:189], v[214:217], v[120:123]
	v_mfma_f32_16x16x32_bf16 v[108:111], v[178:181], v[222:225], v[108:111]
	v_mfma_f32_16x16x32_bf16 v[104:107], v[186:189], v[222:225], v[104:107]
	v_mfma_f32_16x16x32_bf16 v[92:95], v[178:181], v[230:233], v[92:95]
	v_mfma_f32_16x16x32_bf16 v[88:91], v[186:189], v[230:233], v[88:91]
	v_mfma_f32_16x16x32_bf16 v[76:79], v[178:181], v[238:241], v[76:79]
	v_mfma_f32_16x16x32_bf16 v[72:75], v[186:189], v[238:241], v[72:75]
	v_mfma_f32_16x16x32_bf16 v[116:119], v[190:193], v[210:213], v[116:119]
	v_mfma_f32_16x16x32_bf16 v[112:115], v[202:205], v[210:213], v[112:115]
	v_mfma_f32_16x16x32_bf16 v[100:103], v[190:193], v[218:221], v[100:103]
	v_mfma_f32_16x16x32_bf16 v[96:99], v[202:205], v[218:221], v[96:99]
	v_mfma_f32_16x16x32_bf16 v[84:87], v[190:193], v[226:229], v[84:87]
	v_mfma_f32_16x16x32_bf16 v[80:83], v[202:205], v[226:229], v[80:83]
	v_mfma_f32_16x16x32_bf16 v[68:71], v[190:193], v[234:237], v[68:71]
	v_mfma_f32_16x16x32_bf16 v[64:67], v[202:205], v[234:237], v[64:67]
	v_mfma_f32_16x16x32_bf16 v[116:119], v[198:201], v[214:217], v[116:119]
	v_mfma_f32_16x16x32_bf16 v[112:115], v[206:209], v[214:217], v[112:115]
	v_mfma_f32_16x16x32_bf16 v[100:103], v[198:201], v[222:225], v[100:103]
	v_mfma_f32_16x16x32_bf16 v[96:99], v[206:209], v[222:225], v[96:99]
	v_mfma_f32_16x16x32_bf16 v[84:87], v[198:201], v[230:233], v[84:87]
	v_mfma_f32_16x16x32_bf16 v[80:83], v[206:209], v[230:233], v[80:83]
	v_mfma_f32_16x16x32_bf16 v[68:71], v[198:201], v[238:241], v[68:71]
	v_mfma_f32_16x16x32_bf16 v[64:67], v[206:209], v[238:241], v[64:67]
	s_barrier
	s_mov_b32 m0, s31
	s_add_u32 s16, s16, 0x20080
	ds_read_b128 v[210:213], v160 offset:49152
	ds_read_b128 v[214:217], v160 offset:50176
	ds_read_b128 v[218:221], v160 offset:51200
	ds_read_b128 v[222:225], v160 offset:52224
	ds_read_b128 v[226:229], v160 offset:53248
	ds_read_b128 v[230:233], v160 offset:54272
	ds_read_b128 v[234:237], v160 offset:55296
	ds_read_b128 v[238:241], v160 offset:56320
	global_load_lds_dwordx4 v128, s[98:99]
	s_mov_b32 m0, s33
	s_addc_u32 s17, s17, 0
	global_load_lds_dwordx4 v130, s[98:99]
	s_mov_b32 m0, s36
	s_nop 0
	global_load_lds_dwordx4 v128, s[16:17]
	s_mov_b32 m0, s37
	s_nop 0
	global_load_lds_dwordx4 v130, s[16:17]
	s_mov_b32 m0, s34
	s_nop 0
	global_load_lds_dwordx4 v128, s[100:101]
	s_mov_b32 m0, s35
	s_nop 0
	global_load_lds_dwordx4 v130, s[100:101]
	s_waitcnt vmcnt(8)
	s_waitcnt lgkmcnt(0)
	s_barrier
	v_mfma_f32_16x16x32_bf16 v[60:63], v[140:143], v[210:213], v[60:63]
	v_mfma_f32_16x16x32_bf16 v[56:59], v[182:185], v[210:213], v[56:59]
	v_mfma_f32_16x16x32_bf16 v[44:47], v[140:143], v[218:221], v[44:47]
	v_mfma_f32_16x16x32_bf16 v[40:43], v[182:185], v[218:221], v[40:43]
	v_mfma_f32_16x16x32_bf16 v[28:31], v[140:143], v[226:229], v[28:31]
	v_mfma_f32_16x16x32_bf16 v[24:27], v[182:185], v[226:229], v[24:27]
	v_mfma_f32_16x16x32_bf16 v[12:15], v[140:143], v[234:237], v[12:15]
	v_mfma_f32_16x16x32_bf16 v[8:11], v[182:185], v[234:237], v[8:11]
	v_mfma_f32_16x16x32_bf16 v[60:63], v[178:181], v[214:217], v[60:63]
	v_mfma_f32_16x16x32_bf16 v[56:59], v[186:189], v[214:217], v[56:59]
	v_mfma_f32_16x16x32_bf16 v[44:47], v[178:181], v[222:225], v[44:47]
	v_mfma_f32_16x16x32_bf16 v[40:43], v[186:189], v[222:225], v[40:43]
	v_mfma_f32_16x16x32_bf16 v[28:31], v[178:181], v[230:233], v[28:31]
	v_mfma_f32_16x16x32_bf16 v[24:27], v[186:189], v[230:233], v[24:27]
	v_mfma_f32_16x16x32_bf16 v[12:15], v[178:181], v[238:241], v[12:15]
	v_mfma_f32_16x16x32_bf16 v[8:11], v[186:189], v[238:241], v[8:11]
	v_mfma_f32_16x16x32_bf16 v[52:55], v[190:193], v[210:213], v[52:55]
	v_mfma_f32_16x16x32_bf16 v[48:51], v[202:205], v[210:213], v[48:51]
	v_mfma_f32_16x16x32_bf16 v[36:39], v[190:193], v[218:221], v[36:39]
	v_mfma_f32_16x16x32_bf16 v[32:35], v[202:205], v[218:221], v[32:35]
	v_mfma_f32_16x16x32_bf16 v[20:23], v[190:193], v[226:229], v[20:23]
	v_mfma_f32_16x16x32_bf16 v[16:19], v[202:205], v[226:229], v[16:19]
	v_mfma_f32_16x16x32_bf16 v[4:7], v[190:193], v[234:237], v[4:7]
	v_mfma_f32_16x16x32_bf16 v[0:3], v[202:205], v[234:237], v[0:3]
	v_mfma_f32_16x16x32_bf16 v[52:55], v[198:201], v[214:217], v[52:55]
	v_mfma_f32_16x16x32_bf16 v[48:51], v[206:209], v[214:217], v[48:51]
	v_mfma_f32_16x16x32_bf16 v[36:39], v[198:201], v[222:225], v[36:39]
	v_mfma_f32_16x16x32_bf16 v[32:35], v[206:209], v[222:225], v[32:35]
	v_mfma_f32_16x16x32_bf16 v[20:23], v[198:201], v[230:233], v[20:23]
	v_mfma_f32_16x16x32_bf16 v[16:19], v[206:209], v[230:233], v[16:19]
	v_mfma_f32_16x16x32_bf16 v[4:7], v[198:201], v[238:241], v[4:7]
	v_mfma_f32_16x16x32_bf16 v[0:3], v[206:209], v[238:241], v[0:3]
	s_add_i32 s64, s64, 2
	s_add_u32 s0, s0, 0x100
	s_addc_u32 s1, s1, 0
	s_add_u32 s49, s49, 0x100
	s_addc_u32 s51, s51, 0
	s_cmp_gt_u32 s64, 5
	s_barrier
	s_cbranch_scc0 .LBB0_2530
	s_and_b64 vcc, exec, s[46:47]
	s_cbranch_vccz .LBB0_2533
	s_barrier

.LBB0_2628:
	s_add_u32 s65, s48, s64
	s_addc_u32 s70, s49, 0
	s_add_u32 s71, s65, 0x100
	s_addc_u32 s74, s70, 0
	s_and_b64 s[68:69], s[54:55], exec
	s_cselect_b32 s75, s4, s74
	s_cselect_b32 s74, s5, s71
	s_add_u32 s64, s46, s64
	s_addc_u32 s68, s47, 0
	s_add_u32 s64, s64, 0x100
	ds_read_b128 v[170:173], v141
	ds_read_b128 v[174:177], v142
	ds_read_b128 v[178:181], v143
	ds_read_b128 v[182:185], v153
	ds_read_b128 v[186:189], v158
	ds_read_b128 v[190:193], v159
	ds_read_b128 v[196:199], v160
	ds_read_b128 v[200:203], v161
	s_addc_u32 s68, s68, 0
	s_and_b64 s[54:55], s[54:55], exec
	s_cselect_b32 s79, s21, s68
	s_cselect_b32 s78, s23, s64
	s_add_u32 s82, s65, 0x10080
	s_addc_u32 s83, s70, 0
	s_add_u32 s80, s78, 0x10000
	s_addc_u32 s81, s79, 0
	s_add_u32 s64, s74, 0x10000
	s_addc_u32 s65, s75, 0
	s_add_u32 s54, s78, 0x10080
	s_addc_u32 s55, s79, 0
	s_mov_b32 m0, s35
	ds_read_b128 v[204:207], v139
	ds_read_b128 v[208:211], v139 offset:1024
	ds_read_b128 v[212:215], v139 offset:2048
	ds_read_b128 v[216:219], v139 offset:3072
	ds_read_b128 v[220:223], v139 offset:4096
	ds_read_b128 v[224:227], v139 offset:5120
	ds_read_b128 v[228:231], v139 offset:6144
	ds_read_b128 v[232:235], v139 offset:7168
	global_load_lds_dwordx4 v128, s[82:83]
	s_mov_b32 m0, s60
	s_nop 0
	global_load_lds_dwordx4 v130, s[82:83]
	s_waitcnt vmcnt(8)
	s_waitcnt lgkmcnt(0)
	s_barrier
	v_mfma_f32_16x16x32_bf16 v[124:127], v[170:173], v[204:207], v[124:127]
	v_mfma_f32_16x16x32_bf16 v[120:123], v[178:181], v[204:207], v[120:123]
	v_mfma_f32_16x16x32_bf16 v[108:111], v[170:173], v[212:215], v[108:111]
	v_mfma_f32_16x16x32_bf16 v[104:107], v[178:181], v[212:215], v[104:107]
	v_mfma_f32_16x16x32_bf16 v[92:95], v[170:173], v[220:223], v[92:95]
	v_mfma_f32_16x16x32_bf16 v[88:91], v[178:181], v[220:223], v[88:91]
	v_mfma_f32_16x16x32_bf16 v[76:79], v[170:173], v[228:231], v[76:79]
	v_mfma_f32_16x16x32_bf16 v[72:75], v[178:181], v[228:231], v[72:75]
	v_mfma_f32_16x16x32_bf16 v[124:127], v[174:177], v[208:211], v[124:127]
	v_mfma_f32_16x16x32_bf16 v[120:123], v[182:185], v[208:211], v[120:123]
	v_mfma_f32_16x16x32_bf16 v[108:111], v[174:177], v[216:219], v[108:111]
	v_mfma_f32_16x16x32_bf16 v[104:107], v[182:185], v[216:219], v[104:107]
	v_mfma_f32_16x16x32_bf16 v[92:95], v[174:177], v[224:227], v[92:95]
	v_mfma_f32_16x16x32_bf16 v[88:91], v[182:185], v[224:227], v[88:91]
	v_mfma_f32_16x16x32_bf16 v[76:79], v[174:177], v[232:235], v[76:79]
	v_mfma_f32_16x16x32_bf16 v[72:75], v[182:185], v[232:235], v[72:75]
	v_mfma_f32_16x16x32_bf16 v[116:119], v[186:189], v[204:207], v[116:119]
	v_mfma_f32_16x16x32_bf16 v[112:115], v[196:199], v[204:207], v[112:115]
	v_mfma_f32_16x16x32_bf16 v[100:103], v[186:189], v[212:215], v[100:103]
	v_mfma_f32_16x16x32_bf16 v[96:99], v[196:199], v[212:215], v[96:99]
	v_mfma_f32_16x16x32_bf16 v[84:87], v[186:189], v[220:223], v[84:87]
	v_mfma_f32_16x16x32_bf16 v[80:83], v[196:199], v[220:223], v[80:83]
	v_mfma_f32_16x16x32_bf16 v[68:71], v[186:189], v[228:231], v[68:71]
	v_mfma_f32_16x16x32_bf16 v[64:67], v[196:199], v[228:231], v[64:67]
	v_mfma_f32_16x16x32_bf16 v[116:119], v[190:193], v[208:211], v[116:119]
	v_mfma_f32_16x16x32_bf16 v[112:115], v[200:203], v[208:211], v[112:115]
	v_mfma_f32_16x16x32_bf16 v[100:103], v[190:193], v[216:219], v[100:103]
	v_mfma_f32_16x16x32_bf16 v[96:99], v[200:203], v[216:219], v[96:99]
	v_mfma_f32_16x16x32_bf16 v[84:87], v[190:193], v[224:227], v[84:87]
	v_mfma_f32_16x16x32_bf16 v[80:83], v[200:203], v[224:227], v[80:83]
	v_mfma_f32_16x16x32_bf16 v[68:71], v[190:193], v[232:235], v[68:71]
	v_mfma_f32_16x16x32_bf16 v[64:67], v[200:203], v[232:235], v[64:67]
	s_add_u32 s98, s78, s16
	s_addc_u32 s99, s79, s17
	s_add_u32 s100, s74, s16
	s_addc_u32 s101, s75, s17
	s_barrier
	s_mov_b32 m0, s45
	ds_read_b128 v[204:207], v139 offset:16384
	ds_read_b128 v[208:211], v139 offset:17408
	ds_read_b128 v[212:215], v139 offset:18432
	ds_read_b128 v[216:219], v139 offset:19456
	ds_read_b128 v[220:223], v139 offset:20480
	ds_read_b128 v[224:227], v139 offset:21504
	ds_read_b128 v[228:231], v139 offset:22528
	ds_read_b128 v[232:235], v139 offset:23552
	global_load_lds_dwordx4 v128, s[78:79]
	s_mov_b32 m0, s67
	s_nop 0
	global_load_lds_dwordx4 v130, s[78:79]
	s_mov_b32 m0, s84
	s_nop 0
	global_load_lds_dwordx4 v128, s[80:81]
	s_mov_b32 m0, s85
	s_nop 0
	global_load_lds_dwordx4 v130, s[80:81]
	s_mov_b32 m0, s30
	s_nop 0
	global_load_lds_dwordx4 v128, s[74:75]
	s_mov_b32 m0, s86
	s_nop 0
	global_load_lds_dwordx4 v130, s[74:75]
	s_waitcnt vmcnt(8)
	s_waitcnt lgkmcnt(0)
	s_barrier
	v_mfma_f32_16x16x32_bf16 v[60:63], v[170:173], v[204:207], v[60:63]
	v_mfma_f32_16x16x32_bf16 v[56:59], v[178:181], v[204:207], v[56:59]
	v_mfma_f32_16x16x32_bf16 v[44:47], v[170:173], v[212:215], v[44:47]
	v_mfma_f32_16x16x32_bf16 v[40:43], v[178:181], v[212:215], v[40:43]
	v_mfma_f32_16x16x32_bf16 v[28:31], v[170:173], v[220:223], v[28:31]
	v_mfma_f32_16x16x32_bf16 v[24:27], v[178:181], v[220:223], v[24:27]
	v_mfma_f32_16x16x32_bf16 v[12:15], v[170:173], v[228:231], v[12:15]
	v_mfma_f32_16x16x32_bf16 v[8:11], v[178:181], v[228:231], v[8:11]
	v_mfma_f32_16x16x32_bf16 v[60:63], v[174:177], v[208:211], v[60:63]
	v_mfma_f32_16x16x32_bf16 v[56:59], v[182:185], v[208:211], v[56:59]
	v_mfma_f32_16x16x32_bf16 v[44:47], v[174:177], v[216:219], v[44:47]
	v_mfma_f32_16x16x32_bf16 v[40:43], v[182:185], v[216:219], v[40:43]
	v_mfma_f32_16x16x32_bf16 v[28:31], v[174:177], v[224:227], v[28:31]
	v_mfma_f32_16x16x32_bf16 v[24:27], v[182:185], v[224:227], v[24:27]
	v_mfma_f32_16x16x32_bf16 v[12:15], v[174:177], v[232:235], v[12:15]
	v_mfma_f32_16x16x32_bf16 v[8:11], v[182:185], v[232:235], v[8:11]
	v_mfma_f32_16x16x32_bf16 v[52:55], v[186:189], v[204:207], v[52:55]
	v_mfma_f32_16x16x32_bf16 v[48:51], v[196:199], v[204:207], v[48:51]
	v_mfma_f32_16x16x32_bf16 v[36:39], v[186:189], v[212:215], v[36:39]
	v_mfma_f32_16x16x32_bf16 v[32:35], v[196:199], v[212:215], v[32:35]
	v_mfma_f32_16x16x32_bf16 v[20:23], v[186:189], v[220:223], v[20:23]
	v_mfma_f32_16x16x32_bf16 v[16:19], v[196:199], v[220:223], v[16:19]
	v_mfma_f32_16x16x32_bf16 v[4:7], v[186:189], v[228:231], v[4:7]
	v_mfma_f32_16x16x32_bf16 v[0:3], v[196:199], v[228:231], v[0:3]
	v_mfma_f32_16x16x32_bf16 v[52:55], v[190:193], v[208:211], v[52:55]
	v_mfma_f32_16x16x32_bf16 v[48:51], v[200:203], v[208:211], v[48:51]
	v_mfma_f32_16x16x32_bf16 v[36:39], v[190:193], v[216:219], v[36:39]
	v_mfma_f32_16x16x32_bf16 v[32:35], v[200:203], v[216:219], v[32:35]
	v_mfma_f32_16x16x32_bf16 v[20:23], v[190:193], v[224:227], v[20:23]
	v_mfma_f32_16x16x32_bf16 v[16:19], v[200:203], v[224:227], v[16:19]
	v_mfma_f32_16x16x32_bf16 v[4:7], v[190:193], v[232:235], v[4:7]
	v_mfma_f32_16x16x32_bf16 v[0:3], v[200:203], v[232:235], v[0:3]
	s_barrier
	ds_read_b128 v[170:173], v162
	ds_read_b128 v[174:177], v163
	ds_read_b128 v[178:181], v164
	ds_read_b128 v[182:185], v165
	ds_read_b128 v[186:189], v166
	ds_read_b128 v[190:193], v167
	ds_read_b128 v[196:199], v168
	ds_read_b128 v[200:203], v169
	s_mov_b32 m0, s87
	ds_read_b128 v[204:207], v139 offset:32768
	ds_read_b128 v[208:211], v139 offset:33792
	ds_read_b128 v[212:215], v139 offset:34816
	ds_read_b128 v[216:219], v139 offset:35840
	ds_read_b128 v[220:223], v139 offset:36864
	ds_read_b128 v[224:227], v139 offset:37888
	ds_read_b128 v[228:231], v139 offset:38912
	ds_read_b128 v[232:235], v139 offset:39936
	global_load_lds_dwordx4 v128, s[64:65]
	s_mov_b32 m0, s90
	s_nop 0
	global_load_lds_dwordx4 v130, s[64:65]
	s_waitcnt vmcnt(8)
	s_waitcnt lgkmcnt(0)
	s_barrier
	v_mfma_f32_16x16x32_bf16 v[124:127], v[170:173], v[204:207], v[124:127]
	v_mfma_f32_16x16x32_bf16 v[120:123], v[178:181], v[204:207], v[120:123]
	v_mfma_f32_16x16x32_bf16 v[108:111], v[170:173], v[212:215], v[108:111]
	v_mfma_f32_16x16x32_bf16 v[104:107], v[178:181], v[212:215], v[104:107]
	v_mfma_f32_16x16x32_bf16 v[92:95], v[170:173], v[220:223], v[92:95]
	v_mfma_f32_16x16x32_bf16 v[88:91], v[178:181], v[220:223], v[88:91]
	v_mfma_f32_16x16x32_bf16 v[76:79], v[170:173], v[228:231], v[76:79]
	v_mfma_f32_16x16x32_bf16 v[72:75], v[178:181], v[228:231], v[72:75]
	v_mfma_f32_16x16x32_bf16 v[124:127], v[174:177], v[208:211], v[124:127]
	v_mfma_f32_16x16x32_bf16 v[120:123], v[182:185], v[208:211], v[120:123]
	v_mfma_f32_16x16x32_bf16 v[108:111], v[174:177], v[216:219], v[108:111]
	v_mfma_f32_16x16x32_bf16 v[104:107], v[182:185], v[216:219], v[104:107]
	v_mfma_f32_16x16x32_bf16 v[92:95], v[174:177], v[224:227], v[92:95]
	v_mfma_f32_16x16x32_bf16 v[88:91], v[182:185], v[224:227], v[88:91]
	v_mfma_f32_16x16x32_bf16 v[76:79], v[174:177], v[232:235], v[76:79]
	v_mfma_f32_16x16x32_bf16 v[72:75], v[182:185], v[232:235], v[72:75]
	v_mfma_f32_16x16x32_bf16 v[116:119], v[186:189], v[204:207], v[116:119]
	v_mfma_f32_16x16x32_bf16 v[112:115], v[196:199], v[204:207], v[112:115]
	v_mfma_f32_16x16x32_bf16 v[100:103], v[186:189], v[212:215], v[100:103]
	v_mfma_f32_16x16x32_bf16 v[96:99], v[196:199], v[212:215], v[96:99]
	v_mfma_f32_16x16x32_bf16 v[84:87], v[186:189], v[220:223], v[84:87]
	v_mfma_f32_16x16x32_bf16 v[80:83], v[196:199], v[220:223], v[80:83]
	v_mfma_f32_16x16x32_bf16 v[68:71], v[186:189], v[228:231], v[68:71]
	v_mfma_f32_16x16x32_bf16 v[64:67], v[196:199], v[228:231], v[64:67]
	v_mfma_f32_16x16x32_bf16 v[116:119], v[190:193], v[208:211], v[116:119]
	v_mfma_f32_16x16x32_bf16 v[112:115], v[200:203], v[208:211], v[112:115]
	v_mfma_f32_16x16x32_bf16 v[100:103], v[190:193], v[216:219], v[100:103]
	v_mfma_f32_16x16x32_bf16 v[96:99], v[200:203], v[216:219], v[96:99]
	v_mfma_f32_16x16x32_bf16 v[84:87], v[190:193], v[224:227], v[84:87]
	v_mfma_f32_16x16x32_bf16 v[80:83], v[200:203], v[224:227], v[80:83]
	v_mfma_f32_16x16x32_bf16 v[68:71], v[190:193], v[232:235], v[68:71]
	v_mfma_f32_16x16x32_bf16 v[64:67], v[200:203], v[232:235], v[64:67]
	s_barrier
	s_mov_b32 m0, s33
	ds_read_b128 v[204:207], v139 offset:49152
	ds_read_b128 v[208:211], v139 offset:50176
	ds_read_b128 v[212:215], v139 offset:51200
	ds_read_b128 v[216:219], v139 offset:52224
	ds_read_b128 v[220:223], v139 offset:53248
	ds_read_b128 v[224:227], v139 offset:54272
	ds_read_b128 v[228:231], v139 offset:55296
	ds_read_b128 v[232:235], v139 offset:56320
	global_load_lds_dwordx4 v128, s[98:99]
	s_mov_b32 m0, s9
	s_nop 0
	global_load_lds_dwordx4 v130, s[98:99]
	s_mov_b32 m0, s52
	s_nop 0
	global_load_lds_dwordx4 v128, s[54:55]
	s_mov_b32 m0, s61
	s_nop 0
	global_load_lds_dwordx4 v130, s[54:55]
	s_mov_b32 m0, s8
	s_nop 0
	global_load_lds_dwordx4 v128, s[100:101]
	s_mov_b32 m0, s53
	s_nop 0
	global_load_lds_dwordx4 v130, s[100:101]
	s_waitcnt vmcnt(8)
	s_waitcnt lgkmcnt(0)
	s_barrier
	v_mfma_f32_16x16x32_bf16 v[60:63], v[170:173], v[204:207], v[60:63]
	v_mfma_f32_16x16x32_bf16 v[56:59], v[178:181], v[204:207], v[56:59]
	v_mfma_f32_16x16x32_bf16 v[44:47], v[170:173], v[212:215], v[44:47]
	v_mfma_f32_16x16x32_bf16 v[40:43], v[178:181], v[212:215], v[40:43]
	v_mfma_f32_16x16x32_bf16 v[28:31], v[170:173], v[220:223], v[28:31]
	v_mfma_f32_16x16x32_bf16 v[24:27], v[178:181], v[220:223], v[24:27]
	v_mfma_f32_16x16x32_bf16 v[12:15], v[170:173], v[228:231], v[12:15]
	v_mfma_f32_16x16x32_bf16 v[8:11], v[178:181], v[228:231], v[8:11]
	v_mfma_f32_16x16x32_bf16 v[60:63], v[174:177], v[208:211], v[60:63]
	v_mfma_f32_16x16x32_bf16 v[56:59], v[182:185], v[208:211], v[56:59]
	v_mfma_f32_16x16x32_bf16 v[44:47], v[174:177], v[216:219], v[44:47]
	v_mfma_f32_16x16x32_bf16 v[40:43], v[182:185], v[216:219], v[40:43]
	v_mfma_f32_16x16x32_bf16 v[28:31], v[174:177], v[224:227], v[28:31]
	v_mfma_f32_16x16x32_bf16 v[24:27], v[182:185], v[224:227], v[24:27]
	v_mfma_f32_16x16x32_bf16 v[12:15], v[174:177], v[232:235], v[12:15]
	v_mfma_f32_16x16x32_bf16 v[8:11], v[182:185], v[232:235], v[8:11]
	v_mfma_f32_16x16x32_bf16 v[52:55], v[186:189], v[204:207], v[52:55]
	v_mfma_f32_16x16x32_bf16 v[48:51], v[196:199], v[204:207], v[48:51]
	v_mfma_f32_16x16x32_bf16 v[36:39], v[186:189], v[212:215], v[36:39]
	v_mfma_f32_16x16x32_bf16 v[32:35], v[196:199], v[212:215], v[32:35]
	v_mfma_f32_16x16x32_bf16 v[20:23], v[186:189], v[220:223], v[20:23]
	v_mfma_f32_16x16x32_bf16 v[16:19], v[196:199], v[220:223], v[16:19]
	v_mfma_f32_16x16x32_bf16 v[4:7], v[186:189], v[228:231], v[4:7]
	v_mfma_f32_16x16x32_bf16 v[0:3], v[196:199], v[228:231], v[0:3]
	v_mfma_f32_16x16x32_bf16 v[52:55], v[190:193], v[208:211], v[52:55]
	v_mfma_f32_16x16x32_bf16 v[48:51], v[200:203], v[208:211], v[48:51]
	v_mfma_f32_16x16x32_bf16 v[36:39], v[190:193], v[216:219], v[36:39]
	v_mfma_f32_16x16x32_bf16 v[32:35], v[200:203], v[216:219], v[32:35]
	v_mfma_f32_16x16x32_bf16 v[20:23], v[190:193], v[224:227], v[20:23]
	v_mfma_f32_16x16x32_bf16 v[16:19], v[200:203], v[224:227], v[16:19]
	v_mfma_f32_16x16x32_bf16 v[4:7], v[190:193], v[232:235], v[4:7]
	v_mfma_f32_16x16x32_bf16 v[0:3], v[200:203], v[232:235], v[0:3]
	s_barrier
	s_movk_i32 s64, 0x100
	s_andn2_b64 vcc, exec, s[50:51]
	s_mov_b64 s[54:55], -1
	s_mov_b64 s[50:51], 0
	s_cbranch_vccz .LBB0_2628
	s_and_b64 vcc, exec, s[18:19]
	s_cbranch_vccz .LBB0_2631
	s_barrier

.LBB0_2801:
	ds_read_b128 v[128:131], v195
	ds_read_b128 v[132:135], v196
	ds_read_b128 v[136:139], v197
	ds_read_b128 v[140:143], v198
	ds_read_b128 v[170:173], v199
	ds_read_b128 v[174:177], v200
	ds_read_b128 v[178:181], v201
	ds_read_b128 v[182:185], v202
	s_add_u32 s46, s44, 0x100
	s_addc_u32 s47, s45, 0
	s_cmp_eq_u32 s68, 12
	s_cselect_b32 s51, s4, s47
	s_cselect_b32 s50, s5, s46
	s_cselect_b32 s49, s25, s67
	s_cselect_b32 s48, s27, s66
	s_mov_b32 m0, s55
	ds_read_b128 v[186:189], v192
	ds_read_b128 v[212:215], v192 offset:1024
	ds_read_b128 v[216:219], v192 offset:2048
	ds_read_b128 v[220:223], v192 offset:3072
	ds_read_b128 v[224:227], v192 offset:4096
	ds_read_b128 v[228:231], v192 offset:5120
	ds_read_b128 v[232:235], v192 offset:6144
	ds_read_b128 v[236:239], v192 offset:7168
	global_load_lds_dwordx4 v162, s[44:45]
	s_mov_b32 m0, s60
	s_nop 0
	global_load_lds_dwordx4 v164, s[44:45]
	s_waitcnt vmcnt(8)
	s_waitcnt lgkmcnt(0)
	s_barrier
	v_mfma_f32_16x16x32_bf16 v[124:127], v[128:131], v[186:189], v[124:127]
	v_mfma_f32_16x16x32_bf16 v[120:123], v[136:139], v[186:189], v[120:123]
	v_mfma_f32_16x16x32_bf16 v[108:111], v[128:131], v[216:219], v[108:111]
	v_mfma_f32_16x16x32_bf16 v[104:107], v[136:139], v[216:219], v[104:107]
	v_mfma_f32_16x16x32_bf16 v[92:95], v[128:131], v[224:227], v[92:95]
	v_mfma_f32_16x16x32_bf16 v[88:91], v[136:139], v[224:227], v[88:91]
	v_mfma_f32_16x16x32_bf16 v[76:79], v[128:131], v[232:235], v[76:79]
	v_mfma_f32_16x16x32_bf16 v[72:75], v[136:139], v[232:235], v[72:75]
	v_mfma_f32_16x16x32_bf16 v[124:127], v[132:135], v[212:215], v[124:127]
	v_mfma_f32_16x16x32_bf16 v[120:123], v[140:143], v[212:215], v[120:123]
	v_mfma_f32_16x16x32_bf16 v[108:111], v[132:135], v[220:223], v[108:111]
	v_mfma_f32_16x16x32_bf16 v[104:107], v[140:143], v[220:223], v[104:107]
	v_mfma_f32_16x16x32_bf16 v[92:95], v[132:135], v[228:231], v[92:95]
	v_mfma_f32_16x16x32_bf16 v[88:91], v[140:143], v[228:231], v[88:91]
	v_mfma_f32_16x16x32_bf16 v[76:79], v[132:135], v[236:239], v[76:79]
	v_mfma_f32_16x16x32_bf16 v[72:75], v[140:143], v[236:239], v[72:75]
	v_mfma_f32_16x16x32_bf16 v[116:119], v[170:173], v[186:189], v[116:119]
	v_mfma_f32_16x16x32_bf16 v[112:115], v[178:181], v[186:189], v[112:115]
	v_mfma_f32_16x16x32_bf16 v[100:103], v[170:173], v[216:219], v[100:103]
	v_mfma_f32_16x16x32_bf16 v[96:99], v[178:181], v[216:219], v[96:99]
	v_mfma_f32_16x16x32_bf16 v[84:87], v[170:173], v[224:227], v[84:87]
	v_mfma_f32_16x16x32_bf16 v[80:83], v[178:181], v[224:227], v[80:83]
	v_mfma_f32_16x16x32_bf16 v[68:71], v[170:173], v[232:235], v[68:71]
	v_mfma_f32_16x16x32_bf16 v[64:67], v[178:181], v[232:235], v[64:67]
	v_mfma_f32_16x16x32_bf16 v[116:119], v[174:177], v[212:215], v[116:119]
	v_mfma_f32_16x16x32_bf16 v[112:115], v[182:185], v[212:215], v[112:115]
	v_mfma_f32_16x16x32_bf16 v[100:103], v[174:177], v[220:223], v[100:103]
	v_mfma_f32_16x16x32_bf16 v[96:99], v[182:185], v[220:223], v[96:99]
	v_mfma_f32_16x16x32_bf16 v[84:87], v[174:177], v[228:231], v[84:87]
	v_mfma_f32_16x16x32_bf16 v[80:83], v[182:185], v[228:231], v[80:83]
	v_mfma_f32_16x16x32_bf16 v[68:71], v[174:177], v[236:239], v[68:71]
	v_mfma_f32_16x16x32_bf16 v[64:67], v[182:185], v[236:239], v[64:67]
	s_add_u32 s98, s48, s18
	s_addc_u32 s99, s49, s19
	s_add_u32 s100, s50, s18
	s_addc_u32 s101, s51, s19
	s_barrier
	s_mov_b32 m0, s7
	s_add_u32 s44, s48, 0x40000
	ds_read_b128 v[186:189], v192 offset:16384
	ds_read_b128 v[212:215], v192 offset:17408
	ds_read_b128 v[216:219], v192 offset:18432
	ds_read_b128 v[220:223], v192 offset:19456
	ds_read_b128 v[224:227], v192 offset:20480
	ds_read_b128 v[228:231], v192 offset:21504
	ds_read_b128 v[232:235], v192 offset:22528
	ds_read_b128 v[236:239], v192 offset:23552
	global_load_lds_dwordx4 v158, s[48:49]
	s_mov_b32 m0, s8
	s_addc_u32 s45, s49, 0
	global_load_lds_dwordx4 v160, s[48:49]
	s_mov_b32 m0, s9
	s_nop 0
	global_load_lds_dwordx4 v158, s[44:45]
	s_mov_b32 m0, s23
	s_nop 0
	global_load_lds_dwordx4 v160, s[44:45]
	s_mov_b32 m0, s6
	s_nop 0
	global_load_lds_dwordx4 v158, s[50:51]
	s_mov_b32 m0, s28
	s_nop 0
	global_load_lds_dwordx4 v160, s[50:51]
	s_waitcnt vmcnt(8)
	s_waitcnt lgkmcnt(0)
	s_barrier
	v_mfma_f32_16x16x32_bf16 v[60:63], v[128:131], v[186:189], v[60:63]
	v_mfma_f32_16x16x32_bf16 v[56:59], v[136:139], v[186:189], v[56:59]
	v_mfma_f32_16x16x32_bf16 v[44:47], v[128:131], v[216:219], v[44:47]
	v_mfma_f32_16x16x32_bf16 v[40:43], v[136:139], v[216:219], v[40:43]
	v_mfma_f32_16x16x32_bf16 v[28:31], v[128:131], v[224:227], v[28:31]
	v_mfma_f32_16x16x32_bf16 v[24:27], v[136:139], v[224:227], v[24:27]
	v_mfma_f32_16x16x32_bf16 v[12:15], v[128:131], v[232:235], v[12:15]
	v_mfma_f32_16x16x32_bf16 v[8:11], v[136:139], v[232:235], v[8:11]
	v_mfma_f32_16x16x32_bf16 v[60:63], v[132:135], v[212:215], v[60:63]
	v_mfma_f32_16x16x32_bf16 v[56:59], v[140:143], v[212:215], v[56:59]
	v_mfma_f32_16x16x32_bf16 v[44:47], v[132:135], v[220:223], v[44:47]
	v_mfma_f32_16x16x32_bf16 v[40:43], v[140:143], v[220:223], v[40:43]
	v_mfma_f32_16x16x32_bf16 v[28:31], v[132:135], v[228:231], v[28:31]
	v_mfma_f32_16x16x32_bf16 v[24:27], v[140:143], v[228:231], v[24:27]
	v_mfma_f32_16x16x32_bf16 v[12:15], v[132:135], v[236:239], v[12:15]
	v_mfma_f32_16x16x32_bf16 v[8:11], v[140:143], v[236:239], v[8:11]
	v_mfma_f32_16x16x32_bf16 v[52:55], v[170:173], v[186:189], v[52:55]
	v_mfma_f32_16x16x32_bf16 v[48:51], v[178:181], v[186:189], v[48:51]
	v_mfma_f32_16x16x32_bf16 v[36:39], v[170:173], v[216:219], v[36:39]
	v_mfma_f32_16x16x32_bf16 v[32:35], v[178:181], v[216:219], v[32:35]
	v_mfma_f32_16x16x32_bf16 v[20:23], v[170:173], v[224:227], v[20:23]
	v_mfma_f32_16x16x32_bf16 v[16:19], v[178:181], v[224:227], v[16:19]
	v_mfma_f32_16x16x32_bf16 v[4:7], v[170:173], v[232:235], v[4:7]
	v_mfma_f32_16x16x32_bf16 v[0:3], v[178:181], v[232:235], v[0:3]
	v_mfma_f32_16x16x32_bf16 v[52:55], v[174:177], v[212:215], v[52:55]
	v_mfma_f32_16x16x32_bf16 v[48:51], v[182:185], v[212:215], v[48:51]
	v_mfma_f32_16x16x32_bf16 v[36:39], v[174:177], v[220:223], v[36:39]
	v_mfma_f32_16x16x32_bf16 v[32:35], v[182:185], v[220:223], v[32:35]
	v_mfma_f32_16x16x32_bf16 v[20:23], v[174:177], v[228:231], v[20:23]
	v_mfma_f32_16x16x32_bf16 v[16:19], v[182:185], v[228:231], v[16:19]
	v_mfma_f32_16x16x32_bf16 v[4:7], v[174:177], v[236:239], v[4:7]
	v_mfma_f32_16x16x32_bf16 v[0:3], v[182:185], v[236:239], v[0:3]
	s_barrier
	ds_read_b128 v[128:131], v203
	ds_read_b128 v[132:135], v204
	ds_read_b128 v[136:139], v205
	ds_read_b128 v[140:143], v206
	ds_read_b128 v[170:173], v207
	ds_read_b128 v[174:177], v208
	ds_read_b128 v[178:181], v209
	ds_read_b128 v[182:185], v210
	s_add_u32 s44, s50, 0x40000
	s_addc_u32 s45, s51, 0
	s_mov_b32 m0, s29
	ds_read_b128 v[186:189], v192 offset:32768
	ds_read_b128 v[212:215], v192 offset:33792
	ds_read_b128 v[216:219], v192 offset:34816
	ds_read_b128 v[220:223], v192 offset:35840
	ds_read_b128 v[224:227], v192 offset:36864
	ds_read_b128 v[228:231], v192 offset:37888
	ds_read_b128 v[232:235], v192 offset:38912
	ds_read_b128 v[236:239], v192 offset:39936
	global_load_lds_dwordx4 v158, s[44:45]
	s_mov_b32 m0, s30
	s_nop 0
	global_load_lds_dwordx4 v160, s[44:45]
	s_waitcnt vmcnt(8)
	s_waitcnt lgkmcnt(0)
	s_barrier
	v_mfma_f32_16x16x32_bf16 v[124:127], v[128:131], v[186:189], v[124:127]
	v_mfma_f32_16x16x32_bf16 v[120:123], v[136:139], v[186:189], v[120:123]
	v_mfma_f32_16x16x32_bf16 v[108:111], v[128:131], v[216:219], v[108:111]
	v_mfma_f32_16x16x32_bf16 v[104:107], v[136:139], v[216:219], v[104:107]
	v_mfma_f32_16x16x32_bf16 v[92:95], v[128:131], v[224:227], v[92:95]
	v_mfma_f32_16x16x32_bf16 v[88:91], v[136:139], v[224:227], v[88:91]
	v_mfma_f32_16x16x32_bf16 v[76:79], v[128:131], v[232:235], v[76:79]
	v_mfma_f32_16x16x32_bf16 v[72:75], v[136:139], v[232:235], v[72:75]
	v_mfma_f32_16x16x32_bf16 v[124:127], v[132:135], v[212:215], v[124:127]
	v_mfma_f32_16x16x32_bf16 v[120:123], v[140:143], v[212:215], v[120:123]
	v_mfma_f32_16x16x32_bf16 v[108:111], v[132:135], v[220:223], v[108:111]
	v_mfma_f32_16x16x32_bf16 v[104:107], v[140:143], v[220:223], v[104:107]
	v_mfma_f32_16x16x32_bf16 v[92:95], v[132:135], v[228:231], v[92:95]
	v_mfma_f32_16x16x32_bf16 v[88:91], v[140:143], v[228:231], v[88:91]
	v_mfma_f32_16x16x32_bf16 v[76:79], v[132:135], v[236:239], v[76:79]
	v_mfma_f32_16x16x32_bf16 v[72:75], v[140:143], v[236:239], v[72:75]
	v_mfma_f32_16x16x32_bf16 v[116:119], v[170:173], v[186:189], v[116:119]
	v_mfma_f32_16x16x32_bf16 v[112:115], v[178:181], v[186:189], v[112:115]
	v_mfma_f32_16x16x32_bf16 v[100:103], v[170:173], v[216:219], v[100:103]
	v_mfma_f32_16x16x32_bf16 v[96:99], v[178:181], v[216:219], v[96:99]
	v_mfma_f32_16x16x32_bf16 v[84:87], v[170:173], v[224:227], v[84:87]
	v_mfma_f32_16x16x32_bf16 v[80:83], v[178:181], v[224:227], v[80:83]
	v_mfma_f32_16x16x32_bf16 v[68:71], v[170:173], v[232:235], v[68:71]
	v_mfma_f32_16x16x32_bf16 v[64:67], v[178:181], v[232:235], v[64:67]
	v_mfma_f32_16x16x32_bf16 v[116:119], v[174:177], v[212:215], v[116:119]
	v_mfma_f32_16x16x32_bf16 v[112:115], v[182:185], v[212:215], v[112:115]
	v_mfma_f32_16x16x32_bf16 v[100:103], v[174:177], v[220:223], v[100:103]
	v_mfma_f32_16x16x32_bf16 v[96:99], v[182:185], v[220:223], v[96:99]
	v_mfma_f32_16x16x32_bf16 v[84:87], v[174:177], v[228:231], v[84:87]
	v_mfma_f32_16x16x32_bf16 v[80:83], v[182:185], v[228:231], v[80:83]
	v_mfma_f32_16x16x32_bf16 v[68:71], v[174:177], v[236:239], v[68:71]
	v_mfma_f32_16x16x32_bf16 v[64:67], v[182:185], v[236:239], v[64:67]
	s_barrier
	s_mov_b32 m0, s31
	s_add_u32 s44, s48, 0x40080
	ds_read_b128 v[186:189], v192 offset:49152
	ds_read_b128 v[212:215], v192 offset:50176
	ds_read_b128 v[216:219], v192 offset:51200
	ds_read_b128 v[220:223], v192 offset:52224
	ds_read_b128 v[224:227], v192 offset:53248
	ds_read_b128 v[228:231], v192 offset:54272
	ds_read_b128 v[232:235], v192 offset:55296
	ds_read_b128 v[236:239], v192 offset:56320
	global_load_lds_dwordx4 v158, s[98:99]
	s_mov_b32 m0, s33
	s_addc_u32 s45, s49, 0
	global_load_lds_dwordx4 v160, s[98:99]
	s_mov_b32 m0, s36
	s_nop 0
	global_load_lds_dwordx4 v158, s[44:45]
	s_mov_b32 m0, s37
	s_nop 0
	global_load_lds_dwordx4 v160, s[44:45]
	s_mov_b32 m0, s34
	s_nop 0
	global_load_lds_dwordx4 v158, s[100:101]
	s_mov_b32 m0, s35
	s_nop 0
	global_load_lds_dwordx4 v160, s[100:101]
	s_waitcnt vmcnt(8)
	s_waitcnt lgkmcnt(0)
	s_barrier
	v_mfma_f32_16x16x32_bf16 v[60:63], v[128:131], v[186:189], v[60:63]
	v_mfma_f32_16x16x32_bf16 v[56:59], v[136:139], v[186:189], v[56:59]
	v_mfma_f32_16x16x32_bf16 v[44:47], v[128:131], v[216:219], v[44:47]
	v_mfma_f32_16x16x32_bf16 v[40:43], v[136:139], v[216:219], v[40:43]
	v_mfma_f32_16x16x32_bf16 v[28:31], v[128:131], v[224:227], v[28:31]
	v_mfma_f32_16x16x32_bf16 v[24:27], v[136:139], v[224:227], v[24:27]
	v_mfma_f32_16x16x32_bf16 v[12:15], v[128:131], v[232:235], v[12:15]
	v_mfma_f32_16x16x32_bf16 v[8:11], v[136:139], v[232:235], v[8:11]
	v_mfma_f32_16x16x32_bf16 v[60:63], v[132:135], v[212:215], v[60:63]
	v_mfma_f32_16x16x32_bf16 v[56:59], v[140:143], v[212:215], v[56:59]
	v_mfma_f32_16x16x32_bf16 v[44:47], v[132:135], v[220:223], v[44:47]
	v_mfma_f32_16x16x32_bf16 v[40:43], v[140:143], v[220:223], v[40:43]
	v_mfma_f32_16x16x32_bf16 v[28:31], v[132:135], v[228:231], v[28:31]
	v_mfma_f32_16x16x32_bf16 v[24:27], v[140:143], v[228:231], v[24:27]
	v_mfma_f32_16x16x32_bf16 v[12:15], v[132:135], v[236:239], v[12:15]
	v_mfma_f32_16x16x32_bf16 v[8:11], v[140:143], v[236:239], v[8:11]
	v_mfma_f32_16x16x32_bf16 v[52:55], v[170:173], v[186:189], v[52:55]
	v_mfma_f32_16x16x32_bf16 v[48:51], v[178:181], v[186:189], v[48:51]
	v_mfma_f32_16x16x32_bf16 v[36:39], v[170:173], v[216:219], v[36:39]
	v_mfma_f32_16x16x32_bf16 v[32:35], v[178:181], v[216:219], v[32:35]
	v_mfma_f32_16x16x32_bf16 v[20:23], v[170:173], v[224:227], v[20:23]
	v_mfma_f32_16x16x32_bf16 v[16:19], v[178:181], v[224:227], v[16:19]
	v_mfma_f32_16x16x32_bf16 v[4:7], v[170:173], v[232:235], v[4:7]
	v_mfma_f32_16x16x32_bf16 v[0:3], v[178:181], v[232:235], v[0:3]
	v_mfma_f32_16x16x32_bf16 v[52:55], v[174:177], v[212:215], v[52:55]
	v_mfma_f32_16x16x32_bf16 v[48:51], v[182:185], v[212:215], v[48:51]
	v_mfma_f32_16x16x32_bf16 v[36:39], v[174:177], v[220:223], v[36:39]
	v_mfma_f32_16x16x32_bf16 v[32:35], v[182:185], v[220:223], v[32:35]
	v_mfma_f32_16x16x32_bf16 v[20:23], v[174:177], v[228:231], v[20:23]
	v_mfma_f32_16x16x32_bf16 v[16:19], v[182:185], v[228:231], v[16:19]
	v_mfma_f32_16x16x32_bf16 v[4:7], v[174:177], v[236:239], v[4:7]
	v_mfma_f32_16x16x32_bf16 v[0:3], v[182:185], v[236:239], v[0:3]
	s_add_i32 s68, s68, 2
	s_add_u32 s66, s66, 0x100
	s_addc_u32 s67, s67, 0
	s_cmp_gt_u32 s68, 13
	s_mov_b64 s[44:45], s[46:47]
	s_barrier
	s_cbranch_scc0 .LBB0_2801
	s_and_b64 vcc, exec, s[20:21]
	s_cbranch_vccz .LBB0_2804
	s_barrier

.LBB0_2949:
	ds_read_b128 v[172:175], v143
	ds_read_b128 v[176:179], v153
	ds_read_b128 v[180:183], v158
	ds_read_b128 v[184:187], v159
	ds_read_b128 v[188:191], v160
	ds_read_b128 v[196:199], v161
	ds_read_b128 v[200:203], v162
	ds_read_b128 v[204:207], v163
	s_add_u32 s26, s24, 0xfffc0080
	s_addc_u32 s27, s25, -1
	s_cmp_eq_u32 s53, 12
	s_cselect_b32 s37, s4, s27
	s_cselect_b32 s36, s5, s26
	s_cselect_b32 s27, s15, s52
	s_cselect_b32 s26, s17, s51
	s_mov_b32 m0, s47
	ds_read_b128 v[208:211], v141
	ds_read_b128 v[212:215], v141 offset:1024
	ds_read_b128 v[216:219], v141 offset:2048
	ds_read_b128 v[220:223], v141 offset:3072
	ds_read_b128 v[224:227], v141 offset:4096
	ds_read_b128 v[228:231], v141 offset:5120
	ds_read_b128 v[232:235], v141 offset:6144
	ds_read_b128 v[236:239], v141 offset:7168
	global_load_lds_dwordx4 v132, s[24:25]
	s_mov_b32 m0, s48
	s_nop 0
	global_load_lds_dwordx4 v134, s[24:25]
	s_waitcnt vmcnt(8)
	s_waitcnt lgkmcnt(0)
	s_barrier
	v_mfma_f32_16x16x32_bf16 v[124:127], v[172:175], v[208:211], v[124:127]
	v_mfma_f32_16x16x32_bf16 v[120:123], v[180:183], v[208:211], v[120:123]
	v_mfma_f32_16x16x32_bf16 v[108:111], v[172:175], v[216:219], v[108:111]
	v_mfma_f32_16x16x32_bf16 v[104:107], v[180:183], v[216:219], v[104:107]
	v_mfma_f32_16x16x32_bf16 v[92:95], v[172:175], v[224:227], v[92:95]
	v_mfma_f32_16x16x32_bf16 v[88:91], v[180:183], v[224:227], v[88:91]
	v_mfma_f32_16x16x32_bf16 v[76:79], v[172:175], v[232:235], v[76:79]
	v_mfma_f32_16x16x32_bf16 v[72:75], v[180:183], v[232:235], v[72:75]
	v_mfma_f32_16x16x32_bf16 v[124:127], v[176:179], v[212:215], v[124:127]
	v_mfma_f32_16x16x32_bf16 v[120:123], v[184:187], v[212:215], v[120:123]
	v_mfma_f32_16x16x32_bf16 v[108:111], v[176:179], v[220:223], v[108:111]
	v_mfma_f32_16x16x32_bf16 v[104:107], v[184:187], v[220:223], v[104:107]
	v_mfma_f32_16x16x32_bf16 v[92:95], v[176:179], v[228:231], v[92:95]
	v_mfma_f32_16x16x32_bf16 v[88:91], v[184:187], v[228:231], v[88:91]
	v_mfma_f32_16x16x32_bf16 v[76:79], v[176:179], v[236:239], v[76:79]
	v_mfma_f32_16x16x32_bf16 v[72:75], v[184:187], v[236:239], v[72:75]
	v_mfma_f32_16x16x32_bf16 v[116:119], v[188:191], v[208:211], v[116:119]
	v_mfma_f32_16x16x32_bf16 v[112:115], v[200:203], v[208:211], v[112:115]
	v_mfma_f32_16x16x32_bf16 v[100:103], v[188:191], v[216:219], v[100:103]
	v_mfma_f32_16x16x32_bf16 v[96:99], v[200:203], v[216:219], v[96:99]
	v_mfma_f32_16x16x32_bf16 v[84:87], v[188:191], v[224:227], v[84:87]
	v_mfma_f32_16x16x32_bf16 v[80:83], v[200:203], v[224:227], v[80:83]
	v_mfma_f32_16x16x32_bf16 v[68:71], v[188:191], v[232:235], v[68:71]
	v_mfma_f32_16x16x32_bf16 v[64:67], v[200:203], v[232:235], v[64:67]
	v_mfma_f32_16x16x32_bf16 v[116:119], v[196:199], v[212:215], v[116:119]
	v_mfma_f32_16x16x32_bf16 v[112:115], v[204:207], v[212:215], v[112:115]
	v_mfma_f32_16x16x32_bf16 v[100:103], v[196:199], v[220:223], v[100:103]
	v_mfma_f32_16x16x32_bf16 v[96:99], v[204:207], v[220:223], v[96:99]
	v_mfma_f32_16x16x32_bf16 v[84:87], v[196:199], v[228:231], v[84:87]
	v_mfma_f32_16x16x32_bf16 v[80:83], v[204:207], v[228:231], v[80:83]
	v_mfma_f32_16x16x32_bf16 v[68:71], v[196:199], v[236:239], v[68:71]
	v_mfma_f32_16x16x32_bf16 v[64:67], v[204:207], v[236:239], v[64:67]
	s_add_u32 s98, s26, s10
	s_addc_u32 s99, s27, s11
	s_add_u32 s100, s36, s10
	s_addc_u32 s101, s37, s11
	s_barrier
	s_mov_b32 m0, s23
	s_add_u32 s54, s26, 0x40000
	ds_read_b128 v[208:211], v141 offset:16384
	ds_read_b128 v[212:215], v141 offset:17408
	ds_read_b128 v[216:219], v141 offset:18432
	ds_read_b128 v[220:223], v141 offset:19456
	ds_read_b128 v[224:227], v141 offset:20480
	ds_read_b128 v[228:231], v141 offset:21504
	ds_read_b128 v[232:235], v141 offset:22528
	ds_read_b128 v[236:239], v141 offset:23552
	global_load_lds_dwordx4 v130, s[26:27]
	s_mov_b32 m0, s28
	s_addc_u32 s55, s27, 0
	global_load_lds_dwordx4 v128, s[26:27]
	s_mov_b32 m0, s29
	s_nop 0
	global_load_lds_dwordx4 v130, s[54:55]
	s_mov_b32 m0, s30
	s_nop 0
	global_load_lds_dwordx4 v128, s[54:55]
	s_mov_b32 m0, s2
	s_nop 0
	global_load_lds_dwordx4 v130, s[36:37]
	s_mov_b32 m0, s31
	s_nop 0
	global_load_lds_dwordx4 v128, s[36:37]
	s_waitcnt vmcnt(8)
	s_waitcnt lgkmcnt(0)
	s_barrier
	v_mfma_f32_16x16x32_bf16 v[60:63], v[172:175], v[208:211], v[60:63]
	v_mfma_f32_16x16x32_bf16 v[56:59], v[180:183], v[208:211], v[56:59]
	v_mfma_f32_16x16x32_bf16 v[44:47], v[172:175], v[216:219], v[44:47]
	v_mfma_f32_16x16x32_bf16 v[40:43], v[180:183], v[216:219], v[40:43]
	v_mfma_f32_16x16x32_bf16 v[28:31], v[172:175], v[224:227], v[28:31]
	v_mfma_f32_16x16x32_bf16 v[24:27], v[180:183], v[224:227], v[24:27]
	v_mfma_f32_16x16x32_bf16 v[12:15], v[172:175], v[232:235], v[12:15]
	v_mfma_f32_16x16x32_bf16 v[8:11], v[180:183], v[232:235], v[8:11]
	v_mfma_f32_16x16x32_bf16 v[60:63], v[176:179], v[212:215], v[60:63]
	v_mfma_f32_16x16x32_bf16 v[56:59], v[184:187], v[212:215], v[56:59]
	v_mfma_f32_16x16x32_bf16 v[44:47], v[176:179], v[220:223], v[44:47]
	v_mfma_f32_16x16x32_bf16 v[40:43], v[184:187], v[220:223], v[40:43]
	v_mfma_f32_16x16x32_bf16 v[28:31], v[176:179], v[228:231], v[28:31]
	v_mfma_f32_16x16x32_bf16 v[24:27], v[184:187], v[228:231], v[24:27]
	v_mfma_f32_16x16x32_bf16 v[12:15], v[176:179], v[236:239], v[12:15]
	v_mfma_f32_16x16x32_bf16 v[8:11], v[184:187], v[236:239], v[8:11]
	v_mfma_f32_16x16x32_bf16 v[52:55], v[188:191], v[208:211], v[52:55]
	v_mfma_f32_16x16x32_bf16 v[48:51], v[200:203], v[208:211], v[48:51]
	v_mfma_f32_16x16x32_bf16 v[36:39], v[188:191], v[216:219], v[36:39]
	v_mfma_f32_16x16x32_bf16 v[32:35], v[200:203], v[216:219], v[32:35]
	v_mfma_f32_16x16x32_bf16 v[20:23], v[188:191], v[224:227], v[20:23]
	v_mfma_f32_16x16x32_bf16 v[16:19], v[200:203], v[224:227], v[16:19]
	v_mfma_f32_16x16x32_bf16 v[4:7], v[188:191], v[232:235], v[4:7]
	v_mfma_f32_16x16x32_bf16 v[0:3], v[200:203], v[232:235], v[0:3]
	v_mfma_f32_16x16x32_bf16 v[52:55], v[196:199], v[212:215], v[52:55]
	v_mfma_f32_16x16x32_bf16 v[48:51], v[204:207], v[212:215], v[48:51]
	v_mfma_f32_16x16x32_bf16 v[36:39], v[196:199], v[220:223], v[36:39]
	v_mfma_f32_16x16x32_bf16 v[32:35], v[204:207], v[220:223], v[32:35]
	v_mfma_f32_16x16x32_bf16 v[20:23], v[196:199], v[228:231], v[20:23]
	v_mfma_f32_16x16x32_bf16 v[16:19], v[204:207], v[228:231], v[16:19]
	v_mfma_f32_16x16x32_bf16 v[4:7], v[196:199], v[236:239], v[4:7]
	v_mfma_f32_16x16x32_bf16 v[0:3], v[204:207], v[236:239], v[0:3]
	s_barrier
	ds_read_b128 v[172:175], v164
	ds_read_b128 v[176:179], v165
	ds_read_b128 v[180:183], v166
	ds_read_b128 v[184:187], v167
	ds_read_b128 v[188:191], v168
	ds_read_b128 v[196:199], v169
	ds_read_b128 v[200:203], v170
	ds_read_b128 v[204:207], v171
	s_add_u32 s36, s36, 0x40000
	s_addc_u32 s37, s37, 0
	s_mov_b32 m0, s33
	ds_read_b128 v[208:211], v141 offset:32768
	ds_read_b128 v[212:215], v141 offset:33792
	ds_read_b128 v[216:219], v141 offset:34816
	ds_read_b128 v[220:223], v141 offset:35840
	ds_read_b128 v[224:227], v141 offset:36864
	ds_read_b128 v[228:231], v141 offset:37888
	ds_read_b128 v[232:235], v141 offset:38912
	ds_read_b128 v[236:239], v141 offset:39936
	global_load_lds_dwordx4 v130, s[36:37]
	s_mov_b32 m0, s34
	s_nop 0
	global_load_lds_dwordx4 v128, s[36:37]
	s_waitcnt vmcnt(8)
	s_waitcnt lgkmcnt(0)
	s_barrier
	v_mfma_f32_16x16x32_bf16 v[124:127], v[172:175], v[208:211], v[124:127]
	v_mfma_f32_16x16x32_bf16 v[120:123], v[180:183], v[208:211], v[120:123]
	v_mfma_f32_16x16x32_bf16 v[108:111], v[172:175], v[216:219], v[108:111]
	v_mfma_f32_16x16x32_bf16 v[104:107], v[180:183], v[216:219], v[104:107]
	v_mfma_f32_16x16x32_bf16 v[92:95], v[172:175], v[224:227], v[92:95]
	v_mfma_f32_16x16x32_bf16 v[88:91], v[180:183], v[224:227], v[88:91]
	v_mfma_f32_16x16x32_bf16 v[76:79], v[172:175], v[232:235], v[76:79]
	v_mfma_f32_16x16x32_bf16 v[72:75], v[180:183], v[232:235], v[72:75]
	v_mfma_f32_16x16x32_bf16 v[124:127], v[176:179], v[212:215], v[124:127]
	v_mfma_f32_16x16x32_bf16 v[120:123], v[184:187], v[212:215], v[120:123]
	v_mfma_f32_16x16x32_bf16 v[108:111], v[176:179], v[220:223], v[108:111]
	v_mfma_f32_16x16x32_bf16 v[104:107], v[184:187], v[220:223], v[104:107]
	v_mfma_f32_16x16x32_bf16 v[92:95], v[176:179], v[228:231], v[92:95]
	v_mfma_f32_16x16x32_bf16 v[88:91], v[184:187], v[228:231], v[88:91]
	v_mfma_f32_16x16x32_bf16 v[76:79], v[176:179], v[236:239], v[76:79]
	v_mfma_f32_16x16x32_bf16 v[72:75], v[184:187], v[236:239], v[72:75]
	v_mfma_f32_16x16x32_bf16 v[116:119], v[188:191], v[208:211], v[116:119]
	v_mfma_f32_16x16x32_bf16 v[112:115], v[200:203], v[208:211], v[112:115]
	v_mfma_f32_16x16x32_bf16 v[100:103], v[188:191], v[216:219], v[100:103]
	v_mfma_f32_16x16x32_bf16 v[96:99], v[200:203], v[216:219], v[96:99]
	v_mfma_f32_16x16x32_bf16 v[84:87], v[188:191], v[224:227], v[84:87]
	v_mfma_f32_16x16x32_bf16 v[80:83], v[200:203], v[224:227], v[80:83]
	v_mfma_f32_16x16x32_bf16 v[68:71], v[188:191], v[232:235], v[68:71]
	v_mfma_f32_16x16x32_bf16 v[64:67], v[200:203], v[232:235], v[64:67]
	v_mfma_f32_16x16x32_bf16 v[116:119], v[196:199], v[212:215], v[116:119]
	v_mfma_f32_16x16x32_bf16 v[112:115], v[204:207], v[212:215], v[112:115]
	v_mfma_f32_16x16x32_bf16 v[100:103], v[196:199], v[220:223], v[100:103]
	v_mfma_f32_16x16x32_bf16 v[96:99], v[204:207], v[220:223], v[96:99]
	v_mfma_f32_16x16x32_bf16 v[84:87], v[196:199], v[228:231], v[84:87]
	v_mfma_f32_16x16x32_bf16 v[80:83], v[204:207], v[228:231], v[80:83]
	v_mfma_f32_16x16x32_bf16 v[68:71], v[196:199], v[236:239], v[68:71]
	v_mfma_f32_16x16x32_bf16 v[64:67], v[204:207], v[236:239], v[64:67]
	s_barrier
	s_mov_b32 m0, s39
	s_add_u32 s26, s26, 0x40080
	ds_read_b128 v[208:211], v141 offset:49152
	ds_read_b128 v[212:215], v141 offset:50176
	ds_read_b128 v[216:219], v141 offset:51200
	ds_read_b128 v[220:223], v141 offset:52224
	ds_read_b128 v[224:227], v141 offset:53248
	ds_read_b128 v[228:231], v141 offset:54272
	ds_read_b128 v[232:235], v141 offset:55296
	ds_read_b128 v[236:239], v141 offset:56320
	global_load_lds_dwordx4 v130, s[98:99]
	s_mov_b32 m0, s40
	s_addc_u32 s27, s27, 0
	global_load_lds_dwordx4 v128, s[98:99]
	s_mov_b32 m0, s43
	s_nop 0
	global_load_lds_dwordx4 v130, s[26:27]
	s_mov_b32 m0, s44
	s_nop 0
	global_load_lds_dwordx4 v128, s[26:27]
	s_mov_b32 m0, s41
	s_nop 0
	global_load_lds_dwordx4 v130, s[100:101]
	s_mov_b32 m0, s42
	s_nop 0
	global_load_lds_dwordx4 v128, s[100:101]
	s_waitcnt vmcnt(8)
	s_waitcnt lgkmcnt(0)
	s_barrier
	v_mfma_f32_16x16x32_bf16 v[60:63], v[172:175], v[208:211], v[60:63]
	v_mfma_f32_16x16x32_bf16 v[56:59], v[180:183], v[208:211], v[56:59]
	v_mfma_f32_16x16x32_bf16 v[44:47], v[172:175], v[216:219], v[44:47]
	v_mfma_f32_16x16x32_bf16 v[40:43], v[180:183], v[216:219], v[40:43]
	v_mfma_f32_16x16x32_bf16 v[28:31], v[172:175], v[224:227], v[28:31]
	v_mfma_f32_16x16x32_bf16 v[24:27], v[180:183], v[224:227], v[24:27]
	v_mfma_f32_16x16x32_bf16 v[12:15], v[172:175], v[232:235], v[12:15]
	v_mfma_f32_16x16x32_bf16 v[8:11], v[180:183], v[232:235], v[8:11]
	v_mfma_f32_16x16x32_bf16 v[60:63], v[176:179], v[212:215], v[60:63]
	v_mfma_f32_16x16x32_bf16 v[56:59], v[184:187], v[212:215], v[56:59]
	v_mfma_f32_16x16x32_bf16 v[44:47], v[176:179], v[220:223], v[44:47]
	v_mfma_f32_16x16x32_bf16 v[40:43], v[184:187], v[220:223], v[40:43]
	v_mfma_f32_16x16x32_bf16 v[28:31], v[176:179], v[228:231], v[28:31]
	v_mfma_f32_16x16x32_bf16 v[24:27], v[184:187], v[228:231], v[24:27]
	v_mfma_f32_16x16x32_bf16 v[12:15], v[176:179], v[236:239], v[12:15]
	v_mfma_f32_16x16x32_bf16 v[8:11], v[184:187], v[236:239], v[8:11]
	v_mfma_f32_16x16x32_bf16 v[52:55], v[188:191], v[208:211], v[52:55]
	v_mfma_f32_16x16x32_bf16 v[48:51], v[200:203], v[208:211], v[48:51]
	v_mfma_f32_16x16x32_bf16 v[36:39], v[188:191], v[216:219], v[36:39]
	v_mfma_f32_16x16x32_bf16 v[32:35], v[200:203], v[216:219], v[32:35]
	v_mfma_f32_16x16x32_bf16 v[20:23], v[188:191], v[224:227], v[20:23]
	v_mfma_f32_16x16x32_bf16 v[16:19], v[200:203], v[224:227], v[16:19]
	v_mfma_f32_16x16x32_bf16 v[4:7], v[188:191], v[232:235], v[4:7]
	v_mfma_f32_16x16x32_bf16 v[0:3], v[200:203], v[232:235], v[0:3]
	v_mfma_f32_16x16x32_bf16 v[52:55], v[196:199], v[212:215], v[52:55]
	v_mfma_f32_16x16x32_bf16 v[48:51], v[204:207], v[212:215], v[48:51]
	v_mfma_f32_16x16x32_bf16 v[36:39], v[196:199], v[220:223], v[36:39]
	v_mfma_f32_16x16x32_bf16 v[32:35], v[204:207], v[220:223], v[32:35]
	v_mfma_f32_16x16x32_bf16 v[20:23], v[196:199], v[228:231], v[20:23]
	v_mfma_f32_16x16x32_bf16 v[16:19], v[204:207], v[228:231], v[16:19]
	v_mfma_f32_16x16x32_bf16 v[4:7], v[196:199], v[236:239], v[4:7]
	v_mfma_f32_16x16x32_bf16 v[0:3], v[204:207], v[236:239], v[0:3]
	s_add_i32 s53, s53, 2
	s_add_u32 s24, s24, 0x100
	s_addc_u32 s25, s25, 0
	s_add_u32 s51, s51, 0x100
	s_addc_u32 s52, s52, 0
	s_cmp_gt_u32 s53, 13
	s_barrier
	s_cbranch_scc0 .LBB0_2949
	s_and_b64 vcc, exec, s[12:13]
	s_cbranch_vccz .LBB0_2952
	s_barrier

.LBB0_3029:
	ds_read_b128 v[128:131], v195
	ds_read_b128 v[132:135], v196
	ds_read_b128 v[136:139], v197
	ds_read_b128 v[140:143], v198
	ds_read_b128 v[170:173], v199
	ds_read_b128 v[174:177], v200
	ds_read_b128 v[178:181], v201
	ds_read_b128 v[182:185], v202
	s_add_u32 s34, s26, 0x100
	s_addc_u32 s35, s27, 0
	s_cmp_eq_u32 s64, 40
	s_cselect_b32 s39, s11, s35
	s_cselect_b32 s38, s10, s34
	s_cselect_b32 s37, s25, s5
	s_cselect_b32 s36, s24, s4
	s_mov_b32 m0, s50
	ds_read_b128 v[186:189], v192
	ds_read_b128 v[212:215], v192 offset:1024
	ds_read_b128 v[216:219], v192 offset:2048
	ds_read_b128 v[220:223], v192 offset:3072
	ds_read_b128 v[224:227], v192 offset:4096
	ds_read_b128 v[228:231], v192 offset:5120
	ds_read_b128 v[232:235], v192 offset:6144
	ds_read_b128 v[236:239], v192 offset:7168
	global_load_lds_dwordx4 v162, s[26:27]
	s_mov_b32 m0, s51
	s_nop 0
	global_load_lds_dwordx4 v164, s[26:27]
	s_waitcnt vmcnt(8)
	s_waitcnt lgkmcnt(0)
	s_barrier
	v_mfma_f32_16x16x32_bf16 v[124:127], v[128:131], v[186:189], v[124:127]
	v_mfma_f32_16x16x32_bf16 v[120:123], v[136:139], v[186:189], v[120:123]
	v_mfma_f32_16x16x32_bf16 v[108:111], v[128:131], v[216:219], v[108:111]
	v_mfma_f32_16x16x32_bf16 v[104:107], v[136:139], v[216:219], v[104:107]
	v_mfma_f32_16x16x32_bf16 v[92:95], v[128:131], v[224:227], v[92:95]
	v_mfma_f32_16x16x32_bf16 v[88:91], v[136:139], v[224:227], v[88:91]
	v_mfma_f32_16x16x32_bf16 v[76:79], v[128:131], v[232:235], v[76:79]
	v_mfma_f32_16x16x32_bf16 v[72:75], v[136:139], v[232:235], v[72:75]
	v_mfma_f32_16x16x32_bf16 v[124:127], v[132:135], v[212:215], v[124:127]
	v_mfma_f32_16x16x32_bf16 v[120:123], v[140:143], v[212:215], v[120:123]
	v_mfma_f32_16x16x32_bf16 v[108:111], v[132:135], v[220:223], v[108:111]
	v_mfma_f32_16x16x32_bf16 v[104:107], v[140:143], v[220:223], v[104:107]
	v_mfma_f32_16x16x32_bf16 v[92:95], v[132:135], v[228:231], v[92:95]
	v_mfma_f32_16x16x32_bf16 v[88:91], v[140:143], v[228:231], v[88:91]
	v_mfma_f32_16x16x32_bf16 v[76:79], v[132:135], v[236:239], v[76:79]
	v_mfma_f32_16x16x32_bf16 v[72:75], v[140:143], v[236:239], v[72:75]
	v_mfma_f32_16x16x32_bf16 v[116:119], v[170:173], v[186:189], v[116:119]
	v_mfma_f32_16x16x32_bf16 v[112:115], v[178:181], v[186:189], v[112:115]
	v_mfma_f32_16x16x32_bf16 v[100:103], v[170:173], v[216:219], v[100:103]
	v_mfma_f32_16x16x32_bf16 v[96:99], v[178:181], v[216:219], v[96:99]
	v_mfma_f32_16x16x32_bf16 v[84:87], v[170:173], v[224:227], v[84:87]
	v_mfma_f32_16x16x32_bf16 v[80:83], v[178:181], v[224:227], v[80:83]
	v_mfma_f32_16x16x32_bf16 v[68:71], v[170:173], v[232:235], v[68:71]
	v_mfma_f32_16x16x32_bf16 v[64:67], v[178:181], v[232:235], v[64:67]
	v_mfma_f32_16x16x32_bf16 v[116:119], v[174:177], v[212:215], v[116:119]
	v_mfma_f32_16x16x32_bf16 v[112:115], v[182:185], v[212:215], v[112:115]
	v_mfma_f32_16x16x32_bf16 v[100:103], v[174:177], v[220:223], v[100:103]
	v_mfma_f32_16x16x32_bf16 v[96:99], v[182:185], v[220:223], v[96:99]
	v_mfma_f32_16x16x32_bf16 v[84:87], v[174:177], v[228:231], v[84:87]
	v_mfma_f32_16x16x32_bf16 v[80:83], v[182:185], v[228:231], v[80:83]
	v_mfma_f32_16x16x32_bf16 v[68:71], v[174:177], v[236:239], v[68:71]
	v_mfma_f32_16x16x32_bf16 v[64:67], v[182:185], v[236:239], v[64:67]
	s_add_u32 s98, s36, s18
	s_addc_u32 s99, s37, s19
	s_add_u32 s100, s38, s18
	s_addc_u32 s101, s39, s19
	s_barrier
	s_mov_b32 m0, s7
	s_add_u32 s26, s36, 0xb0000
	ds_read_b128 v[186:189], v192 offset:16384
	ds_read_b128 v[212:215], v192 offset:17408
	ds_read_b128 v[216:219], v192 offset:18432
	ds_read_b128 v[220:223], v192 offset:19456
	ds_read_b128 v[224:227], v192 offset:20480
	ds_read_b128 v[228:231], v192 offset:21504
	ds_read_b128 v[232:235], v192 offset:22528
	ds_read_b128 v[236:239], v192 offset:23552
	global_load_lds_dwordx4 v158, s[36:37]
	s_mov_b32 m0, s23
	s_addc_u32 s27, s37, 0
	global_load_lds_dwordx4 v160, s[36:37]
	s_mov_b32 m0, s28
	s_nop 0
	global_load_lds_dwordx4 v158, s[26:27]
	s_mov_b32 m0, s29
	s_nop 0
	global_load_lds_dwordx4 v160, s[26:27]
	s_mov_b32 m0, s6
	s_nop 0
	global_load_lds_dwordx4 v158, s[38:39]
	s_mov_b32 m0, s30
	s_nop 0
	global_load_lds_dwordx4 v160, s[38:39]
	s_waitcnt vmcnt(8)
	s_waitcnt lgkmcnt(0)
	s_barrier
	v_mfma_f32_16x16x32_bf16 v[60:63], v[128:131], v[186:189], v[60:63]
	v_mfma_f32_16x16x32_bf16 v[56:59], v[136:139], v[186:189], v[56:59]
	v_mfma_f32_16x16x32_bf16 v[44:47], v[128:131], v[216:219], v[44:47]
	v_mfma_f32_16x16x32_bf16 v[40:43], v[136:139], v[216:219], v[40:43]
	v_mfma_f32_16x16x32_bf16 v[28:31], v[128:131], v[224:227], v[28:31]
	v_mfma_f32_16x16x32_bf16 v[24:27], v[136:139], v[224:227], v[24:27]
	v_mfma_f32_16x16x32_bf16 v[12:15], v[128:131], v[232:235], v[12:15]
	v_mfma_f32_16x16x32_bf16 v[8:11], v[136:139], v[232:235], v[8:11]
	v_mfma_f32_16x16x32_bf16 v[60:63], v[132:135], v[212:215], v[60:63]
	v_mfma_f32_16x16x32_bf16 v[56:59], v[140:143], v[212:215], v[56:59]
	v_mfma_f32_16x16x32_bf16 v[44:47], v[132:135], v[220:223], v[44:47]
	v_mfma_f32_16x16x32_bf16 v[40:43], v[140:143], v[220:223], v[40:43]
	v_mfma_f32_16x16x32_bf16 v[28:31], v[132:135], v[228:231], v[28:31]
	v_mfma_f32_16x16x32_bf16 v[24:27], v[140:143], v[228:231], v[24:27]
	v_mfma_f32_16x16x32_bf16 v[12:15], v[132:135], v[236:239], v[12:15]
	v_mfma_f32_16x16x32_bf16 v[8:11], v[140:143], v[236:239], v[8:11]
	v_mfma_f32_16x16x32_bf16 v[52:55], v[170:173], v[186:189], v[52:55]
	v_mfma_f32_16x16x32_bf16 v[48:51], v[178:181], v[186:189], v[48:51]
	v_mfma_f32_16x16x32_bf16 v[36:39], v[170:173], v[216:219], v[36:39]
	v_mfma_f32_16x16x32_bf16 v[32:35], v[178:181], v[216:219], v[32:35]
	v_mfma_f32_16x16x32_bf16 v[20:23], v[170:173], v[224:227], v[20:23]
	v_mfma_f32_16x16x32_bf16 v[16:19], v[178:181], v[224:227], v[16:19]
	v_mfma_f32_16x16x32_bf16 v[4:7], v[170:173], v[232:235], v[4:7]
	v_mfma_f32_16x16x32_bf16 v[0:3], v[178:181], v[232:235], v[0:3]
	v_mfma_f32_16x16x32_bf16 v[52:55], v[174:177], v[212:215], v[52:55]
	v_mfma_f32_16x16x32_bf16 v[48:51], v[182:185], v[212:215], v[48:51]
	v_mfma_f32_16x16x32_bf16 v[36:39], v[174:177], v[220:223], v[36:39]
	v_mfma_f32_16x16x32_bf16 v[32:35], v[182:185], v[220:223], v[32:35]
	v_mfma_f32_16x16x32_bf16 v[20:23], v[174:177], v[228:231], v[20:23]
	v_mfma_f32_16x16x32_bf16 v[16:19], v[182:185], v[228:231], v[16:19]
	v_mfma_f32_16x16x32_bf16 v[4:7], v[174:177], v[236:239], v[4:7]
	v_mfma_f32_16x16x32_bf16 v[0:3], v[182:185], v[236:239], v[0:3]
	s_barrier
	ds_read_b128 v[128:131], v203
	ds_read_b128 v[132:135], v204
	ds_read_b128 v[136:139], v205
	ds_read_b128 v[140:143], v206
	ds_read_b128 v[170:173], v207
	ds_read_b128 v[174:177], v208
	ds_read_b128 v[178:181], v209
	ds_read_b128 v[182:185], v210
	s_add_u32 s26, s38, 0xb0000
	s_addc_u32 s27, s39, 0
	s_mov_b32 m0, s31
	ds_read_b128 v[186:189], v192 offset:32768
	ds_read_b128 v[212:215], v192 offset:33792
	ds_read_b128 v[216:219], v192 offset:34816
	ds_read_b128 v[220:223], v192 offset:35840
	ds_read_b128 v[224:227], v192 offset:36864
	ds_read_b128 v[228:231], v192 offset:37888
	ds_read_b128 v[232:235], v192 offset:38912
	ds_read_b128 v[236:239], v192 offset:39936
	global_load_lds_dwordx4 v158, s[26:27]
	s_mov_b32 m0, s33
	s_nop 0
	global_load_lds_dwordx4 v160, s[26:27]
	s_waitcnt vmcnt(8)
	s_waitcnt lgkmcnt(0)
	s_barrier
	v_mfma_f32_16x16x32_bf16 v[124:127], v[128:131], v[186:189], v[124:127]
	v_mfma_f32_16x16x32_bf16 v[120:123], v[136:139], v[186:189], v[120:123]
	v_mfma_f32_16x16x32_bf16 v[108:111], v[128:131], v[216:219], v[108:111]
	v_mfma_f32_16x16x32_bf16 v[104:107], v[136:139], v[216:219], v[104:107]
	v_mfma_f32_16x16x32_bf16 v[92:95], v[128:131], v[224:227], v[92:95]
	v_mfma_f32_16x16x32_bf16 v[88:91], v[136:139], v[224:227], v[88:91]
	v_mfma_f32_16x16x32_bf16 v[76:79], v[128:131], v[232:235], v[76:79]
	v_mfma_f32_16x16x32_bf16 v[72:75], v[136:139], v[232:235], v[72:75]
	v_mfma_f32_16x16x32_bf16 v[124:127], v[132:135], v[212:215], v[124:127]
	v_mfma_f32_16x16x32_bf16 v[120:123], v[140:143], v[212:215], v[120:123]
	v_mfma_f32_16x16x32_bf16 v[108:111], v[132:135], v[220:223], v[108:111]
	v_mfma_f32_16x16x32_bf16 v[104:107], v[140:143], v[220:223], v[104:107]
	v_mfma_f32_16x16x32_bf16 v[92:95], v[132:135], v[228:231], v[92:95]
	v_mfma_f32_16x16x32_bf16 v[88:91], v[140:143], v[228:231], v[88:91]
	v_mfma_f32_16x16x32_bf16 v[76:79], v[132:135], v[236:239], v[76:79]
	v_mfma_f32_16x16x32_bf16 v[72:75], v[140:143], v[236:239], v[72:75]
	v_mfma_f32_16x16x32_bf16 v[116:119], v[170:173], v[186:189], v[116:119]
	v_mfma_f32_16x16x32_bf16 v[112:115], v[178:181], v[186:189], v[112:115]
	v_mfma_f32_16x16x32_bf16 v[100:103], v[170:173], v[216:219], v[100:103]
	v_mfma_f32_16x16x32_bf16 v[96:99], v[178:181], v[216:219], v[96:99]
	v_mfma_f32_16x16x32_bf16 v[84:87], v[170:173], v[224:227], v[84:87]
	v_mfma_f32_16x16x32_bf16 v[80:83], v[178:181], v[224:227], v[80:83]
	v_mfma_f32_16x16x32_bf16 v[68:71], v[170:173], v[232:235], v[68:71]
	v_mfma_f32_16x16x32_bf16 v[64:67], v[178:181], v[232:235], v[64:67]
	v_mfma_f32_16x16x32_bf16 v[116:119], v[174:177], v[212:215], v[116:119]
	v_mfma_f32_16x16x32_bf16 v[112:115], v[182:185], v[212:215], v[112:115]
	v_mfma_f32_16x16x32_bf16 v[100:103], v[174:177], v[220:223], v[100:103]
	v_mfma_f32_16x16x32_bf16 v[96:99], v[182:185], v[220:223], v[96:99]
	v_mfma_f32_16x16x32_bf16 v[84:87], v[174:177], v[228:231], v[84:87]
	v_mfma_f32_16x16x32_bf16 v[80:83], v[182:185], v[228:231], v[80:83]
	v_mfma_f32_16x16x32_bf16 v[68:71], v[174:177], v[236:239], v[68:71]
	v_mfma_f32_16x16x32_bf16 v[64:67], v[182:185], v[236:239], v[64:67]
	s_barrier
	s_mov_b32 m0, s40
	s_add_u32 s26, s36, 0xb0080
	ds_read_b128 v[186:189], v192 offset:49152
	ds_read_b128 v[212:215], v192 offset:50176
	ds_read_b128 v[216:219], v192 offset:51200
	ds_read_b128 v[220:223], v192 offset:52224
	ds_read_b128 v[224:227], v192 offset:53248
	ds_read_b128 v[228:231], v192 offset:54272
	ds_read_b128 v[232:235], v192 offset:55296
	ds_read_b128 v[236:239], v192 offset:56320
	global_load_lds_dwordx4 v158, s[98:99]
	s_mov_b32 m0, s41
	s_addc_u32 s27, s37, 0
	global_load_lds_dwordx4 v160, s[98:99]
	s_mov_b32 m0, s44
	s_nop 0
	global_load_lds_dwordx4 v158, s[26:27]
	s_mov_b32 m0, s45
	s_nop 0
	global_load_lds_dwordx4 v160, s[26:27]
	s_mov_b32 m0, s42
	s_nop 0
	global_load_lds_dwordx4 v158, s[100:101]
	s_mov_b32 m0, s43
	s_nop 0
	global_load_lds_dwordx4 v160, s[100:101]
	s_waitcnt vmcnt(8)
	s_waitcnt lgkmcnt(0)
	s_barrier
	v_mfma_f32_16x16x32_bf16 v[60:63], v[128:131], v[186:189], v[60:63]
	v_mfma_f32_16x16x32_bf16 v[56:59], v[136:139], v[186:189], v[56:59]
	v_mfma_f32_16x16x32_bf16 v[44:47], v[128:131], v[216:219], v[44:47]
	v_mfma_f32_16x16x32_bf16 v[40:43], v[136:139], v[216:219], v[40:43]
	v_mfma_f32_16x16x32_bf16 v[28:31], v[128:131], v[224:227], v[28:31]
	v_mfma_f32_16x16x32_bf16 v[24:27], v[136:139], v[224:227], v[24:27]
	v_mfma_f32_16x16x32_bf16 v[12:15], v[128:131], v[232:235], v[12:15]
	v_mfma_f32_16x16x32_bf16 v[8:11], v[136:139], v[232:235], v[8:11]
	v_mfma_f32_16x16x32_bf16 v[60:63], v[132:135], v[212:215], v[60:63]
	v_mfma_f32_16x16x32_bf16 v[56:59], v[140:143], v[212:215], v[56:59]
	v_mfma_f32_16x16x32_bf16 v[44:47], v[132:135], v[220:223], v[44:47]
	v_mfma_f32_16x16x32_bf16 v[40:43], v[140:143], v[220:223], v[40:43]
	v_mfma_f32_16x16x32_bf16 v[28:31], v[132:135], v[228:231], v[28:31]
	v_mfma_f32_16x16x32_bf16 v[24:27], v[140:143], v[228:231], v[24:27]
	v_mfma_f32_16x16x32_bf16 v[12:15], v[132:135], v[236:239], v[12:15]
	v_mfma_f32_16x16x32_bf16 v[8:11], v[140:143], v[236:239], v[8:11]
	v_mfma_f32_16x16x32_bf16 v[52:55], v[170:173], v[186:189], v[52:55]
	v_mfma_f32_16x16x32_bf16 v[48:51], v[178:181], v[186:189], v[48:51]
	v_mfma_f32_16x16x32_bf16 v[36:39], v[170:173], v[216:219], v[36:39]
	v_mfma_f32_16x16x32_bf16 v[32:35], v[178:181], v[216:219], v[32:35]
	v_mfma_f32_16x16x32_bf16 v[20:23], v[170:173], v[224:227], v[20:23]
	v_mfma_f32_16x16x32_bf16 v[16:19], v[178:181], v[224:227], v[16:19]
	v_mfma_f32_16x16x32_bf16 v[4:7], v[170:173], v[232:235], v[4:7]
	v_mfma_f32_16x16x32_bf16 v[0:3], v[178:181], v[232:235], v[0:3]
	v_mfma_f32_16x16x32_bf16 v[52:55], v[174:177], v[212:215], v[52:55]
	v_mfma_f32_16x16x32_bf16 v[48:51], v[182:185], v[212:215], v[48:51]
	v_mfma_f32_16x16x32_bf16 v[36:39], v[174:177], v[220:223], v[36:39]
	v_mfma_f32_16x16x32_bf16 v[32:35], v[182:185], v[220:223], v[32:35]
	v_mfma_f32_16x16x32_bf16 v[20:23], v[174:177], v[228:231], v[20:23]
	v_mfma_f32_16x16x32_bf16 v[16:19], v[182:185], v[228:231], v[16:19]
	v_mfma_f32_16x16x32_bf16 v[4:7], v[174:177], v[236:239], v[4:7]
	v_mfma_f32_16x16x32_bf16 v[0:3], v[182:185], v[236:239], v[0:3]
	s_add_i32 s64, s64, 2
	s_add_u32 s4, s4, 0x100
	s_addc_u32 s5, s5, 0
	s_cmp_gt_u32 s64, 41
	s_mov_b64 s[26:27], s[34:35]
	s_barrier
	s_cbranch_scc0 .LBB0_3029
	s_and_b64 vcc, exec, s[20:21]
	s_cbranch_vccz .LBB0_3032
	s_barrier

.LBB0_3179:
	ds_read_b128 v[140:143], v154
	ds_read_b128 v[170:173], v155
	ds_read_b128 v[174:177], v156
	ds_read_b128 v[178:181], v157
	ds_read_b128 v[182:185], v158
	ds_read_b128 v[186:189], v159
	ds_read_b128 v[190:193], v160
	ds_read_b128 v[194:197], v161
	s_add_u32 s34, s14, 0xfffc0080
	s_addc_u32 s35, s15, -1
	s_cmp_eq_u32 s54, 12
	s_cselect_b32 s37, s4, s35
	s_cselect_b32 s36, s5, s34
	s_cselect_b32 s35, s11, s25
	s_cselect_b32 s34, s13, s23
	s_mov_b32 m0, s51
	ds_read_b128 v[198:201], v149
	ds_read_b128 v[202:205], v149 offset:1024
	ds_read_b128 v[206:209], v149 offset:2048
	ds_read_b128 v[210:213], v149 offset:3072
	ds_read_b128 v[214:217], v149 offset:4096
	ds_read_b128 v[218:221], v149 offset:5120
	ds_read_b128 v[222:225], v149 offset:6144
	ds_read_b128 v[226:229], v149 offset:7168
	global_load_lds_dwordx4 v132, s[14:15]
	s_mov_b32 m0, s52
	s_nop 0
	global_load_lds_dwordx4 v134, s[14:15]
	s_waitcnt vmcnt(8)
	s_waitcnt lgkmcnt(0)
	s_barrier
	v_mfma_f32_16x16x32_bf16 v[124:127], v[140:143], v[198:201], v[124:127]
	v_mfma_f32_16x16x32_bf16 v[120:123], v[174:177], v[198:201], v[120:123]
	v_mfma_f32_16x16x32_bf16 v[108:111], v[140:143], v[206:209], v[108:111]
	v_mfma_f32_16x16x32_bf16 v[104:107], v[174:177], v[206:209], v[104:107]
	v_mfma_f32_16x16x32_bf16 v[92:95], v[140:143], v[214:217], v[92:95]
	v_mfma_f32_16x16x32_bf16 v[88:91], v[174:177], v[214:217], v[88:91]
	v_mfma_f32_16x16x32_bf16 v[76:79], v[140:143], v[222:225], v[76:79]
	v_mfma_f32_16x16x32_bf16 v[72:75], v[174:177], v[222:225], v[72:75]
	v_mfma_f32_16x16x32_bf16 v[124:127], v[170:173], v[202:205], v[124:127]
	v_mfma_f32_16x16x32_bf16 v[120:123], v[178:181], v[202:205], v[120:123]
	v_mfma_f32_16x16x32_bf16 v[108:111], v[170:173], v[210:213], v[108:111]
	v_mfma_f32_16x16x32_bf16 v[104:107], v[178:181], v[210:213], v[104:107]
	v_mfma_f32_16x16x32_bf16 v[92:95], v[170:173], v[218:221], v[92:95]
	v_mfma_f32_16x16x32_bf16 v[88:91], v[178:181], v[218:221], v[88:91]
	v_mfma_f32_16x16x32_bf16 v[76:79], v[170:173], v[226:229], v[76:79]
	v_mfma_f32_16x16x32_bf16 v[72:75], v[178:181], v[226:229], v[72:75]
	v_mfma_f32_16x16x32_bf16 v[116:119], v[182:185], v[198:201], v[116:119]
	v_mfma_f32_16x16x32_bf16 v[112:115], v[190:193], v[198:201], v[112:115]
	v_mfma_f32_16x16x32_bf16 v[100:103], v[182:185], v[206:209], v[100:103]
	v_mfma_f32_16x16x32_bf16 v[96:99], v[190:193], v[206:209], v[96:99]
	v_mfma_f32_16x16x32_bf16 v[84:87], v[182:185], v[214:217], v[84:87]
	v_mfma_f32_16x16x32_bf16 v[80:83], v[190:193], v[214:217], v[80:83]
	v_mfma_f32_16x16x32_bf16 v[68:71], v[182:185], v[222:225], v[68:71]
	v_mfma_f32_16x16x32_bf16 v[64:67], v[190:193], v[222:225], v[64:67]
	v_mfma_f32_16x16x32_bf16 v[116:119], v[186:189], v[202:205], v[116:119]
	v_mfma_f32_16x16x32_bf16 v[112:115], v[194:197], v[202:205], v[112:115]
	v_mfma_f32_16x16x32_bf16 v[100:103], v[186:189], v[210:213], v[100:103]
	v_mfma_f32_16x16x32_bf16 v[96:99], v[194:197], v[210:213], v[96:99]
	v_mfma_f32_16x16x32_bf16 v[84:87], v[186:189], v[218:221], v[84:87]
	v_mfma_f32_16x16x32_bf16 v[80:83], v[194:197], v[218:221], v[80:83]
	v_mfma_f32_16x16x32_bf16 v[68:71], v[186:189], v[226:229], v[68:71]
	v_mfma_f32_16x16x32_bf16 v[64:67], v[194:197], v[226:229], v[64:67]
	s_add_u32 s98, s34, s16
	s_addc_u32 s99, s35, s17
	s_add_u32 s100, s36, s16
	s_addc_u32 s101, s37, s17
	s_barrier
	s_mov_b32 m0, s6
	s_add_u32 s60, s34, 0x40000
	ds_read_b128 v[198:201], v149 offset:16384
	ds_read_b128 v[202:205], v149 offset:17408
	ds_read_b128 v[206:209], v149 offset:18432
	ds_read_b128 v[210:213], v149 offset:19456
	ds_read_b128 v[214:217], v149 offset:20480
	ds_read_b128 v[218:221], v149 offset:21504
	ds_read_b128 v[222:225], v149 offset:22528
	ds_read_b128 v[226:229], v149 offset:23552
	global_load_lds_dwordx4 v128, s[34:35]
	s_mov_b32 m0, s7
	s_addc_u32 s61, s35, 0
	global_load_lds_dwordx4 v130, s[34:35]
	s_mov_b32 m0, s21
	s_nop 0
	global_load_lds_dwordx4 v128, s[60:61]
	s_mov_b32 m0, s28
	s_nop 0
	global_load_lds_dwordx4 v130, s[60:61]
	s_mov_b32 m0, s2
	s_nop 0
	global_load_lds_dwordx4 v128, s[36:37]
	s_mov_b32 m0, s29
	s_nop 0
	global_load_lds_dwordx4 v130, s[36:37]
	s_waitcnt vmcnt(8)
	s_waitcnt lgkmcnt(0)
	s_barrier
	v_mfma_f32_16x16x32_bf16 v[60:63], v[140:143], v[198:201], v[60:63]
	v_mfma_f32_16x16x32_bf16 v[56:59], v[174:177], v[198:201], v[56:59]
	v_mfma_f32_16x16x32_bf16 v[44:47], v[140:143], v[206:209], v[44:47]
	v_mfma_f32_16x16x32_bf16 v[40:43], v[174:177], v[206:209], v[40:43]
	v_mfma_f32_16x16x32_bf16 v[28:31], v[140:143], v[214:217], v[28:31]
	v_mfma_f32_16x16x32_bf16 v[24:27], v[174:177], v[214:217], v[24:27]
	v_mfma_f32_16x16x32_bf16 v[12:15], v[140:143], v[222:225], v[12:15]
	v_mfma_f32_16x16x32_bf16 v[8:11], v[174:177], v[222:225], v[8:11]
	v_mfma_f32_16x16x32_bf16 v[60:63], v[170:173], v[202:205], v[60:63]
	v_mfma_f32_16x16x32_bf16 v[56:59], v[178:181], v[202:205], v[56:59]
	v_mfma_f32_16x16x32_bf16 v[44:47], v[170:173], v[210:213], v[44:47]
	v_mfma_f32_16x16x32_bf16 v[40:43], v[178:181], v[210:213], v[40:43]
	v_mfma_f32_16x16x32_bf16 v[28:31], v[170:173], v[218:221], v[28:31]
	v_mfma_f32_16x16x32_bf16 v[24:27], v[178:181], v[218:221], v[24:27]
	v_mfma_f32_16x16x32_bf16 v[12:15], v[170:173], v[226:229], v[12:15]
	v_mfma_f32_16x16x32_bf16 v[8:11], v[178:181], v[226:229], v[8:11]
	v_mfma_f32_16x16x32_bf16 v[52:55], v[182:185], v[198:201], v[52:55]
	v_mfma_f32_16x16x32_bf16 v[48:51], v[190:193], v[198:201], v[48:51]
	v_mfma_f32_16x16x32_bf16 v[36:39], v[182:185], v[206:209], v[36:39]
	v_mfma_f32_16x16x32_bf16 v[32:35], v[190:193], v[206:209], v[32:35]
	v_mfma_f32_16x16x32_bf16 v[20:23], v[182:185], v[214:217], v[20:23]
	v_mfma_f32_16x16x32_bf16 v[16:19], v[190:193], v[214:217], v[16:19]
	v_mfma_f32_16x16x32_bf16 v[4:7], v[182:185], v[222:225], v[4:7]
	v_mfma_f32_16x16x32_bf16 v[0:3], v[190:193], v[222:225], v[0:3]
	v_mfma_f32_16x16x32_bf16 v[52:55], v[186:189], v[202:205], v[52:55]
	v_mfma_f32_16x16x32_bf16 v[48:51], v[194:197], v[202:205], v[48:51]
	v_mfma_f32_16x16x32_bf16 v[36:39], v[186:189], v[210:213], v[36:39]
	v_mfma_f32_16x16x32_bf16 v[32:35], v[194:197], v[210:213], v[32:35]
	v_mfma_f32_16x16x32_bf16 v[20:23], v[186:189], v[218:221], v[20:23]
	v_mfma_f32_16x16x32_bf16 v[16:19], v[194:197], v[218:221], v[16:19]
	v_mfma_f32_16x16x32_bf16 v[4:7], v[186:189], v[226:229], v[4:7]
	v_mfma_f32_16x16x32_bf16 v[0:3], v[194:197], v[226:229], v[0:3]
	s_barrier
	ds_read_b128 v[140:143], v162
	ds_read_b128 v[170:173], v163
	ds_read_b128 v[174:177], v164
	ds_read_b128 v[178:181], v165
	ds_read_b128 v[182:185], v166
	ds_read_b128 v[186:189], v167
	ds_read_b128 v[190:193], v168
	ds_read_b128 v[194:197], v169
	s_add_u32 s36, s36, 0x40000
	s_addc_u32 s37, s37, 0
	s_mov_b32 m0, s33
	ds_read_b128 v[198:201], v149 offset:32768
	ds_read_b128 v[202:205], v149 offset:33792
	ds_read_b128 v[206:209], v149 offset:34816
	ds_read_b128 v[210:213], v149 offset:35840
	ds_read_b128 v[214:217], v149 offset:36864
	ds_read_b128 v[218:221], v149 offset:37888
	ds_read_b128 v[222:225], v149 offset:38912
	ds_read_b128 v[226:229], v149 offset:39936
	global_load_lds_dwordx4 v128, s[36:37]
	s_mov_b32 m0, s38
	s_nop 0
	global_load_lds_dwordx4 v130, s[36:37]
	s_waitcnt vmcnt(8)
	s_waitcnt lgkmcnt(0)
	s_barrier
	v_mfma_f32_16x16x32_bf16 v[124:127], v[140:143], v[198:201], v[124:127]
	v_mfma_f32_16x16x32_bf16 v[120:123], v[174:177], v[198:201], v[120:123]
	v_mfma_f32_16x16x32_bf16 v[108:111], v[140:143], v[206:209], v[108:111]
	v_mfma_f32_16x16x32_bf16 v[104:107], v[174:177], v[206:209], v[104:107]
	v_mfma_f32_16x16x32_bf16 v[92:95], v[140:143], v[214:217], v[92:95]
	v_mfma_f32_16x16x32_bf16 v[88:91], v[174:177], v[214:217], v[88:91]
	v_mfma_f32_16x16x32_bf16 v[76:79], v[140:143], v[222:225], v[76:79]
	v_mfma_f32_16x16x32_bf16 v[72:75], v[174:177], v[222:225], v[72:75]
	v_mfma_f32_16x16x32_bf16 v[124:127], v[170:173], v[202:205], v[124:127]
	v_mfma_f32_16x16x32_bf16 v[120:123], v[178:181], v[202:205], v[120:123]
	v_mfma_f32_16x16x32_bf16 v[108:111], v[170:173], v[210:213], v[108:111]
	v_mfma_f32_16x16x32_bf16 v[104:107], v[178:181], v[210:213], v[104:107]
	v_mfma_f32_16x16x32_bf16 v[92:95], v[170:173], v[218:221], v[92:95]
	v_mfma_f32_16x16x32_bf16 v[88:91], v[178:181], v[218:221], v[88:91]
	v_mfma_f32_16x16x32_bf16 v[76:79], v[170:173], v[226:229], v[76:79]
	v_mfma_f32_16x16x32_bf16 v[72:75], v[178:181], v[226:229], v[72:75]
	v_mfma_f32_16x16x32_bf16 v[116:119], v[182:185], v[198:201], v[116:119]
	v_mfma_f32_16x16x32_bf16 v[112:115], v[190:193], v[198:201], v[112:115]
	v_mfma_f32_16x16x32_bf16 v[100:103], v[182:185], v[206:209], v[100:103]
	v_mfma_f32_16x16x32_bf16 v[96:99], v[190:193], v[206:209], v[96:99]
	v_mfma_f32_16x16x32_bf16 v[84:87], v[182:185], v[214:217], v[84:87]
	v_mfma_f32_16x16x32_bf16 v[80:83], v[190:193], v[214:217], v[80:83]
	v_mfma_f32_16x16x32_bf16 v[68:71], v[182:185], v[222:225], v[68:71]
	v_mfma_f32_16x16x32_bf16 v[64:67], v[190:193], v[222:225], v[64:67]
	v_mfma_f32_16x16x32_bf16 v[116:119], v[186:189], v[202:205], v[116:119]
	v_mfma_f32_16x16x32_bf16 v[112:115], v[194:197], v[202:205], v[112:115]
	v_mfma_f32_16x16x32_bf16 v[100:103], v[186:189], v[210:213], v[100:103]
	v_mfma_f32_16x16x32_bf16 v[96:99], v[194:197], v[210:213], v[96:99]
	v_mfma_f32_16x16x32_bf16 v[84:87], v[186:189], v[218:221], v[84:87]
	v_mfma_f32_16x16x32_bf16 v[80:83], v[194:197], v[218:221], v[80:83]
	v_mfma_f32_16x16x32_bf16 v[68:71], v[186:189], v[226:229], v[68:71]
	v_mfma_f32_16x16x32_bf16 v[64:67], v[194:197], v[226:229], v[64:67]
	s_barrier
	s_mov_b32 m0, s40
	s_add_u32 s34, s34, 0x40080
	ds_read_b128 v[198:201], v149 offset:49152
	ds_read_b128 v[202:205], v149 offset:50176
	ds_read_b128 v[206:209], v149 offset:51200
	ds_read_b128 v[210:213], v149 offset:52224
	ds_read_b128 v[214:217], v149 offset:53248
	ds_read_b128 v[218:221], v149 offset:54272
	ds_read_b128 v[222:225], v149 offset:55296
	ds_read_b128 v[226:229], v149 offset:56320
	global_load_lds_dwordx4 v128, s[98:99]
	s_mov_b32 m0, s41
	s_addc_u32 s35, s35, 0
	global_load_lds_dwordx4 v130, s[98:99]
	s_mov_b32 m0, s44
	s_nop 0
	global_load_lds_dwordx4 v128, s[34:35]
	s_mov_b32 m0, s45
	s_nop 0
	global_load_lds_dwordx4 v130, s[34:35]
	s_mov_b32 m0, s42
	s_nop 0
	global_load_lds_dwordx4 v128, s[100:101]
	s_mov_b32 m0, s43
	s_nop 0
	global_load_lds_dwordx4 v130, s[100:101]
	s_waitcnt vmcnt(8)
	s_waitcnt lgkmcnt(0)
	s_barrier
	v_mfma_f32_16x16x32_bf16 v[60:63], v[140:143], v[198:201], v[60:63]
	v_mfma_f32_16x16x32_bf16 v[56:59], v[174:177], v[198:201], v[56:59]
	v_mfma_f32_16x16x32_bf16 v[44:47], v[140:143], v[206:209], v[44:47]
	v_mfma_f32_16x16x32_bf16 v[40:43], v[174:177], v[206:209], v[40:43]
	v_mfma_f32_16x16x32_bf16 v[28:31], v[140:143], v[214:217], v[28:31]
	v_mfma_f32_16x16x32_bf16 v[24:27], v[174:177], v[214:217], v[24:27]
	v_mfma_f32_16x16x32_bf16 v[12:15], v[140:143], v[222:225], v[12:15]
	v_mfma_f32_16x16x32_bf16 v[8:11], v[174:177], v[222:225], v[8:11]
	v_mfma_f32_16x16x32_bf16 v[60:63], v[170:173], v[202:205], v[60:63]
	v_mfma_f32_16x16x32_bf16 v[56:59], v[178:181], v[202:205], v[56:59]
	v_mfma_f32_16x16x32_bf16 v[44:47], v[170:173], v[210:213], v[44:47]
	v_mfma_f32_16x16x32_bf16 v[40:43], v[178:181], v[210:213], v[40:43]
	v_mfma_f32_16x16x32_bf16 v[28:31], v[170:173], v[218:221], v[28:31]
	v_mfma_f32_16x16x32_bf16 v[24:27], v[178:181], v[218:221], v[24:27]
	v_mfma_f32_16x16x32_bf16 v[12:15], v[170:173], v[226:229], v[12:15]
	v_mfma_f32_16x16x32_bf16 v[8:11], v[178:181], v[226:229], v[8:11]
	v_mfma_f32_16x16x32_bf16 v[52:55], v[182:185], v[198:201], v[52:55]
	v_mfma_f32_16x16x32_bf16 v[48:51], v[190:193], v[198:201], v[48:51]
	v_mfma_f32_16x16x32_bf16 v[36:39], v[182:185], v[206:209], v[36:39]
	v_mfma_f32_16x16x32_bf16 v[32:35], v[190:193], v[206:209], v[32:35]
	v_mfma_f32_16x16x32_bf16 v[20:23], v[182:185], v[214:217], v[20:23]
	v_mfma_f32_16x16x32_bf16 v[16:19], v[190:193], v[214:217], v[16:19]
	v_mfma_f32_16x16x32_bf16 v[4:7], v[182:185], v[222:225], v[4:7]
	v_mfma_f32_16x16x32_bf16 v[0:3], v[190:193], v[222:225], v[0:3]
	v_mfma_f32_16x16x32_bf16 v[52:55], v[186:189], v[202:205], v[52:55]
	v_mfma_f32_16x16x32_bf16 v[48:51], v[194:197], v[202:205], v[48:51]
	v_mfma_f32_16x16x32_bf16 v[36:39], v[186:189], v[210:213], v[36:39]
	v_mfma_f32_16x16x32_bf16 v[32:35], v[194:197], v[210:213], v[32:35]
	v_mfma_f32_16x16x32_bf16 v[20:23], v[186:189], v[218:221], v[20:23]
	v_mfma_f32_16x16x32_bf16 v[16:19], v[194:197], v[218:221], v[16:19]
	v_mfma_f32_16x16x32_bf16 v[4:7], v[186:189], v[226:229], v[4:7]
	v_mfma_f32_16x16x32_bf16 v[0:3], v[194:197], v[226:229], v[0:3]
	s_add_i32 s54, s54, 2
	s_add_u32 s14, s14, 0x100
	s_addc_u32 s15, s15, 0
	s_add_u32 s23, s23, 0x100
	s_addc_u32 s25, s25, 0
	s_cmp_gt_u32 s54, 13
	s_barrier
	s_cbranch_scc0 .LBB0_3179
	s_and_b64 vcc, exec, s[18:19]
	s_cbranch_vccz .LBB0_3182
	s_barrier

.LBB0_3534:
	ds_read_b128 v[128:131], v188
	ds_read_b128 v[132:135], v189
	ds_read_b128 v[136:139], v190
	ds_read_b128 v[140:143], v191
	ds_read_b128 v[166:169], v192
	ds_read_b128 v[170:173], v193
	ds_read_b128 v[174:177], v194
	ds_read_b128 v[178:181], v195
	s_add_u32 s34, s30, 0x100
	s_addc_u32 s35, s31, 0
	s_cmp_eq_u32 s68, 12
	s_cselect_b32 s39, s4, s35
	s_cselect_b32 s38, s5, s34
	s_cselect_b32 s37, s21, s67
	s_cselect_b32 s36, s23, s66
	s_mov_b32 m0, s55
	ds_read_b128 v[182:185], v149
	ds_read_b128 v[206:209], v149 offset:1024
	ds_read_b128 v[210:213], v149 offset:2048
	ds_read_b128 v[214:217], v149 offset:3072
	ds_read_b128 v[218:221], v149 offset:4096
	ds_read_b128 v[222:225], v149 offset:5120
	ds_read_b128 v[226:229], v149 offset:6144
	ds_read_b128 v[230:233], v149 offset:7168
	global_load_lds_dwordx4 v158, s[30:31]
	s_mov_b32 m0, s60
	s_nop 0
	global_load_lds_dwordx4 v160, s[30:31]
	s_waitcnt vmcnt(8)
	s_waitcnt lgkmcnt(0)
	s_barrier
	v_mfma_f32_16x16x32_bf16 v[124:127], v[128:131], v[182:185], v[124:127]
	v_mfma_f32_16x16x32_bf16 v[120:123], v[136:139], v[182:185], v[120:123]
	v_mfma_f32_16x16x32_bf16 v[108:111], v[128:131], v[210:213], v[108:111]
	v_mfma_f32_16x16x32_bf16 v[104:107], v[136:139], v[210:213], v[104:107]
	v_mfma_f32_16x16x32_bf16 v[92:95], v[128:131], v[218:221], v[92:95]
	v_mfma_f32_16x16x32_bf16 v[88:91], v[136:139], v[218:221], v[88:91]
	v_mfma_f32_16x16x32_bf16 v[76:79], v[128:131], v[226:229], v[76:79]
	v_mfma_f32_16x16x32_bf16 v[72:75], v[136:139], v[226:229], v[72:75]
	v_mfma_f32_16x16x32_bf16 v[124:127], v[132:135], v[206:209], v[124:127]
	v_mfma_f32_16x16x32_bf16 v[120:123], v[140:143], v[206:209], v[120:123]
	v_mfma_f32_16x16x32_bf16 v[108:111], v[132:135], v[214:217], v[108:111]
	v_mfma_f32_16x16x32_bf16 v[104:107], v[140:143], v[214:217], v[104:107]
	v_mfma_f32_16x16x32_bf16 v[92:95], v[132:135], v[222:225], v[92:95]
	v_mfma_f32_16x16x32_bf16 v[88:91], v[140:143], v[222:225], v[88:91]
	v_mfma_f32_16x16x32_bf16 v[76:79], v[132:135], v[230:233], v[76:79]
	v_mfma_f32_16x16x32_bf16 v[72:75], v[140:143], v[230:233], v[72:75]
	v_mfma_f32_16x16x32_bf16 v[116:119], v[166:169], v[182:185], v[116:119]
	v_mfma_f32_16x16x32_bf16 v[112:115], v[174:177], v[182:185], v[112:115]
	v_mfma_f32_16x16x32_bf16 v[100:103], v[166:169], v[210:213], v[100:103]
	v_mfma_f32_16x16x32_bf16 v[96:99], v[174:177], v[210:213], v[96:99]
	v_mfma_f32_16x16x32_bf16 v[84:87], v[166:169], v[218:221], v[84:87]
	v_mfma_f32_16x16x32_bf16 v[80:83], v[174:177], v[218:221], v[80:83]
	v_mfma_f32_16x16x32_bf16 v[68:71], v[166:169], v[226:229], v[68:71]
	v_mfma_f32_16x16x32_bf16 v[64:67], v[174:177], v[226:229], v[64:67]
	v_mfma_f32_16x16x32_bf16 v[116:119], v[170:173], v[206:209], v[116:119]
	v_mfma_f32_16x16x32_bf16 v[112:115], v[178:181], v[206:209], v[112:115]
	v_mfma_f32_16x16x32_bf16 v[100:103], v[170:173], v[214:217], v[100:103]
	v_mfma_f32_16x16x32_bf16 v[96:99], v[178:181], v[214:217], v[96:99]
	v_mfma_f32_16x16x32_bf16 v[84:87], v[170:173], v[222:225], v[84:87]
	v_mfma_f32_16x16x32_bf16 v[80:83], v[178:181], v[222:225], v[80:83]
	v_mfma_f32_16x16x32_bf16 v[68:71], v[170:173], v[230:233], v[68:71]
	v_mfma_f32_16x16x32_bf16 v[64:67], v[178:181], v[230:233], v[64:67]
	s_add_u32 s98, s36, s14
	s_addc_u32 s99, s37, s15
	s_add_u32 s100, s38, s14
	s_addc_u32 s101, s39, s15
	s_barrier
	s_mov_b32 m0, s29
	s_add_u32 s30, s36, 0x40000
	ds_read_b128 v[182:185], v149 offset:16384
	ds_read_b128 v[206:209], v149 offset:17408
	ds_read_b128 v[210:213], v149 offset:18432
	ds_read_b128 v[214:217], v149 offset:19456
	ds_read_b128 v[218:221], v149 offset:20480
	ds_read_b128 v[222:225], v149 offset:21504
	ds_read_b128 v[226:229], v149 offset:22528
	ds_read_b128 v[230:233], v149 offset:23552
	global_load_lds_dwordx4 v154, s[36:37]
	s_mov_b32 m0, s33
	s_addc_u32 s31, s37, 0
	global_load_lds_dwordx4 v156, s[36:37]
	s_mov_b32 m0, s40
	s_nop 0
	global_load_lds_dwordx4 v154, s[30:31]
	s_mov_b32 m0, s41
	s_nop 0
	global_load_lds_dwordx4 v156, s[30:31]
	s_mov_b32 m0, s19
	s_nop 0
	global_load_lds_dwordx4 v154, s[38:39]
	s_mov_b32 m0, s42
	s_nop 0
	global_load_lds_dwordx4 v156, s[38:39]
	s_waitcnt vmcnt(8)
	s_waitcnt lgkmcnt(0)
	s_barrier
	v_mfma_f32_16x16x32_bf16 v[60:63], v[128:131], v[182:185], v[60:63]
	v_mfma_f32_16x16x32_bf16 v[56:59], v[136:139], v[182:185], v[56:59]
	v_mfma_f32_16x16x32_bf16 v[44:47], v[128:131], v[210:213], v[44:47]
	v_mfma_f32_16x16x32_bf16 v[40:43], v[136:139], v[210:213], v[40:43]
	v_mfma_f32_16x16x32_bf16 v[28:31], v[128:131], v[218:221], v[28:31]
	v_mfma_f32_16x16x32_bf16 v[24:27], v[136:139], v[218:221], v[24:27]
	v_mfma_f32_16x16x32_bf16 v[12:15], v[128:131], v[226:229], v[12:15]
	v_mfma_f32_16x16x32_bf16 v[8:11], v[136:139], v[226:229], v[8:11]
	v_mfma_f32_16x16x32_bf16 v[60:63], v[132:135], v[206:209], v[60:63]
	v_mfma_f32_16x16x32_bf16 v[56:59], v[140:143], v[206:209], v[56:59]
	v_mfma_f32_16x16x32_bf16 v[44:47], v[132:135], v[214:217], v[44:47]
	v_mfma_f32_16x16x32_bf16 v[40:43], v[140:143], v[214:217], v[40:43]
	v_mfma_f32_16x16x32_bf16 v[28:31], v[132:135], v[222:225], v[28:31]
	v_mfma_f32_16x16x32_bf16 v[24:27], v[140:143], v[222:225], v[24:27]
	v_mfma_f32_16x16x32_bf16 v[12:15], v[132:135], v[230:233], v[12:15]
	v_mfma_f32_16x16x32_bf16 v[8:11], v[140:143], v[230:233], v[8:11]
	v_mfma_f32_16x16x32_bf16 v[52:55], v[166:169], v[182:185], v[52:55]
	v_mfma_f32_16x16x32_bf16 v[48:51], v[174:177], v[182:185], v[48:51]
	v_mfma_f32_16x16x32_bf16 v[36:39], v[166:169], v[210:213], v[36:39]
	v_mfma_f32_16x16x32_bf16 v[32:35], v[174:177], v[210:213], v[32:35]
	v_mfma_f32_16x16x32_bf16 v[20:23], v[166:169], v[218:221], v[20:23]
	v_mfma_f32_16x16x32_bf16 v[16:19], v[174:177], v[218:221], v[16:19]
	v_mfma_f32_16x16x32_bf16 v[4:7], v[166:169], v[226:229], v[4:7]
	v_mfma_f32_16x16x32_bf16 v[0:3], v[174:177], v[226:229], v[0:3]
	v_mfma_f32_16x16x32_bf16 v[52:55], v[170:173], v[206:209], v[52:55]
	v_mfma_f32_16x16x32_bf16 v[48:51], v[178:181], v[206:209], v[48:51]
	v_mfma_f32_16x16x32_bf16 v[36:39], v[170:173], v[214:217], v[36:39]
	v_mfma_f32_16x16x32_bf16 v[32:35], v[178:181], v[214:217], v[32:35]
	v_mfma_f32_16x16x32_bf16 v[20:23], v[170:173], v[222:225], v[20:23]
	v_mfma_f32_16x16x32_bf16 v[16:19], v[178:181], v[222:225], v[16:19]
	v_mfma_f32_16x16x32_bf16 v[4:7], v[170:173], v[230:233], v[4:7]
	v_mfma_f32_16x16x32_bf16 v[0:3], v[178:181], v[230:233], v[0:3]
	s_barrier
	ds_read_b128 v[128:131], v196
	ds_read_b128 v[132:135], v197
	ds_read_b128 v[136:139], v198
	ds_read_b128 v[140:143], v199
	ds_read_b128 v[166:169], v200
	ds_read_b128 v[170:173], v201
	ds_read_b128 v[174:177], v202
	ds_read_b128 v[178:181], v203
	s_add_u32 s30, s38, 0x40000
	s_addc_u32 s31, s39, 0
	s_mov_b32 m0, s43
	ds_read_b128 v[182:185], v149 offset:32768
	ds_read_b128 v[206:209], v149 offset:33792
	ds_read_b128 v[210:213], v149 offset:34816
	ds_read_b128 v[214:217], v149 offset:35840
	ds_read_b128 v[218:221], v149 offset:36864
	ds_read_b128 v[222:225], v149 offset:37888
	ds_read_b128 v[226:229], v149 offset:38912
	ds_read_b128 v[230:233], v149 offset:39936
	global_load_lds_dwordx4 v154, s[30:31]
	s_mov_b32 m0, s44
	s_nop 0
	global_load_lds_dwordx4 v156, s[30:31]
	s_waitcnt vmcnt(8)
	s_waitcnt lgkmcnt(0)
	s_barrier
	v_mfma_f32_16x16x32_bf16 v[124:127], v[128:131], v[182:185], v[124:127]
	v_mfma_f32_16x16x32_bf16 v[120:123], v[136:139], v[182:185], v[120:123]
	v_mfma_f32_16x16x32_bf16 v[108:111], v[128:131], v[210:213], v[108:111]
	v_mfma_f32_16x16x32_bf16 v[104:107], v[136:139], v[210:213], v[104:107]
	v_mfma_f32_16x16x32_bf16 v[92:95], v[128:131], v[218:221], v[92:95]
	v_mfma_f32_16x16x32_bf16 v[88:91], v[136:139], v[218:221], v[88:91]
	v_mfma_f32_16x16x32_bf16 v[76:79], v[128:131], v[226:229], v[76:79]
	v_mfma_f32_16x16x32_bf16 v[72:75], v[136:139], v[226:229], v[72:75]
	v_mfma_f32_16x16x32_bf16 v[124:127], v[132:135], v[206:209], v[124:127]
	v_mfma_f32_16x16x32_bf16 v[120:123], v[140:143], v[206:209], v[120:123]
	v_mfma_f32_16x16x32_bf16 v[108:111], v[132:135], v[214:217], v[108:111]
	v_mfma_f32_16x16x32_bf16 v[104:107], v[140:143], v[214:217], v[104:107]
	v_mfma_f32_16x16x32_bf16 v[92:95], v[132:135], v[222:225], v[92:95]
	v_mfma_f32_16x16x32_bf16 v[88:91], v[140:143], v[222:225], v[88:91]
	v_mfma_f32_16x16x32_bf16 v[76:79], v[132:135], v[230:233], v[76:79]
	v_mfma_f32_16x16x32_bf16 v[72:75], v[140:143], v[230:233], v[72:75]
	v_mfma_f32_16x16x32_bf16 v[116:119], v[166:169], v[182:185], v[116:119]
	v_mfma_f32_16x16x32_bf16 v[112:115], v[174:177], v[182:185], v[112:115]
	v_mfma_f32_16x16x32_bf16 v[100:103], v[166:169], v[210:213], v[100:103]
	v_mfma_f32_16x16x32_bf16 v[96:99], v[174:177], v[210:213], v[96:99]
	v_mfma_f32_16x16x32_bf16 v[84:87], v[166:169], v[218:221], v[84:87]
	v_mfma_f32_16x16x32_bf16 v[80:83], v[174:177], v[218:221], v[80:83]
	v_mfma_f32_16x16x32_bf16 v[68:71], v[166:169], v[226:229], v[68:71]
	v_mfma_f32_16x16x32_bf16 v[64:67], v[174:177], v[226:229], v[64:67]
	v_mfma_f32_16x16x32_bf16 v[116:119], v[170:173], v[206:209], v[116:119]
	v_mfma_f32_16x16x32_bf16 v[112:115], v[178:181], v[206:209], v[112:115]
	v_mfma_f32_16x16x32_bf16 v[100:103], v[170:173], v[214:217], v[100:103]
	v_mfma_f32_16x16x32_bf16 v[96:99], v[178:181], v[214:217], v[96:99]
	v_mfma_f32_16x16x32_bf16 v[84:87], v[170:173], v[222:225], v[84:87]
	v_mfma_f32_16x16x32_bf16 v[80:83], v[178:181], v[222:225], v[80:83]
	v_mfma_f32_16x16x32_bf16 v[68:71], v[170:173], v[230:233], v[68:71]
	v_mfma_f32_16x16x32_bf16 v[64:67], v[178:181], v[230:233], v[64:67]
	s_barrier
	s_mov_b32 m0, s45
	s_add_u32 s30, s36, 0x40080
	ds_read_b128 v[182:185], v149 offset:49152
	ds_read_b128 v[206:209], v149 offset:50176
	ds_read_b128 v[210:213], v149 offset:51200
	ds_read_b128 v[214:217], v149 offset:52224
	ds_read_b128 v[218:221], v149 offset:53248
	ds_read_b128 v[222:225], v149 offset:54272
	ds_read_b128 v[226:229], v149 offset:55296
	ds_read_b128 v[230:233], v149 offset:56320
	global_load_lds_dwordx4 v154, s[98:99]
	s_mov_b32 m0, s46
	s_addc_u32 s31, s37, 0
	global_load_lds_dwordx4 v156, s[98:99]
	s_mov_b32 m0, s49
	s_nop 0
	global_load_lds_dwordx4 v154, s[30:31]
	s_mov_b32 m0, s50
	s_nop 0
	global_load_lds_dwordx4 v156, s[30:31]
	s_mov_b32 m0, s47
	s_nop 0
	global_load_lds_dwordx4 v154, s[100:101]
	s_mov_b32 m0, s48
	s_nop 0
	global_load_lds_dwordx4 v156, s[100:101]
	s_waitcnt vmcnt(8)
	s_waitcnt lgkmcnt(0)
	s_barrier
	v_mfma_f32_16x16x32_bf16 v[60:63], v[128:131], v[182:185], v[60:63]
	v_mfma_f32_16x16x32_bf16 v[56:59], v[136:139], v[182:185], v[56:59]
	v_mfma_f32_16x16x32_bf16 v[44:47], v[128:131], v[210:213], v[44:47]
	v_mfma_f32_16x16x32_bf16 v[40:43], v[136:139], v[210:213], v[40:43]
	v_mfma_f32_16x16x32_bf16 v[28:31], v[128:131], v[218:221], v[28:31]
	v_mfma_f32_16x16x32_bf16 v[24:27], v[136:139], v[218:221], v[24:27]
	v_mfma_f32_16x16x32_bf16 v[12:15], v[128:131], v[226:229], v[12:15]
	v_mfma_f32_16x16x32_bf16 v[8:11], v[136:139], v[226:229], v[8:11]
	v_mfma_f32_16x16x32_bf16 v[60:63], v[132:135], v[206:209], v[60:63]
	v_mfma_f32_16x16x32_bf16 v[56:59], v[140:143], v[206:209], v[56:59]
	v_mfma_f32_16x16x32_bf16 v[44:47], v[132:135], v[214:217], v[44:47]
	v_mfma_f32_16x16x32_bf16 v[40:43], v[140:143], v[214:217], v[40:43]
	v_mfma_f32_16x16x32_bf16 v[28:31], v[132:135], v[222:225], v[28:31]
	v_mfma_f32_16x16x32_bf16 v[24:27], v[140:143], v[222:225], v[24:27]
	v_mfma_f32_16x16x32_bf16 v[12:15], v[132:135], v[230:233], v[12:15]
	v_mfma_f32_16x16x32_bf16 v[8:11], v[140:143], v[230:233], v[8:11]
	v_mfma_f32_16x16x32_bf16 v[52:55], v[166:169], v[182:185], v[52:55]
	v_mfma_f32_16x16x32_bf16 v[48:51], v[174:177], v[182:185], v[48:51]
	v_mfma_f32_16x16x32_bf16 v[36:39], v[166:169], v[210:213], v[36:39]
	v_mfma_f32_16x16x32_bf16 v[32:35], v[174:177], v[210:213], v[32:35]
	v_mfma_f32_16x16x32_bf16 v[20:23], v[166:169], v[218:221], v[20:23]
	v_mfma_f32_16x16x32_bf16 v[16:19], v[174:177], v[218:221], v[16:19]
	v_mfma_f32_16x16x32_bf16 v[4:7], v[166:169], v[226:229], v[4:7]
	v_mfma_f32_16x16x32_bf16 v[0:3], v[174:177], v[226:229], v[0:3]
	v_mfma_f32_16x16x32_bf16 v[52:55], v[170:173], v[206:209], v[52:55]
	v_mfma_f32_16x16x32_bf16 v[48:51], v[178:181], v[206:209], v[48:51]
	v_mfma_f32_16x16x32_bf16 v[36:39], v[170:173], v[214:217], v[36:39]
	v_mfma_f32_16x16x32_bf16 v[32:35], v[178:181], v[214:217], v[32:35]
	v_mfma_f32_16x16x32_bf16 v[20:23], v[170:173], v[222:225], v[20:23]
	v_mfma_f32_16x16x32_bf16 v[16:19], v[178:181], v[222:225], v[16:19]
	v_mfma_f32_16x16x32_bf16 v[4:7], v[170:173], v[230:233], v[4:7]
	v_mfma_f32_16x16x32_bf16 v[0:3], v[178:181], v[230:233], v[0:3]
	s_add_i32 s68, s68, 2
	s_add_u32 s66, s66, 0x100
	s_addc_u32 s67, s67, 0
	s_cmp_gt_u32 s68, 13
	s_mov_b64 s[30:31], s[34:35]
	s_barrier
	s_cbranch_scc0 .LBB0_3534
	s_and_b64 vcc, exec, s[16:17]
	s_cbranch_vccz .LBB0_3537
	s_barrier

.LBB0_3663:
	ds_read_b128 v[164:167], v143
	ds_read_b128 v[168:171], v147
	ds_read_b128 v[172:175], v148
	ds_read_b128 v[176:179], v149
	ds_read_b128 v[180:183], v151
	ds_read_b128 v[184:187], v153
	ds_read_b128 v[188:191], v154
	ds_read_b128 v[192:195], v155
	s_add_u32 s24, s22, 0xfffc0080
	s_addc_u32 s25, s23, -1
	s_cmp_eq_u32 s53, 12
	s_cselect_b32 s27, s4, s25
	s_cselect_b32 s26, s5, s24
	s_cselect_b32 s25, s13, s52
	s_cselect_b32 s24, s15, s51
	s_mov_b32 m0, s47
	ds_read_b128 v[196:199], v141
	ds_read_b128 v[200:203], v141 offset:1024
	ds_read_b128 v[204:207], v141 offset:2048
	ds_read_b128 v[208:211], v141 offset:3072
	ds_read_b128 v[212:215], v141 offset:4096
	ds_read_b128 v[216:219], v141 offset:5120
	ds_read_b128 v[220:223], v141 offset:6144
	ds_read_b128 v[224:227], v141 offset:7168
	global_load_lds_dwordx4 v132, s[22:23]
	s_mov_b32 m0, s48
	s_nop 0
	global_load_lds_dwordx4 v134, s[22:23]
	s_waitcnt vmcnt(8)
	s_waitcnt lgkmcnt(0)
	s_barrier
	v_mfma_f32_16x16x32_bf16 v[124:127], v[164:167], v[196:199], v[124:127]
	v_mfma_f32_16x16x32_bf16 v[120:123], v[172:175], v[196:199], v[120:123]
	v_mfma_f32_16x16x32_bf16 v[108:111], v[164:167], v[204:207], v[108:111]
	v_mfma_f32_16x16x32_bf16 v[104:107], v[172:175], v[204:207], v[104:107]
	v_mfma_f32_16x16x32_bf16 v[92:95], v[164:167], v[212:215], v[92:95]
	v_mfma_f32_16x16x32_bf16 v[88:91], v[172:175], v[212:215], v[88:91]
	v_mfma_f32_16x16x32_bf16 v[76:79], v[164:167], v[220:223], v[76:79]
	v_mfma_f32_16x16x32_bf16 v[72:75], v[172:175], v[220:223], v[72:75]
	v_mfma_f32_16x16x32_bf16 v[124:127], v[168:171], v[200:203], v[124:127]
	v_mfma_f32_16x16x32_bf16 v[120:123], v[176:179], v[200:203], v[120:123]
	v_mfma_f32_16x16x32_bf16 v[108:111], v[168:171], v[208:211], v[108:111]
	v_mfma_f32_16x16x32_bf16 v[104:107], v[176:179], v[208:211], v[104:107]
	v_mfma_f32_16x16x32_bf16 v[92:95], v[168:171], v[216:219], v[92:95]
	v_mfma_f32_16x16x32_bf16 v[88:91], v[176:179], v[216:219], v[88:91]
	v_mfma_f32_16x16x32_bf16 v[76:79], v[168:171], v[224:227], v[76:79]
	v_mfma_f32_16x16x32_bf16 v[72:75], v[176:179], v[224:227], v[72:75]
	v_mfma_f32_16x16x32_bf16 v[116:119], v[180:183], v[196:199], v[116:119]
	v_mfma_f32_16x16x32_bf16 v[112:115], v[188:191], v[196:199], v[112:115]
	v_mfma_f32_16x16x32_bf16 v[100:103], v[180:183], v[204:207], v[100:103]
	v_mfma_f32_16x16x32_bf16 v[96:99], v[188:191], v[204:207], v[96:99]
	v_mfma_f32_16x16x32_bf16 v[84:87], v[180:183], v[212:215], v[84:87]
	v_mfma_f32_16x16x32_bf16 v[80:83], v[188:191], v[212:215], v[80:83]
	v_mfma_f32_16x16x32_bf16 v[68:71], v[180:183], v[220:223], v[68:71]
	v_mfma_f32_16x16x32_bf16 v[64:67], v[188:191], v[220:223], v[64:67]
	v_mfma_f32_16x16x32_bf16 v[116:119], v[184:187], v[200:203], v[116:119]
	v_mfma_f32_16x16x32_bf16 v[112:115], v[192:195], v[200:203], v[112:115]
	v_mfma_f32_16x16x32_bf16 v[100:103], v[184:187], v[208:211], v[100:103]
	v_mfma_f32_16x16x32_bf16 v[96:99], v[192:195], v[208:211], v[96:99]
	v_mfma_f32_16x16x32_bf16 v[84:87], v[184:187], v[216:219], v[84:87]
	v_mfma_f32_16x16x32_bf16 v[80:83], v[192:195], v[216:219], v[80:83]
	v_mfma_f32_16x16x32_bf16 v[68:71], v[184:187], v[224:227], v[68:71]
	v_mfma_f32_16x16x32_bf16 v[64:67], v[192:195], v[224:227], v[64:67]
	s_add_u32 s98, s24, s8
	s_addc_u32 s99, s25, s9
	s_add_u32 s100, s26, s8
	s_addc_u32 s101, s27, s9
	s_barrier
	s_mov_b32 m0, s21
	s_add_u32 s54, s24, 0x40000
	ds_read_b128 v[196:199], v141 offset:16384
	ds_read_b128 v[200:203], v141 offset:17408
	ds_read_b128 v[204:207], v141 offset:18432
	ds_read_b128 v[208:211], v141 offset:19456
	ds_read_b128 v[212:215], v141 offset:20480
	ds_read_b128 v[216:219], v141 offset:21504
	ds_read_b128 v[220:223], v141 offset:22528
	ds_read_b128 v[224:227], v141 offset:23552
	global_load_lds_dwordx4 v130, s[24:25]
	s_mov_b32 m0, s30
	s_addc_u32 s55, s25, 0
	global_load_lds_dwordx4 v128, s[24:25]
	s_mov_b32 m0, s31
	s_nop 0
	global_load_lds_dwordx4 v130, s[54:55]
	s_mov_b32 m0, s33
	s_nop 0
	global_load_lds_dwordx4 v128, s[54:55]
	s_mov_b32 m0, s2
	s_nop 0
	global_load_lds_dwordx4 v130, s[26:27]
	s_mov_b32 m0, s34
	s_nop 0
	global_load_lds_dwordx4 v128, s[26:27]
	s_waitcnt vmcnt(8)
	s_waitcnt lgkmcnt(0)
	s_barrier
	v_mfma_f32_16x16x32_bf16 v[60:63], v[164:167], v[196:199], v[60:63]
	v_mfma_f32_16x16x32_bf16 v[56:59], v[172:175], v[196:199], v[56:59]
	v_mfma_f32_16x16x32_bf16 v[44:47], v[164:167], v[204:207], v[44:47]
	v_mfma_f32_16x16x32_bf16 v[40:43], v[172:175], v[204:207], v[40:43]
	v_mfma_f32_16x16x32_bf16 v[28:31], v[164:167], v[212:215], v[28:31]
	v_mfma_f32_16x16x32_bf16 v[24:27], v[172:175], v[212:215], v[24:27]
	v_mfma_f32_16x16x32_bf16 v[12:15], v[164:167], v[220:223], v[12:15]
	v_mfma_f32_16x16x32_bf16 v[8:11], v[172:175], v[220:223], v[8:11]
	v_mfma_f32_16x16x32_bf16 v[60:63], v[168:171], v[200:203], v[60:63]
	v_mfma_f32_16x16x32_bf16 v[56:59], v[176:179], v[200:203], v[56:59]
	v_mfma_f32_16x16x32_bf16 v[44:47], v[168:171], v[208:211], v[44:47]
	v_mfma_f32_16x16x32_bf16 v[40:43], v[176:179], v[208:211], v[40:43]
	v_mfma_f32_16x16x32_bf16 v[28:31], v[168:171], v[216:219], v[28:31]
	v_mfma_f32_16x16x32_bf16 v[24:27], v[176:179], v[216:219], v[24:27]
	v_mfma_f32_16x16x32_bf16 v[12:15], v[168:171], v[224:227], v[12:15]
	v_mfma_f32_16x16x32_bf16 v[8:11], v[176:179], v[224:227], v[8:11]
	v_mfma_f32_16x16x32_bf16 v[52:55], v[180:183], v[196:199], v[52:55]
	v_mfma_f32_16x16x32_bf16 v[48:51], v[188:191], v[196:199], v[48:51]
	v_mfma_f32_16x16x32_bf16 v[36:39], v[180:183], v[204:207], v[36:39]
	v_mfma_f32_16x16x32_bf16 v[32:35], v[188:191], v[204:207], v[32:35]
	v_mfma_f32_16x16x32_bf16 v[20:23], v[180:183], v[212:215], v[20:23]
	v_mfma_f32_16x16x32_bf16 v[16:19], v[188:191], v[212:215], v[16:19]
	v_mfma_f32_16x16x32_bf16 v[4:7], v[180:183], v[220:223], v[4:7]
	v_mfma_f32_16x16x32_bf16 v[0:3], v[188:191], v[220:223], v[0:3]
	v_mfma_f32_16x16x32_bf16 v[52:55], v[184:187], v[200:203], v[52:55]
	v_mfma_f32_16x16x32_bf16 v[48:51], v[192:195], v[200:203], v[48:51]
	v_mfma_f32_16x16x32_bf16 v[36:39], v[184:187], v[208:211], v[36:39]
	v_mfma_f32_16x16x32_bf16 v[32:35], v[192:195], v[208:211], v[32:35]
	v_mfma_f32_16x16x32_bf16 v[20:23], v[184:187], v[216:219], v[20:23]
	v_mfma_f32_16x16x32_bf16 v[16:19], v[192:195], v[216:219], v[16:19]
	v_mfma_f32_16x16x32_bf16 v[4:7], v[184:187], v[224:227], v[4:7]
	v_mfma_f32_16x16x32_bf16 v[0:3], v[192:195], v[224:227], v[0:3]
	s_barrier
	ds_read_b128 v[164:167], v156
	ds_read_b128 v[168:171], v157
	ds_read_b128 v[172:175], v158
	ds_read_b128 v[176:179], v159
	ds_read_b128 v[180:183], v160
	ds_read_b128 v[184:187], v161
	ds_read_b128 v[188:191], v162
	ds_read_b128 v[192:195], v163
	s_add_u32 s26, s26, 0x40000
	s_addc_u32 s27, s27, 0
	s_mov_b32 m0, s35
	ds_read_b128 v[196:199], v141 offset:32768
	ds_read_b128 v[200:203], v141 offset:33792
	ds_read_b128 v[204:207], v141 offset:34816
	ds_read_b128 v[208:211], v141 offset:35840
	ds_read_b128 v[212:215], v141 offset:36864
	ds_read_b128 v[216:219], v141 offset:37888
	ds_read_b128 v[220:223], v141 offset:38912
	ds_read_b128 v[224:227], v141 offset:39936
	global_load_lds_dwordx4 v130, s[26:27]
	s_mov_b32 m0, s36
	s_nop 0
	global_load_lds_dwordx4 v128, s[26:27]
	s_waitcnt vmcnt(8)
	s_waitcnt lgkmcnt(0)
	s_barrier
	v_mfma_f32_16x16x32_bf16 v[124:127], v[164:167], v[196:199], v[124:127]
	v_mfma_f32_16x16x32_bf16 v[120:123], v[172:175], v[196:199], v[120:123]
	v_mfma_f32_16x16x32_bf16 v[108:111], v[164:167], v[204:207], v[108:111]
	v_mfma_f32_16x16x32_bf16 v[104:107], v[172:175], v[204:207], v[104:107]
	v_mfma_f32_16x16x32_bf16 v[92:95], v[164:167], v[212:215], v[92:95]
	v_mfma_f32_16x16x32_bf16 v[88:91], v[172:175], v[212:215], v[88:91]
	v_mfma_f32_16x16x32_bf16 v[76:79], v[164:167], v[220:223], v[76:79]
	v_mfma_f32_16x16x32_bf16 v[72:75], v[172:175], v[220:223], v[72:75]
	v_mfma_f32_16x16x32_bf16 v[124:127], v[168:171], v[200:203], v[124:127]
	v_mfma_f32_16x16x32_bf16 v[120:123], v[176:179], v[200:203], v[120:123]
	v_mfma_f32_16x16x32_bf16 v[108:111], v[168:171], v[208:211], v[108:111]
	v_mfma_f32_16x16x32_bf16 v[104:107], v[176:179], v[208:211], v[104:107]
	v_mfma_f32_16x16x32_bf16 v[92:95], v[168:171], v[216:219], v[92:95]
	v_mfma_f32_16x16x32_bf16 v[88:91], v[176:179], v[216:219], v[88:91]
	v_mfma_f32_16x16x32_bf16 v[76:79], v[168:171], v[224:227], v[76:79]
	v_mfma_f32_16x16x32_bf16 v[72:75], v[176:179], v[224:227], v[72:75]
	v_mfma_f32_16x16x32_bf16 v[116:119], v[180:183], v[196:199], v[116:119]
	v_mfma_f32_16x16x32_bf16 v[112:115], v[188:191], v[196:199], v[112:115]
	v_mfma_f32_16x16x32_bf16 v[100:103], v[180:183], v[204:207], v[100:103]
	v_mfma_f32_16x16x32_bf16 v[96:99], v[188:191], v[204:207], v[96:99]
	v_mfma_f32_16x16x32_bf16 v[84:87], v[180:183], v[212:215], v[84:87]
	v_mfma_f32_16x16x32_bf16 v[80:83], v[188:191], v[212:215], v[80:83]
	v_mfma_f32_16x16x32_bf16 v[68:71], v[180:183], v[220:223], v[68:71]
	v_mfma_f32_16x16x32_bf16 v[64:67], v[188:191], v[220:223], v[64:67]
	v_mfma_f32_16x16x32_bf16 v[116:119], v[184:187], v[200:203], v[116:119]
	v_mfma_f32_16x16x32_bf16 v[112:115], v[192:195], v[200:203], v[112:115]
	v_mfma_f32_16x16x32_bf16 v[100:103], v[184:187], v[208:211], v[100:103]
	v_mfma_f32_16x16x32_bf16 v[96:99], v[192:195], v[208:211], v[96:99]
	v_mfma_f32_16x16x32_bf16 v[84:87], v[184:187], v[216:219], v[84:87]
	v_mfma_f32_16x16x32_bf16 v[80:83], v[192:195], v[216:219], v[80:83]
	v_mfma_f32_16x16x32_bf16 v[68:71], v[184:187], v[224:227], v[68:71]
	v_mfma_f32_16x16x32_bf16 v[64:67], v[192:195], v[224:227], v[64:67]
	s_barrier
	s_mov_b32 m0, s39
	s_add_u32 s24, s24, 0x40080
	ds_read_b128 v[196:199], v141 offset:49152
	ds_read_b128 v[200:203], v141 offset:50176
	ds_read_b128 v[204:207], v141 offset:51200
	ds_read_b128 v[208:211], v141 offset:52224
	ds_read_b128 v[212:215], v141 offset:53248
	ds_read_b128 v[216:219], v141 offset:54272
	ds_read_b128 v[220:223], v141 offset:55296
	ds_read_b128 v[224:227], v141 offset:56320
	global_load_lds_dwordx4 v130, s[98:99]
	s_mov_b32 m0, s40
	s_addc_u32 s25, s25, 0
	global_load_lds_dwordx4 v128, s[98:99]
	s_mov_b32 m0, s43
	s_nop 0
	global_load_lds_dwordx4 v130, s[24:25]
	s_mov_b32 m0, s44
	s_nop 0
	global_load_lds_dwordx4 v128, s[24:25]
	s_mov_b32 m0, s41
	s_nop 0
	global_load_lds_dwordx4 v130, s[100:101]
	s_mov_b32 m0, s42
	s_nop 0
	global_load_lds_dwordx4 v128, s[100:101]
	s_waitcnt vmcnt(8)
	s_waitcnt lgkmcnt(0)
	s_barrier
	v_mfma_f32_16x16x32_bf16 v[60:63], v[164:167], v[196:199], v[60:63]
	v_mfma_f32_16x16x32_bf16 v[56:59], v[172:175], v[196:199], v[56:59]
	v_mfma_f32_16x16x32_bf16 v[44:47], v[164:167], v[204:207], v[44:47]
	v_mfma_f32_16x16x32_bf16 v[40:43], v[172:175], v[204:207], v[40:43]
	v_mfma_f32_16x16x32_bf16 v[28:31], v[164:167], v[212:215], v[28:31]
	v_mfma_f32_16x16x32_bf16 v[24:27], v[172:175], v[212:215], v[24:27]
	v_mfma_f32_16x16x32_bf16 v[12:15], v[164:167], v[220:223], v[12:15]
	v_mfma_f32_16x16x32_bf16 v[8:11], v[172:175], v[220:223], v[8:11]
	v_mfma_f32_16x16x32_bf16 v[60:63], v[168:171], v[200:203], v[60:63]
	v_mfma_f32_16x16x32_bf16 v[56:59], v[176:179], v[200:203], v[56:59]
	v_mfma_f32_16x16x32_bf16 v[44:47], v[168:171], v[208:211], v[44:47]
	v_mfma_f32_16x16x32_bf16 v[40:43], v[176:179], v[208:211], v[40:43]
	v_mfma_f32_16x16x32_bf16 v[28:31], v[168:171], v[216:219], v[28:31]
	v_mfma_f32_16x16x32_bf16 v[24:27], v[176:179], v[216:219], v[24:27]
	v_mfma_f32_16x16x32_bf16 v[12:15], v[168:171], v[224:227], v[12:15]
	v_mfma_f32_16x16x32_bf16 v[8:11], v[176:179], v[224:227], v[8:11]
	v_mfma_f32_16x16x32_bf16 v[52:55], v[180:183], v[196:199], v[52:55]
	v_mfma_f32_16x16x32_bf16 v[48:51], v[188:191], v[196:199], v[48:51]
	v_mfma_f32_16x16x32_bf16 v[36:39], v[180:183], v[204:207], v[36:39]
	v_mfma_f32_16x16x32_bf16 v[32:35], v[188:191], v[204:207], v[32:35]
	v_mfma_f32_16x16x32_bf16 v[20:23], v[180:183], v[212:215], v[20:23]
	v_mfma_f32_16x16x32_bf16 v[16:19], v[188:191], v[212:215], v[16:19]
	v_mfma_f32_16x16x32_bf16 v[4:7], v[180:183], v[220:223], v[4:7]
	v_mfma_f32_16x16x32_bf16 v[0:3], v[188:191], v[220:223], v[0:3]
	v_mfma_f32_16x16x32_bf16 v[52:55], v[184:187], v[200:203], v[52:55]
	v_mfma_f32_16x16x32_bf16 v[48:51], v[192:195], v[200:203], v[48:51]
	v_mfma_f32_16x16x32_bf16 v[36:39], v[184:187], v[208:211], v[36:39]
	v_mfma_f32_16x16x32_bf16 v[32:35], v[192:195], v[208:211], v[32:35]
	v_mfma_f32_16x16x32_bf16 v[20:23], v[184:187], v[216:219], v[20:23]
	v_mfma_f32_16x16x32_bf16 v[16:19], v[192:195], v[216:219], v[16:19]
	v_mfma_f32_16x16x32_bf16 v[4:7], v[184:187], v[224:227], v[4:7]
	v_mfma_f32_16x16x32_bf16 v[0:3], v[192:195], v[224:227], v[0:3]
	s_add_i32 s53, s53, 2
	s_add_u32 s22, s22, 0x100
	s_addc_u32 s23, s23, 0
	s_add_u32 s51, s51, 0x100
	s_addc_u32 s52, s52, 0
	s_cmp_gt_u32 s53, 13
	s_barrier
	s_cbranch_scc0 .LBB0_3663
	s_and_b64 vcc, exec, s[10:11]
	s_cbranch_vccz .LBB0_3666
	s_barrier

.LBB0_3743:
	ds_read_b128 v[128:131], v185
	ds_read_b128 v[132:135], v186
	ds_read_b128 v[136:139], v187
	ds_read_b128 v[140:143], v188
	ds_read_b128 v[162:165], v189
	ds_read_b128 v[166:169], v190
	ds_read_b128 v[170:173], v191
	ds_read_b128 v[174:177], v192
	s_add_u32 s26, s24, 0x100
	s_addc_u32 s27, s25, 0
	s_cmp_eq_u32 s60, 40
	s_cselect_b32 s31, s7, s27
	s_cselect_b32 s30, s6, s26
	s_cselect_b32 s29, s23, s59
	s_cselect_b32 s28, s22, s58
	s_mov_b32 m0, s48
	ds_read_b128 v[178:181], v153
	ds_read_b128 v[202:205], v153 offset:1024
	ds_read_b128 v[206:209], v153 offset:2048
	ds_read_b128 v[210:213], v153 offset:3072
	ds_read_b128 v[214:217], v153 offset:4096
	ds_read_b128 v[218:221], v153 offset:5120
	ds_read_b128 v[222:225], v153 offset:6144
	ds_read_b128 v[226:229], v153 offset:7168
	global_load_lds_dwordx4 v146, s[24:25]
	s_mov_b32 m0, s49
	s_nop 0
	global_load_lds_dwordx4 v156, s[24:25]
	s_waitcnt vmcnt(8)
	s_waitcnt lgkmcnt(0)
	s_barrier
	v_mfma_f32_16x16x32_bf16 v[124:127], v[128:131], v[178:181], v[124:127]
	v_mfma_f32_16x16x32_bf16 v[120:123], v[136:139], v[178:181], v[120:123]
	v_mfma_f32_16x16x32_bf16 v[108:111], v[128:131], v[206:209], v[108:111]
	v_mfma_f32_16x16x32_bf16 v[104:107], v[136:139], v[206:209], v[104:107]
	v_mfma_f32_16x16x32_bf16 v[92:95], v[128:131], v[214:217], v[92:95]
	v_mfma_f32_16x16x32_bf16 v[88:91], v[136:139], v[214:217], v[88:91]
	v_mfma_f32_16x16x32_bf16 v[76:79], v[128:131], v[222:225], v[76:79]
	v_mfma_f32_16x16x32_bf16 v[72:75], v[136:139], v[222:225], v[72:75]
	v_mfma_f32_16x16x32_bf16 v[124:127], v[132:135], v[202:205], v[124:127]
	v_mfma_f32_16x16x32_bf16 v[120:123], v[140:143], v[202:205], v[120:123]
	v_mfma_f32_16x16x32_bf16 v[108:111], v[132:135], v[210:213], v[108:111]
	v_mfma_f32_16x16x32_bf16 v[104:107], v[140:143], v[210:213], v[104:107]
	v_mfma_f32_16x16x32_bf16 v[92:95], v[132:135], v[218:221], v[92:95]
	v_mfma_f32_16x16x32_bf16 v[88:91], v[140:143], v[218:221], v[88:91]
	v_mfma_f32_16x16x32_bf16 v[76:79], v[132:135], v[226:229], v[76:79]
	v_mfma_f32_16x16x32_bf16 v[72:75], v[140:143], v[226:229], v[72:75]
	v_mfma_f32_16x16x32_bf16 v[116:119], v[162:165], v[178:181], v[116:119]
	v_mfma_f32_16x16x32_bf16 v[112:115], v[170:173], v[178:181], v[112:115]
	v_mfma_f32_16x16x32_bf16 v[100:103], v[162:165], v[206:209], v[100:103]
	v_mfma_f32_16x16x32_bf16 v[96:99], v[170:173], v[206:209], v[96:99]
	v_mfma_f32_16x16x32_bf16 v[84:87], v[162:165], v[214:217], v[84:87]
	v_mfma_f32_16x16x32_bf16 v[80:83], v[170:173], v[214:217], v[80:83]
	v_mfma_f32_16x16x32_bf16 v[68:71], v[162:165], v[222:225], v[68:71]
	v_mfma_f32_16x16x32_bf16 v[64:67], v[170:173], v[222:225], v[64:67]
	v_mfma_f32_16x16x32_bf16 v[116:119], v[166:169], v[202:205], v[116:119]
	v_mfma_f32_16x16x32_bf16 v[112:115], v[174:177], v[202:205], v[112:115]
	v_mfma_f32_16x16x32_bf16 v[100:103], v[166:169], v[210:213], v[100:103]
	v_mfma_f32_16x16x32_bf16 v[96:99], v[174:177], v[210:213], v[96:99]
	v_mfma_f32_16x16x32_bf16 v[84:87], v[166:169], v[218:221], v[84:87]
	v_mfma_f32_16x16x32_bf16 v[80:83], v[174:177], v[218:221], v[80:83]
	v_mfma_f32_16x16x32_bf16 v[68:71], v[166:169], v[226:229], v[68:71]
	v_mfma_f32_16x16x32_bf16 v[64:67], v[174:177], v[226:229], v[64:67]
	s_add_u32 s98, s28, s16
	s_addc_u32 s99, s29, s17
	s_add_u32 s100, s30, s16
	s_addc_u32 s101, s31, s17
	s_barrier
	s_mov_b32 m0, s5
	s_add_u32 s24, s28, 0xb0000
	ds_read_b128 v[178:181], v153 offset:16384
	ds_read_b128 v[202:205], v153 offset:17408
	ds_read_b128 v[206:209], v153 offset:18432
	ds_read_b128 v[210:213], v153 offset:19456
	ds_read_b128 v[214:217], v153 offset:20480
	ds_read_b128 v[218:221], v153 offset:21504
	ds_read_b128 v[222:225], v153 offset:22528
	ds_read_b128 v[226:229], v153 offset:23552
	global_load_lds_dwordx4 v148, s[28:29]
	s_mov_b32 m0, s21
	s_addc_u32 s25, s29, 0
	global_load_lds_dwordx4 v154, s[28:29]
	s_mov_b32 m0, s33
	s_nop 0
	global_load_lds_dwordx4 v148, s[24:25]
	s_mov_b32 m0, s34
	s_nop 0
	global_load_lds_dwordx4 v154, s[24:25]
	s_mov_b32 m0, s4
	s_nop 0
	global_load_lds_dwordx4 v148, s[30:31]
	s_mov_b32 m0, s35
	s_nop 0
	global_load_lds_dwordx4 v154, s[30:31]
	s_waitcnt vmcnt(8)
	s_waitcnt lgkmcnt(0)
	s_barrier
	v_mfma_f32_16x16x32_bf16 v[60:63], v[128:131], v[178:181], v[60:63]
	v_mfma_f32_16x16x32_bf16 v[56:59], v[136:139], v[178:181], v[56:59]
	v_mfma_f32_16x16x32_bf16 v[44:47], v[128:131], v[206:209], v[44:47]
	v_mfma_f32_16x16x32_bf16 v[40:43], v[136:139], v[206:209], v[40:43]
	v_mfma_f32_16x16x32_bf16 v[28:31], v[128:131], v[214:217], v[28:31]
	v_mfma_f32_16x16x32_bf16 v[24:27], v[136:139], v[214:217], v[24:27]
	v_mfma_f32_16x16x32_bf16 v[12:15], v[128:131], v[222:225], v[12:15]
	v_mfma_f32_16x16x32_bf16 v[8:11], v[136:139], v[222:225], v[8:11]
	v_mfma_f32_16x16x32_bf16 v[60:63], v[132:135], v[202:205], v[60:63]
	v_mfma_f32_16x16x32_bf16 v[56:59], v[140:143], v[202:205], v[56:59]
	v_mfma_f32_16x16x32_bf16 v[44:47], v[132:135], v[210:213], v[44:47]
	v_mfma_f32_16x16x32_bf16 v[40:43], v[140:143], v[210:213], v[40:43]
	v_mfma_f32_16x16x32_bf16 v[28:31], v[132:135], v[218:221], v[28:31]
	v_mfma_f32_16x16x32_bf16 v[24:27], v[140:143], v[218:221], v[24:27]
	v_mfma_f32_16x16x32_bf16 v[12:15], v[132:135], v[226:229], v[12:15]
	v_mfma_f32_16x16x32_bf16 v[8:11], v[140:143], v[226:229], v[8:11]
	v_mfma_f32_16x16x32_bf16 v[52:55], v[162:165], v[178:181], v[52:55]
	v_mfma_f32_16x16x32_bf16 v[48:51], v[170:173], v[178:181], v[48:51]
	v_mfma_f32_16x16x32_bf16 v[36:39], v[162:165], v[206:209], v[36:39]
	v_mfma_f32_16x16x32_bf16 v[32:35], v[170:173], v[206:209], v[32:35]
	v_mfma_f32_16x16x32_bf16 v[20:23], v[162:165], v[214:217], v[20:23]
	v_mfma_f32_16x16x32_bf16 v[16:19], v[170:173], v[214:217], v[16:19]
	v_mfma_f32_16x16x32_bf16 v[4:7], v[162:165], v[222:225], v[4:7]
	v_mfma_f32_16x16x32_bf16 v[0:3], v[170:173], v[222:225], v[0:3]
	v_mfma_f32_16x16x32_bf16 v[52:55], v[166:169], v[202:205], v[52:55]
	v_mfma_f32_16x16x32_bf16 v[48:51], v[174:177], v[202:205], v[48:51]
	v_mfma_f32_16x16x32_bf16 v[36:39], v[166:169], v[210:213], v[36:39]
	v_mfma_f32_16x16x32_bf16 v[32:35], v[174:177], v[210:213], v[32:35]
	v_mfma_f32_16x16x32_bf16 v[20:23], v[166:169], v[218:221], v[20:23]
	v_mfma_f32_16x16x32_bf16 v[16:19], v[174:177], v[218:221], v[16:19]
	v_mfma_f32_16x16x32_bf16 v[4:7], v[166:169], v[226:229], v[4:7]
	v_mfma_f32_16x16x32_bf16 v[0:3], v[174:177], v[226:229], v[0:3]
	s_barrier
	ds_read_b128 v[128:131], v193
	ds_read_b128 v[132:135], v194
	ds_read_b128 v[136:139], v195
	ds_read_b128 v[140:143], v196
	ds_read_b128 v[162:165], v197
	ds_read_b128 v[166:169], v198
	ds_read_b128 v[170:173], v199
	ds_read_b128 v[174:177], v200
	s_add_u32 s24, s30, 0xb0000
	s_addc_u32 s25, s31, 0
	s_mov_b32 m0, s36
	ds_read_b128 v[178:181], v153 offset:32768
	ds_read_b128 v[202:205], v153 offset:33792
	ds_read_b128 v[206:209], v153 offset:34816
	ds_read_b128 v[210:213], v153 offset:35840
	ds_read_b128 v[214:217], v153 offset:36864
	ds_read_b128 v[218:221], v153 offset:37888
	ds_read_b128 v[222:225], v153 offset:38912
	ds_read_b128 v[226:229], v153 offset:39936
	global_load_lds_dwordx4 v148, s[24:25]
	s_mov_b32 m0, s37
	s_nop 0
	global_load_lds_dwordx4 v154, s[24:25]
	s_waitcnt vmcnt(8)
	s_waitcnt lgkmcnt(0)
	s_barrier
	v_mfma_f32_16x16x32_bf16 v[124:127], v[128:131], v[178:181], v[124:127]
	v_mfma_f32_16x16x32_bf16 v[120:123], v[136:139], v[178:181], v[120:123]
	v_mfma_f32_16x16x32_bf16 v[108:111], v[128:131], v[206:209], v[108:111]
	v_mfma_f32_16x16x32_bf16 v[104:107], v[136:139], v[206:209], v[104:107]
	v_mfma_f32_16x16x32_bf16 v[92:95], v[128:131], v[214:217], v[92:95]
	v_mfma_f32_16x16x32_bf16 v[88:91], v[136:139], v[214:217], v[88:91]
	v_mfma_f32_16x16x32_bf16 v[76:79], v[128:131], v[222:225], v[76:79]
	v_mfma_f32_16x16x32_bf16 v[72:75], v[136:139], v[222:225], v[72:75]
	v_mfma_f32_16x16x32_bf16 v[124:127], v[132:135], v[202:205], v[124:127]
	v_mfma_f32_16x16x32_bf16 v[120:123], v[140:143], v[202:205], v[120:123]
	v_mfma_f32_16x16x32_bf16 v[108:111], v[132:135], v[210:213], v[108:111]
	v_mfma_f32_16x16x32_bf16 v[104:107], v[140:143], v[210:213], v[104:107]
	v_mfma_f32_16x16x32_bf16 v[92:95], v[132:135], v[218:221], v[92:95]
	v_mfma_f32_16x16x32_bf16 v[88:91], v[140:143], v[218:221], v[88:91]
	v_mfma_f32_16x16x32_bf16 v[76:79], v[132:135], v[226:229], v[76:79]
	v_mfma_f32_16x16x32_bf16 v[72:75], v[140:143], v[226:229], v[72:75]
	v_mfma_f32_16x16x32_bf16 v[116:119], v[162:165], v[178:181], v[116:119]
	v_mfma_f32_16x16x32_bf16 v[112:115], v[170:173], v[178:181], v[112:115]
	v_mfma_f32_16x16x32_bf16 v[100:103], v[162:165], v[206:209], v[100:103]
	v_mfma_f32_16x16x32_bf16 v[96:99], v[170:173], v[206:209], v[96:99]
	v_mfma_f32_16x16x32_bf16 v[84:87], v[162:165], v[214:217], v[84:87]
	v_mfma_f32_16x16x32_bf16 v[80:83], v[170:173], v[214:217], v[80:83]
	v_mfma_f32_16x16x32_bf16 v[68:71], v[162:165], v[222:225], v[68:71]
	v_mfma_f32_16x16x32_bf16 v[64:67], v[170:173], v[222:225], v[64:67]
	v_mfma_f32_16x16x32_bf16 v[116:119], v[166:169], v[202:205], v[116:119]
	v_mfma_f32_16x16x32_bf16 v[112:115], v[174:177], v[202:205], v[112:115]
	v_mfma_f32_16x16x32_bf16 v[100:103], v[166:169], v[210:213], v[100:103]
	v_mfma_f32_16x16x32_bf16 v[96:99], v[174:177], v[210:213], v[96:99]
	v_mfma_f32_16x16x32_bf16 v[84:87], v[166:169], v[218:221], v[84:87]
	v_mfma_f32_16x16x32_bf16 v[80:83], v[174:177], v[218:221], v[80:83]
	v_mfma_f32_16x16x32_bf16 v[68:71], v[166:169], v[226:229], v[68:71]
	v_mfma_f32_16x16x32_bf16 v[64:67], v[174:177], v[226:229], v[64:67]
	s_barrier
	s_mov_b32 m0, s38
	s_add_u32 s24, s28, 0xb0080
	ds_read_b128 v[178:181], v153 offset:49152
	ds_read_b128 v[202:205], v153 offset:50176
	ds_read_b128 v[206:209], v153 offset:51200
	ds_read_b128 v[210:213], v153 offset:52224
	ds_read_b128 v[214:217], v153 offset:53248
	ds_read_b128 v[218:221], v153 offset:54272
	ds_read_b128 v[222:225], v153 offset:55296
	ds_read_b128 v[226:229], v153 offset:56320
	global_load_lds_dwordx4 v148, s[98:99]
	s_mov_b32 m0, s39
	s_addc_u32 s25, s29, 0
	global_load_lds_dwordx4 v154, s[98:99]
	s_mov_b32 m0, s42
	s_nop 0
	global_load_lds_dwordx4 v148, s[24:25]
	s_mov_b32 m0, s43
	s_nop 0
	global_load_lds_dwordx4 v154, s[24:25]
	s_mov_b32 m0, s40
	s_nop 0
	global_load_lds_dwordx4 v148, s[100:101]
	s_mov_b32 m0, s41
	s_nop 0
	global_load_lds_dwordx4 v154, s[100:101]
	s_waitcnt vmcnt(8)
	s_waitcnt lgkmcnt(0)
	s_barrier
	v_mfma_f32_16x16x32_bf16 v[60:63], v[128:131], v[178:181], v[60:63]
	v_mfma_f32_16x16x32_bf16 v[56:59], v[136:139], v[178:181], v[56:59]
	v_mfma_f32_16x16x32_bf16 v[44:47], v[128:131], v[206:209], v[44:47]
	v_mfma_f32_16x16x32_bf16 v[40:43], v[136:139], v[206:209], v[40:43]
	v_mfma_f32_16x16x32_bf16 v[28:31], v[128:131], v[214:217], v[28:31]
	v_mfma_f32_16x16x32_bf16 v[24:27], v[136:139], v[214:217], v[24:27]
	v_mfma_f32_16x16x32_bf16 v[12:15], v[128:131], v[222:225], v[12:15]
	v_mfma_f32_16x16x32_bf16 v[8:11], v[136:139], v[222:225], v[8:11]
	v_mfma_f32_16x16x32_bf16 v[60:63], v[132:135], v[202:205], v[60:63]
	v_mfma_f32_16x16x32_bf16 v[56:59], v[140:143], v[202:205], v[56:59]
	v_mfma_f32_16x16x32_bf16 v[44:47], v[132:135], v[210:213], v[44:47]
	v_mfma_f32_16x16x32_bf16 v[40:43], v[140:143], v[210:213], v[40:43]
	v_mfma_f32_16x16x32_bf16 v[28:31], v[132:135], v[218:221], v[28:31]
	v_mfma_f32_16x16x32_bf16 v[24:27], v[140:143], v[218:221], v[24:27]
	v_mfma_f32_16x16x32_bf16 v[12:15], v[132:135], v[226:229], v[12:15]
	v_mfma_f32_16x16x32_bf16 v[8:11], v[140:143], v[226:229], v[8:11]
	v_mfma_f32_16x16x32_bf16 v[52:55], v[162:165], v[178:181], v[52:55]
	v_mfma_f32_16x16x32_bf16 v[48:51], v[170:173], v[178:181], v[48:51]
	v_mfma_f32_16x16x32_bf16 v[36:39], v[162:165], v[206:209], v[36:39]
	v_mfma_f32_16x16x32_bf16 v[32:35], v[170:173], v[206:209], v[32:35]
	v_mfma_f32_16x16x32_bf16 v[20:23], v[162:165], v[214:217], v[20:23]
	v_mfma_f32_16x16x32_bf16 v[16:19], v[170:173], v[214:217], v[16:19]
	v_mfma_f32_16x16x32_bf16 v[4:7], v[162:165], v[222:225], v[4:7]
	v_mfma_f32_16x16x32_bf16 v[0:3], v[170:173], v[222:225], v[0:3]
	v_mfma_f32_16x16x32_bf16 v[52:55], v[166:169], v[202:205], v[52:55]
	v_mfma_f32_16x16x32_bf16 v[48:51], v[174:177], v[202:205], v[48:51]
	v_mfma_f32_16x16x32_bf16 v[36:39], v[166:169], v[210:213], v[36:39]
	v_mfma_f32_16x16x32_bf16 v[32:35], v[174:177], v[210:213], v[32:35]
	v_mfma_f32_16x16x32_bf16 v[20:23], v[166:169], v[218:221], v[20:23]
	v_mfma_f32_16x16x32_bf16 v[16:19], v[174:177], v[218:221], v[16:19]
	v_mfma_f32_16x16x32_bf16 v[4:7], v[166:169], v[226:229], v[4:7]
	v_mfma_f32_16x16x32_bf16 v[0:3], v[174:177], v[226:229], v[0:3]
	s_add_i32 s60, s60, 2
	s_add_u32 s58, s58, 0x100
	s_addc_u32 s59, s59, 0
	s_cmp_gt_u32 s60, 41
	s_mov_b64 s[24:25], s[26:27]
	s_barrier
	s_cbranch_scc0 .LBB0_3743
	s_and_b64 vcc, exec, s[18:19]
	s_cbranch_vccz .LBB0_3746
	s_barrier
